# v035 with one static s_setprio 1 for waves 4-7 at kernel entry instead of the per-MMA-segment priority toggles in the GEMM loops
# speedup vs baseline: 1.0049x; 1.0049x over previous
; #define LAS __attribute__((address_space(3)))
; __global__ void __launch_bounds__(512) fwd_megakernel(Params p) {
;     extern __shared__ __attribute__((aligned(16))) unsigned char lds_raw[];
;     LAS unsigned char* lds = (LAS unsigned char*)lds_raw;
;     cg::grid_group grid = cg::this_grid();
;     const int G = gridDim.x, blk = blockIdx.x;
;     unsigned char* ws = p.ws;
;     ...
;     volatile LAS unsigned* xst = (volatile LAS unsigned*)(lds + 131072);
;     unsigned* barw = (unsigned*)ws;
;     if (threadIdx.x < 2) xst[threadIdx.x] = 0u;
;     if (blk == 0) for (int i = threadIdx.x; i < XCD_BAR_WORDS; i += 512) barw[i] = 0u;
_Z14fwd_megakernel6Params:
	s_load_dwordx4 s[28:31], s[0:1], 0xc0
	s_load_dword s3, s[0:1], 0xd0
	s_add_u32 s6, s0, 0xc8
	v_and_b32_e32 v162, 0x3ff, v0
	s_addc_u32 s7, s1, 0
	v_readfirstlane_b32 s4, v162
	s_nop 3
	s_cmpk_lt_u32 s4, 0x100
	s_cbranch_scc1 .Lprio_lo
	s_setprio 1
.Lprio_lo:
	v_cmp_gt_u32_e32 vcc, 2, v162
	s_waitcnt lgkmcnt(0)
	v_writelane_b32 v245, s3, 0
	s_and_saveexec_b64 s[4:5], vcc
	v_lshl_add_u32 v1, v162, 2, 0
	v_add_u32_e32 v1, 0x20000, v1
	v_mov_b32_e32 v2, 0
	ds_write_b32 v1, v2
	s_or_b64 exec, exec, s[4:5]
	s_load_dwordx16 s[36:51], s[0:1], 0x0
	s_load_dwordx16 s[52:67], s[0:1], 0x40
	s_cmp_lg_u32 s2, 0
	s_mov_b32 s8, 0
	s_cbranch_scc1 .LBB0_10
	v_sub_u32_e32 v1, 0xd7f, v162
	v_lshrrev_b32_e32 v2, 9, v1
	v_add_u32_e32 v1, 2, v2
	v_add_u32_e32 v163, 0x200, v162
	v_and_b32_e32 v3, 14, v1
	v_mov_b32_e32 v1, v2
	s_mov_b64 s[10:11], 0
	s_mov_b32 s9, 1
	v_mov_b32_e32 v5, 0
	s_mov_b32 s12, s8
	v_mov_b64_e32 v[6:7], v[162:163]
	s_branch .LBB0_5

; #define PG8_STAGE(bufoff, gbase, voff) do { _Pragma("unroll") for (int _i = 0; _i < 2; ++_i) \
;         __builtin_amdgcn_global_load_lds((const unsigned*)((const char*)(gbase) + (voff)[_i]), (LAS unsigned*)(lds + (bufoff) + ldsw + _i * 8192), 16, 0, 0); } while (0)
; #define PG8_LDA(dst, b, h) do { _Pragma("unroll") for (int m = 0; m < 4; ++m) _Pragma("unroll") for (int k = 0; k < 2; ++k) dst[m][k] = *(const LAS bf16x8*)(lds + PG8_SA(b, h) + aoff + m * 2048 + k * 1024); } while (0)
; #define PG8_LDB(dst, b, h) do { _Pragma("unroll") for (int n = 0; n < 2; ++n) _Pragma("unroll") for (int k = 0; k < 2; ++k) dst[n][k] = *(const LAS bf16x8*)(lds + PG8_SB(b, h) + boff + n * 2048 + k * 1024); } while (0)
; #define PG8_MMA(ai, bj, At, Bt) do { __builtin_amdgcn_s_setprio(1); _Pragma("unroll") for (int m = 0; m < 4; ++m) _Pragma("unroll") for (int n = 0; n < 2; ++n) _Pragma("unroll") for (int k = 0; k < 2; ++k) \
;         acc[ai][bj][m][n] = __builtin_amdgcn_mfma_f32_16x16x32_bf16(Bt[n][k], At[m][k], acc[ai][bj][m][n], 0, 0, 0); __builtin_amdgcn_s_setprio(0); } while (0)
; #define PG8_WAIT_V(n) asm volatile("s_waitcnt vmcnt(" #n ")" ::: "memory")
; #define PG8_WAIT_L(n) asm volatile("s_waitcnt lgkmcnt(" #n ")" ::: "memory")
; #define PG8_BAR __builtin_amdgcn_s_barrier()
; #define PG8_SCHED __builtin_amdgcn_sched_barrier(0)
; template <int GI>
; __device__ __forceinline__ void gemm_phase(LAS unsigned char* lds, unsigned char* ws, int G, int cblk) {
;     ...
;             PG8_LDB(B0, 0, 0); PG8_LDB(B1, 0, 1); PG8_SCHED; PG8_LDA(At, 0, 0); PG8_STAGE(PG8_SA(1, 1), a1 + hstepA, voffA);
;             PG8_WAIT_V(8); PG8_WAIT_L(0); PG8_BAR; PG8_MMA(0, 0, At, B0); PG8_MMA(0, 1, At, B1); PG8_BAR; PG8_SCHED;
;             PG8_LDA(At, 0, 1); PG8_STAGE(PG8_SB(0, 0), b2, voffB); PG8_STAGE(PG8_SB(0, 1), b2 + hstepB, voffB); PG8_STAGE(PG8_SA(0, 0), a2, voffA);
;             PG8_WAIT_V(8); PG8_WAIT_L(0); PG8_BAR; PG8_MMA(1, 0, At, B0); PG8_MMA(1, 1, At, B1); PG8_BAR; PG8_SCHED;
.LBB0_97:
	s_add_u32 s4, s94, 0x80080
	s_addc_u32 s5, s95, 0
	s_add_u32 s15, s92, 0x100
	s_addc_u32 s58, s93, 0
	s_mov_b32 s94, -2
	ds_read_b128 v[164:167], v154
	ds_read_b128 v[168:171], v154 offset:1024
	ds_read_b128 v[172:175], v154 offset:2048
	ds_read_b128 v[176:179], v154 offset:3072
	ds_read_b128 v[180:183], v155
	ds_read_b128 v[184:187], v155 offset:1024
	ds_read_b128 v[192:195], v155 offset:2048
	ds_read_b128 v[196:199], v155 offset:3072
	s_add_u32 s6, s4, 0xfff80080
	s_addc_u32 s7, s5, -1
	s_cmp_eq_u32 s94, 28
	s_cselect_b32 s93, s81, s7
	s_cselect_b32 s92, s80, s6
	s_cselect_b32 s7, s85, s58
	s_cselect_b32 s6, s84, s15
	v_lshl_add_u64 v[158:159], s[4:5], 0, v[148:149]
	s_add_i32 m0, s19, 0xc000
	ds_read_b128 v[200:203], v156
	ds_read_b128 v[204:207], v156 offset:1024
	ds_read_b128 v[208:211], v156 offset:2048
	ds_read_b128 v[212:215], v156 offset:3072
	ds_read_b128 v[216:219], v156 offset:4096
	ds_read_b128 v[220:223], v156 offset:5120
	ds_read_b128 v[224:227], v156 offset:6144
	ds_read_b128 v[228:231], v156 offset:7168
	global_load_lds_dwordx4 v[158:159], off
	v_lshl_add_u64 v[158:159], s[4:5], 0, v[150:151]
	s_add_i32 m0, s19, 0xe000
	s_nop 0
	global_load_lds_dwordx4 v[158:159], off
	s_waitcnt vmcnt(8)
	s_waitcnt lgkmcnt(0)
	s_barrier
	s_waitcnt lgkmcnt(0)
	v_mfma_f32_16x16x32_bf16 v[124:127], v[164:167], v[200:203], 0
	v_mfma_f32_16x16x32_bf16 v[120:123], v[172:175], v[200:203], 0
	v_mfma_f32_16x16x32_bf16 v[112:115], v[164:167], v[208:211], 0
	v_mfma_f32_16x16x32_bf16 v[104:107], v[172:175], v[208:211], 0
	v_mfma_f32_16x16x32_bf16 v[96:99], v[164:167], v[216:219], 0
	v_mfma_f32_16x16x32_bf16 v[88:91], v[172:175], v[216:219], 0
	v_mfma_f32_16x16x32_bf16 v[80:83], v[164:167], v[224:227], 0
	v_mfma_f32_16x16x32_bf16 v[72:75], v[172:175], v[224:227], 0
	v_mfma_f32_16x16x32_bf16 v[124:127], v[168:171], v[204:207], v[124:127]
	v_mfma_f32_16x16x32_bf16 v[120:123], v[176:179], v[204:207], v[120:123]
	v_mfma_f32_16x16x32_bf16 v[112:115], v[168:171], v[212:215], v[112:115]
	v_mfma_f32_16x16x32_bf16 v[104:107], v[176:179], v[212:215], v[104:107]
	v_mfma_f32_16x16x32_bf16 v[96:99], v[168:171], v[220:223], v[96:99]
	v_mfma_f32_16x16x32_bf16 v[88:91], v[176:179], v[220:223], v[88:91]
	v_mfma_f32_16x16x32_bf16 v[80:83], v[168:171], v[228:231], v[80:83]
	v_mfma_f32_16x16x32_bf16 v[72:75], v[176:179], v[228:231], v[72:75]
	v_mfma_f32_16x16x32_bf16 v[116:119], v[180:183], v[200:203], 0
	v_mfma_f32_16x16x32_bf16 v[108:111], v[192:195], v[200:203], 0
	v_mfma_f32_16x16x32_bf16 v[100:103], v[180:183], v[208:211], 0
	v_mfma_f32_16x16x32_bf16 v[92:95], v[192:195], v[208:211], 0
	v_mfma_f32_16x16x32_bf16 v[84:87], v[180:183], v[216:219], 0
	v_mfma_f32_16x16x32_bf16 v[76:79], v[192:195], v[216:219], 0
	v_mfma_f32_16x16x32_bf16 v[68:71], v[180:183], v[224:227], 0
	v_mfma_f32_16x16x32_bf16 v[64:67], v[192:195], v[224:227], 0
	v_mfma_f32_16x16x32_bf16 v[116:119], v[184:187], v[204:207], v[116:119]
	v_mfma_f32_16x16x32_bf16 v[108:111], v[196:199], v[204:207], v[108:111]
	v_mfma_f32_16x16x32_bf16 v[100:103], v[184:187], v[212:215], v[100:103]
	v_mfma_f32_16x16x32_bf16 v[92:95], v[196:199], v[212:215], v[92:95]
	v_mfma_f32_16x16x32_bf16 v[84:87], v[184:187], v[220:223], v[84:87]
	v_mfma_f32_16x16x32_bf16 v[76:79], v[196:199], v[220:223], v[76:79]
	v_mfma_f32_16x16x32_bf16 v[68:71], v[184:187], v[228:231], v[68:71]
	v_mfma_f32_16x16x32_bf16 v[64:67], v[196:199], v[228:231], v[64:67]
	s_barrier
	s_add_i32 s34, s27, s18
	v_lshl_add_u64 v[158:159], s[6:7], 0, v[130:131]
	s_mov_b32 m0, s34
	ds_read_b128 v[200:203], v156 offset:16384
	ds_read_b128 v[204:207], v156 offset:17408
	ds_read_b128 v[208:211], v156 offset:18432
	ds_read_b128 v[212:215], v156 offset:19456
	ds_read_b128 v[216:219], v156 offset:20480
	ds_read_b128 v[220:223], v156 offset:21504
	ds_read_b128 v[224:227], v156 offset:22528
	ds_read_b128 v[228:231], v156 offset:23552
	global_load_lds_dwordx4 v[158:159], off
	s_add_i32 m0, s34, 0x2000
	s_add_u32 s96, s6, 0x80000
	v_lshl_add_u64 v[188:189], s[6:7], 0, v[134:135]
	s_addc_u32 s97, s7, 0
	s_add_i32 s34, s24, s18
	global_load_lds_dwordx4 v[188:189], off
	v_lshl_add_u64 v[232:233], s[96:97], 0, v[130:131]
	s_mov_b32 m0, s34
	v_lshl_add_u64 v[234:235], s[92:93], 0, v[132:133]
	global_load_lds_dwordx4 v[232:233], off
	v_lshl_add_u64 v[232:233], s[96:97], 0, v[134:135]
	s_add_i32 m0, s34, 0x2000
	s_nop 0
	global_load_lds_dwordx4 v[232:233], off
	v_lshl_add_u64 v[232:233], s[92:93], 0, v[128:129]
	s_mov_b32 m0, s19
	s_nop 0
	global_load_lds_dwordx4 v[232:233], off
	s_mov_b32 m0, s20
	s_nop 0
	global_load_lds_dwordx4 v[234:235], off
	s_waitcnt vmcnt(8)
	s_waitcnt lgkmcnt(0)
	s_barrier
; #define PG8_STAGE(bufoff, gbase, voff) do { _Pragma("unroll") for (int _i = 0; _i < 2; ++_i) \
;         __builtin_amdgcn_global_load_lds((const unsigned*)((const char*)(gbase) + (voff)[_i]), (LAS unsigned*)(lds + (bufoff) + ldsw + _i * 8192), 16, 0, 0); } while (0)
; #define PG8_LDA(dst, b, h) do { _Pragma("unroll") for (int m = 0; m < 4; ++m) _Pragma("unroll") for (int k = 0; k < 2; ++k) dst[m][k] = *(const LAS bf16x8*)(lds + PG8_SA(b, h) + aoff + m * 2048 + k * 1024); } while (0)
; #define PG8_LDB(dst, b, h) do { _Pragma("unroll") for (int n = 0; n < 2; ++n) _Pragma("unroll") for (int k = 0; k < 2; ++k) dst[n][k] = *(const LAS bf16x8*)(lds + PG8_SB(b, h) + boff + n * 2048 + k * 1024); } while (0)
; #define PG8_MMA(ai, bj, At, Bt) do { __builtin_amdgcn_s_setprio(1); _Pragma("unroll") for (int m = 0; m < 4; ++m) _Pragma("unroll") for (int n = 0; n < 2; ++n) _Pragma("unroll") for (int k = 0; k < 2; ++k) \
;         acc[ai][bj][m][n] = __builtin_amdgcn_mfma_f32_16x16x32_bf16(Bt[n][k], At[m][k], acc[ai][bj][m][n], 0, 0, 0); __builtin_amdgcn_s_setprio(0); } while (0)
; #define PG8_WAIT_V(n) asm volatile("s_waitcnt vmcnt(" #n ")" ::: "memory")
; #define PG8_WAIT_L(n) asm volatile("s_waitcnt lgkmcnt(" #n ")" ::: "memory")
; #define PG8_BAR __builtin_amdgcn_s_barrier()
; #define PG8_SCHED __builtin_amdgcn_sched_barrier(0)
; template <int GI>
; __device__ __forceinline__ void gemm_phase(LAS unsigned char* lds, unsigned char* ws, int G, int cblk) {
;     ...
;             PG8_WAIT_V(8); PG8_WAIT_L(0); PG8_BAR; PG8_MMA(1, 0, At, B0); PG8_MMA(1, 1, At, B1); PG8_BAR; PG8_SCHED;
;             PG8_LDB(B0, 1, 0); PG8_LDB(B1, 1, 1); PG8_SCHED; PG8_LDA(At, 1, 0); PG8_STAGE(PG8_SA(0, 1), a2 + hstepA, voffA);
;             PG8_WAIT_V(8); PG8_WAIT_L(0); PG8_BAR; PG8_MMA(0, 0, At, B0); PG8_MMA(0, 1, At, B1); PG8_BAR; PG8_SCHED;
	s_waitcnt lgkmcnt(0)
	v_mfma_f32_16x16x32_bf16 v[60:63], v[164:167], v[200:203], 0
	v_mfma_f32_16x16x32_bf16 v[56:59], v[172:175], v[200:203], 0
	v_mfma_f32_16x16x32_bf16 v[52:55], v[164:167], v[208:211], 0
	v_mfma_f32_16x16x32_bf16 v[44:47], v[172:175], v[208:211], 0
	v_mfma_f32_16x16x32_bf16 v[36:39], v[164:167], v[216:219], 0
	v_mfma_f32_16x16x32_bf16 v[28:31], v[172:175], v[216:219], 0
	v_mfma_f32_16x16x32_bf16 v[20:23], v[164:167], v[224:227], 0
	v_mfma_f32_16x16x32_bf16 v[12:15], v[172:175], v[224:227], 0
	v_mfma_f32_16x16x32_bf16 v[60:63], v[168:171], v[204:207], v[60:63]
	v_mfma_f32_16x16x32_bf16 v[56:59], v[176:179], v[204:207], v[56:59]
	v_mfma_f32_16x16x32_bf16 v[52:55], v[168:171], v[212:215], v[52:55]
	v_mfma_f32_16x16x32_bf16 v[44:47], v[176:179], v[212:215], v[44:47]
	v_mfma_f32_16x16x32_bf16 v[36:39], v[168:171], v[220:223], v[36:39]
	v_mfma_f32_16x16x32_bf16 v[28:31], v[176:179], v[220:223], v[28:31]
	v_mfma_f32_16x16x32_bf16 v[20:23], v[168:171], v[228:231], v[20:23]
	v_mfma_f32_16x16x32_bf16 v[12:15], v[176:179], v[228:231], v[12:15]
	v_mfma_f32_16x16x32_bf16 v[48:51], v[180:183], v[200:203], 0
	v_mfma_f32_16x16x32_bf16 v[40:43], v[192:195], v[200:203], 0
	v_mfma_f32_16x16x32_bf16 v[32:35], v[180:183], v[208:211], 0
	v_mfma_f32_16x16x32_bf16 v[24:27], v[192:195], v[208:211], 0
	v_mfma_f32_16x16x32_bf16 v[16:19], v[180:183], v[216:219], 0
	v_mfma_f32_16x16x32_bf16 v[8:11], v[192:195], v[216:219], 0
	v_mfma_f32_16x16x32_bf16 v[4:7], v[180:183], v[224:227], 0
	v_mfma_f32_16x16x32_bf16 v[0:3], v[192:195], v[224:227], 0
	v_mfma_f32_16x16x32_bf16 v[48:51], v[184:187], v[204:207], v[48:51]
	v_mfma_f32_16x16x32_bf16 v[40:43], v[196:199], v[204:207], v[40:43]
	v_mfma_f32_16x16x32_bf16 v[32:35], v[184:187], v[212:215], v[32:35]
	v_mfma_f32_16x16x32_bf16 v[24:27], v[196:199], v[212:215], v[24:27]
	v_mfma_f32_16x16x32_bf16 v[16:19], v[184:187], v[220:223], v[16:19]
	v_mfma_f32_16x16x32_bf16 v[8:11], v[196:199], v[220:223], v[8:11]
	v_mfma_f32_16x16x32_bf16 v[4:7], v[184:187], v[228:231], v[4:7]
	v_mfma_f32_16x16x32_bf16 v[0:3], v[196:199], v[228:231], v[0:3]
	s_barrier
	s_add_i32 s34, 0, 0x18000
	v_add_u32_e32 v161, s34, v153
	s_add_i32 s95, 0, 0x1c000
	ds_read_b128 v[164:167], v161
	ds_read_b128 v[168:171], v161 offset:1024
	ds_read_b128 v[172:175], v161 offset:2048
	ds_read_b128 v[176:179], v161 offset:3072
	v_add_u32_e32 v161, s95, v153
	ds_read_b128 v[180:183], v161
	ds_read_b128 v[184:187], v161 offset:1024
	ds_read_b128 v[192:195], v161 offset:2048
	ds_read_b128 v[196:199], v161 offset:3072
	s_add_u32 s92, s92, 0x80000
	s_addc_u32 s93, s93, 0
	s_mov_b32 m0, s21
	v_lshl_add_u64 v[236:237], s[92:93], 0, v[128:129]
	ds_read_b128 v[200:203], v156 offset:32768
	ds_read_b128 v[204:207], v156 offset:33792
	ds_read_b128 v[208:211], v156 offset:34816
	ds_read_b128 v[212:215], v156 offset:35840
	ds_read_b128 v[216:219], v156 offset:36864
	ds_read_b128 v[220:223], v156 offset:37888
	ds_read_b128 v[224:227], v156 offset:38912
	ds_read_b128 v[228:231], v156 offset:39936
	global_load_lds_dwordx4 v[236:237], off
	v_lshl_add_u64 v[236:237], s[92:93], 0, v[132:133]
	s_mov_b32 m0, s35
	s_nop 0
	global_load_lds_dwordx4 v[236:237], off
	s_waitcnt vmcnt(8)
	s_waitcnt lgkmcnt(0)
	s_barrier
	s_waitcnt lgkmcnt(0)
	v_mfma_f32_16x16x32_bf16 v[124:127], v[164:167], v[200:203], v[124:127]
	v_mfma_f32_16x16x32_bf16 v[120:123], v[172:175], v[200:203], v[120:123]
	v_mfma_f32_16x16x32_bf16 v[112:115], v[164:167], v[208:211], v[112:115]
	v_mfma_f32_16x16x32_bf16 v[104:107], v[172:175], v[208:211], v[104:107]
	v_mfma_f32_16x16x32_bf16 v[96:99], v[164:167], v[216:219], v[96:99]
	v_mfma_f32_16x16x32_bf16 v[88:91], v[172:175], v[216:219], v[88:91]
	v_mfma_f32_16x16x32_bf16 v[80:83], v[164:167], v[224:227], v[80:83]
	v_mfma_f32_16x16x32_bf16 v[72:75], v[172:175], v[224:227], v[72:75]
	v_mfma_f32_16x16x32_bf16 v[124:127], v[168:171], v[204:207], v[124:127]
	v_mfma_f32_16x16x32_bf16 v[120:123], v[176:179], v[204:207], v[120:123]
	v_mfma_f32_16x16x32_bf16 v[112:115], v[168:171], v[212:215], v[112:115]
	v_mfma_f32_16x16x32_bf16 v[104:107], v[176:179], v[212:215], v[104:107]
	v_mfma_f32_16x16x32_bf16 v[96:99], v[168:171], v[220:223], v[96:99]
	v_mfma_f32_16x16x32_bf16 v[88:91], v[176:179], v[220:223], v[88:91]
	v_mfma_f32_16x16x32_bf16 v[80:83], v[168:171], v[228:231], v[80:83]
	v_mfma_f32_16x16x32_bf16 v[72:75], v[176:179], v[228:231], v[72:75]
	v_mfma_f32_16x16x32_bf16 v[116:119], v[180:183], v[200:203], v[116:119]
	v_mfma_f32_16x16x32_bf16 v[108:111], v[192:195], v[200:203], v[108:111]
	v_mfma_f32_16x16x32_bf16 v[100:103], v[180:183], v[208:211], v[100:103]
	v_mfma_f32_16x16x32_bf16 v[92:95], v[192:195], v[208:211], v[92:95]
	v_mfma_f32_16x16x32_bf16 v[84:87], v[180:183], v[216:219], v[84:87]
	v_mfma_f32_16x16x32_bf16 v[76:79], v[192:195], v[216:219], v[76:79]
	v_mfma_f32_16x16x32_bf16 v[68:71], v[180:183], v[224:227], v[68:71]
	v_mfma_f32_16x16x32_bf16 v[64:67], v[192:195], v[224:227], v[64:67]
	v_mfma_f32_16x16x32_bf16 v[116:119], v[184:187], v[204:207], v[116:119]
	v_mfma_f32_16x16x32_bf16 v[108:111], v[196:199], v[204:207], v[108:111]
	v_mfma_f32_16x16x32_bf16 v[100:103], v[184:187], v[212:215], v[100:103]
	v_mfma_f32_16x16x32_bf16 v[92:95], v[196:199], v[212:215], v[92:95]
	v_mfma_f32_16x16x32_bf16 v[84:87], v[184:187], v[220:223], v[84:87]
	v_mfma_f32_16x16x32_bf16 v[76:79], v[196:199], v[220:223], v[76:79]
	v_mfma_f32_16x16x32_bf16 v[68:71], v[184:187], v[228:231], v[68:71]
	v_mfma_f32_16x16x32_bf16 v[64:67], v[196:199], v[228:231], v[64:67]
	s_barrier
; #define PG8_STAGE(bufoff, gbase, voff) do { _Pragma("unroll") for (int _i = 0; _i < 2; ++_i) \
;         __builtin_amdgcn_global_load_lds((const unsigned*)((const char*)(gbase) + (voff)[_i]), (LAS unsigned*)(lds + (bufoff) + ldsw + _i * 8192), 16, 0, 0); } while (0)
; #define PG8_LDA(dst, b, h) do { _Pragma("unroll") for (int m = 0; m < 4; ++m) _Pragma("unroll") for (int k = 0; k < 2; ++k) dst[m][k] = *(const LAS bf16x8*)(lds + PG8_SA(b, h) + aoff + m * 2048 + k * 1024); } while (0)
; #define PG8_LDB(dst, b, h) do { _Pragma("unroll") for (int n = 0; n < 2; ++n) _Pragma("unroll") for (int k = 0; k < 2; ++k) dst[n][k] = *(const LAS bf16x8*)(lds + PG8_SB(b, h) + boff + n * 2048 + k * 1024); } while (0)
; #define PG8_MMA(ai, bj, At, Bt) do { __builtin_amdgcn_s_setprio(1); _Pragma("unroll") for (int m = 0; m < 4; ++m) _Pragma("unroll") for (int n = 0; n < 2; ++n) _Pragma("unroll") for (int k = 0; k < 2; ++k) \
;         acc[ai][bj][m][n] = __builtin_amdgcn_mfma_f32_16x16x32_bf16(Bt[n][k], At[m][k], acc[ai][bj][m][n], 0, 0, 0); __builtin_amdgcn_s_setprio(0); } while (0)
; #define PG8_WAIT_V(n) asm volatile("s_waitcnt vmcnt(" #n ")" ::: "memory")
; #define PG8_WAIT_L(n) asm volatile("s_waitcnt lgkmcnt(" #n ")" ::: "memory")
; #define PG8_BAR __builtin_amdgcn_s_barrier()
; #define PG8_SCHED __builtin_amdgcn_sched_barrier(0)
; template <int GI>
; __device__ __forceinline__ void gemm_phase(LAS unsigned char* lds, unsigned char* ws, int G, int cblk) {
;     ...
;             PG8_LDB(B0, 0, 0); PG8_LDB(B1, 0, 1); PG8_SCHED; PG8_LDA(At, 0, 0); PG8_STAGE(PG8_SA(1, 1), a1 + hstepA, voffA);
;             PG8_WAIT_V(8); PG8_WAIT_L(0); PG8_BAR; PG8_MMA(0, 0, At, B0); PG8_MMA(0, 1, At, B1); PG8_BAR; PG8_SCHED;
;     ...
;             PG8_LDA(At, 1, 1); PG8_STAGE(PG8_SB(1, 0), b3, voffB); PG8_STAGE(PG8_SB(1, 1), b3 + hstepB, voffB); PG8_STAGE(PG8_SA(1, 0), a3, voffA);
;             PG8_WAIT_V(8); PG8_WAIT_L(0); PG8_BAR; PG8_MMA(1, 0, At, B0); PG8_MMA(1, 1, At, B1); PG8_BAR; PG8_SCHED;
;         }
	s_add_i32 s34, s34, s18
	v_lshl_add_u64 v[158:159], v[158:159], 0, s[70:71]
	s_mov_b32 m0, s34
	ds_read_b128 v[200:203], v156 offset:49152
	ds_read_b128 v[204:207], v156 offset:50176
	ds_read_b128 v[208:211], v156 offset:51200
	ds_read_b128 v[212:215], v156 offset:52224
	ds_read_b128 v[216:219], v156 offset:53248
	ds_read_b128 v[220:223], v156 offset:54272
	ds_read_b128 v[224:227], v156 offset:55296
	ds_read_b128 v[228:231], v156 offset:56320
	global_load_lds_dwordx4 v[158:159], off
	s_add_i32 m0, s34, 0x2000
	s_add_u32 s6, s6, 0x80080
	v_lshl_add_u64 v[158:159], v[188:189], 0, s[70:71]
	s_addc_u32 s7, s7, 0
	s_add_i32 s34, s95, s18
	global_load_lds_dwordx4 v[158:159], off
	v_lshl_add_u64 v[158:159], s[6:7], 0, v[130:131]
	s_mov_b32 m0, s34
	s_nop 0
	global_load_lds_dwordx4 v[158:159], off
	v_lshl_add_u64 v[158:159], s[6:7], 0, v[134:135]
	s_add_i32 m0, s34, 0x2000
	s_nop 0
	global_load_lds_dwordx4 v[158:159], off
	v_lshl_add_u64 v[158:159], v[232:233], 0, s[70:71]
	s_mov_b32 m0, s0
	s_nop 0
	global_load_lds_dwordx4 v[158:159], off
	v_lshl_add_u64 v[158:159], v[234:235], 0, s[70:71]
	s_mov_b32 m0, s1
	s_nop 0
	global_load_lds_dwordx4 v[158:159], off
	s_waitcnt vmcnt(8)
	s_waitcnt lgkmcnt(0)
	s_barrier
	s_waitcnt lgkmcnt(0)
	v_mfma_f32_16x16x32_bf16 v[60:63], v[164:167], v[200:203], v[60:63]
	v_mfma_f32_16x16x32_bf16 v[56:59], v[172:175], v[200:203], v[56:59]
	v_mfma_f32_16x16x32_bf16 v[52:55], v[164:167], v[208:211], v[52:55]
	v_mfma_f32_16x16x32_bf16 v[44:47], v[172:175], v[208:211], v[44:47]
	v_mfma_f32_16x16x32_bf16 v[36:39], v[164:167], v[216:219], v[36:39]
	v_mfma_f32_16x16x32_bf16 v[28:31], v[172:175], v[216:219], v[28:31]
	v_mfma_f32_16x16x32_bf16 v[20:23], v[164:167], v[224:227], v[20:23]
	v_mfma_f32_16x16x32_bf16 v[12:15], v[172:175], v[224:227], v[12:15]
	v_mfma_f32_16x16x32_bf16 v[60:63], v[168:171], v[204:207], v[60:63]
	v_mfma_f32_16x16x32_bf16 v[56:59], v[176:179], v[204:207], v[56:59]
	v_mfma_f32_16x16x32_bf16 v[52:55], v[168:171], v[212:215], v[52:55]
	v_mfma_f32_16x16x32_bf16 v[44:47], v[176:179], v[212:215], v[44:47]
	v_mfma_f32_16x16x32_bf16 v[36:39], v[168:171], v[220:223], v[36:39]
	v_mfma_f32_16x16x32_bf16 v[28:31], v[176:179], v[220:223], v[28:31]
	v_mfma_f32_16x16x32_bf16 v[20:23], v[168:171], v[228:231], v[20:23]
	v_mfma_f32_16x16x32_bf16 v[12:15], v[176:179], v[228:231], v[12:15]
	v_mfma_f32_16x16x32_bf16 v[48:51], v[180:183], v[200:203], v[48:51]
	v_mfma_f32_16x16x32_bf16 v[40:43], v[192:195], v[200:203], v[40:43]
	v_mfma_f32_16x16x32_bf16 v[32:35], v[180:183], v[208:211], v[32:35]
	v_mfma_f32_16x16x32_bf16 v[24:27], v[192:195], v[208:211], v[24:27]
	v_mfma_f32_16x16x32_bf16 v[16:19], v[180:183], v[216:219], v[16:19]
	v_mfma_f32_16x16x32_bf16 v[8:11], v[192:195], v[216:219], v[8:11]
	v_mfma_f32_16x16x32_bf16 v[4:7], v[180:183], v[224:227], v[4:7]
	v_mfma_f32_16x16x32_bf16 v[0:3], v[192:195], v[224:227], v[0:3]
	v_mfma_f32_16x16x32_bf16 v[48:51], v[184:187], v[204:207], v[48:51]
	v_mfma_f32_16x16x32_bf16 v[40:43], v[196:199], v[204:207], v[40:43]
	v_mfma_f32_16x16x32_bf16 v[32:35], v[184:187], v[212:215], v[32:35]
	v_mfma_f32_16x16x32_bf16 v[24:27], v[196:199], v[212:215], v[24:27]
	v_mfma_f32_16x16x32_bf16 v[16:19], v[184:187], v[220:223], v[16:19]
	v_mfma_f32_16x16x32_bf16 v[8:11], v[196:199], v[220:223], v[8:11]
	v_mfma_f32_16x16x32_bf16 v[4:7], v[184:187], v[228:231], v[4:7]
	v_mfma_f32_16x16x32_bf16 v[0:3], v[196:199], v[228:231], v[0:3]
	s_barrier
	s_add_i32 s94, s94, 2
	s_add_u32 s4, s4, 0x100
	s_addc_u32 s5, s5, 0
	s_add_u32 s15, s15, 0x100
	s_addc_u32 s58, s58, 0
	s_cmp_gt_u32 s94, 29
	s_cbranch_scc0 .LBB0_98
	s_branch .Lpeel_exit_0
.LBB0_98:
	ds_read_b128 v[164:167], v154
	ds_read_b128 v[168:171], v154 offset:1024
	ds_read_b128 v[172:175], v154 offset:2048
	ds_read_b128 v[176:179], v154 offset:3072
	ds_read_b128 v[180:183], v155
	ds_read_b128 v[184:187], v155 offset:1024
	ds_read_b128 v[192:195], v155 offset:2048
	ds_read_b128 v[196:199], v155 offset:3072
	s_add_u32 s6, s4, 0xfff80080
	s_addc_u32 s7, s5, -1
	s_cmp_eq_u32 s94, 28
	s_cselect_b32 s93, s81, s7
	s_cselect_b32 s92, s80, s6
	s_cselect_b32 s7, s85, s58
	s_cselect_b32 s6, s84, s15
	v_lshl_add_u64 v[158:159], s[4:5], 0, v[148:149]
	s_add_i32 m0, s19, 0xc000
	ds_read_b128 v[200:203], v156
	ds_read_b128 v[204:207], v156 offset:1024
	ds_read_b128 v[208:211], v156 offset:2048
	ds_read_b128 v[212:215], v156 offset:3072
	ds_read_b128 v[216:219], v156 offset:4096
	ds_read_b128 v[220:223], v156 offset:5120
	ds_read_b128 v[224:227], v156 offset:6144
	ds_read_b128 v[228:231], v156 offset:7168
	global_load_lds_dwordx4 v[158:159], off
	v_lshl_add_u64 v[158:159], s[4:5], 0, v[150:151]
	s_add_i32 m0, s19, 0xe000
	s_nop 0
	global_load_lds_dwordx4 v[158:159], off
	s_waitcnt vmcnt(8)
	s_waitcnt lgkmcnt(0)
	s_barrier
; #define PG8_STAGE(bufoff, gbase, voff) do { _Pragma("unroll") for (int _i = 0; _i < 2; ++_i) \
;         __builtin_amdgcn_global_load_lds((const unsigned*)((const char*)(gbase) + (voff)[_i]), (LAS unsigned*)(lds + (bufoff) + ldsw + _i * 8192), 16, 0, 0); } while (0)
; #define PG8_LDA(dst, b, h) do { _Pragma("unroll") for (int m = 0; m < 4; ++m) _Pragma("unroll") for (int k = 0; k < 2; ++k) dst[m][k] = *(const LAS bf16x8*)(lds + PG8_SA(b, h) + aoff + m * 2048 + k * 1024); } while (0)
; #define PG8_MMA(ai, bj, At, Bt) do { __builtin_amdgcn_s_setprio(1); _Pragma("unroll") for (int m = 0; m < 4; ++m) _Pragma("unroll") for (int n = 0; n < 2; ++n) _Pragma("unroll") for (int k = 0; k < 2; ++k) \
;         acc[ai][bj][m][n] = __builtin_amdgcn_mfma_f32_16x16x32_bf16(Bt[n][k], At[m][k], acc[ai][bj][m][n], 0, 0, 0); __builtin_amdgcn_s_setprio(0); } while (0)
; #define PG8_WAIT_V(n) asm volatile("s_waitcnt vmcnt(" #n ")" ::: "memory")
; #define PG8_WAIT_L(n) asm volatile("s_waitcnt lgkmcnt(" #n ")" ::: "memory")
; #define PG8_BAR __builtin_amdgcn_s_barrier()
; #define PG8_SCHED __builtin_amdgcn_sched_barrier(0)
; template <int GI>
; __device__ __forceinline__ void gemm_phase(LAS unsigned char* lds, unsigned char* ws, int G, int cblk) {
;     ...
;             PG8_WAIT_V(8); PG8_WAIT_L(0); PG8_BAR; PG8_MMA(0, 0, At, B0); PG8_MMA(0, 1, At, B1); PG8_BAR; PG8_SCHED;
;             PG8_LDA(At, 0, 1); PG8_STAGE(PG8_SB(0, 0), b2, voffB); PG8_STAGE(PG8_SB(0, 1), b2 + hstepB, voffB); PG8_STAGE(PG8_SA(0, 0), a2, voffA);
;             PG8_WAIT_V(8); PG8_WAIT_L(0); PG8_BAR; PG8_MMA(1, 0, At, B0); PG8_MMA(1, 1, At, B1); PG8_BAR; PG8_SCHED;
	s_waitcnt lgkmcnt(0)
	v_mfma_f32_16x16x32_bf16 v[124:127], v[164:167], v[200:203], v[124:127]
	v_mfma_f32_16x16x32_bf16 v[120:123], v[172:175], v[200:203], v[120:123]
	v_mfma_f32_16x16x32_bf16 v[112:115], v[164:167], v[208:211], v[112:115]
	v_mfma_f32_16x16x32_bf16 v[104:107], v[172:175], v[208:211], v[104:107]
	v_mfma_f32_16x16x32_bf16 v[96:99], v[164:167], v[216:219], v[96:99]
	v_mfma_f32_16x16x32_bf16 v[88:91], v[172:175], v[216:219], v[88:91]
	v_mfma_f32_16x16x32_bf16 v[80:83], v[164:167], v[224:227], v[80:83]
	v_mfma_f32_16x16x32_bf16 v[72:75], v[172:175], v[224:227], v[72:75]
	v_mfma_f32_16x16x32_bf16 v[124:127], v[168:171], v[204:207], v[124:127]
	v_mfma_f32_16x16x32_bf16 v[120:123], v[176:179], v[204:207], v[120:123]
	v_mfma_f32_16x16x32_bf16 v[112:115], v[168:171], v[212:215], v[112:115]
	v_mfma_f32_16x16x32_bf16 v[104:107], v[176:179], v[212:215], v[104:107]
	v_mfma_f32_16x16x32_bf16 v[96:99], v[168:171], v[220:223], v[96:99]
	v_mfma_f32_16x16x32_bf16 v[88:91], v[176:179], v[220:223], v[88:91]
	v_mfma_f32_16x16x32_bf16 v[80:83], v[168:171], v[228:231], v[80:83]
	v_mfma_f32_16x16x32_bf16 v[72:75], v[176:179], v[228:231], v[72:75]
	v_mfma_f32_16x16x32_bf16 v[116:119], v[180:183], v[200:203], v[116:119]
	v_mfma_f32_16x16x32_bf16 v[108:111], v[192:195], v[200:203], v[108:111]
	v_mfma_f32_16x16x32_bf16 v[100:103], v[180:183], v[208:211], v[100:103]
	v_mfma_f32_16x16x32_bf16 v[92:95], v[192:195], v[208:211], v[92:95]
	v_mfma_f32_16x16x32_bf16 v[84:87], v[180:183], v[216:219], v[84:87]
	v_mfma_f32_16x16x32_bf16 v[76:79], v[192:195], v[216:219], v[76:79]
	v_mfma_f32_16x16x32_bf16 v[68:71], v[180:183], v[224:227], v[68:71]
	v_mfma_f32_16x16x32_bf16 v[64:67], v[192:195], v[224:227], v[64:67]
	v_mfma_f32_16x16x32_bf16 v[116:119], v[184:187], v[204:207], v[116:119]
	v_mfma_f32_16x16x32_bf16 v[108:111], v[196:199], v[204:207], v[108:111]
	v_mfma_f32_16x16x32_bf16 v[100:103], v[184:187], v[212:215], v[100:103]
	v_mfma_f32_16x16x32_bf16 v[92:95], v[196:199], v[212:215], v[92:95]
	v_mfma_f32_16x16x32_bf16 v[84:87], v[184:187], v[220:223], v[84:87]
	v_mfma_f32_16x16x32_bf16 v[76:79], v[196:199], v[220:223], v[76:79]
	v_mfma_f32_16x16x32_bf16 v[68:71], v[184:187], v[228:231], v[68:71]
	v_mfma_f32_16x16x32_bf16 v[64:67], v[196:199], v[228:231], v[64:67]
	s_barrier
	s_add_i32 s34, s27, s18
	v_lshl_add_u64 v[158:159], s[6:7], 0, v[130:131]
	s_mov_b32 m0, s34
	ds_read_b128 v[200:203], v156 offset:16384
	ds_read_b128 v[204:207], v156 offset:17408
	ds_read_b128 v[208:211], v156 offset:18432
	ds_read_b128 v[212:215], v156 offset:19456
	ds_read_b128 v[216:219], v156 offset:20480
	ds_read_b128 v[220:223], v156 offset:21504
	ds_read_b128 v[224:227], v156 offset:22528
	ds_read_b128 v[228:231], v156 offset:23552
	global_load_lds_dwordx4 v[158:159], off
	s_add_i32 m0, s34, 0x2000
	s_add_u32 s96, s6, 0x80000
	v_lshl_add_u64 v[188:189], s[6:7], 0, v[134:135]
	s_addc_u32 s97, s7, 0
	s_add_i32 s34, s24, s18
	global_load_lds_dwordx4 v[188:189], off
	v_lshl_add_u64 v[232:233], s[96:97], 0, v[130:131]
	s_mov_b32 m0, s34
	v_lshl_add_u64 v[234:235], s[92:93], 0, v[132:133]
	global_load_lds_dwordx4 v[232:233], off
	v_lshl_add_u64 v[232:233], s[96:97], 0, v[134:135]
	s_add_i32 m0, s34, 0x2000
	s_nop 0
	global_load_lds_dwordx4 v[232:233], off
	v_lshl_add_u64 v[232:233], s[92:93], 0, v[128:129]
	s_mov_b32 m0, s19
	s_nop 0
	global_load_lds_dwordx4 v[232:233], off
	s_mov_b32 m0, s20
	s_nop 0
	global_load_lds_dwordx4 v[234:235], off
	s_waitcnt vmcnt(8)
	s_waitcnt lgkmcnt(0)
	s_barrier
	s_waitcnt lgkmcnt(0)
	v_mfma_f32_16x16x32_bf16 v[60:63], v[164:167], v[200:203], v[60:63]
	v_mfma_f32_16x16x32_bf16 v[56:59], v[172:175], v[200:203], v[56:59]
	v_mfma_f32_16x16x32_bf16 v[52:55], v[164:167], v[208:211], v[52:55]
	v_mfma_f32_16x16x32_bf16 v[44:47], v[172:175], v[208:211], v[44:47]
	v_mfma_f32_16x16x32_bf16 v[36:39], v[164:167], v[216:219], v[36:39]
	v_mfma_f32_16x16x32_bf16 v[28:31], v[172:175], v[216:219], v[28:31]
	v_mfma_f32_16x16x32_bf16 v[20:23], v[164:167], v[224:227], v[20:23]
	v_mfma_f32_16x16x32_bf16 v[12:15], v[172:175], v[224:227], v[12:15]
	v_mfma_f32_16x16x32_bf16 v[60:63], v[168:171], v[204:207], v[60:63]
	v_mfma_f32_16x16x32_bf16 v[56:59], v[176:179], v[204:207], v[56:59]
	v_mfma_f32_16x16x32_bf16 v[52:55], v[168:171], v[212:215], v[52:55]
	v_mfma_f32_16x16x32_bf16 v[44:47], v[176:179], v[212:215], v[44:47]
	v_mfma_f32_16x16x32_bf16 v[36:39], v[168:171], v[220:223], v[36:39]
	v_mfma_f32_16x16x32_bf16 v[28:31], v[176:179], v[220:223], v[28:31]
	v_mfma_f32_16x16x32_bf16 v[20:23], v[168:171], v[228:231], v[20:23]
	v_mfma_f32_16x16x32_bf16 v[12:15], v[176:179], v[228:231], v[12:15]
	v_mfma_f32_16x16x32_bf16 v[48:51], v[180:183], v[200:203], v[48:51]
	v_mfma_f32_16x16x32_bf16 v[40:43], v[192:195], v[200:203], v[40:43]
	v_mfma_f32_16x16x32_bf16 v[32:35], v[180:183], v[208:211], v[32:35]
	v_mfma_f32_16x16x32_bf16 v[24:27], v[192:195], v[208:211], v[24:27]
	v_mfma_f32_16x16x32_bf16 v[16:19], v[180:183], v[216:219], v[16:19]
	v_mfma_f32_16x16x32_bf16 v[8:11], v[192:195], v[216:219], v[8:11]
	v_mfma_f32_16x16x32_bf16 v[4:7], v[180:183], v[224:227], v[4:7]
	v_mfma_f32_16x16x32_bf16 v[0:3], v[192:195], v[224:227], v[0:3]
	v_mfma_f32_16x16x32_bf16 v[48:51], v[184:187], v[204:207], v[48:51]
	v_mfma_f32_16x16x32_bf16 v[40:43], v[196:199], v[204:207], v[40:43]
	v_mfma_f32_16x16x32_bf16 v[32:35], v[184:187], v[212:215], v[32:35]
	v_mfma_f32_16x16x32_bf16 v[24:27], v[196:199], v[212:215], v[24:27]
	v_mfma_f32_16x16x32_bf16 v[16:19], v[184:187], v[220:223], v[16:19]
	v_mfma_f32_16x16x32_bf16 v[8:11], v[196:199], v[220:223], v[8:11]
	v_mfma_f32_16x16x32_bf16 v[4:7], v[184:187], v[228:231], v[4:7]
	v_mfma_f32_16x16x32_bf16 v[0:3], v[196:199], v[228:231], v[0:3]
	s_barrier
; #define PG8_STAGE(bufoff, gbase, voff) do { _Pragma("unroll") for (int _i = 0; _i < 2; ++_i) \
;         __builtin_amdgcn_global_load_lds((const unsigned*)((const char*)(gbase) + (voff)[_i]), (LAS unsigned*)(lds + (bufoff) + ldsw + _i * 8192), 16, 0, 0); } while (0)
; #define PG8_LDA(dst, b, h) do { _Pragma("unroll") for (int m = 0; m < 4; ++m) _Pragma("unroll") for (int k = 0; k < 2; ++k) dst[m][k] = *(const LAS bf16x8*)(lds + PG8_SA(b, h) + aoff + m * 2048 + k * 1024); } while (0)
; #define PG8_LDB(dst, b, h) do { _Pragma("unroll") for (int n = 0; n < 2; ++n) _Pragma("unroll") for (int k = 0; k < 2; ++k) dst[n][k] = *(const LAS bf16x8*)(lds + PG8_SB(b, h) + boff + n * 2048 + k * 1024); } while (0)
; #define PG8_MMA(ai, bj, At, Bt) do { __builtin_amdgcn_s_setprio(1); _Pragma("unroll") for (int m = 0; m < 4; ++m) _Pragma("unroll") for (int n = 0; n < 2; ++n) _Pragma("unroll") for (int k = 0; k < 2; ++k) \
;         acc[ai][bj][m][n] = __builtin_amdgcn_mfma_f32_16x16x32_bf16(Bt[n][k], At[m][k], acc[ai][bj][m][n], 0, 0, 0); __builtin_amdgcn_s_setprio(0); } while (0)
; #define PG8_WAIT_V(n) asm volatile("s_waitcnt vmcnt(" #n ")" ::: "memory")
; #define PG8_WAIT_L(n) asm volatile("s_waitcnt lgkmcnt(" #n ")" ::: "memory")
; #define PG8_BAR __builtin_amdgcn_s_barrier()
; #define PG8_SCHED __builtin_amdgcn_sched_barrier(0)
; template <int GI>
; __device__ __forceinline__ void gemm_phase(LAS unsigned char* lds, unsigned char* ws, int G, int cblk) {
;     ...
;             PG8_LDB(B0, 1, 0); PG8_LDB(B1, 1, 1); PG8_SCHED; PG8_LDA(At, 1, 0); PG8_STAGE(PG8_SA(0, 1), a2 + hstepA, voffA);
;             PG8_WAIT_V(8); PG8_WAIT_L(0); PG8_BAR; PG8_MMA(0, 0, At, B0); PG8_MMA(0, 1, At, B1); PG8_BAR; PG8_SCHED;
;             PG8_LDA(At, 1, 1); PG8_STAGE(PG8_SB(1, 0), b3, voffB); PG8_STAGE(PG8_SB(1, 1), b3 + hstepB, voffB); PG8_STAGE(PG8_SA(1, 0), a3, voffA);
;             PG8_WAIT_V(8); PG8_WAIT_L(0); PG8_BAR; PG8_MMA(1, 0, At, B0); PG8_MMA(1, 1, At, B1); PG8_BAR; PG8_SCHED;
;         }
	s_add_i32 s34, 0, 0x18000
	v_add_u32_e32 v161, s34, v153
	s_add_i32 s95, 0, 0x1c000
	ds_read_b128 v[164:167], v161
	ds_read_b128 v[168:171], v161 offset:1024
	ds_read_b128 v[172:175], v161 offset:2048
	ds_read_b128 v[176:179], v161 offset:3072
	v_add_u32_e32 v161, s95, v153
	ds_read_b128 v[180:183], v161
	ds_read_b128 v[184:187], v161 offset:1024
	ds_read_b128 v[192:195], v161 offset:2048
	ds_read_b128 v[196:199], v161 offset:3072
	s_add_u32 s92, s92, 0x80000
	s_addc_u32 s93, s93, 0
	s_mov_b32 m0, s21
	v_lshl_add_u64 v[236:237], s[92:93], 0, v[128:129]
	ds_read_b128 v[200:203], v156 offset:32768
	ds_read_b128 v[204:207], v156 offset:33792
	ds_read_b128 v[208:211], v156 offset:34816
	ds_read_b128 v[212:215], v156 offset:35840
	ds_read_b128 v[216:219], v156 offset:36864
	ds_read_b128 v[220:223], v156 offset:37888
	ds_read_b128 v[224:227], v156 offset:38912
	ds_read_b128 v[228:231], v156 offset:39936
	global_load_lds_dwordx4 v[236:237], off
	v_lshl_add_u64 v[236:237], s[92:93], 0, v[132:133]
	s_mov_b32 m0, s35
	s_nop 0
	global_load_lds_dwordx4 v[236:237], off
	s_waitcnt vmcnt(8)
	s_waitcnt lgkmcnt(0)
	s_barrier
	s_waitcnt lgkmcnt(0)
	v_mfma_f32_16x16x32_bf16 v[124:127], v[164:167], v[200:203], v[124:127]
	v_mfma_f32_16x16x32_bf16 v[120:123], v[172:175], v[200:203], v[120:123]
	v_mfma_f32_16x16x32_bf16 v[112:115], v[164:167], v[208:211], v[112:115]
	v_mfma_f32_16x16x32_bf16 v[104:107], v[172:175], v[208:211], v[104:107]
	v_mfma_f32_16x16x32_bf16 v[96:99], v[164:167], v[216:219], v[96:99]
	v_mfma_f32_16x16x32_bf16 v[88:91], v[172:175], v[216:219], v[88:91]
	v_mfma_f32_16x16x32_bf16 v[80:83], v[164:167], v[224:227], v[80:83]
	v_mfma_f32_16x16x32_bf16 v[72:75], v[172:175], v[224:227], v[72:75]
	v_mfma_f32_16x16x32_bf16 v[124:127], v[168:171], v[204:207], v[124:127]
	v_mfma_f32_16x16x32_bf16 v[120:123], v[176:179], v[204:207], v[120:123]
	v_mfma_f32_16x16x32_bf16 v[112:115], v[168:171], v[212:215], v[112:115]
	v_mfma_f32_16x16x32_bf16 v[104:107], v[176:179], v[212:215], v[104:107]
	v_mfma_f32_16x16x32_bf16 v[96:99], v[168:171], v[220:223], v[96:99]
	v_mfma_f32_16x16x32_bf16 v[88:91], v[176:179], v[220:223], v[88:91]
	v_mfma_f32_16x16x32_bf16 v[80:83], v[168:171], v[228:231], v[80:83]
	v_mfma_f32_16x16x32_bf16 v[72:75], v[176:179], v[228:231], v[72:75]
	v_mfma_f32_16x16x32_bf16 v[116:119], v[180:183], v[200:203], v[116:119]
	v_mfma_f32_16x16x32_bf16 v[108:111], v[192:195], v[200:203], v[108:111]
	v_mfma_f32_16x16x32_bf16 v[100:103], v[180:183], v[208:211], v[100:103]
	v_mfma_f32_16x16x32_bf16 v[92:95], v[192:195], v[208:211], v[92:95]
	v_mfma_f32_16x16x32_bf16 v[84:87], v[180:183], v[216:219], v[84:87]
	v_mfma_f32_16x16x32_bf16 v[76:79], v[192:195], v[216:219], v[76:79]
	v_mfma_f32_16x16x32_bf16 v[68:71], v[180:183], v[224:227], v[68:71]
	v_mfma_f32_16x16x32_bf16 v[64:67], v[192:195], v[224:227], v[64:67]
	v_mfma_f32_16x16x32_bf16 v[116:119], v[184:187], v[204:207], v[116:119]
	v_mfma_f32_16x16x32_bf16 v[108:111], v[196:199], v[204:207], v[108:111]
	v_mfma_f32_16x16x32_bf16 v[100:103], v[184:187], v[212:215], v[100:103]
	v_mfma_f32_16x16x32_bf16 v[92:95], v[196:199], v[212:215], v[92:95]
	v_mfma_f32_16x16x32_bf16 v[84:87], v[184:187], v[220:223], v[84:87]
	v_mfma_f32_16x16x32_bf16 v[76:79], v[196:199], v[220:223], v[76:79]
	v_mfma_f32_16x16x32_bf16 v[68:71], v[184:187], v[228:231], v[68:71]
	v_mfma_f32_16x16x32_bf16 v[64:67], v[196:199], v[228:231], v[64:67]
	s_barrier
	s_add_i32 s34, s34, s18
	v_lshl_add_u64 v[158:159], v[158:159], 0, s[70:71]
	s_mov_b32 m0, s34
	ds_read_b128 v[200:203], v156 offset:49152
	ds_read_b128 v[204:207], v156 offset:50176
	ds_read_b128 v[208:211], v156 offset:51200
	ds_read_b128 v[212:215], v156 offset:52224
	ds_read_b128 v[216:219], v156 offset:53248
	ds_read_b128 v[220:223], v156 offset:54272
	ds_read_b128 v[224:227], v156 offset:55296
	ds_read_b128 v[228:231], v156 offset:56320
	global_load_lds_dwordx4 v[158:159], off
	s_add_i32 m0, s34, 0x2000
	s_add_u32 s6, s6, 0x80080
	v_lshl_add_u64 v[158:159], v[188:189], 0, s[70:71]
	s_addc_u32 s7, s7, 0
	s_add_i32 s34, s95, s18
	global_load_lds_dwordx4 v[158:159], off
	v_lshl_add_u64 v[158:159], s[6:7], 0, v[130:131]
	s_mov_b32 m0, s34
	s_nop 0
	global_load_lds_dwordx4 v[158:159], off
	v_lshl_add_u64 v[158:159], s[6:7], 0, v[134:135]
	s_add_i32 m0, s34, 0x2000
	s_nop 0
	global_load_lds_dwordx4 v[158:159], off
	v_lshl_add_u64 v[158:159], v[232:233], 0, s[70:71]
	s_mov_b32 m0, s0
	s_nop 0
	global_load_lds_dwordx4 v[158:159], off
	v_lshl_add_u64 v[158:159], v[234:235], 0, s[70:71]
	s_mov_b32 m0, s1
	s_nop 0
	global_load_lds_dwordx4 v[158:159], off
	s_waitcnt vmcnt(8)
	s_waitcnt lgkmcnt(0)
	s_barrier
	s_waitcnt lgkmcnt(0)
	v_mfma_f32_16x16x32_bf16 v[60:63], v[164:167], v[200:203], v[60:63]
	v_mfma_f32_16x16x32_bf16 v[56:59], v[172:175], v[200:203], v[56:59]
	v_mfma_f32_16x16x32_bf16 v[52:55], v[164:167], v[208:211], v[52:55]
	v_mfma_f32_16x16x32_bf16 v[44:47], v[172:175], v[208:211], v[44:47]
	v_mfma_f32_16x16x32_bf16 v[36:39], v[164:167], v[216:219], v[36:39]
	v_mfma_f32_16x16x32_bf16 v[28:31], v[172:175], v[216:219], v[28:31]
	v_mfma_f32_16x16x32_bf16 v[20:23], v[164:167], v[224:227], v[20:23]
	v_mfma_f32_16x16x32_bf16 v[12:15], v[172:175], v[224:227], v[12:15]
	v_mfma_f32_16x16x32_bf16 v[60:63], v[168:171], v[204:207], v[60:63]
	v_mfma_f32_16x16x32_bf16 v[56:59], v[176:179], v[204:207], v[56:59]
	v_mfma_f32_16x16x32_bf16 v[52:55], v[168:171], v[212:215], v[52:55]
	v_mfma_f32_16x16x32_bf16 v[44:47], v[176:179], v[212:215], v[44:47]
	v_mfma_f32_16x16x32_bf16 v[36:39], v[168:171], v[220:223], v[36:39]
	v_mfma_f32_16x16x32_bf16 v[28:31], v[176:179], v[220:223], v[28:31]
	v_mfma_f32_16x16x32_bf16 v[20:23], v[168:171], v[228:231], v[20:23]
	v_mfma_f32_16x16x32_bf16 v[12:15], v[176:179], v[228:231], v[12:15]
	v_mfma_f32_16x16x32_bf16 v[48:51], v[180:183], v[200:203], v[48:51]
	v_mfma_f32_16x16x32_bf16 v[40:43], v[192:195], v[200:203], v[40:43]
	v_mfma_f32_16x16x32_bf16 v[32:35], v[180:183], v[208:211], v[32:35]
	v_mfma_f32_16x16x32_bf16 v[24:27], v[192:195], v[208:211], v[24:27]
	v_mfma_f32_16x16x32_bf16 v[16:19], v[180:183], v[216:219], v[16:19]
	v_mfma_f32_16x16x32_bf16 v[8:11], v[192:195], v[216:219], v[8:11]
	v_mfma_f32_16x16x32_bf16 v[4:7], v[180:183], v[224:227], v[4:7]
	v_mfma_f32_16x16x32_bf16 v[0:3], v[192:195], v[224:227], v[0:3]
	v_mfma_f32_16x16x32_bf16 v[48:51], v[184:187], v[204:207], v[48:51]
	v_mfma_f32_16x16x32_bf16 v[40:43], v[196:199], v[204:207], v[40:43]
	v_mfma_f32_16x16x32_bf16 v[32:35], v[184:187], v[212:215], v[32:35]
	v_mfma_f32_16x16x32_bf16 v[24:27], v[196:199], v[212:215], v[24:27]
	v_mfma_f32_16x16x32_bf16 v[16:19], v[184:187], v[220:223], v[16:19]
	v_mfma_f32_16x16x32_bf16 v[8:11], v[196:199], v[220:223], v[8:11]
	v_mfma_f32_16x16x32_bf16 v[4:7], v[184:187], v[228:231], v[4:7]
	v_mfma_f32_16x16x32_bf16 v[0:3], v[196:199], v[228:231], v[0:3]
	s_barrier
	s_add_i32 s94, s94, 2
	s_add_u32 s4, s4, 0x100
	s_addc_u32 s5, s5, 0
	s_add_u32 s15, s15, 0x100
	s_addc_u32 s58, s58, 0
	s_cmp_gt_u32 s94, 29
	s_cbranch_scc0 .LBB0_98

; #define PG8_STAGE(bufoff, gbase, voff) do { _Pragma("unroll") for (int _i = 0; _i < 2; ++_i) \
;         __builtin_amdgcn_global_load_lds((const unsigned*)((const char*)(gbase) + (voff)[_i]), (LAS unsigned*)(lds + (bufoff) + ldsw + _i * 8192), 16, 0, 0); } while (0)
; #define PG8_LDA(dst, b, h) do { _Pragma("unroll") for (int m = 0; m < 4; ++m) _Pragma("unroll") for (int k = 0; k < 2; ++k) dst[m][k] = *(const LAS bf16x8*)(lds + PG8_SA(b, h) + aoff + m * 2048 + k * 1024); } while (0)
; #define PG8_LDB(dst, b, h) do { _Pragma("unroll") for (int n = 0; n < 2; ++n) _Pragma("unroll") for (int k = 0; k < 2; ++k) dst[n][k] = *(const LAS bf16x8*)(lds + PG8_SB(b, h) + boff + n * 2048 + k * 1024); } while (0)
; #define PG8_MMA(ai, bj, At, Bt) do { __builtin_amdgcn_s_setprio(1); _Pragma("unroll") for (int m = 0; m < 4; ++m) _Pragma("unroll") for (int n = 0; n < 2; ++n) _Pragma("unroll") for (int k = 0; k < 2; ++k) \
;         acc[ai][bj][m][n] = __builtin_amdgcn_mfma_f32_16x16x32_bf16(Bt[n][k], At[m][k], acc[ai][bj][m][n], 0, 0, 0); __builtin_amdgcn_s_setprio(0); } while (0)
; #define PG8_WAIT_V(n) asm volatile("s_waitcnt vmcnt(" #n ")" ::: "memory")
; #define PG8_WAIT_L(n) asm volatile("s_waitcnt lgkmcnt(" #n ")" ::: "memory")
; #define PG8_BAR __builtin_amdgcn_s_barrier()
; #define PG8_SCHED __builtin_amdgcn_sched_barrier(0)
; template <int GI>
; __device__ __forceinline__ void gemm_phase(LAS unsigned char* lds, unsigned char* ws, int G, int cblk) {
;     ...
;             PG8_LDB(B0, 0, 0); PG8_LDB(B1, 0, 1); PG8_SCHED; PG8_LDA(At, 0, 0); PG8_STAGE(PG8_SA(1, 1), a1 + hstepA, voffA);
;             PG8_WAIT_V(8); PG8_WAIT_L(0); PG8_BAR; PG8_MMA(0, 0, At, B0); PG8_MMA(0, 1, At, B1); PG8_BAR; PG8_SCHED;
;             PG8_LDA(At, 0, 1); PG8_STAGE(PG8_SB(0, 0), b2, voffB); PG8_STAGE(PG8_SB(0, 1), b2 + hstepB, voffB); PG8_STAGE(PG8_SA(0, 0), a2, voffA);
;             PG8_WAIT_V(8); PG8_WAIT_L(0); PG8_BAR; PG8_MMA(1, 0, At, B0); PG8_MMA(1, 1, At, B1); PG8_BAR; PG8_SCHED;
.LBB0_123:
	s_add_u32 s86, s86, 0x80080
	s_addc_u32 s87, s87, 0
	s_add_u32 s4, s88, 0x100
	s_addc_u32 s14, s89, 0
	s_mov_b32 s15, -2
	ds_read_b128 v[154:157], v151
	ds_read_b128 v[164:167], v151 offset:1024
	ds_read_b128 v[168:171], v151 offset:2048
	ds_read_b128 v[172:175], v151 offset:3072
	ds_read_b128 v[176:179], v152
	ds_read_b128 v[180:183], v152 offset:1024
	ds_read_b128 v[184:187], v152 offset:2048
	ds_read_b128 v[192:195], v152 offset:3072
	s_add_u32 s34, s86, 0xfff80080
	s_addc_u32 s63, s87, -1
	s_cmp_eq_u32 s15, 28
	s_cselect_b32 s91, s75, s63
	s_cselect_b32 s90, s74, s34
	s_cselect_b32 s89, s77, s14
	s_cselect_b32 s88, s76, s4
	v_lshl_add_u64 v[158:159], s[86:87], 0, v[146:147]
	s_add_i32 m0, s16, 0xc000
	ds_read_b128 v[196:199], v153
	ds_read_b128 v[200:203], v153 offset:1024
	ds_read_b128 v[204:207], v153 offset:2048
	ds_read_b128 v[208:211], v153 offset:3072
	ds_read_b128 v[212:215], v153 offset:4096
	ds_read_b128 v[216:219], v153 offset:5120
	ds_read_b128 v[220:223], v153 offset:6144
	ds_read_b128 v[224:227], v153 offset:7168
	global_load_lds_dwordx4 v[158:159], off
	v_lshl_add_u64 v[158:159], s[86:87], 0, v[148:149]
	s_add_i32 m0, s16, 0xe000
	s_nop 0
	global_load_lds_dwordx4 v[158:159], off
	s_waitcnt vmcnt(8)
	s_waitcnt lgkmcnt(0)
	s_barrier
	s_waitcnt lgkmcnt(0)
	v_mfma_f32_16x16x32_bf16 v[124:127], v[154:157], v[196:199], 0
	v_mfma_f32_16x16x32_bf16 v[120:123], v[168:171], v[196:199], 0
	v_mfma_f32_16x16x32_bf16 v[116:119], v[154:157], v[204:207], 0
	v_mfma_f32_16x16x32_bf16 v[108:111], v[168:171], v[204:207], 0
	v_mfma_f32_16x16x32_bf16 v[100:103], v[154:157], v[212:215], 0
	v_mfma_f32_16x16x32_bf16 v[92:95], v[168:171], v[212:215], 0
	v_mfma_f32_16x16x32_bf16 v[84:87], v[154:157], v[220:223], 0
	v_mfma_f32_16x16x32_bf16 v[76:79], v[168:171], v[220:223], 0
	v_mfma_f32_16x16x32_bf16 v[124:127], v[164:167], v[200:203], v[124:127]
	v_mfma_f32_16x16x32_bf16 v[120:123], v[172:175], v[200:203], v[120:123]
	v_mfma_f32_16x16x32_bf16 v[116:119], v[164:167], v[208:211], v[116:119]
	v_mfma_f32_16x16x32_bf16 v[108:111], v[172:175], v[208:211], v[108:111]
	v_mfma_f32_16x16x32_bf16 v[100:103], v[164:167], v[216:219], v[100:103]
	v_mfma_f32_16x16x32_bf16 v[92:95], v[172:175], v[216:219], v[92:95]
	v_mfma_f32_16x16x32_bf16 v[84:87], v[164:167], v[224:227], v[84:87]
	v_mfma_f32_16x16x32_bf16 v[76:79], v[172:175], v[224:227], v[76:79]
	v_mfma_f32_16x16x32_bf16 v[112:115], v[176:179], v[196:199], 0
	v_mfma_f32_16x16x32_bf16 v[104:107], v[184:187], v[196:199], 0
	v_mfma_f32_16x16x32_bf16 v[96:99], v[176:179], v[204:207], 0
	v_mfma_f32_16x16x32_bf16 v[88:91], v[184:187], v[204:207], 0
	v_mfma_f32_16x16x32_bf16 v[80:83], v[176:179], v[212:215], 0
	v_mfma_f32_16x16x32_bf16 v[72:75], v[184:187], v[212:215], 0
	v_mfma_f32_16x16x32_bf16 v[68:71], v[176:179], v[220:223], 0
	v_mfma_f32_16x16x32_bf16 v[64:67], v[184:187], v[220:223], 0
	v_mfma_f32_16x16x32_bf16 v[112:115], v[180:183], v[200:203], v[112:115]
	v_mfma_f32_16x16x32_bf16 v[104:107], v[192:195], v[200:203], v[104:107]
	v_mfma_f32_16x16x32_bf16 v[96:99], v[180:183], v[208:211], v[96:99]
	v_mfma_f32_16x16x32_bf16 v[88:91], v[192:195], v[208:211], v[88:91]
	v_mfma_f32_16x16x32_bf16 v[80:83], v[180:183], v[216:219], v[80:83]
	v_mfma_f32_16x16x32_bf16 v[72:75], v[192:195], v[216:219], v[72:75]
	v_mfma_f32_16x16x32_bf16 v[68:71], v[180:183], v[224:227], v[68:71]
	v_mfma_f32_16x16x32_bf16 v[64:67], v[192:195], v[224:227], v[64:67]
	s_barrier
	s_add_i32 s34, s25, s0
	v_lshl_add_u64 v[158:159], s[88:89], 0, v[130:131]
	s_mov_b32 m0, s34
	ds_read_b128 v[196:199], v153 offset:16384
	ds_read_b128 v[200:203], v153 offset:17408
	ds_read_b128 v[204:207], v153 offset:18432
	ds_read_b128 v[208:211], v153 offset:19456
	ds_read_b128 v[212:215], v153 offset:20480
	ds_read_b128 v[216:219], v153 offset:21504
	ds_read_b128 v[220:223], v153 offset:22528
	ds_read_b128 v[224:227], v153 offset:23552
	global_load_lds_dwordx4 v[158:159], off
	s_add_i32 m0, s34, 0x2000
	s_add_u32 s92, s88, 0x80000
	v_lshl_add_u64 v[188:189], s[88:89], 0, v[134:135]
	s_addc_u32 s93, s89, 0
	s_add_i32 s34, s26, s0
	global_load_lds_dwordx4 v[188:189], off
	v_lshl_add_u64 v[228:229], s[92:93], 0, v[130:131]
	s_mov_b32 m0, s34
	v_lshl_add_u64 v[230:231], s[90:91], 0, v[132:133]
	global_load_lds_dwordx4 v[228:229], off
	v_lshl_add_u64 v[228:229], s[92:93], 0, v[134:135]
	s_add_i32 m0, s34, 0x2000
	s_nop 0
	global_load_lds_dwordx4 v[228:229], off
	v_lshl_add_u64 v[228:229], s[90:91], 0, v[128:129]
	s_mov_b32 m0, s16
	s_nop 0
	global_load_lds_dwordx4 v[228:229], off
	s_mov_b32 m0, s17
	s_nop 0
	global_load_lds_dwordx4 v[230:231], off
	s_waitcnt vmcnt(8)
	s_waitcnt lgkmcnt(0)
	s_barrier
; #define PG8_STAGE(bufoff, gbase, voff) do { _Pragma("unroll") for (int _i = 0; _i < 2; ++_i) \
;         __builtin_amdgcn_global_load_lds((const unsigned*)((const char*)(gbase) + (voff)[_i]), (LAS unsigned*)(lds + (bufoff) + ldsw + _i * 8192), 16, 0, 0); } while (0)
; #define PG8_LDA(dst, b, h) do { _Pragma("unroll") for (int m = 0; m < 4; ++m) _Pragma("unroll") for (int k = 0; k < 2; ++k) dst[m][k] = *(const LAS bf16x8*)(lds + PG8_SA(b, h) + aoff + m * 2048 + k * 1024); } while (0)
; #define PG8_LDB(dst, b, h) do { _Pragma("unroll") for (int n = 0; n < 2; ++n) _Pragma("unroll") for (int k = 0; k < 2; ++k) dst[n][k] = *(const LAS bf16x8*)(lds + PG8_SB(b, h) + boff + n * 2048 + k * 1024); } while (0)
; #define PG8_MMA(ai, bj, At, Bt) do { __builtin_amdgcn_s_setprio(1); _Pragma("unroll") for (int m = 0; m < 4; ++m) _Pragma("unroll") for (int n = 0; n < 2; ++n) _Pragma("unroll") for (int k = 0; k < 2; ++k) \
;         acc[ai][bj][m][n] = __builtin_amdgcn_mfma_f32_16x16x32_bf16(Bt[n][k], At[m][k], acc[ai][bj][m][n], 0, 0, 0); __builtin_amdgcn_s_setprio(0); } while (0)
; #define PG8_WAIT_V(n) asm volatile("s_waitcnt vmcnt(" #n ")" ::: "memory")
; #define PG8_WAIT_L(n) asm volatile("s_waitcnt lgkmcnt(" #n ")" ::: "memory")
; #define PG8_BAR __builtin_amdgcn_s_barrier()
; #define PG8_SCHED __builtin_amdgcn_sched_barrier(0)
; template <int GI>
; __device__ __forceinline__ void gemm_phase(LAS unsigned char* lds, unsigned char* ws, int G, int cblk) {
;     ...
;             PG8_WAIT_V(8); PG8_WAIT_L(0); PG8_BAR; PG8_MMA(1, 0, At, B0); PG8_MMA(1, 1, At, B1); PG8_BAR; PG8_SCHED;
;             PG8_LDB(B0, 1, 0); PG8_LDB(B1, 1, 1); PG8_SCHED; PG8_LDA(At, 1, 0); PG8_STAGE(PG8_SA(0, 1), a2 + hstepA, voffA);
;             PG8_WAIT_V(8); PG8_WAIT_L(0); PG8_BAR; PG8_MMA(0, 0, At, B0); PG8_MMA(0, 1, At, B1); PG8_BAR; PG8_SCHED;
	s_waitcnt lgkmcnt(0)
	v_mfma_f32_16x16x32_bf16 v[60:63], v[154:157], v[196:199], 0
	v_mfma_f32_16x16x32_bf16 v[56:59], v[168:171], v[196:199], 0
	v_mfma_f32_16x16x32_bf16 v[52:55], v[154:157], v[204:207], 0
	v_mfma_f32_16x16x32_bf16 v[48:51], v[168:171], v[204:207], 0
	v_mfma_f32_16x16x32_bf16 v[36:39], v[154:157], v[212:215], 0
	v_mfma_f32_16x16x32_bf16 v[32:35], v[168:171], v[212:215], 0
	v_mfma_f32_16x16x32_bf16 v[20:23], v[154:157], v[220:223], 0
	v_mfma_f32_16x16x32_bf16 v[16:19], v[168:171], v[220:223], 0
	v_mfma_f32_16x16x32_bf16 v[60:63], v[164:167], v[200:203], v[60:63]
	v_mfma_f32_16x16x32_bf16 v[56:59], v[172:175], v[200:203], v[56:59]
	v_mfma_f32_16x16x32_bf16 v[52:55], v[164:167], v[208:211], v[52:55]
	v_mfma_f32_16x16x32_bf16 v[48:51], v[172:175], v[208:211], v[48:51]
	v_mfma_f32_16x16x32_bf16 v[36:39], v[164:167], v[216:219], v[36:39]
	v_mfma_f32_16x16x32_bf16 v[32:35], v[172:175], v[216:219], v[32:35]
	v_mfma_f32_16x16x32_bf16 v[20:23], v[164:167], v[224:227], v[20:23]
	v_mfma_f32_16x16x32_bf16 v[16:19], v[172:175], v[224:227], v[16:19]
	v_mfma_f32_16x16x32_bf16 v[44:47], v[176:179], v[196:199], 0
	v_mfma_f32_16x16x32_bf16 v[40:43], v[184:187], v[196:199], 0
	v_mfma_f32_16x16x32_bf16 v[28:31], v[176:179], v[204:207], 0
	v_mfma_f32_16x16x32_bf16 v[24:27], v[184:187], v[204:207], 0
	v_mfma_f32_16x16x32_bf16 v[12:15], v[176:179], v[212:215], 0
	v_mfma_f32_16x16x32_bf16 v[8:11], v[184:187], v[212:215], 0
	v_mfma_f32_16x16x32_bf16 v[4:7], v[176:179], v[220:223], 0
	v_mfma_f32_16x16x32_bf16 v[0:3], v[184:187], v[220:223], 0
	v_mfma_f32_16x16x32_bf16 v[44:47], v[180:183], v[200:203], v[44:47]
	v_mfma_f32_16x16x32_bf16 v[40:43], v[192:195], v[200:203], v[40:43]
	v_mfma_f32_16x16x32_bf16 v[28:31], v[180:183], v[208:211], v[28:31]
	v_mfma_f32_16x16x32_bf16 v[24:27], v[192:195], v[208:211], v[24:27]
	v_mfma_f32_16x16x32_bf16 v[12:15], v[180:183], v[216:219], v[12:15]
	v_mfma_f32_16x16x32_bf16 v[8:11], v[192:195], v[216:219], v[8:11]
	v_mfma_f32_16x16x32_bf16 v[4:7], v[180:183], v[224:227], v[4:7]
	v_mfma_f32_16x16x32_bf16 v[0:3], v[192:195], v[224:227], v[0:3]
	s_barrier
	s_add_i32 s34, 0, 0x18000
	v_add_u32_e32 v161, s34, v150
	s_add_i32 s63, 0, 0x1c000
	ds_read_b128 v[154:157], v161
	ds_read_b128 v[164:167], v161 offset:1024
	ds_read_b128 v[168:171], v161 offset:2048
	ds_read_b128 v[172:175], v161 offset:3072
	v_add_u32_e32 v161, s63, v150
	ds_read_b128 v[176:179], v161
	ds_read_b128 v[180:183], v161 offset:1024
	ds_read_b128 v[184:187], v161 offset:2048
	ds_read_b128 v[192:195], v161 offset:3072
	s_add_u32 s90, s90, 0x80000
	s_addc_u32 s91, s91, 0
	s_mov_b32 m0, s18
	v_lshl_add_u64 v[232:233], s[90:91], 0, v[128:129]
	ds_read_b128 v[196:199], v153 offset:32768
	ds_read_b128 v[200:203], v153 offset:33792
	ds_read_b128 v[204:207], v153 offset:34816
	ds_read_b128 v[208:211], v153 offset:35840
	ds_read_b128 v[212:215], v153 offset:36864
	ds_read_b128 v[216:219], v153 offset:37888
	ds_read_b128 v[220:223], v153 offset:38912
	ds_read_b128 v[224:227], v153 offset:39936
	global_load_lds_dwordx4 v[232:233], off
	v_lshl_add_u64 v[232:233], s[90:91], 0, v[132:133]
	s_mov_b32 m0, s19
	s_nop 0
	global_load_lds_dwordx4 v[232:233], off
	s_waitcnt vmcnt(8)
	s_waitcnt lgkmcnt(0)
	s_barrier
	s_waitcnt lgkmcnt(0)
	v_mfma_f32_16x16x32_bf16 v[124:127], v[154:157], v[196:199], v[124:127]
	v_mfma_f32_16x16x32_bf16 v[120:123], v[168:171], v[196:199], v[120:123]
	v_mfma_f32_16x16x32_bf16 v[116:119], v[154:157], v[204:207], v[116:119]
	v_mfma_f32_16x16x32_bf16 v[108:111], v[168:171], v[204:207], v[108:111]
	v_mfma_f32_16x16x32_bf16 v[100:103], v[154:157], v[212:215], v[100:103]
	v_mfma_f32_16x16x32_bf16 v[92:95], v[168:171], v[212:215], v[92:95]
	v_mfma_f32_16x16x32_bf16 v[84:87], v[154:157], v[220:223], v[84:87]
	v_mfma_f32_16x16x32_bf16 v[76:79], v[168:171], v[220:223], v[76:79]
	v_mfma_f32_16x16x32_bf16 v[124:127], v[164:167], v[200:203], v[124:127]
	v_mfma_f32_16x16x32_bf16 v[120:123], v[172:175], v[200:203], v[120:123]
	v_mfma_f32_16x16x32_bf16 v[116:119], v[164:167], v[208:211], v[116:119]
	v_mfma_f32_16x16x32_bf16 v[108:111], v[172:175], v[208:211], v[108:111]
	v_mfma_f32_16x16x32_bf16 v[100:103], v[164:167], v[216:219], v[100:103]
	v_mfma_f32_16x16x32_bf16 v[92:95], v[172:175], v[216:219], v[92:95]
	v_mfma_f32_16x16x32_bf16 v[84:87], v[164:167], v[224:227], v[84:87]
	v_mfma_f32_16x16x32_bf16 v[76:79], v[172:175], v[224:227], v[76:79]
	v_mfma_f32_16x16x32_bf16 v[112:115], v[176:179], v[196:199], v[112:115]
	v_mfma_f32_16x16x32_bf16 v[104:107], v[184:187], v[196:199], v[104:107]
	v_mfma_f32_16x16x32_bf16 v[96:99], v[176:179], v[204:207], v[96:99]
	v_mfma_f32_16x16x32_bf16 v[88:91], v[184:187], v[204:207], v[88:91]
	v_mfma_f32_16x16x32_bf16 v[80:83], v[176:179], v[212:215], v[80:83]
	v_mfma_f32_16x16x32_bf16 v[72:75], v[184:187], v[212:215], v[72:75]
	v_mfma_f32_16x16x32_bf16 v[68:71], v[176:179], v[220:223], v[68:71]
	v_mfma_f32_16x16x32_bf16 v[64:67], v[184:187], v[220:223], v[64:67]
	v_mfma_f32_16x16x32_bf16 v[112:115], v[180:183], v[200:203], v[112:115]
	v_mfma_f32_16x16x32_bf16 v[104:107], v[192:195], v[200:203], v[104:107]
	v_mfma_f32_16x16x32_bf16 v[96:99], v[180:183], v[208:211], v[96:99]
	v_mfma_f32_16x16x32_bf16 v[88:91], v[192:195], v[208:211], v[88:91]
	v_mfma_f32_16x16x32_bf16 v[80:83], v[180:183], v[216:219], v[80:83]
	v_mfma_f32_16x16x32_bf16 v[72:75], v[192:195], v[216:219], v[72:75]
	v_mfma_f32_16x16x32_bf16 v[68:71], v[180:183], v[224:227], v[68:71]
	v_mfma_f32_16x16x32_bf16 v[64:67], v[192:195], v[224:227], v[64:67]
	s_barrier
; #define PG8_STAGE(bufoff, gbase, voff) do { _Pragma("unroll") for (int _i = 0; _i < 2; ++_i) \
;         __builtin_amdgcn_global_load_lds((const unsigned*)((const char*)(gbase) + (voff)[_i]), (LAS unsigned*)(lds + (bufoff) + ldsw + _i * 8192), 16, 0, 0); } while (0)
; #define PG8_LDA(dst, b, h) do { _Pragma("unroll") for (int m = 0; m < 4; ++m) _Pragma("unroll") for (int k = 0; k < 2; ++k) dst[m][k] = *(const LAS bf16x8*)(lds + PG8_SA(b, h) + aoff + m * 2048 + k * 1024); } while (0)
; #define PG8_LDB(dst, b, h) do { _Pragma("unroll") for (int n = 0; n < 2; ++n) _Pragma("unroll") for (int k = 0; k < 2; ++k) dst[n][k] = *(const LAS bf16x8*)(lds + PG8_SB(b, h) + boff + n * 2048 + k * 1024); } while (0)
; #define PG8_MMA(ai, bj, At, Bt) do { __builtin_amdgcn_s_setprio(1); _Pragma("unroll") for (int m = 0; m < 4; ++m) _Pragma("unroll") for (int n = 0; n < 2; ++n) _Pragma("unroll") for (int k = 0; k < 2; ++k) \
;         acc[ai][bj][m][n] = __builtin_amdgcn_mfma_f32_16x16x32_bf16(Bt[n][k], At[m][k], acc[ai][bj][m][n], 0, 0, 0); __builtin_amdgcn_s_setprio(0); } while (0)
; #define PG8_WAIT_V(n) asm volatile("s_waitcnt vmcnt(" #n ")" ::: "memory")
; #define PG8_WAIT_L(n) asm volatile("s_waitcnt lgkmcnt(" #n ")" ::: "memory")
; #define PG8_BAR __builtin_amdgcn_s_barrier()
; #define PG8_SCHED __builtin_amdgcn_sched_barrier(0)
; template <int GI>
; __device__ __forceinline__ void gemm_phase(LAS unsigned char* lds, unsigned char* ws, int G, int cblk) {
;     ...
;             PG8_LDB(B0, 0, 0); PG8_LDB(B1, 0, 1); PG8_SCHED; PG8_LDA(At, 0, 0); PG8_STAGE(PG8_SA(1, 1), a1 + hstepA, voffA);
;             PG8_WAIT_V(8); PG8_WAIT_L(0); PG8_BAR; PG8_MMA(0, 0, At, B0); PG8_MMA(0, 1, At, B1); PG8_BAR; PG8_SCHED;
;     ...
;             PG8_LDA(At, 1, 1); PG8_STAGE(PG8_SB(1, 0), b3, voffB); PG8_STAGE(PG8_SB(1, 1), b3 + hstepB, voffB); PG8_STAGE(PG8_SA(1, 0), a3, voffA);
;             PG8_WAIT_V(8); PG8_WAIT_L(0); PG8_BAR; PG8_MMA(1, 0, At, B0); PG8_MMA(1, 1, At, B1); PG8_BAR; PG8_SCHED;
;         }
	s_add_i32 s34, s34, s0
	v_lshl_add_u64 v[158:159], v[158:159], 0, s[38:39]
	s_mov_b32 m0, s34
	ds_read_b128 v[196:199], v153 offset:49152
	ds_read_b128 v[200:203], v153 offset:50176
	ds_read_b128 v[204:207], v153 offset:51200
	ds_read_b128 v[208:211], v153 offset:52224
	ds_read_b128 v[212:215], v153 offset:53248
	ds_read_b128 v[216:219], v153 offset:54272
	ds_read_b128 v[220:223], v153 offset:55296
	ds_read_b128 v[224:227], v153 offset:56320
	global_load_lds_dwordx4 v[158:159], off
	s_add_i32 m0, s34, 0x2000
	s_add_u32 s88, s88, 0x80080
	v_lshl_add_u64 v[158:159], v[188:189], 0, s[38:39]
	s_addc_u32 s89, s89, 0
	s_add_i32 s34, s63, s0
	global_load_lds_dwordx4 v[158:159], off
	v_lshl_add_u64 v[158:159], s[88:89], 0, v[130:131]
	s_mov_b32 m0, s34
	s_nop 0
	global_load_lds_dwordx4 v[158:159], off
	v_lshl_add_u64 v[158:159], s[88:89], 0, v[134:135]
	s_add_i32 m0, s34, 0x2000
	s_nop 0
	global_load_lds_dwordx4 v[158:159], off
	v_lshl_add_u64 v[158:159], v[228:229], 0, s[38:39]
	s_mov_b32 m0, s22
	s_nop 0
	global_load_lds_dwordx4 v[158:159], off
	v_lshl_add_u64 v[158:159], v[230:231], 0, s[38:39]
	s_mov_b32 m0, s23
	s_nop 0
	global_load_lds_dwordx4 v[158:159], off
	s_waitcnt vmcnt(8)
	s_waitcnt lgkmcnt(0)
	s_barrier
	s_waitcnt lgkmcnt(0)
	v_mfma_f32_16x16x32_bf16 v[60:63], v[154:157], v[196:199], v[60:63]
	v_mfma_f32_16x16x32_bf16 v[56:59], v[168:171], v[196:199], v[56:59]
	v_mfma_f32_16x16x32_bf16 v[52:55], v[154:157], v[204:207], v[52:55]
	v_mfma_f32_16x16x32_bf16 v[48:51], v[168:171], v[204:207], v[48:51]
	v_mfma_f32_16x16x32_bf16 v[36:39], v[154:157], v[212:215], v[36:39]
	v_mfma_f32_16x16x32_bf16 v[32:35], v[168:171], v[212:215], v[32:35]
	v_mfma_f32_16x16x32_bf16 v[20:23], v[154:157], v[220:223], v[20:23]
	v_mfma_f32_16x16x32_bf16 v[16:19], v[168:171], v[220:223], v[16:19]
	v_mfma_f32_16x16x32_bf16 v[60:63], v[164:167], v[200:203], v[60:63]
	v_mfma_f32_16x16x32_bf16 v[56:59], v[172:175], v[200:203], v[56:59]
	v_mfma_f32_16x16x32_bf16 v[52:55], v[164:167], v[208:211], v[52:55]
	v_mfma_f32_16x16x32_bf16 v[48:51], v[172:175], v[208:211], v[48:51]
	v_mfma_f32_16x16x32_bf16 v[36:39], v[164:167], v[216:219], v[36:39]
	v_mfma_f32_16x16x32_bf16 v[32:35], v[172:175], v[216:219], v[32:35]
	v_mfma_f32_16x16x32_bf16 v[20:23], v[164:167], v[224:227], v[20:23]
	v_mfma_f32_16x16x32_bf16 v[16:19], v[172:175], v[224:227], v[16:19]
	v_mfma_f32_16x16x32_bf16 v[44:47], v[176:179], v[196:199], v[44:47]
	v_mfma_f32_16x16x32_bf16 v[40:43], v[184:187], v[196:199], v[40:43]
	v_mfma_f32_16x16x32_bf16 v[28:31], v[176:179], v[204:207], v[28:31]
	v_mfma_f32_16x16x32_bf16 v[24:27], v[184:187], v[204:207], v[24:27]
	v_mfma_f32_16x16x32_bf16 v[12:15], v[176:179], v[212:215], v[12:15]
	v_mfma_f32_16x16x32_bf16 v[8:11], v[184:187], v[212:215], v[8:11]
	v_mfma_f32_16x16x32_bf16 v[4:7], v[176:179], v[220:223], v[4:7]
	v_mfma_f32_16x16x32_bf16 v[0:3], v[184:187], v[220:223], v[0:3]
	v_mfma_f32_16x16x32_bf16 v[44:47], v[180:183], v[200:203], v[44:47]
	v_mfma_f32_16x16x32_bf16 v[40:43], v[192:195], v[200:203], v[40:43]
	v_mfma_f32_16x16x32_bf16 v[28:31], v[180:183], v[208:211], v[28:31]
	v_mfma_f32_16x16x32_bf16 v[24:27], v[192:195], v[208:211], v[24:27]
	v_mfma_f32_16x16x32_bf16 v[12:15], v[180:183], v[216:219], v[12:15]
	v_mfma_f32_16x16x32_bf16 v[8:11], v[192:195], v[216:219], v[8:11]
	v_mfma_f32_16x16x32_bf16 v[4:7], v[180:183], v[224:227], v[4:7]
	v_mfma_f32_16x16x32_bf16 v[0:3], v[192:195], v[224:227], v[0:3]
	s_barrier
	s_add_i32 s15, s15, 2
	s_add_u32 s86, s86, 0x100
	s_addc_u32 s87, s87, 0
	s_add_u32 s4, s4, 0x100
	s_addc_u32 s14, s14, 0
	s_cmp_gt_u32 s15, 29
	s_cbranch_scc0 .LBB0_124
	s_branch .Lpeel_exit_1
.LBB0_124:
	ds_read_b128 v[154:157], v151
	ds_read_b128 v[164:167], v151 offset:1024
	ds_read_b128 v[168:171], v151 offset:2048
	ds_read_b128 v[172:175], v151 offset:3072
	ds_read_b128 v[176:179], v152
	ds_read_b128 v[180:183], v152 offset:1024
	ds_read_b128 v[184:187], v152 offset:2048
	ds_read_b128 v[192:195], v152 offset:3072
	s_add_u32 s34, s86, 0xfff80080
	s_addc_u32 s63, s87, -1
	s_cmp_eq_u32 s15, 28
	s_cselect_b32 s91, s75, s63
	s_cselect_b32 s90, s74, s34
	s_cselect_b32 s89, s77, s14
	s_cselect_b32 s88, s76, s4
	v_lshl_add_u64 v[158:159], s[86:87], 0, v[146:147]
	s_add_i32 m0, s16, 0xc000
	ds_read_b128 v[196:199], v153
	ds_read_b128 v[200:203], v153 offset:1024
	ds_read_b128 v[204:207], v153 offset:2048
	ds_read_b128 v[208:211], v153 offset:3072
	ds_read_b128 v[212:215], v153 offset:4096
	ds_read_b128 v[216:219], v153 offset:5120
	ds_read_b128 v[220:223], v153 offset:6144
	ds_read_b128 v[224:227], v153 offset:7168
	global_load_lds_dwordx4 v[158:159], off
	v_lshl_add_u64 v[158:159], s[86:87], 0, v[148:149]
	s_add_i32 m0, s16, 0xe000
	s_nop 0
	global_load_lds_dwordx4 v[158:159], off
	s_waitcnt vmcnt(8)
	s_waitcnt lgkmcnt(0)
	s_barrier
; #define PG8_STAGE(bufoff, gbase, voff) do { _Pragma("unroll") for (int _i = 0; _i < 2; ++_i) \
;         __builtin_amdgcn_global_load_lds((const unsigned*)((const char*)(gbase) + (voff)[_i]), (LAS unsigned*)(lds + (bufoff) + ldsw + _i * 8192), 16, 0, 0); } while (0)
; #define PG8_LDA(dst, b, h) do { _Pragma("unroll") for (int m = 0; m < 4; ++m) _Pragma("unroll") for (int k = 0; k < 2; ++k) dst[m][k] = *(const LAS bf16x8*)(lds + PG8_SA(b, h) + aoff + m * 2048 + k * 1024); } while (0)
; #define PG8_MMA(ai, bj, At, Bt) do { __builtin_amdgcn_s_setprio(1); _Pragma("unroll") for (int m = 0; m < 4; ++m) _Pragma("unroll") for (int n = 0; n < 2; ++n) _Pragma("unroll") for (int k = 0; k < 2; ++k) \
;         acc[ai][bj][m][n] = __builtin_amdgcn_mfma_f32_16x16x32_bf16(Bt[n][k], At[m][k], acc[ai][bj][m][n], 0, 0, 0); __builtin_amdgcn_s_setprio(0); } while (0)
; #define PG8_WAIT_V(n) asm volatile("s_waitcnt vmcnt(" #n ")" ::: "memory")
; #define PG8_WAIT_L(n) asm volatile("s_waitcnt lgkmcnt(" #n ")" ::: "memory")
; #define PG8_BAR __builtin_amdgcn_s_barrier()
; #define PG8_SCHED __builtin_amdgcn_sched_barrier(0)
; template <int GI>
; __device__ __forceinline__ void gemm_phase(LAS unsigned char* lds, unsigned char* ws, int G, int cblk) {
;     ...
;             PG8_WAIT_V(8); PG8_WAIT_L(0); PG8_BAR; PG8_MMA(0, 0, At, B0); PG8_MMA(0, 1, At, B1); PG8_BAR; PG8_SCHED;
;             PG8_LDA(At, 0, 1); PG8_STAGE(PG8_SB(0, 0), b2, voffB); PG8_STAGE(PG8_SB(0, 1), b2 + hstepB, voffB); PG8_STAGE(PG8_SA(0, 0), a2, voffA);
;             PG8_WAIT_V(8); PG8_WAIT_L(0); PG8_BAR; PG8_MMA(1, 0, At, B0); PG8_MMA(1, 1, At, B1); PG8_BAR; PG8_SCHED;
	s_waitcnt lgkmcnt(0)
	v_mfma_f32_16x16x32_bf16 v[124:127], v[154:157], v[196:199], v[124:127]
	v_mfma_f32_16x16x32_bf16 v[120:123], v[168:171], v[196:199], v[120:123]
	v_mfma_f32_16x16x32_bf16 v[116:119], v[154:157], v[204:207], v[116:119]
	v_mfma_f32_16x16x32_bf16 v[108:111], v[168:171], v[204:207], v[108:111]
	v_mfma_f32_16x16x32_bf16 v[100:103], v[154:157], v[212:215], v[100:103]
	v_mfma_f32_16x16x32_bf16 v[92:95], v[168:171], v[212:215], v[92:95]
	v_mfma_f32_16x16x32_bf16 v[84:87], v[154:157], v[220:223], v[84:87]
	v_mfma_f32_16x16x32_bf16 v[76:79], v[168:171], v[220:223], v[76:79]
	v_mfma_f32_16x16x32_bf16 v[124:127], v[164:167], v[200:203], v[124:127]
	v_mfma_f32_16x16x32_bf16 v[120:123], v[172:175], v[200:203], v[120:123]
	v_mfma_f32_16x16x32_bf16 v[116:119], v[164:167], v[208:211], v[116:119]
	v_mfma_f32_16x16x32_bf16 v[108:111], v[172:175], v[208:211], v[108:111]
	v_mfma_f32_16x16x32_bf16 v[100:103], v[164:167], v[216:219], v[100:103]
	v_mfma_f32_16x16x32_bf16 v[92:95], v[172:175], v[216:219], v[92:95]
	v_mfma_f32_16x16x32_bf16 v[84:87], v[164:167], v[224:227], v[84:87]
	v_mfma_f32_16x16x32_bf16 v[76:79], v[172:175], v[224:227], v[76:79]
	v_mfma_f32_16x16x32_bf16 v[112:115], v[176:179], v[196:199], v[112:115]
	v_mfma_f32_16x16x32_bf16 v[104:107], v[184:187], v[196:199], v[104:107]
	v_mfma_f32_16x16x32_bf16 v[96:99], v[176:179], v[204:207], v[96:99]
	v_mfma_f32_16x16x32_bf16 v[88:91], v[184:187], v[204:207], v[88:91]
	v_mfma_f32_16x16x32_bf16 v[80:83], v[176:179], v[212:215], v[80:83]
	v_mfma_f32_16x16x32_bf16 v[72:75], v[184:187], v[212:215], v[72:75]
	v_mfma_f32_16x16x32_bf16 v[68:71], v[176:179], v[220:223], v[68:71]
	v_mfma_f32_16x16x32_bf16 v[64:67], v[184:187], v[220:223], v[64:67]
	v_mfma_f32_16x16x32_bf16 v[112:115], v[180:183], v[200:203], v[112:115]
	v_mfma_f32_16x16x32_bf16 v[104:107], v[192:195], v[200:203], v[104:107]
	v_mfma_f32_16x16x32_bf16 v[96:99], v[180:183], v[208:211], v[96:99]
	v_mfma_f32_16x16x32_bf16 v[88:91], v[192:195], v[208:211], v[88:91]
	v_mfma_f32_16x16x32_bf16 v[80:83], v[180:183], v[216:219], v[80:83]
	v_mfma_f32_16x16x32_bf16 v[72:75], v[192:195], v[216:219], v[72:75]
	v_mfma_f32_16x16x32_bf16 v[68:71], v[180:183], v[224:227], v[68:71]
	v_mfma_f32_16x16x32_bf16 v[64:67], v[192:195], v[224:227], v[64:67]
	s_barrier
	s_add_i32 s34, s25, s0
	v_lshl_add_u64 v[158:159], s[88:89], 0, v[130:131]
	s_mov_b32 m0, s34
	ds_read_b128 v[196:199], v153 offset:16384
	ds_read_b128 v[200:203], v153 offset:17408
	ds_read_b128 v[204:207], v153 offset:18432
	ds_read_b128 v[208:211], v153 offset:19456
	ds_read_b128 v[212:215], v153 offset:20480
	ds_read_b128 v[216:219], v153 offset:21504
	ds_read_b128 v[220:223], v153 offset:22528
	ds_read_b128 v[224:227], v153 offset:23552
	global_load_lds_dwordx4 v[158:159], off
	s_add_i32 m0, s34, 0x2000
	s_add_u32 s92, s88, 0x80000
	v_lshl_add_u64 v[188:189], s[88:89], 0, v[134:135]
	s_addc_u32 s93, s89, 0
	s_add_i32 s34, s26, s0
	global_load_lds_dwordx4 v[188:189], off
	v_lshl_add_u64 v[228:229], s[92:93], 0, v[130:131]
	s_mov_b32 m0, s34
	v_lshl_add_u64 v[230:231], s[90:91], 0, v[132:133]
	global_load_lds_dwordx4 v[228:229], off
	v_lshl_add_u64 v[228:229], s[92:93], 0, v[134:135]
	s_add_i32 m0, s34, 0x2000
	s_nop 0
	global_load_lds_dwordx4 v[228:229], off
	v_lshl_add_u64 v[228:229], s[90:91], 0, v[128:129]
	s_mov_b32 m0, s16
	s_nop 0
	global_load_lds_dwordx4 v[228:229], off
	s_mov_b32 m0, s17
	s_nop 0
	global_load_lds_dwordx4 v[230:231], off
	s_waitcnt vmcnt(8)
	s_waitcnt lgkmcnt(0)
	s_barrier
	s_waitcnt lgkmcnt(0)
	v_mfma_f32_16x16x32_bf16 v[60:63], v[154:157], v[196:199], v[60:63]
	v_mfma_f32_16x16x32_bf16 v[56:59], v[168:171], v[196:199], v[56:59]
	v_mfma_f32_16x16x32_bf16 v[52:55], v[154:157], v[204:207], v[52:55]
	v_mfma_f32_16x16x32_bf16 v[48:51], v[168:171], v[204:207], v[48:51]
	v_mfma_f32_16x16x32_bf16 v[36:39], v[154:157], v[212:215], v[36:39]
	v_mfma_f32_16x16x32_bf16 v[32:35], v[168:171], v[212:215], v[32:35]
	v_mfma_f32_16x16x32_bf16 v[20:23], v[154:157], v[220:223], v[20:23]
	v_mfma_f32_16x16x32_bf16 v[16:19], v[168:171], v[220:223], v[16:19]
	v_mfma_f32_16x16x32_bf16 v[60:63], v[164:167], v[200:203], v[60:63]
	v_mfma_f32_16x16x32_bf16 v[56:59], v[172:175], v[200:203], v[56:59]
	v_mfma_f32_16x16x32_bf16 v[52:55], v[164:167], v[208:211], v[52:55]
	v_mfma_f32_16x16x32_bf16 v[48:51], v[172:175], v[208:211], v[48:51]
	v_mfma_f32_16x16x32_bf16 v[36:39], v[164:167], v[216:219], v[36:39]
	v_mfma_f32_16x16x32_bf16 v[32:35], v[172:175], v[216:219], v[32:35]
	v_mfma_f32_16x16x32_bf16 v[20:23], v[164:167], v[224:227], v[20:23]
	v_mfma_f32_16x16x32_bf16 v[16:19], v[172:175], v[224:227], v[16:19]
	v_mfma_f32_16x16x32_bf16 v[44:47], v[176:179], v[196:199], v[44:47]
	v_mfma_f32_16x16x32_bf16 v[40:43], v[184:187], v[196:199], v[40:43]
	v_mfma_f32_16x16x32_bf16 v[28:31], v[176:179], v[204:207], v[28:31]
	v_mfma_f32_16x16x32_bf16 v[24:27], v[184:187], v[204:207], v[24:27]
	v_mfma_f32_16x16x32_bf16 v[12:15], v[176:179], v[212:215], v[12:15]
	v_mfma_f32_16x16x32_bf16 v[8:11], v[184:187], v[212:215], v[8:11]
	v_mfma_f32_16x16x32_bf16 v[4:7], v[176:179], v[220:223], v[4:7]
	v_mfma_f32_16x16x32_bf16 v[0:3], v[184:187], v[220:223], v[0:3]
	v_mfma_f32_16x16x32_bf16 v[44:47], v[180:183], v[200:203], v[44:47]
	v_mfma_f32_16x16x32_bf16 v[40:43], v[192:195], v[200:203], v[40:43]
	v_mfma_f32_16x16x32_bf16 v[28:31], v[180:183], v[208:211], v[28:31]
	v_mfma_f32_16x16x32_bf16 v[24:27], v[192:195], v[208:211], v[24:27]
	v_mfma_f32_16x16x32_bf16 v[12:15], v[180:183], v[216:219], v[12:15]
	v_mfma_f32_16x16x32_bf16 v[8:11], v[192:195], v[216:219], v[8:11]
	v_mfma_f32_16x16x32_bf16 v[4:7], v[180:183], v[224:227], v[4:7]
	v_mfma_f32_16x16x32_bf16 v[0:3], v[192:195], v[224:227], v[0:3]
	s_barrier
; #define PG8_STAGE(bufoff, gbase, voff) do { _Pragma("unroll") for (int _i = 0; _i < 2; ++_i) \
;         __builtin_amdgcn_global_load_lds((const unsigned*)((const char*)(gbase) + (voff)[_i]), (LAS unsigned*)(lds + (bufoff) + ldsw + _i * 8192), 16, 0, 0); } while (0)
; #define PG8_LDA(dst, b, h) do { _Pragma("unroll") for (int m = 0; m < 4; ++m) _Pragma("unroll") for (int k = 0; k < 2; ++k) dst[m][k] = *(const LAS bf16x8*)(lds + PG8_SA(b, h) + aoff + m * 2048 + k * 1024); } while (0)
; #define PG8_LDB(dst, b, h) do { _Pragma("unroll") for (int n = 0; n < 2; ++n) _Pragma("unroll") for (int k = 0; k < 2; ++k) dst[n][k] = *(const LAS bf16x8*)(lds + PG8_SB(b, h) + boff + n * 2048 + k * 1024); } while (0)
; #define PG8_MMA(ai, bj, At, Bt) do { __builtin_amdgcn_s_setprio(1); _Pragma("unroll") for (int m = 0; m < 4; ++m) _Pragma("unroll") for (int n = 0; n < 2; ++n) _Pragma("unroll") for (int k = 0; k < 2; ++k) \
;         acc[ai][bj][m][n] = __builtin_amdgcn_mfma_f32_16x16x32_bf16(Bt[n][k], At[m][k], acc[ai][bj][m][n], 0, 0, 0); __builtin_amdgcn_s_setprio(0); } while (0)
; #define PG8_WAIT_V(n) asm volatile("s_waitcnt vmcnt(" #n ")" ::: "memory")
; #define PG8_WAIT_L(n) asm volatile("s_waitcnt lgkmcnt(" #n ")" ::: "memory")
; #define PG8_BAR __builtin_amdgcn_s_barrier()
; #define PG8_SCHED __builtin_amdgcn_sched_barrier(0)
; template <int GI>
; __device__ __forceinline__ void gemm_phase(LAS unsigned char* lds, unsigned char* ws, int G, int cblk) {
;     ...
;             PG8_LDB(B0, 1, 0); PG8_LDB(B1, 1, 1); PG8_SCHED; PG8_LDA(At, 1, 0); PG8_STAGE(PG8_SA(0, 1), a2 + hstepA, voffA);
;             PG8_WAIT_V(8); PG8_WAIT_L(0); PG8_BAR; PG8_MMA(0, 0, At, B0); PG8_MMA(0, 1, At, B1); PG8_BAR; PG8_SCHED;
;             PG8_LDA(At, 1, 1); PG8_STAGE(PG8_SB(1, 0), b3, voffB); PG8_STAGE(PG8_SB(1, 1), b3 + hstepB, voffB); PG8_STAGE(PG8_SA(1, 0), a3, voffA);
;             PG8_WAIT_V(8); PG8_WAIT_L(0); PG8_BAR; PG8_MMA(1, 0, At, B0); PG8_MMA(1, 1, At, B1); PG8_BAR; PG8_SCHED;
;         }
	s_add_i32 s34, 0, 0x18000
	v_add_u32_e32 v161, s34, v150
	s_add_i32 s63, 0, 0x1c000
	ds_read_b128 v[154:157], v161
	ds_read_b128 v[164:167], v161 offset:1024
	ds_read_b128 v[168:171], v161 offset:2048
	ds_read_b128 v[172:175], v161 offset:3072
	v_add_u32_e32 v161, s63, v150
	ds_read_b128 v[176:179], v161
	ds_read_b128 v[180:183], v161 offset:1024
	ds_read_b128 v[184:187], v161 offset:2048
	ds_read_b128 v[192:195], v161 offset:3072
	s_add_u32 s90, s90, 0x80000
	s_addc_u32 s91, s91, 0
	s_mov_b32 m0, s18
	v_lshl_add_u64 v[232:233], s[90:91], 0, v[128:129]
	ds_read_b128 v[196:199], v153 offset:32768
	ds_read_b128 v[200:203], v153 offset:33792
	ds_read_b128 v[204:207], v153 offset:34816
	ds_read_b128 v[208:211], v153 offset:35840
	ds_read_b128 v[212:215], v153 offset:36864
	ds_read_b128 v[216:219], v153 offset:37888
	ds_read_b128 v[220:223], v153 offset:38912
	ds_read_b128 v[224:227], v153 offset:39936
	global_load_lds_dwordx4 v[232:233], off
	v_lshl_add_u64 v[232:233], s[90:91], 0, v[132:133]
	s_mov_b32 m0, s19
	s_nop 0
	global_load_lds_dwordx4 v[232:233], off
	s_waitcnt vmcnt(8)
	s_waitcnt lgkmcnt(0)
	s_barrier
	s_waitcnt lgkmcnt(0)
	v_mfma_f32_16x16x32_bf16 v[124:127], v[154:157], v[196:199], v[124:127]
	v_mfma_f32_16x16x32_bf16 v[120:123], v[168:171], v[196:199], v[120:123]
	v_mfma_f32_16x16x32_bf16 v[116:119], v[154:157], v[204:207], v[116:119]
	v_mfma_f32_16x16x32_bf16 v[108:111], v[168:171], v[204:207], v[108:111]
	v_mfma_f32_16x16x32_bf16 v[100:103], v[154:157], v[212:215], v[100:103]
	v_mfma_f32_16x16x32_bf16 v[92:95], v[168:171], v[212:215], v[92:95]
	v_mfma_f32_16x16x32_bf16 v[84:87], v[154:157], v[220:223], v[84:87]
	v_mfma_f32_16x16x32_bf16 v[76:79], v[168:171], v[220:223], v[76:79]
	v_mfma_f32_16x16x32_bf16 v[124:127], v[164:167], v[200:203], v[124:127]
	v_mfma_f32_16x16x32_bf16 v[120:123], v[172:175], v[200:203], v[120:123]
	v_mfma_f32_16x16x32_bf16 v[116:119], v[164:167], v[208:211], v[116:119]
	v_mfma_f32_16x16x32_bf16 v[108:111], v[172:175], v[208:211], v[108:111]
	v_mfma_f32_16x16x32_bf16 v[100:103], v[164:167], v[216:219], v[100:103]
	v_mfma_f32_16x16x32_bf16 v[92:95], v[172:175], v[216:219], v[92:95]
	v_mfma_f32_16x16x32_bf16 v[84:87], v[164:167], v[224:227], v[84:87]
	v_mfma_f32_16x16x32_bf16 v[76:79], v[172:175], v[224:227], v[76:79]
	v_mfma_f32_16x16x32_bf16 v[112:115], v[176:179], v[196:199], v[112:115]
	v_mfma_f32_16x16x32_bf16 v[104:107], v[184:187], v[196:199], v[104:107]
	v_mfma_f32_16x16x32_bf16 v[96:99], v[176:179], v[204:207], v[96:99]
	v_mfma_f32_16x16x32_bf16 v[88:91], v[184:187], v[204:207], v[88:91]
	v_mfma_f32_16x16x32_bf16 v[80:83], v[176:179], v[212:215], v[80:83]
	v_mfma_f32_16x16x32_bf16 v[72:75], v[184:187], v[212:215], v[72:75]
	v_mfma_f32_16x16x32_bf16 v[68:71], v[176:179], v[220:223], v[68:71]
	v_mfma_f32_16x16x32_bf16 v[64:67], v[184:187], v[220:223], v[64:67]
	v_mfma_f32_16x16x32_bf16 v[112:115], v[180:183], v[200:203], v[112:115]
	v_mfma_f32_16x16x32_bf16 v[104:107], v[192:195], v[200:203], v[104:107]
	v_mfma_f32_16x16x32_bf16 v[96:99], v[180:183], v[208:211], v[96:99]
	v_mfma_f32_16x16x32_bf16 v[88:91], v[192:195], v[208:211], v[88:91]
	v_mfma_f32_16x16x32_bf16 v[80:83], v[180:183], v[216:219], v[80:83]
	v_mfma_f32_16x16x32_bf16 v[72:75], v[192:195], v[216:219], v[72:75]
	v_mfma_f32_16x16x32_bf16 v[68:71], v[180:183], v[224:227], v[68:71]
	v_mfma_f32_16x16x32_bf16 v[64:67], v[192:195], v[224:227], v[64:67]
	s_barrier
	s_add_i32 s34, s34, s0
	v_lshl_add_u64 v[158:159], v[158:159], 0, s[38:39]
	s_mov_b32 m0, s34
	ds_read_b128 v[196:199], v153 offset:49152
	ds_read_b128 v[200:203], v153 offset:50176
	ds_read_b128 v[204:207], v153 offset:51200
	ds_read_b128 v[208:211], v153 offset:52224
	ds_read_b128 v[212:215], v153 offset:53248
	ds_read_b128 v[216:219], v153 offset:54272
	ds_read_b128 v[220:223], v153 offset:55296
	ds_read_b128 v[224:227], v153 offset:56320
	global_load_lds_dwordx4 v[158:159], off
	s_add_i32 m0, s34, 0x2000
	s_add_u32 s88, s88, 0x80080
	v_lshl_add_u64 v[158:159], v[188:189], 0, s[38:39]
	s_addc_u32 s89, s89, 0
	s_add_i32 s34, s63, s0
	global_load_lds_dwordx4 v[158:159], off
	v_lshl_add_u64 v[158:159], s[88:89], 0, v[130:131]
	s_mov_b32 m0, s34
	s_nop 0
	global_load_lds_dwordx4 v[158:159], off
	v_lshl_add_u64 v[158:159], s[88:89], 0, v[134:135]
	s_add_i32 m0, s34, 0x2000
	s_nop 0
	global_load_lds_dwordx4 v[158:159], off
	v_lshl_add_u64 v[158:159], v[228:229], 0, s[38:39]
	s_mov_b32 m0, s22
	s_nop 0
	global_load_lds_dwordx4 v[158:159], off
	v_lshl_add_u64 v[158:159], v[230:231], 0, s[38:39]
	s_mov_b32 m0, s23
	s_nop 0
	global_load_lds_dwordx4 v[158:159], off
	s_waitcnt vmcnt(8)
	s_waitcnt lgkmcnt(0)
	s_barrier
	s_waitcnt lgkmcnt(0)
	v_mfma_f32_16x16x32_bf16 v[60:63], v[154:157], v[196:199], v[60:63]
	v_mfma_f32_16x16x32_bf16 v[56:59], v[168:171], v[196:199], v[56:59]
	v_mfma_f32_16x16x32_bf16 v[52:55], v[154:157], v[204:207], v[52:55]
	v_mfma_f32_16x16x32_bf16 v[48:51], v[168:171], v[204:207], v[48:51]
	v_mfma_f32_16x16x32_bf16 v[36:39], v[154:157], v[212:215], v[36:39]
	v_mfma_f32_16x16x32_bf16 v[32:35], v[168:171], v[212:215], v[32:35]
	v_mfma_f32_16x16x32_bf16 v[20:23], v[154:157], v[220:223], v[20:23]
	v_mfma_f32_16x16x32_bf16 v[16:19], v[168:171], v[220:223], v[16:19]
	v_mfma_f32_16x16x32_bf16 v[60:63], v[164:167], v[200:203], v[60:63]
	v_mfma_f32_16x16x32_bf16 v[56:59], v[172:175], v[200:203], v[56:59]
	v_mfma_f32_16x16x32_bf16 v[52:55], v[164:167], v[208:211], v[52:55]
	v_mfma_f32_16x16x32_bf16 v[48:51], v[172:175], v[208:211], v[48:51]
	v_mfma_f32_16x16x32_bf16 v[36:39], v[164:167], v[216:219], v[36:39]
	v_mfma_f32_16x16x32_bf16 v[32:35], v[172:175], v[216:219], v[32:35]
	v_mfma_f32_16x16x32_bf16 v[20:23], v[164:167], v[224:227], v[20:23]
	v_mfma_f32_16x16x32_bf16 v[16:19], v[172:175], v[224:227], v[16:19]
	v_mfma_f32_16x16x32_bf16 v[44:47], v[176:179], v[196:199], v[44:47]
	v_mfma_f32_16x16x32_bf16 v[40:43], v[184:187], v[196:199], v[40:43]
	v_mfma_f32_16x16x32_bf16 v[28:31], v[176:179], v[204:207], v[28:31]
	v_mfma_f32_16x16x32_bf16 v[24:27], v[184:187], v[204:207], v[24:27]
	v_mfma_f32_16x16x32_bf16 v[12:15], v[176:179], v[212:215], v[12:15]
	v_mfma_f32_16x16x32_bf16 v[8:11], v[184:187], v[212:215], v[8:11]
	v_mfma_f32_16x16x32_bf16 v[4:7], v[176:179], v[220:223], v[4:7]
	v_mfma_f32_16x16x32_bf16 v[0:3], v[184:187], v[220:223], v[0:3]
	v_mfma_f32_16x16x32_bf16 v[44:47], v[180:183], v[200:203], v[44:47]
	v_mfma_f32_16x16x32_bf16 v[40:43], v[192:195], v[200:203], v[40:43]
	v_mfma_f32_16x16x32_bf16 v[28:31], v[180:183], v[208:211], v[28:31]
	v_mfma_f32_16x16x32_bf16 v[24:27], v[192:195], v[208:211], v[24:27]
	v_mfma_f32_16x16x32_bf16 v[12:15], v[180:183], v[216:219], v[12:15]
	v_mfma_f32_16x16x32_bf16 v[8:11], v[192:195], v[216:219], v[8:11]
	v_mfma_f32_16x16x32_bf16 v[4:7], v[180:183], v[224:227], v[4:7]
	v_mfma_f32_16x16x32_bf16 v[0:3], v[192:195], v[224:227], v[0:3]
	s_barrier
	s_add_i32 s15, s15, 2
	s_add_u32 s86, s86, 0x100
	s_addc_u32 s87, s87, 0
	s_add_u32 s4, s4, 0x100
	s_addc_u32 s14, s14, 0
	s_cmp_gt_u32 s15, 29
	s_cbranch_scc0 .LBB0_124

; #define PG8_STAGE(bufoff, gbase, voff) do { _Pragma("unroll") for (int _i = 0; _i < 2; ++_i) \
;         __builtin_amdgcn_global_load_lds((const unsigned*)((const char*)(gbase) + (voff)[_i]), (LAS unsigned*)(lds + (bufoff) + ldsw + _i * 8192), 16, 0, 0); } while (0)
; #define PG8_LDA(dst, b, h) do { _Pragma("unroll") for (int m = 0; m < 4; ++m) _Pragma("unroll") for (int k = 0; k < 2; ++k) dst[m][k] = *(const LAS bf16x8*)(lds + PG8_SA(b, h) + aoff + m * 2048 + k * 1024); } while (0)
; #define PG8_LDB(dst, b, h) do { _Pragma("unroll") for (int n = 0; n < 2; ++n) _Pragma("unroll") for (int k = 0; k < 2; ++k) dst[n][k] = *(const LAS bf16x8*)(lds + PG8_SB(b, h) + boff + n * 2048 + k * 1024); } while (0)
; #define PG8_MMA(ai, bj, At, Bt) do { __builtin_amdgcn_s_setprio(1); _Pragma("unroll") for (int m = 0; m < 4; ++m) _Pragma("unroll") for (int n = 0; n < 2; ++n) _Pragma("unroll") for (int k = 0; k < 2; ++k) \
;         acc[ai][bj][m][n] = __builtin_amdgcn_mfma_f32_16x16x32_bf16(Bt[n][k], At[m][k], acc[ai][bj][m][n], 0, 0, 0); __builtin_amdgcn_s_setprio(0); } while (0)
; #define PG8_WAIT_V(n) asm volatile("s_waitcnt vmcnt(" #n ")" ::: "memory")
; #define PG8_WAIT_L(n) asm volatile("s_waitcnt lgkmcnt(" #n ")" ::: "memory")
; #define PG8_BAR __builtin_amdgcn_s_barrier()
; #define PG8_SCHED __builtin_amdgcn_sched_barrier(0)
; template <int GI>
; __device__ __forceinline__ void gemm_phase(LAS unsigned char* lds, unsigned char* ws, int G, int cblk) {
;     ...
;             PG8_LDB(B0, 0, 0); PG8_LDB(B1, 0, 1); PG8_SCHED; PG8_LDA(At, 0, 0); PG8_STAGE(PG8_SA(1, 1), a1 + hstepA, voffA);
;             PG8_WAIT_V(8); PG8_WAIT_L(0); PG8_BAR; PG8_MMA(0, 0, At, B0); PG8_MMA(0, 1, At, B1); PG8_BAR; PG8_SCHED;
;             PG8_LDA(At, 0, 1); PG8_STAGE(PG8_SB(0, 0), b2, voffB); PG8_STAGE(PG8_SB(0, 1), b2 + hstepB, voffB); PG8_STAGE(PG8_SA(0, 0), a2, voffA);
;             PG8_WAIT_V(8); PG8_WAIT_L(0); PG8_BAR; PG8_MMA(1, 0, At, B0); PG8_MMA(1, 1, At, B1); PG8_BAR; PG8_SCHED;
.LBB0_147:
	s_add_u32 s78, s78, 0x80080
	s_addc_u32 s79, s79, 0
	s_add_u32 s14, s80, 0x100
	s_addc_u32 s15, s81, 0
	s_mov_b32 s27, -2
	ds_read_b128 v[154:157], v151
	ds_read_b128 v[164:167], v151 offset:1024
	ds_read_b128 v[168:171], v151 offset:2048
	ds_read_b128 v[172:175], v151 offset:3072
	ds_read_b128 v[176:179], v152
	ds_read_b128 v[180:183], v152 offset:1024
	ds_read_b128 v[184:187], v152 offset:2048
	ds_read_b128 v[192:195], v152 offset:3072
	s_add_u32 s33, s78, 0xfff80080
	s_addc_u32 s34, s79, -1
	s_cmp_eq_u32 s27, 28
	s_cselect_b32 s83, s73, s34
	s_cselect_b32 s82, s72, s33
	s_cselect_b32 s81, s75, s15
	s_cselect_b32 s80, s74, s14
	v_lshl_add_u64 v[158:159], s[78:79], 0, v[138:139]
	s_add_i32 m0, s16, 0xc000
	ds_read_b128 v[196:199], v153
	ds_read_b128 v[200:203], v153 offset:1024
	ds_read_b128 v[204:207], v153 offset:2048
	ds_read_b128 v[208:211], v153 offset:3072
	ds_read_b128 v[212:215], v153 offset:4096
	ds_read_b128 v[216:219], v153 offset:5120
	ds_read_b128 v[220:223], v153 offset:6144
	ds_read_b128 v[224:227], v153 offset:7168
	global_load_lds_dwordx4 v[158:159], off
	v_lshl_add_u64 v[158:159], s[78:79], 0, v[140:141]
	s_add_i32 m0, s16, 0xe000
	s_nop 0
	global_load_lds_dwordx4 v[158:159], off
	s_waitcnt vmcnt(8)
	s_waitcnt lgkmcnt(0)
	s_barrier
	s_waitcnt lgkmcnt(0)
	v_mfma_f32_16x16x32_bf16 v[124:127], v[154:157], v[196:199], 0
	v_mfma_f32_16x16x32_bf16 v[120:123], v[168:171], v[196:199], 0
	v_mfma_f32_16x16x32_bf16 v[116:119], v[154:157], v[204:207], 0
	v_mfma_f32_16x16x32_bf16 v[112:115], v[168:171], v[204:207], 0
	v_mfma_f32_16x16x32_bf16 v[100:103], v[154:157], v[212:215], 0
	v_mfma_f32_16x16x32_bf16 v[96:99], v[168:171], v[212:215], 0
	v_mfma_f32_16x16x32_bf16 v[84:87], v[154:157], v[220:223], 0
	v_mfma_f32_16x16x32_bf16 v[80:83], v[168:171], v[220:223], 0
	v_mfma_f32_16x16x32_bf16 v[124:127], v[164:167], v[200:203], v[124:127]
	v_mfma_f32_16x16x32_bf16 v[120:123], v[172:175], v[200:203], v[120:123]
	v_mfma_f32_16x16x32_bf16 v[116:119], v[164:167], v[208:211], v[116:119]
	v_mfma_f32_16x16x32_bf16 v[112:115], v[172:175], v[208:211], v[112:115]
	v_mfma_f32_16x16x32_bf16 v[100:103], v[164:167], v[216:219], v[100:103]
	v_mfma_f32_16x16x32_bf16 v[96:99], v[172:175], v[216:219], v[96:99]
	v_mfma_f32_16x16x32_bf16 v[84:87], v[164:167], v[224:227], v[84:87]
	v_mfma_f32_16x16x32_bf16 v[80:83], v[172:175], v[224:227], v[80:83]
	v_mfma_f32_16x16x32_bf16 v[108:111], v[176:179], v[196:199], 0
	v_mfma_f32_16x16x32_bf16 v[104:107], v[184:187], v[196:199], 0
	v_mfma_f32_16x16x32_bf16 v[92:95], v[176:179], v[204:207], 0
	v_mfma_f32_16x16x32_bf16 v[88:91], v[184:187], v[204:207], 0
	v_mfma_f32_16x16x32_bf16 v[76:79], v[176:179], v[212:215], 0
	v_mfma_f32_16x16x32_bf16 v[72:75], v[184:187], v[212:215], 0
	v_mfma_f32_16x16x32_bf16 v[68:71], v[176:179], v[220:223], 0
	v_mfma_f32_16x16x32_bf16 v[64:67], v[184:187], v[220:223], 0
	v_mfma_f32_16x16x32_bf16 v[108:111], v[180:183], v[200:203], v[108:111]
	v_mfma_f32_16x16x32_bf16 v[104:107], v[192:195], v[200:203], v[104:107]
	v_mfma_f32_16x16x32_bf16 v[92:95], v[180:183], v[208:211], v[92:95]
	v_mfma_f32_16x16x32_bf16 v[88:91], v[192:195], v[208:211], v[88:91]
	v_mfma_f32_16x16x32_bf16 v[76:79], v[180:183], v[216:219], v[76:79]
	v_mfma_f32_16x16x32_bf16 v[72:75], v[192:195], v[216:219], v[72:75]
	v_mfma_f32_16x16x32_bf16 v[68:71], v[180:183], v[224:227], v[68:71]
	v_mfma_f32_16x16x32_bf16 v[64:67], v[192:195], v[224:227], v[64:67]
	s_barrier
	s_add_i32 s33, s24, s0
	v_lshl_add_u64 v[158:159], s[80:81], 0, v[130:131]
	s_mov_b32 m0, s33
	ds_read_b128 v[196:199], v153 offset:16384
	ds_read_b128 v[200:203], v153 offset:17408
	ds_read_b128 v[204:207], v153 offset:18432
	ds_read_b128 v[208:211], v153 offset:19456
	ds_read_b128 v[212:215], v153 offset:20480
	ds_read_b128 v[216:219], v153 offset:21504
	ds_read_b128 v[220:223], v153 offset:22528
	ds_read_b128 v[224:227], v153 offset:23552
	global_load_lds_dwordx4 v[158:159], off
	s_add_i32 m0, s33, 0x2000
	s_add_u32 s34, s80, 0x80000
	v_lshl_add_u64 v[188:189], s[80:81], 0, v[134:135]
	s_addc_u32 s35, s81, 0
	s_add_i32 s33, s25, s0
	global_load_lds_dwordx4 v[188:189], off
	v_lshl_add_u64 v[228:229], s[34:35], 0, v[130:131]
	s_mov_b32 m0, s33
	v_lshl_add_u64 v[230:231], s[82:83], 0, v[132:133]
	global_load_lds_dwordx4 v[228:229], off
	v_lshl_add_u64 v[228:229], s[34:35], 0, v[134:135]
	s_add_i32 m0, s33, 0x2000
	s_nop 0
	global_load_lds_dwordx4 v[228:229], off
	v_lshl_add_u64 v[228:229], s[82:83], 0, v[128:129]
	s_mov_b32 m0, s16
	s_nop 0
	global_load_lds_dwordx4 v[228:229], off
	s_mov_b32 m0, s17
	s_nop 0
	global_load_lds_dwordx4 v[230:231], off
	s_waitcnt vmcnt(8)
	s_waitcnt lgkmcnt(0)
	s_barrier
; #define PG8_STAGE(bufoff, gbase, voff) do { _Pragma("unroll") for (int _i = 0; _i < 2; ++_i) \
;         __builtin_amdgcn_global_load_lds((const unsigned*)((const char*)(gbase) + (voff)[_i]), (LAS unsigned*)(lds + (bufoff) + ldsw + _i * 8192), 16, 0, 0); } while (0)
; #define PG8_LDA(dst, b, h) do { _Pragma("unroll") for (int m = 0; m < 4; ++m) _Pragma("unroll") for (int k = 0; k < 2; ++k) dst[m][k] = *(const LAS bf16x8*)(lds + PG8_SA(b, h) + aoff + m * 2048 + k * 1024); } while (0)
; #define PG8_LDB(dst, b, h) do { _Pragma("unroll") for (int n = 0; n < 2; ++n) _Pragma("unroll") for (int k = 0; k < 2; ++k) dst[n][k] = *(const LAS bf16x8*)(lds + PG8_SB(b, h) + boff + n * 2048 + k * 1024); } while (0)
; #define PG8_MMA(ai, bj, At, Bt) do { __builtin_amdgcn_s_setprio(1); _Pragma("unroll") for (int m = 0; m < 4; ++m) _Pragma("unroll") for (int n = 0; n < 2; ++n) _Pragma("unroll") for (int k = 0; k < 2; ++k) \
;         acc[ai][bj][m][n] = __builtin_amdgcn_mfma_f32_16x16x32_bf16(Bt[n][k], At[m][k], acc[ai][bj][m][n], 0, 0, 0); __builtin_amdgcn_s_setprio(0); } while (0)
; #define PG8_WAIT_V(n) asm volatile("s_waitcnt vmcnt(" #n ")" ::: "memory")
; #define PG8_WAIT_L(n) asm volatile("s_waitcnt lgkmcnt(" #n ")" ::: "memory")
; #define PG8_BAR __builtin_amdgcn_s_barrier()
; #define PG8_SCHED __builtin_amdgcn_sched_barrier(0)
; template <int GI>
; __device__ __forceinline__ void gemm_phase(LAS unsigned char* lds, unsigned char* ws, int G, int cblk) {
;     ...
;             PG8_WAIT_V(8); PG8_WAIT_L(0); PG8_BAR; PG8_MMA(1, 0, At, B0); PG8_MMA(1, 1, At, B1); PG8_BAR; PG8_SCHED;
;             PG8_LDB(B0, 1, 0); PG8_LDB(B1, 1, 1); PG8_SCHED; PG8_LDA(At, 1, 0); PG8_STAGE(PG8_SA(0, 1), a2 + hstepA, voffA);
;             PG8_WAIT_V(8); PG8_WAIT_L(0); PG8_BAR; PG8_MMA(0, 0, At, B0); PG8_MMA(0, 1, At, B1); PG8_BAR; PG8_SCHED;
	s_waitcnt lgkmcnt(0)
	v_mfma_f32_16x16x32_bf16 v[60:63], v[154:157], v[196:199], 0
	v_mfma_f32_16x16x32_bf16 v[56:59], v[168:171], v[196:199], 0
	v_mfma_f32_16x16x32_bf16 v[52:55], v[154:157], v[204:207], 0
	v_mfma_f32_16x16x32_bf16 v[48:51], v[168:171], v[204:207], 0
	v_mfma_f32_16x16x32_bf16 v[36:39], v[154:157], v[212:215], 0
	v_mfma_f32_16x16x32_bf16 v[32:35], v[168:171], v[212:215], 0
	v_mfma_f32_16x16x32_bf16 v[20:23], v[154:157], v[220:223], 0
	v_mfma_f32_16x16x32_bf16 v[16:19], v[168:171], v[220:223], 0
	v_mfma_f32_16x16x32_bf16 v[60:63], v[164:167], v[200:203], v[60:63]
	v_mfma_f32_16x16x32_bf16 v[56:59], v[172:175], v[200:203], v[56:59]
	v_mfma_f32_16x16x32_bf16 v[52:55], v[164:167], v[208:211], v[52:55]
	v_mfma_f32_16x16x32_bf16 v[48:51], v[172:175], v[208:211], v[48:51]
	v_mfma_f32_16x16x32_bf16 v[36:39], v[164:167], v[216:219], v[36:39]
	v_mfma_f32_16x16x32_bf16 v[32:35], v[172:175], v[216:219], v[32:35]
	v_mfma_f32_16x16x32_bf16 v[20:23], v[164:167], v[224:227], v[20:23]
	v_mfma_f32_16x16x32_bf16 v[16:19], v[172:175], v[224:227], v[16:19]
	v_mfma_f32_16x16x32_bf16 v[44:47], v[176:179], v[196:199], 0
	v_mfma_f32_16x16x32_bf16 v[40:43], v[184:187], v[196:199], 0
	v_mfma_f32_16x16x32_bf16 v[28:31], v[176:179], v[204:207], 0
	v_mfma_f32_16x16x32_bf16 v[24:27], v[184:187], v[204:207], 0
	v_mfma_f32_16x16x32_bf16 v[12:15], v[176:179], v[212:215], 0
	v_mfma_f32_16x16x32_bf16 v[8:11], v[184:187], v[212:215], 0
	v_mfma_f32_16x16x32_bf16 v[4:7], v[176:179], v[220:223], 0
	v_mfma_f32_16x16x32_bf16 v[0:3], v[184:187], v[220:223], 0
	v_mfma_f32_16x16x32_bf16 v[44:47], v[180:183], v[200:203], v[44:47]
	v_mfma_f32_16x16x32_bf16 v[40:43], v[192:195], v[200:203], v[40:43]
	v_mfma_f32_16x16x32_bf16 v[28:31], v[180:183], v[208:211], v[28:31]
	v_mfma_f32_16x16x32_bf16 v[24:27], v[192:195], v[208:211], v[24:27]
	v_mfma_f32_16x16x32_bf16 v[12:15], v[180:183], v[216:219], v[12:15]
	v_mfma_f32_16x16x32_bf16 v[8:11], v[192:195], v[216:219], v[8:11]
	v_mfma_f32_16x16x32_bf16 v[4:7], v[180:183], v[224:227], v[4:7]
	v_mfma_f32_16x16x32_bf16 v[0:3], v[192:195], v[224:227], v[0:3]
	s_barrier
	s_add_i32 s33, 0, 0x18000
	v_add_u32_e32 v161, s33, v150
	s_add_i32 s63, 0, 0x1c000
	ds_read_b128 v[154:157], v161
	ds_read_b128 v[164:167], v161 offset:1024
	ds_read_b128 v[168:171], v161 offset:2048
	ds_read_b128 v[172:175], v161 offset:3072
	v_add_u32_e32 v161, s63, v150
	ds_read_b128 v[176:179], v161
	ds_read_b128 v[180:183], v161 offset:1024
	ds_read_b128 v[184:187], v161 offset:2048
	ds_read_b128 v[192:195], v161 offset:3072
	s_add_u32 s34, s82, 0x80000
	s_addc_u32 s35, s83, 0
	s_mov_b32 m0, s18
	v_lshl_add_u64 v[232:233], s[34:35], 0, v[128:129]
	ds_read_b128 v[196:199], v153 offset:32768
	ds_read_b128 v[200:203], v153 offset:33792
	ds_read_b128 v[204:207], v153 offset:34816
	ds_read_b128 v[208:211], v153 offset:35840
	ds_read_b128 v[212:215], v153 offset:36864
	ds_read_b128 v[216:219], v153 offset:37888
	ds_read_b128 v[220:223], v153 offset:38912
	ds_read_b128 v[224:227], v153 offset:39936
	global_load_lds_dwordx4 v[232:233], off
	v_lshl_add_u64 v[232:233], s[34:35], 0, v[132:133]
	s_mov_b32 m0, s19
	s_nop 0
	global_load_lds_dwordx4 v[232:233], off
	s_waitcnt vmcnt(8)
	s_waitcnt lgkmcnt(0)
	s_barrier
	s_waitcnt lgkmcnt(0)
	v_mfma_f32_16x16x32_bf16 v[124:127], v[154:157], v[196:199], v[124:127]
	v_mfma_f32_16x16x32_bf16 v[120:123], v[168:171], v[196:199], v[120:123]
	v_mfma_f32_16x16x32_bf16 v[116:119], v[154:157], v[204:207], v[116:119]
	v_mfma_f32_16x16x32_bf16 v[112:115], v[168:171], v[204:207], v[112:115]
	v_mfma_f32_16x16x32_bf16 v[100:103], v[154:157], v[212:215], v[100:103]
	v_mfma_f32_16x16x32_bf16 v[96:99], v[168:171], v[212:215], v[96:99]
	v_mfma_f32_16x16x32_bf16 v[84:87], v[154:157], v[220:223], v[84:87]
	v_mfma_f32_16x16x32_bf16 v[80:83], v[168:171], v[220:223], v[80:83]
	v_mfma_f32_16x16x32_bf16 v[124:127], v[164:167], v[200:203], v[124:127]
	v_mfma_f32_16x16x32_bf16 v[120:123], v[172:175], v[200:203], v[120:123]
	v_mfma_f32_16x16x32_bf16 v[116:119], v[164:167], v[208:211], v[116:119]
	v_mfma_f32_16x16x32_bf16 v[112:115], v[172:175], v[208:211], v[112:115]
	v_mfma_f32_16x16x32_bf16 v[100:103], v[164:167], v[216:219], v[100:103]
	v_mfma_f32_16x16x32_bf16 v[96:99], v[172:175], v[216:219], v[96:99]
	v_mfma_f32_16x16x32_bf16 v[84:87], v[164:167], v[224:227], v[84:87]
	v_mfma_f32_16x16x32_bf16 v[80:83], v[172:175], v[224:227], v[80:83]
	v_mfma_f32_16x16x32_bf16 v[108:111], v[176:179], v[196:199], v[108:111]
	v_mfma_f32_16x16x32_bf16 v[104:107], v[184:187], v[196:199], v[104:107]
	v_mfma_f32_16x16x32_bf16 v[92:95], v[176:179], v[204:207], v[92:95]
	v_mfma_f32_16x16x32_bf16 v[88:91], v[184:187], v[204:207], v[88:91]
	v_mfma_f32_16x16x32_bf16 v[76:79], v[176:179], v[212:215], v[76:79]
	v_mfma_f32_16x16x32_bf16 v[72:75], v[184:187], v[212:215], v[72:75]
	v_mfma_f32_16x16x32_bf16 v[68:71], v[176:179], v[220:223], v[68:71]
	v_mfma_f32_16x16x32_bf16 v[64:67], v[184:187], v[220:223], v[64:67]
	v_mfma_f32_16x16x32_bf16 v[108:111], v[180:183], v[200:203], v[108:111]
	v_mfma_f32_16x16x32_bf16 v[104:107], v[192:195], v[200:203], v[104:107]
	v_mfma_f32_16x16x32_bf16 v[92:95], v[180:183], v[208:211], v[92:95]
	v_mfma_f32_16x16x32_bf16 v[88:91], v[192:195], v[208:211], v[88:91]
	v_mfma_f32_16x16x32_bf16 v[76:79], v[180:183], v[216:219], v[76:79]
	v_mfma_f32_16x16x32_bf16 v[72:75], v[192:195], v[216:219], v[72:75]
	v_mfma_f32_16x16x32_bf16 v[68:71], v[180:183], v[224:227], v[68:71]
	v_mfma_f32_16x16x32_bf16 v[64:67], v[192:195], v[224:227], v[64:67]
	s_barrier
; #define PG8_STAGE(bufoff, gbase, voff) do { _Pragma("unroll") for (int _i = 0; _i < 2; ++_i) \
;         __builtin_amdgcn_global_load_lds((const unsigned*)((const char*)(gbase) + (voff)[_i]), (LAS unsigned*)(lds + (bufoff) + ldsw + _i * 8192), 16, 0, 0); } while (0)
; #define PG8_LDA(dst, b, h) do { _Pragma("unroll") for (int m = 0; m < 4; ++m) _Pragma("unroll") for (int k = 0; k < 2; ++k) dst[m][k] = *(const LAS bf16x8*)(lds + PG8_SA(b, h) + aoff + m * 2048 + k * 1024); } while (0)
; #define PG8_LDB(dst, b, h) do { _Pragma("unroll") for (int n = 0; n < 2; ++n) _Pragma("unroll") for (int k = 0; k < 2; ++k) dst[n][k] = *(const LAS bf16x8*)(lds + PG8_SB(b, h) + boff + n * 2048 + k * 1024); } while (0)
; #define PG8_WAIT_V(n) asm volatile("s_waitcnt vmcnt(" #n ")" ::: "memory")
; #define PG8_WAIT_L(n) asm volatile("s_waitcnt lgkmcnt(" #n ")" ::: "memory")
; template <int GI>
; __device__ __forceinline__ void gemm_phase(LAS unsigned char* lds, unsigned char* ws, int G, int cblk) {
;     ...
;         for (int t = 0; t < nt; t += 2) {
;             const bool last = (t == nt - 2);
;             const char* a1 = cA + (size_t)(t + 1) * kstep;
;             const char* a2 = last ? nA : cA + (size_t)(t + 2) * kstep; const char* b2 = last ? nB : cB + (size_t)(t + 2) * kstep;
;             const char* a3 = a2 + kstep; const char* b3 = b2 + kstep;
;             PG8_LDB(B0, 0, 0); PG8_LDB(B1, 0, 1); PG8_SCHED; PG8_LDA(At, 0, 0); PG8_STAGE(PG8_SA(1, 1), a1 + hstepA, voffA);
;             PG8_WAIT_V(8); PG8_WAIT_L(0); PG8_BAR; PG8_MMA(0, 0, At, B0); PG8_MMA(0, 1, At, B1); PG8_BAR; PG8_SCHED;
;             PG8_LDA(At, 0, 1); PG8_STAGE(PG8_SB(0, 0), b2, voffB); PG8_STAGE(PG8_SB(0, 1), b2 + hstepB, voffB); PG8_STAGE(PG8_SA(0, 0), a2, voffA);
;             PG8_WAIT_V(8); PG8_WAIT_L(0); PG8_BAR; PG8_MMA(1, 0, At, B0); PG8_MMA(1, 1, At, B1); PG8_BAR; PG8_SCHED;
;             PG8_LDB(B0, 1, 0); PG8_LDB(B1, 1, 1); PG8_SCHED; PG8_LDA(At, 1, 0); PG8_STAGE(PG8_SA(0, 1), a2 + hstepA, voffA);
;             PG8_WAIT_V(8); PG8_WAIT_L(0); PG8_BAR; PG8_MMA(0, 0, At, B0); PG8_MMA(0, 1, At, B1); PG8_BAR; PG8_SCHED;
;             PG8_LDA(At, 1, 1); PG8_STAGE(PG8_SB(1, 0), b3, voffB); PG8_STAGE(PG8_SB(1, 1), b3 + hstepB, voffB); PG8_STAGE(PG8_SA(1, 0), a3, voffA);
;             PG8_WAIT_V(8); PG8_WAIT_L(0); PG8_BAR; PG8_MMA(1, 0, At, B0); PG8_MMA(1, 1, At, B1); PG8_BAR; PG8_SCHED;
	s_add_i32 s33, s33, s0
	v_lshl_add_u64 v[158:159], v[158:159], 0, s[38:39]
	s_mov_b32 m0, s33
	ds_read_b128 v[196:199], v153 offset:49152
	ds_read_b128 v[200:203], v153 offset:50176
	ds_read_b128 v[204:207], v153 offset:51200
	ds_read_b128 v[208:211], v153 offset:52224
	ds_read_b128 v[212:215], v153 offset:53248
	ds_read_b128 v[216:219], v153 offset:54272
	ds_read_b128 v[220:223], v153 offset:55296
	ds_read_b128 v[224:227], v153 offset:56320
	global_load_lds_dwordx4 v[158:159], off
	s_add_i32 m0, s33, 0x2000
	s_add_u32 s34, s80, 0x80080
	v_lshl_add_u64 v[158:159], v[188:189], 0, s[38:39]
	s_addc_u32 s35, s81, 0
	s_add_i32 s33, s63, s0
	global_load_lds_dwordx4 v[158:159], off
	v_lshl_add_u64 v[158:159], s[34:35], 0, v[130:131]
	s_mov_b32 m0, s33
	s_nop 0
	global_load_lds_dwordx4 v[158:159], off
	v_lshl_add_u64 v[158:159], s[34:35], 0, v[134:135]
	s_add_i32 m0, s33, 0x2000
	s_nop 0
	global_load_lds_dwordx4 v[158:159], off
	v_lshl_add_u64 v[158:159], v[228:229], 0, s[38:39]
	s_mov_b32 m0, s22
	s_nop 0
	global_load_lds_dwordx4 v[158:159], off
	v_lshl_add_u64 v[158:159], v[230:231], 0, s[38:39]
	s_mov_b32 m0, s23
	s_nop 0
	global_load_lds_dwordx4 v[158:159], off
	s_waitcnt vmcnt(8)
	s_waitcnt lgkmcnt(0)
	s_barrier
	s_waitcnt lgkmcnt(0)
	v_mfma_f32_16x16x32_bf16 v[60:63], v[154:157], v[196:199], v[60:63]
	v_mfma_f32_16x16x32_bf16 v[56:59], v[168:171], v[196:199], v[56:59]
	v_mfma_f32_16x16x32_bf16 v[52:55], v[154:157], v[204:207], v[52:55]
	v_mfma_f32_16x16x32_bf16 v[48:51], v[168:171], v[204:207], v[48:51]
	v_mfma_f32_16x16x32_bf16 v[36:39], v[154:157], v[212:215], v[36:39]
	v_mfma_f32_16x16x32_bf16 v[32:35], v[168:171], v[212:215], v[32:35]
	v_mfma_f32_16x16x32_bf16 v[20:23], v[154:157], v[220:223], v[20:23]
	v_mfma_f32_16x16x32_bf16 v[16:19], v[168:171], v[220:223], v[16:19]
	v_mfma_f32_16x16x32_bf16 v[60:63], v[164:167], v[200:203], v[60:63]
	v_mfma_f32_16x16x32_bf16 v[56:59], v[172:175], v[200:203], v[56:59]
	v_mfma_f32_16x16x32_bf16 v[52:55], v[164:167], v[208:211], v[52:55]
	v_mfma_f32_16x16x32_bf16 v[48:51], v[172:175], v[208:211], v[48:51]
	v_mfma_f32_16x16x32_bf16 v[36:39], v[164:167], v[216:219], v[36:39]
	v_mfma_f32_16x16x32_bf16 v[32:35], v[172:175], v[216:219], v[32:35]
	v_mfma_f32_16x16x32_bf16 v[20:23], v[164:167], v[224:227], v[20:23]
	v_mfma_f32_16x16x32_bf16 v[16:19], v[172:175], v[224:227], v[16:19]
	v_mfma_f32_16x16x32_bf16 v[44:47], v[176:179], v[196:199], v[44:47]
	v_mfma_f32_16x16x32_bf16 v[40:43], v[184:187], v[196:199], v[40:43]
	v_mfma_f32_16x16x32_bf16 v[28:31], v[176:179], v[204:207], v[28:31]
	v_mfma_f32_16x16x32_bf16 v[24:27], v[184:187], v[204:207], v[24:27]
	v_mfma_f32_16x16x32_bf16 v[12:15], v[176:179], v[212:215], v[12:15]
	v_mfma_f32_16x16x32_bf16 v[8:11], v[184:187], v[212:215], v[8:11]
	v_mfma_f32_16x16x32_bf16 v[4:7], v[176:179], v[220:223], v[4:7]
	v_mfma_f32_16x16x32_bf16 v[0:3], v[184:187], v[220:223], v[0:3]
	v_mfma_f32_16x16x32_bf16 v[44:47], v[180:183], v[200:203], v[44:47]
	v_mfma_f32_16x16x32_bf16 v[40:43], v[192:195], v[200:203], v[40:43]
	v_mfma_f32_16x16x32_bf16 v[28:31], v[180:183], v[208:211], v[28:31]
	v_mfma_f32_16x16x32_bf16 v[24:27], v[192:195], v[208:211], v[24:27]
	v_mfma_f32_16x16x32_bf16 v[12:15], v[180:183], v[216:219], v[12:15]
	v_mfma_f32_16x16x32_bf16 v[8:11], v[192:195], v[216:219], v[8:11]
	v_mfma_f32_16x16x32_bf16 v[4:7], v[180:183], v[224:227], v[4:7]
	v_mfma_f32_16x16x32_bf16 v[0:3], v[192:195], v[224:227], v[0:3]
	s_barrier
	s_add_i32 s27, s27, 2
	s_add_u32 s78, s78, 0x100
	s_addc_u32 s79, s79, 0
	s_add_u32 s14, s14, 0x100
	s_addc_u32 s15, s15, 0
	s_cmp_gt_u32 s27, 29
	s_cbranch_scc0 .LBB0_148
	s_branch .Lpeel_exit_2
.LBB0_148:
	ds_read_b128 v[154:157], v151
	ds_read_b128 v[164:167], v151 offset:1024
	ds_read_b128 v[168:171], v151 offset:2048
	ds_read_b128 v[172:175], v151 offset:3072
	ds_read_b128 v[176:179], v152
	ds_read_b128 v[180:183], v152 offset:1024
	ds_read_b128 v[184:187], v152 offset:2048
	ds_read_b128 v[192:195], v152 offset:3072
	s_add_u32 s33, s78, 0xfff80080
	s_addc_u32 s34, s79, -1
	s_cmp_eq_u32 s27, 28
	s_cselect_b32 s83, s73, s34
	s_cselect_b32 s82, s72, s33
	s_cselect_b32 s81, s75, s15
	s_cselect_b32 s80, s74, s14
	v_lshl_add_u64 v[158:159], s[78:79], 0, v[138:139]
	s_add_i32 m0, s16, 0xc000
	ds_read_b128 v[196:199], v153
	ds_read_b128 v[200:203], v153 offset:1024
	ds_read_b128 v[204:207], v153 offset:2048
	ds_read_b128 v[208:211], v153 offset:3072
	ds_read_b128 v[212:215], v153 offset:4096
	ds_read_b128 v[216:219], v153 offset:5120
	ds_read_b128 v[220:223], v153 offset:6144
	ds_read_b128 v[224:227], v153 offset:7168
	global_load_lds_dwordx4 v[158:159], off
	v_lshl_add_u64 v[158:159], s[78:79], 0, v[140:141]
	s_add_i32 m0, s16, 0xe000
	s_nop 0
	global_load_lds_dwordx4 v[158:159], off
	s_waitcnt vmcnt(8)
	s_waitcnt lgkmcnt(0)
	s_barrier
; #define PG8_STAGE(bufoff, gbase, voff) do { _Pragma("unroll") for (int _i = 0; _i < 2; ++_i) \
;         __builtin_amdgcn_global_load_lds((const unsigned*)((const char*)(gbase) + (voff)[_i]), (LAS unsigned*)(lds + (bufoff) + ldsw + _i * 8192), 16, 0, 0); } while (0)
; #define PG8_LDA(dst, b, h) do { _Pragma("unroll") for (int m = 0; m < 4; ++m) _Pragma("unroll") for (int k = 0; k < 2; ++k) dst[m][k] = *(const LAS bf16x8*)(lds + PG8_SA(b, h) + aoff + m * 2048 + k * 1024); } while (0)
; #define PG8_MMA(ai, bj, At, Bt) do { __builtin_amdgcn_s_setprio(1); _Pragma("unroll") for (int m = 0; m < 4; ++m) _Pragma("unroll") for (int n = 0; n < 2; ++n) _Pragma("unroll") for (int k = 0; k < 2; ++k) \
;         acc[ai][bj][m][n] = __builtin_amdgcn_mfma_f32_16x16x32_bf16(Bt[n][k], At[m][k], acc[ai][bj][m][n], 0, 0, 0); __builtin_amdgcn_s_setprio(0); } while (0)
; #define PG8_WAIT_V(n) asm volatile("s_waitcnt vmcnt(" #n ")" ::: "memory")
; #define PG8_WAIT_L(n) asm volatile("s_waitcnt lgkmcnt(" #n ")" ::: "memory")
; #define PG8_BAR __builtin_amdgcn_s_barrier()
; #define PG8_SCHED __builtin_amdgcn_sched_barrier(0)
; template <int GI>
; __device__ __forceinline__ void gemm_phase(LAS unsigned char* lds, unsigned char* ws, int G, int cblk) {
;     ...
;             PG8_WAIT_V(8); PG8_WAIT_L(0); PG8_BAR; PG8_MMA(0, 0, At, B0); PG8_MMA(0, 1, At, B1); PG8_BAR; PG8_SCHED;
;             PG8_LDA(At, 0, 1); PG8_STAGE(PG8_SB(0, 0), b2, voffB); PG8_STAGE(PG8_SB(0, 1), b2 + hstepB, voffB); PG8_STAGE(PG8_SA(0, 0), a2, voffA);
;             PG8_WAIT_V(8); PG8_WAIT_L(0); PG8_BAR; PG8_MMA(1, 0, At, B0); PG8_MMA(1, 1, At, B1); PG8_BAR; PG8_SCHED;
	s_waitcnt lgkmcnt(0)
	v_mfma_f32_16x16x32_bf16 v[124:127], v[154:157], v[196:199], v[124:127]
	v_mfma_f32_16x16x32_bf16 v[120:123], v[168:171], v[196:199], v[120:123]
	v_mfma_f32_16x16x32_bf16 v[116:119], v[154:157], v[204:207], v[116:119]
	v_mfma_f32_16x16x32_bf16 v[112:115], v[168:171], v[204:207], v[112:115]
	v_mfma_f32_16x16x32_bf16 v[100:103], v[154:157], v[212:215], v[100:103]
	v_mfma_f32_16x16x32_bf16 v[96:99], v[168:171], v[212:215], v[96:99]
	v_mfma_f32_16x16x32_bf16 v[84:87], v[154:157], v[220:223], v[84:87]
	v_mfma_f32_16x16x32_bf16 v[80:83], v[168:171], v[220:223], v[80:83]
	v_mfma_f32_16x16x32_bf16 v[124:127], v[164:167], v[200:203], v[124:127]
	v_mfma_f32_16x16x32_bf16 v[120:123], v[172:175], v[200:203], v[120:123]
	v_mfma_f32_16x16x32_bf16 v[116:119], v[164:167], v[208:211], v[116:119]
	v_mfma_f32_16x16x32_bf16 v[112:115], v[172:175], v[208:211], v[112:115]
	v_mfma_f32_16x16x32_bf16 v[100:103], v[164:167], v[216:219], v[100:103]
	v_mfma_f32_16x16x32_bf16 v[96:99], v[172:175], v[216:219], v[96:99]
	v_mfma_f32_16x16x32_bf16 v[84:87], v[164:167], v[224:227], v[84:87]
	v_mfma_f32_16x16x32_bf16 v[80:83], v[172:175], v[224:227], v[80:83]
	v_mfma_f32_16x16x32_bf16 v[108:111], v[176:179], v[196:199], v[108:111]
	v_mfma_f32_16x16x32_bf16 v[104:107], v[184:187], v[196:199], v[104:107]
	v_mfma_f32_16x16x32_bf16 v[92:95], v[176:179], v[204:207], v[92:95]
	v_mfma_f32_16x16x32_bf16 v[88:91], v[184:187], v[204:207], v[88:91]
	v_mfma_f32_16x16x32_bf16 v[76:79], v[176:179], v[212:215], v[76:79]
	v_mfma_f32_16x16x32_bf16 v[72:75], v[184:187], v[212:215], v[72:75]
	v_mfma_f32_16x16x32_bf16 v[68:71], v[176:179], v[220:223], v[68:71]
	v_mfma_f32_16x16x32_bf16 v[64:67], v[184:187], v[220:223], v[64:67]
	v_mfma_f32_16x16x32_bf16 v[108:111], v[180:183], v[200:203], v[108:111]
	v_mfma_f32_16x16x32_bf16 v[104:107], v[192:195], v[200:203], v[104:107]
	v_mfma_f32_16x16x32_bf16 v[92:95], v[180:183], v[208:211], v[92:95]
	v_mfma_f32_16x16x32_bf16 v[88:91], v[192:195], v[208:211], v[88:91]
	v_mfma_f32_16x16x32_bf16 v[76:79], v[180:183], v[216:219], v[76:79]
	v_mfma_f32_16x16x32_bf16 v[72:75], v[192:195], v[216:219], v[72:75]
	v_mfma_f32_16x16x32_bf16 v[68:71], v[180:183], v[224:227], v[68:71]
	v_mfma_f32_16x16x32_bf16 v[64:67], v[192:195], v[224:227], v[64:67]
	s_barrier
	s_add_i32 s33, s24, s0
	v_lshl_add_u64 v[158:159], s[80:81], 0, v[130:131]
	s_mov_b32 m0, s33
	ds_read_b128 v[196:199], v153 offset:16384
	ds_read_b128 v[200:203], v153 offset:17408
	ds_read_b128 v[204:207], v153 offset:18432
	ds_read_b128 v[208:211], v153 offset:19456
	ds_read_b128 v[212:215], v153 offset:20480
	ds_read_b128 v[216:219], v153 offset:21504
	ds_read_b128 v[220:223], v153 offset:22528
	ds_read_b128 v[224:227], v153 offset:23552
	global_load_lds_dwordx4 v[158:159], off
	s_add_i32 m0, s33, 0x2000
	s_add_u32 s34, s80, 0x80000
	v_lshl_add_u64 v[188:189], s[80:81], 0, v[134:135]
	s_addc_u32 s35, s81, 0
	s_add_i32 s33, s25, s0
	global_load_lds_dwordx4 v[188:189], off
	v_lshl_add_u64 v[228:229], s[34:35], 0, v[130:131]
	s_mov_b32 m0, s33
	v_lshl_add_u64 v[230:231], s[82:83], 0, v[132:133]
	global_load_lds_dwordx4 v[228:229], off
	v_lshl_add_u64 v[228:229], s[34:35], 0, v[134:135]
	s_add_i32 m0, s33, 0x2000
	s_nop 0
	global_load_lds_dwordx4 v[228:229], off
	v_lshl_add_u64 v[228:229], s[82:83], 0, v[128:129]
	s_mov_b32 m0, s16
	s_nop 0
	global_load_lds_dwordx4 v[228:229], off
	s_mov_b32 m0, s17
	s_nop 0
	global_load_lds_dwordx4 v[230:231], off
	s_waitcnt vmcnt(8)
	s_waitcnt lgkmcnt(0)
	s_barrier
	s_waitcnt lgkmcnt(0)
	v_mfma_f32_16x16x32_bf16 v[60:63], v[154:157], v[196:199], v[60:63]
	v_mfma_f32_16x16x32_bf16 v[56:59], v[168:171], v[196:199], v[56:59]
	v_mfma_f32_16x16x32_bf16 v[52:55], v[154:157], v[204:207], v[52:55]
	v_mfma_f32_16x16x32_bf16 v[48:51], v[168:171], v[204:207], v[48:51]
	v_mfma_f32_16x16x32_bf16 v[36:39], v[154:157], v[212:215], v[36:39]
	v_mfma_f32_16x16x32_bf16 v[32:35], v[168:171], v[212:215], v[32:35]
	v_mfma_f32_16x16x32_bf16 v[20:23], v[154:157], v[220:223], v[20:23]
	v_mfma_f32_16x16x32_bf16 v[16:19], v[168:171], v[220:223], v[16:19]
	v_mfma_f32_16x16x32_bf16 v[60:63], v[164:167], v[200:203], v[60:63]
	v_mfma_f32_16x16x32_bf16 v[56:59], v[172:175], v[200:203], v[56:59]
	v_mfma_f32_16x16x32_bf16 v[52:55], v[164:167], v[208:211], v[52:55]
	v_mfma_f32_16x16x32_bf16 v[48:51], v[172:175], v[208:211], v[48:51]
	v_mfma_f32_16x16x32_bf16 v[36:39], v[164:167], v[216:219], v[36:39]
	v_mfma_f32_16x16x32_bf16 v[32:35], v[172:175], v[216:219], v[32:35]
	v_mfma_f32_16x16x32_bf16 v[20:23], v[164:167], v[224:227], v[20:23]
	v_mfma_f32_16x16x32_bf16 v[16:19], v[172:175], v[224:227], v[16:19]
	v_mfma_f32_16x16x32_bf16 v[44:47], v[176:179], v[196:199], v[44:47]
	v_mfma_f32_16x16x32_bf16 v[40:43], v[184:187], v[196:199], v[40:43]
	v_mfma_f32_16x16x32_bf16 v[28:31], v[176:179], v[204:207], v[28:31]
	v_mfma_f32_16x16x32_bf16 v[24:27], v[184:187], v[204:207], v[24:27]
	v_mfma_f32_16x16x32_bf16 v[12:15], v[176:179], v[212:215], v[12:15]
	v_mfma_f32_16x16x32_bf16 v[8:11], v[184:187], v[212:215], v[8:11]
	v_mfma_f32_16x16x32_bf16 v[4:7], v[176:179], v[220:223], v[4:7]
	v_mfma_f32_16x16x32_bf16 v[0:3], v[184:187], v[220:223], v[0:3]
	v_mfma_f32_16x16x32_bf16 v[44:47], v[180:183], v[200:203], v[44:47]
	v_mfma_f32_16x16x32_bf16 v[40:43], v[192:195], v[200:203], v[40:43]
	v_mfma_f32_16x16x32_bf16 v[28:31], v[180:183], v[208:211], v[28:31]
	v_mfma_f32_16x16x32_bf16 v[24:27], v[192:195], v[208:211], v[24:27]
	v_mfma_f32_16x16x32_bf16 v[12:15], v[180:183], v[216:219], v[12:15]
	v_mfma_f32_16x16x32_bf16 v[8:11], v[192:195], v[216:219], v[8:11]
	v_mfma_f32_16x16x32_bf16 v[4:7], v[180:183], v[224:227], v[4:7]
	v_mfma_f32_16x16x32_bf16 v[0:3], v[192:195], v[224:227], v[0:3]
	s_barrier
; #define PG8_STAGE(bufoff, gbase, voff) do { _Pragma("unroll") for (int _i = 0; _i < 2; ++_i) \
;         __builtin_amdgcn_global_load_lds((const unsigned*)((const char*)(gbase) + (voff)[_i]), (LAS unsigned*)(lds + (bufoff) + ldsw + _i * 8192), 16, 0, 0); } while (0)
; #define PG8_LDA(dst, b, h) do { _Pragma("unroll") for (int m = 0; m < 4; ++m) _Pragma("unroll") for (int k = 0; k < 2; ++k) dst[m][k] = *(const LAS bf16x8*)(lds + PG8_SA(b, h) + aoff + m * 2048 + k * 1024); } while (0)
; #define PG8_LDB(dst, b, h) do { _Pragma("unroll") for (int n = 0; n < 2; ++n) _Pragma("unroll") for (int k = 0; k < 2; ++k) dst[n][k] = *(const LAS bf16x8*)(lds + PG8_SB(b, h) + boff + n * 2048 + k * 1024); } while (0)
; #define PG8_MMA(ai, bj, At, Bt) do { __builtin_amdgcn_s_setprio(1); _Pragma("unroll") for (int m = 0; m < 4; ++m) _Pragma("unroll") for (int n = 0; n < 2; ++n) _Pragma("unroll") for (int k = 0; k < 2; ++k) \
;         acc[ai][bj][m][n] = __builtin_amdgcn_mfma_f32_16x16x32_bf16(Bt[n][k], At[m][k], acc[ai][bj][m][n], 0, 0, 0); __builtin_amdgcn_s_setprio(0); } while (0)
; #define PG8_WAIT_V(n) asm volatile("s_waitcnt vmcnt(" #n ")" ::: "memory")
; #define PG8_WAIT_L(n) asm volatile("s_waitcnt lgkmcnt(" #n ")" ::: "memory")
; #define PG8_BAR __builtin_amdgcn_s_barrier()
; #define PG8_SCHED __builtin_amdgcn_sched_barrier(0)
; template <int GI>
; __device__ __forceinline__ void gemm_phase(LAS unsigned char* lds, unsigned char* ws, int G, int cblk) {
;     ...
;             PG8_LDB(B0, 1, 0); PG8_LDB(B1, 1, 1); PG8_SCHED; PG8_LDA(At, 1, 0); PG8_STAGE(PG8_SA(0, 1), a2 + hstepA, voffA);
;             PG8_WAIT_V(8); PG8_WAIT_L(0); PG8_BAR; PG8_MMA(0, 0, At, B0); PG8_MMA(0, 1, At, B1); PG8_BAR; PG8_SCHED;
;             PG8_LDA(At, 1, 1); PG8_STAGE(PG8_SB(1, 0), b3, voffB); PG8_STAGE(PG8_SB(1, 1), b3 + hstepB, voffB); PG8_STAGE(PG8_SA(1, 0), a3, voffA);
;             PG8_WAIT_V(8); PG8_WAIT_L(0); PG8_BAR; PG8_MMA(1, 0, At, B0); PG8_MMA(1, 1, At, B1); PG8_BAR; PG8_SCHED;
;         }
	s_add_i32 s33, 0, 0x18000
	v_add_u32_e32 v161, s33, v150
	s_add_i32 s63, 0, 0x1c000
	ds_read_b128 v[154:157], v161
	ds_read_b128 v[164:167], v161 offset:1024
	ds_read_b128 v[168:171], v161 offset:2048
	ds_read_b128 v[172:175], v161 offset:3072
	v_add_u32_e32 v161, s63, v150
	ds_read_b128 v[176:179], v161
	ds_read_b128 v[180:183], v161 offset:1024
	ds_read_b128 v[184:187], v161 offset:2048
	ds_read_b128 v[192:195], v161 offset:3072
	s_add_u32 s34, s82, 0x80000
	s_addc_u32 s35, s83, 0
	s_mov_b32 m0, s18
	v_lshl_add_u64 v[232:233], s[34:35], 0, v[128:129]
	ds_read_b128 v[196:199], v153 offset:32768
	ds_read_b128 v[200:203], v153 offset:33792
	ds_read_b128 v[204:207], v153 offset:34816
	ds_read_b128 v[208:211], v153 offset:35840
	ds_read_b128 v[212:215], v153 offset:36864
	ds_read_b128 v[216:219], v153 offset:37888
	ds_read_b128 v[220:223], v153 offset:38912
	ds_read_b128 v[224:227], v153 offset:39936
	global_load_lds_dwordx4 v[232:233], off
	v_lshl_add_u64 v[232:233], s[34:35], 0, v[132:133]
	s_mov_b32 m0, s19
	s_nop 0
	global_load_lds_dwordx4 v[232:233], off
	s_waitcnt vmcnt(8)
	s_waitcnt lgkmcnt(0)
	s_barrier
	s_waitcnt lgkmcnt(0)
	v_mfma_f32_16x16x32_bf16 v[124:127], v[154:157], v[196:199], v[124:127]
	v_mfma_f32_16x16x32_bf16 v[120:123], v[168:171], v[196:199], v[120:123]
	v_mfma_f32_16x16x32_bf16 v[116:119], v[154:157], v[204:207], v[116:119]
	v_mfma_f32_16x16x32_bf16 v[112:115], v[168:171], v[204:207], v[112:115]
	v_mfma_f32_16x16x32_bf16 v[100:103], v[154:157], v[212:215], v[100:103]
	v_mfma_f32_16x16x32_bf16 v[96:99], v[168:171], v[212:215], v[96:99]
	v_mfma_f32_16x16x32_bf16 v[84:87], v[154:157], v[220:223], v[84:87]
	v_mfma_f32_16x16x32_bf16 v[80:83], v[168:171], v[220:223], v[80:83]
	v_mfma_f32_16x16x32_bf16 v[124:127], v[164:167], v[200:203], v[124:127]
	v_mfma_f32_16x16x32_bf16 v[120:123], v[172:175], v[200:203], v[120:123]
	v_mfma_f32_16x16x32_bf16 v[116:119], v[164:167], v[208:211], v[116:119]
	v_mfma_f32_16x16x32_bf16 v[112:115], v[172:175], v[208:211], v[112:115]
	v_mfma_f32_16x16x32_bf16 v[100:103], v[164:167], v[216:219], v[100:103]
	v_mfma_f32_16x16x32_bf16 v[96:99], v[172:175], v[216:219], v[96:99]
	v_mfma_f32_16x16x32_bf16 v[84:87], v[164:167], v[224:227], v[84:87]
	v_mfma_f32_16x16x32_bf16 v[80:83], v[172:175], v[224:227], v[80:83]
	v_mfma_f32_16x16x32_bf16 v[108:111], v[176:179], v[196:199], v[108:111]
	v_mfma_f32_16x16x32_bf16 v[104:107], v[184:187], v[196:199], v[104:107]
	v_mfma_f32_16x16x32_bf16 v[92:95], v[176:179], v[204:207], v[92:95]
	v_mfma_f32_16x16x32_bf16 v[88:91], v[184:187], v[204:207], v[88:91]
	v_mfma_f32_16x16x32_bf16 v[76:79], v[176:179], v[212:215], v[76:79]
	v_mfma_f32_16x16x32_bf16 v[72:75], v[184:187], v[212:215], v[72:75]
	v_mfma_f32_16x16x32_bf16 v[68:71], v[176:179], v[220:223], v[68:71]
	v_mfma_f32_16x16x32_bf16 v[64:67], v[184:187], v[220:223], v[64:67]
	v_mfma_f32_16x16x32_bf16 v[108:111], v[180:183], v[200:203], v[108:111]
	v_mfma_f32_16x16x32_bf16 v[104:107], v[192:195], v[200:203], v[104:107]
	v_mfma_f32_16x16x32_bf16 v[92:95], v[180:183], v[208:211], v[92:95]
	v_mfma_f32_16x16x32_bf16 v[88:91], v[192:195], v[208:211], v[88:91]
	v_mfma_f32_16x16x32_bf16 v[76:79], v[180:183], v[216:219], v[76:79]
	v_mfma_f32_16x16x32_bf16 v[72:75], v[192:195], v[216:219], v[72:75]
	v_mfma_f32_16x16x32_bf16 v[68:71], v[180:183], v[224:227], v[68:71]
	v_mfma_f32_16x16x32_bf16 v[64:67], v[192:195], v[224:227], v[64:67]
	s_barrier
	s_add_i32 s33, s33, s0
	v_lshl_add_u64 v[158:159], v[158:159], 0, s[38:39]
	s_mov_b32 m0, s33
	ds_read_b128 v[196:199], v153 offset:49152
	ds_read_b128 v[200:203], v153 offset:50176
	ds_read_b128 v[204:207], v153 offset:51200
	ds_read_b128 v[208:211], v153 offset:52224
	ds_read_b128 v[212:215], v153 offset:53248
	ds_read_b128 v[216:219], v153 offset:54272
	ds_read_b128 v[220:223], v153 offset:55296
	ds_read_b128 v[224:227], v153 offset:56320
	global_load_lds_dwordx4 v[158:159], off
	s_add_i32 m0, s33, 0x2000
	s_add_u32 s34, s80, 0x80080
	v_lshl_add_u64 v[158:159], v[188:189], 0, s[38:39]
	s_addc_u32 s35, s81, 0
	s_add_i32 s33, s63, s0
	global_load_lds_dwordx4 v[158:159], off
	v_lshl_add_u64 v[158:159], s[34:35], 0, v[130:131]
	s_mov_b32 m0, s33
	s_nop 0
	global_load_lds_dwordx4 v[158:159], off
	v_lshl_add_u64 v[158:159], s[34:35], 0, v[134:135]
	s_add_i32 m0, s33, 0x2000
	s_nop 0
	global_load_lds_dwordx4 v[158:159], off
	v_lshl_add_u64 v[158:159], v[228:229], 0, s[38:39]
	s_mov_b32 m0, s22
	s_nop 0
	global_load_lds_dwordx4 v[158:159], off
	v_lshl_add_u64 v[158:159], v[230:231], 0, s[38:39]
	s_mov_b32 m0, s23
	s_nop 0
	global_load_lds_dwordx4 v[158:159], off
	s_waitcnt vmcnt(8)
	s_waitcnt lgkmcnt(0)
	s_barrier
	s_waitcnt lgkmcnt(0)
	v_mfma_f32_16x16x32_bf16 v[60:63], v[154:157], v[196:199], v[60:63]
	v_mfma_f32_16x16x32_bf16 v[56:59], v[168:171], v[196:199], v[56:59]
	v_mfma_f32_16x16x32_bf16 v[52:55], v[154:157], v[204:207], v[52:55]
	v_mfma_f32_16x16x32_bf16 v[48:51], v[168:171], v[204:207], v[48:51]
	v_mfma_f32_16x16x32_bf16 v[36:39], v[154:157], v[212:215], v[36:39]
	v_mfma_f32_16x16x32_bf16 v[32:35], v[168:171], v[212:215], v[32:35]
	v_mfma_f32_16x16x32_bf16 v[20:23], v[154:157], v[220:223], v[20:23]
	v_mfma_f32_16x16x32_bf16 v[16:19], v[168:171], v[220:223], v[16:19]
	v_mfma_f32_16x16x32_bf16 v[60:63], v[164:167], v[200:203], v[60:63]
	v_mfma_f32_16x16x32_bf16 v[56:59], v[172:175], v[200:203], v[56:59]
	v_mfma_f32_16x16x32_bf16 v[52:55], v[164:167], v[208:211], v[52:55]
	v_mfma_f32_16x16x32_bf16 v[48:51], v[172:175], v[208:211], v[48:51]
	v_mfma_f32_16x16x32_bf16 v[36:39], v[164:167], v[216:219], v[36:39]
	v_mfma_f32_16x16x32_bf16 v[32:35], v[172:175], v[216:219], v[32:35]
	v_mfma_f32_16x16x32_bf16 v[20:23], v[164:167], v[224:227], v[20:23]
	v_mfma_f32_16x16x32_bf16 v[16:19], v[172:175], v[224:227], v[16:19]
	v_mfma_f32_16x16x32_bf16 v[44:47], v[176:179], v[196:199], v[44:47]
	v_mfma_f32_16x16x32_bf16 v[40:43], v[184:187], v[196:199], v[40:43]
	v_mfma_f32_16x16x32_bf16 v[28:31], v[176:179], v[204:207], v[28:31]
	v_mfma_f32_16x16x32_bf16 v[24:27], v[184:187], v[204:207], v[24:27]
	v_mfma_f32_16x16x32_bf16 v[12:15], v[176:179], v[212:215], v[12:15]
	v_mfma_f32_16x16x32_bf16 v[8:11], v[184:187], v[212:215], v[8:11]
	v_mfma_f32_16x16x32_bf16 v[4:7], v[176:179], v[220:223], v[4:7]
	v_mfma_f32_16x16x32_bf16 v[0:3], v[184:187], v[220:223], v[0:3]
	v_mfma_f32_16x16x32_bf16 v[44:47], v[180:183], v[200:203], v[44:47]
	v_mfma_f32_16x16x32_bf16 v[40:43], v[192:195], v[200:203], v[40:43]
	v_mfma_f32_16x16x32_bf16 v[28:31], v[180:183], v[208:211], v[28:31]
	v_mfma_f32_16x16x32_bf16 v[24:27], v[192:195], v[208:211], v[24:27]
	v_mfma_f32_16x16x32_bf16 v[12:15], v[180:183], v[216:219], v[12:15]
	v_mfma_f32_16x16x32_bf16 v[8:11], v[192:195], v[216:219], v[8:11]
	v_mfma_f32_16x16x32_bf16 v[4:7], v[180:183], v[224:227], v[4:7]
	v_mfma_f32_16x16x32_bf16 v[0:3], v[192:195], v[224:227], v[0:3]
	s_barrier
	s_add_i32 s27, s27, 2
	s_add_u32 s78, s78, 0x100
	s_addc_u32 s79, s79, 0
	s_add_u32 s14, s14, 0x100
	s_addc_u32 s15, s15, 0
	s_cmp_gt_u32 s27, 29
	s_cbranch_scc0 .LBB0_148

; #define PG8_STAGE(bufoff, gbase, voff) do { _Pragma("unroll") for (int _i = 0; _i < 2; ++_i) \
;         __builtin_amdgcn_global_load_lds((const unsigned*)((const char*)(gbase) + (voff)[_i]), (LAS unsigned*)(lds + (bufoff) + ldsw + _i * 8192), 16, 0, 0); } while (0)
; #define PG8_LDA(dst, b, h) do { _Pragma("unroll") for (int m = 0; m < 4; ++m) _Pragma("unroll") for (int k = 0; k < 2; ++k) dst[m][k] = *(const LAS bf16x8*)(lds + PG8_SA(b, h) + aoff + m * 2048 + k * 1024); } while (0)
; #define PG8_LDB(dst, b, h) do { _Pragma("unroll") for (int n = 0; n < 2; ++n) _Pragma("unroll") for (int k = 0; k < 2; ++k) dst[n][k] = *(const LAS bf16x8*)(lds + PG8_SB(b, h) + boff + n * 2048 + k * 1024); } while (0)
; #define PG8_MMA(ai, bj, At, Bt) do { __builtin_amdgcn_s_setprio(1); _Pragma("unroll") for (int m = 0; m < 4; ++m) _Pragma("unroll") for (int n = 0; n < 2; ++n) _Pragma("unroll") for (int k = 0; k < 2; ++k) \
;         acc[ai][bj][m][n] = __builtin_amdgcn_mfma_f32_16x16x32_bf16(Bt[n][k], At[m][k], acc[ai][bj][m][n], 0, 0, 0); __builtin_amdgcn_s_setprio(0); } while (0)
; #define PG8_WAIT_V(n) asm volatile("s_waitcnt vmcnt(" #n ")" ::: "memory")
; #define PG8_WAIT_L(n) asm volatile("s_waitcnt lgkmcnt(" #n ")" ::: "memory")
; #define PG8_BAR __builtin_amdgcn_s_barrier()
; #define PG8_SCHED __builtin_amdgcn_sched_barrier(0)
; template <int GI>
; __device__ __forceinline__ void gemm_phase(LAS unsigned char* lds, unsigned char* ws, int G, int cblk) {
;     ...
;         for (int t = 0; t < nt; t += 2) {
;             const bool last = (t == nt - 2);
;             const char* a1 = cA + (size_t)(t + 1) * kstep;
;             const char* a2 = last ? nA : cA + (size_t)(t + 2) * kstep; const char* b2 = last ? nB : cB + (size_t)(t + 2) * kstep;
;             const char* a3 = a2 + kstep; const char* b3 = b2 + kstep;
;             PG8_LDB(B0, 0, 0); PG8_LDB(B1, 0, 1); PG8_SCHED; PG8_LDA(At, 0, 0); PG8_STAGE(PG8_SA(1, 1), a1 + hstepA, voffA);
;             PG8_WAIT_V(8); PG8_WAIT_L(0); PG8_BAR; PG8_MMA(0, 0, At, B0); PG8_MMA(0, 1, At, B1); PG8_BAR; PG8_SCHED;
;             PG8_LDA(At, 0, 1); PG8_STAGE(PG8_SB(0, 0), b2, voffB); PG8_STAGE(PG8_SB(0, 1), b2 + hstepB, voffB); PG8_STAGE(PG8_SA(0, 0), a2, voffA);
.LBB0_399:
	s_add_u32 s46, s46, 0x80080
	s_addc_u32 s47, s47, 0
	s_add_u32 s14, s48, 0x100
	s_addc_u32 s15, s49, 0
	s_mov_b32 s19, -2
	ds_read_b128 v[154:157], v151
	ds_read_b128 v[164:167], v151 offset:1024
	ds_read_b128 v[168:171], v151 offset:2048
	ds_read_b128 v[172:175], v151 offset:3072
	ds_read_b128 v[176:179], v152
	ds_read_b128 v[180:183], v152 offset:1024
	ds_read_b128 v[184:187], v152 offset:2048
	ds_read_b128 v[192:195], v152 offset:3072
	s_add_u32 s34, s46, 0xfff80080
	s_addc_u32 s48, s47, -1
	s_cmp_eq_u32 s19, 28
	s_cselect_b32 s51, s41, s48
	s_cselect_b32 s50, s40, s34
	s_cselect_b32 s49, s43, s15
	s_cselect_b32 s48, s42, s14
	v_lshl_add_u64 v[158:159], s[46:47], 0, v[138:139]
	s_add_i32 m0, s16, 0xc000
	ds_read_b128 v[196:199], v153
	ds_read_b128 v[200:203], v153 offset:1024
	ds_read_b128 v[204:207], v153 offset:2048
	ds_read_b128 v[208:211], v153 offset:3072
	ds_read_b128 v[212:215], v153 offset:4096
	ds_read_b128 v[216:219], v153 offset:5120
	ds_read_b128 v[220:223], v153 offset:6144
	ds_read_b128 v[224:227], v153 offset:7168
	global_load_lds_dwordx4 v[158:159], off
	v_lshl_add_u64 v[158:159], s[46:47], 0, v[140:141]
	s_add_i32 m0, s16, 0xe000
	s_nop 0
	global_load_lds_dwordx4 v[158:159], off
	s_waitcnt vmcnt(8)
	s_waitcnt lgkmcnt(0)
	s_barrier
	s_waitcnt lgkmcnt(0)
	v_mfma_f32_16x16x32_bf16 v[124:127], v[154:157], v[196:199], 0
	v_mfma_f32_16x16x32_bf16 v[120:123], v[168:171], v[196:199], 0
	v_mfma_f32_16x16x32_bf16 v[116:119], v[154:157], v[204:207], 0
	v_mfma_f32_16x16x32_bf16 v[112:115], v[168:171], v[204:207], 0
	v_mfma_f32_16x16x32_bf16 v[100:103], v[154:157], v[212:215], 0
	v_mfma_f32_16x16x32_bf16 v[96:99], v[168:171], v[212:215], 0
	v_mfma_f32_16x16x32_bf16 v[84:87], v[154:157], v[220:223], 0
	v_mfma_f32_16x16x32_bf16 v[80:83], v[168:171], v[220:223], 0
	v_mfma_f32_16x16x32_bf16 v[124:127], v[164:167], v[200:203], v[124:127]
	v_mfma_f32_16x16x32_bf16 v[120:123], v[172:175], v[200:203], v[120:123]
	v_mfma_f32_16x16x32_bf16 v[116:119], v[164:167], v[208:211], v[116:119]
	v_mfma_f32_16x16x32_bf16 v[112:115], v[172:175], v[208:211], v[112:115]
	v_mfma_f32_16x16x32_bf16 v[100:103], v[164:167], v[216:219], v[100:103]
	v_mfma_f32_16x16x32_bf16 v[96:99], v[172:175], v[216:219], v[96:99]
	v_mfma_f32_16x16x32_bf16 v[84:87], v[164:167], v[224:227], v[84:87]
	v_mfma_f32_16x16x32_bf16 v[80:83], v[172:175], v[224:227], v[80:83]
	v_mfma_f32_16x16x32_bf16 v[108:111], v[176:179], v[196:199], 0
	v_mfma_f32_16x16x32_bf16 v[104:107], v[184:187], v[196:199], 0
	v_mfma_f32_16x16x32_bf16 v[92:95], v[176:179], v[204:207], 0
	v_mfma_f32_16x16x32_bf16 v[88:91], v[184:187], v[204:207], 0
	v_mfma_f32_16x16x32_bf16 v[76:79], v[176:179], v[212:215], 0
	v_mfma_f32_16x16x32_bf16 v[72:75], v[184:187], v[212:215], 0
	v_mfma_f32_16x16x32_bf16 v[68:71], v[176:179], v[220:223], 0
	v_mfma_f32_16x16x32_bf16 v[64:67], v[184:187], v[220:223], 0
	v_mfma_f32_16x16x32_bf16 v[108:111], v[180:183], v[200:203], v[108:111]
	v_mfma_f32_16x16x32_bf16 v[104:107], v[192:195], v[200:203], v[104:107]
	v_mfma_f32_16x16x32_bf16 v[92:95], v[180:183], v[208:211], v[92:95]
	v_mfma_f32_16x16x32_bf16 v[88:91], v[192:195], v[208:211], v[88:91]
	v_mfma_f32_16x16x32_bf16 v[76:79], v[180:183], v[216:219], v[76:79]
	v_mfma_f32_16x16x32_bf16 v[72:75], v[192:195], v[216:219], v[72:75]
	v_mfma_f32_16x16x32_bf16 v[68:71], v[180:183], v[224:227], v[68:71]
	v_mfma_f32_16x16x32_bf16 v[64:67], v[192:195], v[224:227], v[64:67]
	s_barrier
	s_add_i32 s34, s33, s0
	v_lshl_add_u64 v[158:159], s[48:49], 0, v[130:131]
	s_mov_b32 m0, s34
	ds_read_b128 v[196:199], v153 offset:16384
	ds_read_b128 v[200:203], v153 offset:17408
	ds_read_b128 v[204:207], v153 offset:18432
	ds_read_b128 v[208:211], v153 offset:19456
	ds_read_b128 v[212:215], v153 offset:20480
	ds_read_b128 v[216:219], v153 offset:21504
	ds_read_b128 v[220:223], v153 offset:22528
	ds_read_b128 v[224:227], v153 offset:23552
	global_load_lds_dwordx4 v[158:159], off
	s_add_i32 m0, s34, 0x2000
	s_add_u32 s54, s48, 0x80000
	v_lshl_add_u64 v[188:189], s[48:49], 0, v[134:135]
	s_addc_u32 s55, s49, 0
	s_add_i32 s34, s35, s0
	global_load_lds_dwordx4 v[188:189], off
	v_lshl_add_u64 v[228:229], s[54:55], 0, v[130:131]
	s_mov_b32 m0, s34
	v_lshl_add_u64 v[230:231], s[50:51], 0, v[132:133]
	global_load_lds_dwordx4 v[228:229], off
	v_lshl_add_u64 v[228:229], s[54:55], 0, v[134:135]
	s_add_i32 m0, s34, 0x2000
	s_nop 0
	global_load_lds_dwordx4 v[228:229], off
	v_lshl_add_u64 v[228:229], s[50:51], 0, v[128:129]
	s_mov_b32 m0, s16
	s_nop 0
	global_load_lds_dwordx4 v[228:229], off
	s_mov_b32 m0, s17
	s_nop 0
	global_load_lds_dwordx4 v[230:231], off
	s_waitcnt vmcnt(8)
	s_waitcnt lgkmcnt(0)
	s_barrier
; #define PG8_STAGE(bufoff, gbase, voff) do { _Pragma("unroll") for (int _i = 0; _i < 2; ++_i) \
;         __builtin_amdgcn_global_load_lds((const unsigned*)((const char*)(gbase) + (voff)[_i]), (LAS unsigned*)(lds + (bufoff) + ldsw + _i * 8192), 16, 0, 0); } while (0)
; #define PG8_LDA(dst, b, h) do { _Pragma("unroll") for (int m = 0; m < 4; ++m) _Pragma("unroll") for (int k = 0; k < 2; ++k) dst[m][k] = *(const LAS bf16x8*)(lds + PG8_SA(b, h) + aoff + m * 2048 + k * 1024); } while (0)
; #define PG8_LDB(dst, b, h) do { _Pragma("unroll") for (int n = 0; n < 2; ++n) _Pragma("unroll") for (int k = 0; k < 2; ++k) dst[n][k] = *(const LAS bf16x8*)(lds + PG8_SB(b, h) + boff + n * 2048 + k * 1024); } while (0)
; #define PG8_MMA(ai, bj, At, Bt) do { __builtin_amdgcn_s_setprio(1); _Pragma("unroll") for (int m = 0; m < 4; ++m) _Pragma("unroll") for (int n = 0; n < 2; ++n) _Pragma("unroll") for (int k = 0; k < 2; ++k) \
;         acc[ai][bj][m][n] = __builtin_amdgcn_mfma_f32_16x16x32_bf16(Bt[n][k], At[m][k], acc[ai][bj][m][n], 0, 0, 0); __builtin_amdgcn_s_setprio(0); } while (0)
; #define PG8_WAIT_V(n) asm volatile("s_waitcnt vmcnt(" #n ")" ::: "memory")
; #define PG8_WAIT_L(n) asm volatile("s_waitcnt lgkmcnt(" #n ")" ::: "memory")
; #define PG8_BAR __builtin_amdgcn_s_barrier()
; #define PG8_SCHED __builtin_amdgcn_sched_barrier(0)
; template <int GI>
; __device__ __forceinline__ void gemm_phase(LAS unsigned char* lds, unsigned char* ws, int G, int cblk) {
;     ...
;             PG8_WAIT_V(8); PG8_WAIT_L(0); PG8_BAR; PG8_MMA(0, 0, At, B0); PG8_MMA(0, 1, At, B1); PG8_BAR; PG8_SCHED;
;             PG8_LDA(At, 0, 1); PG8_STAGE(PG8_SB(0, 0), b2, voffB); PG8_STAGE(PG8_SB(0, 1), b2 + hstepB, voffB); PG8_STAGE(PG8_SA(0, 0), a2, voffA);
;             PG8_WAIT_V(8); PG8_WAIT_L(0); PG8_BAR; PG8_MMA(1, 0, At, B0); PG8_MMA(1, 1, At, B1); PG8_BAR; PG8_SCHED;
;             PG8_LDB(B0, 1, 0); PG8_LDB(B1, 1, 1); PG8_SCHED; PG8_LDA(At, 1, 0); PG8_STAGE(PG8_SA(0, 1), a2 + hstepA, voffA);
;             PG8_WAIT_V(8); PG8_WAIT_L(0); PG8_BAR; PG8_MMA(0, 0, At, B0); PG8_MMA(0, 1, At, B1); PG8_BAR; PG8_SCHED;
	s_waitcnt lgkmcnt(0)
	v_mfma_f32_16x16x32_bf16 v[60:63], v[154:157], v[196:199], 0
	v_mfma_f32_16x16x32_bf16 v[56:59], v[168:171], v[196:199], 0
	v_mfma_f32_16x16x32_bf16 v[52:55], v[154:157], v[204:207], 0
	v_mfma_f32_16x16x32_bf16 v[48:51], v[168:171], v[204:207], 0
	v_mfma_f32_16x16x32_bf16 v[36:39], v[154:157], v[212:215], 0
	v_mfma_f32_16x16x32_bf16 v[32:35], v[168:171], v[212:215], 0
	v_mfma_f32_16x16x32_bf16 v[20:23], v[154:157], v[220:223], 0
	v_mfma_f32_16x16x32_bf16 v[16:19], v[168:171], v[220:223], 0
	v_mfma_f32_16x16x32_bf16 v[60:63], v[164:167], v[200:203], v[60:63]
	v_mfma_f32_16x16x32_bf16 v[56:59], v[172:175], v[200:203], v[56:59]
	v_mfma_f32_16x16x32_bf16 v[52:55], v[164:167], v[208:211], v[52:55]
	v_mfma_f32_16x16x32_bf16 v[48:51], v[172:175], v[208:211], v[48:51]
	v_mfma_f32_16x16x32_bf16 v[36:39], v[164:167], v[216:219], v[36:39]
	v_mfma_f32_16x16x32_bf16 v[32:35], v[172:175], v[216:219], v[32:35]
	v_mfma_f32_16x16x32_bf16 v[20:23], v[164:167], v[224:227], v[20:23]
	v_mfma_f32_16x16x32_bf16 v[16:19], v[172:175], v[224:227], v[16:19]
	v_mfma_f32_16x16x32_bf16 v[44:47], v[176:179], v[196:199], 0
	v_mfma_f32_16x16x32_bf16 v[40:43], v[184:187], v[196:199], 0
	v_mfma_f32_16x16x32_bf16 v[28:31], v[176:179], v[204:207], 0
	v_mfma_f32_16x16x32_bf16 v[24:27], v[184:187], v[204:207], 0
	v_mfma_f32_16x16x32_bf16 v[12:15], v[176:179], v[212:215], 0
	v_mfma_f32_16x16x32_bf16 v[8:11], v[184:187], v[212:215], 0
	v_mfma_f32_16x16x32_bf16 v[4:7], v[176:179], v[220:223], 0
	v_mfma_f32_16x16x32_bf16 v[0:3], v[184:187], v[220:223], 0
	v_mfma_f32_16x16x32_bf16 v[44:47], v[180:183], v[200:203], v[44:47]
	v_mfma_f32_16x16x32_bf16 v[40:43], v[192:195], v[200:203], v[40:43]
	v_mfma_f32_16x16x32_bf16 v[28:31], v[180:183], v[208:211], v[28:31]
	v_mfma_f32_16x16x32_bf16 v[24:27], v[192:195], v[208:211], v[24:27]
	v_mfma_f32_16x16x32_bf16 v[12:15], v[180:183], v[216:219], v[12:15]
	v_mfma_f32_16x16x32_bf16 v[8:11], v[192:195], v[216:219], v[8:11]
	v_mfma_f32_16x16x32_bf16 v[4:7], v[180:183], v[224:227], v[4:7]
	v_mfma_f32_16x16x32_bf16 v[0:3], v[192:195], v[224:227], v[0:3]
	s_barrier
	s_add_i32 s34, 0, 0x18000
	v_add_u32_e32 v161, s34, v150
	s_add_i32 s53, 0, 0x1c000
	ds_read_b128 v[154:157], v161
	ds_read_b128 v[164:167], v161 offset:1024
	ds_read_b128 v[168:171], v161 offset:2048
	ds_read_b128 v[172:175], v161 offset:3072
	v_add_u32_e32 v161, s53, v150
	ds_read_b128 v[176:179], v161
	ds_read_b128 v[180:183], v161 offset:1024
	ds_read_b128 v[184:187], v161 offset:2048
	ds_read_b128 v[192:195], v161 offset:3072
	s_add_u32 s50, s50, 0x80000
	s_addc_u32 s51, s51, 0
	s_mov_b32 m0, s22
	v_lshl_add_u64 v[232:233], s[50:51], 0, v[128:129]
	ds_read_b128 v[196:199], v153 offset:32768
	ds_read_b128 v[200:203], v153 offset:33792
	ds_read_b128 v[204:207], v153 offset:34816
	ds_read_b128 v[208:211], v153 offset:35840
	ds_read_b128 v[212:215], v153 offset:36864
	ds_read_b128 v[216:219], v153 offset:37888
	ds_read_b128 v[220:223], v153 offset:38912
	ds_read_b128 v[224:227], v153 offset:39936
	global_load_lds_dwordx4 v[232:233], off
	v_lshl_add_u64 v[232:233], s[50:51], 0, v[132:133]
	s_mov_b32 m0, s23
	s_nop 0
	global_load_lds_dwordx4 v[232:233], off
	s_waitcnt vmcnt(8)
	s_waitcnt lgkmcnt(0)
	s_barrier
	s_waitcnt lgkmcnt(0)
	v_mfma_f32_16x16x32_bf16 v[124:127], v[154:157], v[196:199], v[124:127]
	v_mfma_f32_16x16x32_bf16 v[120:123], v[168:171], v[196:199], v[120:123]
	v_mfma_f32_16x16x32_bf16 v[116:119], v[154:157], v[204:207], v[116:119]
	v_mfma_f32_16x16x32_bf16 v[112:115], v[168:171], v[204:207], v[112:115]
	v_mfma_f32_16x16x32_bf16 v[100:103], v[154:157], v[212:215], v[100:103]
	v_mfma_f32_16x16x32_bf16 v[96:99], v[168:171], v[212:215], v[96:99]
	v_mfma_f32_16x16x32_bf16 v[84:87], v[154:157], v[220:223], v[84:87]
	v_mfma_f32_16x16x32_bf16 v[80:83], v[168:171], v[220:223], v[80:83]
	v_mfma_f32_16x16x32_bf16 v[124:127], v[164:167], v[200:203], v[124:127]
	v_mfma_f32_16x16x32_bf16 v[120:123], v[172:175], v[200:203], v[120:123]
	v_mfma_f32_16x16x32_bf16 v[116:119], v[164:167], v[208:211], v[116:119]
	v_mfma_f32_16x16x32_bf16 v[112:115], v[172:175], v[208:211], v[112:115]
	v_mfma_f32_16x16x32_bf16 v[100:103], v[164:167], v[216:219], v[100:103]
	v_mfma_f32_16x16x32_bf16 v[96:99], v[172:175], v[216:219], v[96:99]
	v_mfma_f32_16x16x32_bf16 v[84:87], v[164:167], v[224:227], v[84:87]
	v_mfma_f32_16x16x32_bf16 v[80:83], v[172:175], v[224:227], v[80:83]
	v_mfma_f32_16x16x32_bf16 v[108:111], v[176:179], v[196:199], v[108:111]
	v_mfma_f32_16x16x32_bf16 v[104:107], v[184:187], v[196:199], v[104:107]
	v_mfma_f32_16x16x32_bf16 v[92:95], v[176:179], v[204:207], v[92:95]
	v_mfma_f32_16x16x32_bf16 v[88:91], v[184:187], v[204:207], v[88:91]
	v_mfma_f32_16x16x32_bf16 v[76:79], v[176:179], v[212:215], v[76:79]
	v_mfma_f32_16x16x32_bf16 v[72:75], v[184:187], v[212:215], v[72:75]
	v_mfma_f32_16x16x32_bf16 v[68:71], v[176:179], v[220:223], v[68:71]
	v_mfma_f32_16x16x32_bf16 v[64:67], v[184:187], v[220:223], v[64:67]
	v_mfma_f32_16x16x32_bf16 v[108:111], v[180:183], v[200:203], v[108:111]
	v_mfma_f32_16x16x32_bf16 v[104:107], v[192:195], v[200:203], v[104:107]
	v_mfma_f32_16x16x32_bf16 v[92:95], v[180:183], v[208:211], v[92:95]
	v_mfma_f32_16x16x32_bf16 v[88:91], v[192:195], v[208:211], v[88:91]
	v_mfma_f32_16x16x32_bf16 v[76:79], v[180:183], v[216:219], v[76:79]
	v_mfma_f32_16x16x32_bf16 v[72:75], v[192:195], v[216:219], v[72:75]
	v_mfma_f32_16x16x32_bf16 v[68:71], v[180:183], v[224:227], v[68:71]
	v_mfma_f32_16x16x32_bf16 v[64:67], v[192:195], v[224:227], v[64:67]
	s_barrier
; #define PG8_STAGE(bufoff, gbase, voff) do { _Pragma("unroll") for (int _i = 0; _i < 2; ++_i) \
;         __builtin_amdgcn_global_load_lds((const unsigned*)((const char*)(gbase) + (voff)[_i]), (LAS unsigned*)(lds + (bufoff) + ldsw + _i * 8192), 16, 0, 0); } while (0)
; #define PG8_LDA(dst, b, h) do { _Pragma("unroll") for (int m = 0; m < 4; ++m) _Pragma("unroll") for (int k = 0; k < 2; ++k) dst[m][k] = *(const LAS bf16x8*)(lds + PG8_SA(b, h) + aoff + m * 2048 + k * 1024); } while (0)
; #define PG8_LDB(dst, b, h) do { _Pragma("unroll") for (int n = 0; n < 2; ++n) _Pragma("unroll") for (int k = 0; k < 2; ++k) dst[n][k] = *(const LAS bf16x8*)(lds + PG8_SB(b, h) + boff + n * 2048 + k * 1024); } while (0)
; #define PG8_WAIT_V(n) asm volatile("s_waitcnt vmcnt(" #n ")" ::: "memory")
; #define PG8_WAIT_L(n) asm volatile("s_waitcnt lgkmcnt(" #n ")" ::: "memory")
; template <int GI>
; __device__ __forceinline__ void gemm_phase(LAS unsigned char* lds, unsigned char* ws, int G, int cblk) {
;     ...
;         for (int t = 0; t < nt; t += 2) {
;             const bool last = (t == nt - 2);
;             const char* a1 = cA + (size_t)(t + 1) * kstep;
;             const char* a2 = last ? nA : cA + (size_t)(t + 2) * kstep; const char* b2 = last ? nB : cB + (size_t)(t + 2) * kstep;
;             const char* a3 = a2 + kstep; const char* b3 = b2 + kstep;
;             PG8_LDB(B0, 0, 0); PG8_LDB(B1, 0, 1); PG8_SCHED; PG8_LDA(At, 0, 0); PG8_STAGE(PG8_SA(1, 1), a1 + hstepA, voffA);
;             PG8_WAIT_V(8); PG8_WAIT_L(0); PG8_BAR; PG8_MMA(0, 0, At, B0); PG8_MMA(0, 1, At, B1); PG8_BAR; PG8_SCHED;
;             PG8_LDA(At, 0, 1); PG8_STAGE(PG8_SB(0, 0), b2, voffB); PG8_STAGE(PG8_SB(0, 1), b2 + hstepB, voffB); PG8_STAGE(PG8_SA(0, 0), a2, voffA);
;             PG8_WAIT_V(8); PG8_WAIT_L(0); PG8_BAR; PG8_MMA(1, 0, At, B0); PG8_MMA(1, 1, At, B1); PG8_BAR; PG8_SCHED;
;             PG8_LDB(B0, 1, 0); PG8_LDB(B1, 1, 1); PG8_SCHED; PG8_LDA(At, 1, 0); PG8_STAGE(PG8_SA(0, 1), a2 + hstepA, voffA);
;             PG8_WAIT_V(8); PG8_WAIT_L(0); PG8_BAR; PG8_MMA(0, 0, At, B0); PG8_MMA(0, 1, At, B1); PG8_BAR; PG8_SCHED;
;             PG8_LDA(At, 1, 1); PG8_STAGE(PG8_SB(1, 0), b3, voffB); PG8_STAGE(PG8_SB(1, 1), b3 + hstepB, voffB); PG8_STAGE(PG8_SA(1, 0), a3, voffA);
;             PG8_WAIT_V(8); PG8_WAIT_L(0); PG8_BAR; PG8_MMA(1, 0, At, B0); PG8_MMA(1, 1, At, B1); PG8_BAR; PG8_SCHED;
	s_add_i32 s34, s34, s0
	v_lshl_add_u64 v[158:159], v[158:159], 0, s[8:9]
	s_mov_b32 m0, s34
	ds_read_b128 v[196:199], v153 offset:49152
	ds_read_b128 v[200:203], v153 offset:50176
	ds_read_b128 v[204:207], v153 offset:51200
	ds_read_b128 v[208:211], v153 offset:52224
	ds_read_b128 v[212:215], v153 offset:53248
	ds_read_b128 v[216:219], v153 offset:54272
	ds_read_b128 v[220:223], v153 offset:55296
	ds_read_b128 v[224:227], v153 offset:56320
	global_load_lds_dwordx4 v[158:159], off
	s_add_i32 m0, s34, 0x2000
	s_add_u32 s48, s48, 0x80080
	v_lshl_add_u64 v[158:159], v[188:189], 0, s[8:9]
	s_addc_u32 s49, s49, 0
	s_add_i32 s34, s53, s0
	global_load_lds_dwordx4 v[158:159], off
	v_lshl_add_u64 v[158:159], s[48:49], 0, v[130:131]
	s_mov_b32 m0, s34
	s_nop 0
	global_load_lds_dwordx4 v[158:159], off
	v_lshl_add_u64 v[158:159], s[48:49], 0, v[134:135]
	s_add_i32 m0, s34, 0x2000
	s_nop 0
	global_load_lds_dwordx4 v[158:159], off
	v_lshl_add_u64 v[158:159], v[228:229], 0, s[8:9]
	s_mov_b32 m0, s26
	s_nop 0
	global_load_lds_dwordx4 v[158:159], off
	v_lshl_add_u64 v[158:159], v[230:231], 0, s[8:9]
	s_mov_b32 m0, s27
	s_nop 0
	global_load_lds_dwordx4 v[158:159], off
	s_waitcnt vmcnt(8)
	s_waitcnt lgkmcnt(0)
	s_barrier
	s_waitcnt lgkmcnt(0)
	v_mfma_f32_16x16x32_bf16 v[60:63], v[154:157], v[196:199], v[60:63]
	v_mfma_f32_16x16x32_bf16 v[56:59], v[168:171], v[196:199], v[56:59]
	v_mfma_f32_16x16x32_bf16 v[52:55], v[154:157], v[204:207], v[52:55]
	v_mfma_f32_16x16x32_bf16 v[48:51], v[168:171], v[204:207], v[48:51]
	v_mfma_f32_16x16x32_bf16 v[36:39], v[154:157], v[212:215], v[36:39]
	v_mfma_f32_16x16x32_bf16 v[32:35], v[168:171], v[212:215], v[32:35]
	v_mfma_f32_16x16x32_bf16 v[20:23], v[154:157], v[220:223], v[20:23]
	v_mfma_f32_16x16x32_bf16 v[16:19], v[168:171], v[220:223], v[16:19]
	v_mfma_f32_16x16x32_bf16 v[60:63], v[164:167], v[200:203], v[60:63]
	v_mfma_f32_16x16x32_bf16 v[56:59], v[172:175], v[200:203], v[56:59]
	v_mfma_f32_16x16x32_bf16 v[52:55], v[164:167], v[208:211], v[52:55]
	v_mfma_f32_16x16x32_bf16 v[48:51], v[172:175], v[208:211], v[48:51]
	v_mfma_f32_16x16x32_bf16 v[36:39], v[164:167], v[216:219], v[36:39]
	v_mfma_f32_16x16x32_bf16 v[32:35], v[172:175], v[216:219], v[32:35]
	v_mfma_f32_16x16x32_bf16 v[20:23], v[164:167], v[224:227], v[20:23]
	v_mfma_f32_16x16x32_bf16 v[16:19], v[172:175], v[224:227], v[16:19]
	v_mfma_f32_16x16x32_bf16 v[44:47], v[176:179], v[196:199], v[44:47]
	v_mfma_f32_16x16x32_bf16 v[40:43], v[184:187], v[196:199], v[40:43]
	v_mfma_f32_16x16x32_bf16 v[28:31], v[176:179], v[204:207], v[28:31]
	v_mfma_f32_16x16x32_bf16 v[24:27], v[184:187], v[204:207], v[24:27]
	v_mfma_f32_16x16x32_bf16 v[12:15], v[176:179], v[212:215], v[12:15]
	v_mfma_f32_16x16x32_bf16 v[8:11], v[184:187], v[212:215], v[8:11]
	v_mfma_f32_16x16x32_bf16 v[4:7], v[176:179], v[220:223], v[4:7]
	v_mfma_f32_16x16x32_bf16 v[0:3], v[184:187], v[220:223], v[0:3]
	v_mfma_f32_16x16x32_bf16 v[44:47], v[180:183], v[200:203], v[44:47]
	v_mfma_f32_16x16x32_bf16 v[40:43], v[192:195], v[200:203], v[40:43]
	v_mfma_f32_16x16x32_bf16 v[28:31], v[180:183], v[208:211], v[28:31]
	v_mfma_f32_16x16x32_bf16 v[24:27], v[192:195], v[208:211], v[24:27]
	v_mfma_f32_16x16x32_bf16 v[12:15], v[180:183], v[216:219], v[12:15]
	v_mfma_f32_16x16x32_bf16 v[8:11], v[192:195], v[216:219], v[8:11]
	v_mfma_f32_16x16x32_bf16 v[4:7], v[180:183], v[224:227], v[4:7]
	v_mfma_f32_16x16x32_bf16 v[0:3], v[192:195], v[224:227], v[0:3]
	s_barrier
	s_add_i32 s19, s19, 2
	s_add_u32 s46, s46, 0x100
	s_addc_u32 s47, s47, 0
	s_add_u32 s14, s14, 0x100
	s_addc_u32 s15, s15, 0
	s_cmp_gt_u32 s19, 29
	s_cbranch_scc0 .LBB0_400
	s_branch .Lpeel_exit_3
.LBB0_400:
	ds_read_b128 v[154:157], v151
	ds_read_b128 v[164:167], v151 offset:1024
	ds_read_b128 v[168:171], v151 offset:2048
	ds_read_b128 v[172:175], v151 offset:3072
	ds_read_b128 v[176:179], v152
	ds_read_b128 v[180:183], v152 offset:1024
	ds_read_b128 v[184:187], v152 offset:2048
	ds_read_b128 v[192:195], v152 offset:3072
	s_add_u32 s34, s46, 0xfff80080
	s_addc_u32 s48, s47, -1
	s_cmp_eq_u32 s19, 28
	s_cselect_b32 s51, s41, s48
	s_cselect_b32 s50, s40, s34
	s_cselect_b32 s49, s43, s15
	s_cselect_b32 s48, s42, s14
	v_lshl_add_u64 v[158:159], s[46:47], 0, v[138:139]
	s_add_i32 m0, s16, 0xc000
	ds_read_b128 v[196:199], v153
	ds_read_b128 v[200:203], v153 offset:1024
	ds_read_b128 v[204:207], v153 offset:2048
	ds_read_b128 v[208:211], v153 offset:3072
	ds_read_b128 v[212:215], v153 offset:4096
	ds_read_b128 v[216:219], v153 offset:5120
	ds_read_b128 v[220:223], v153 offset:6144
	ds_read_b128 v[224:227], v153 offset:7168
	global_load_lds_dwordx4 v[158:159], off
	v_lshl_add_u64 v[158:159], s[46:47], 0, v[140:141]
	s_add_i32 m0, s16, 0xe000
	s_nop 0
	global_load_lds_dwordx4 v[158:159], off
	s_waitcnt vmcnt(8)
	s_waitcnt lgkmcnt(0)
	s_barrier
; #define PG8_STAGE(bufoff, gbase, voff) do { _Pragma("unroll") for (int _i = 0; _i < 2; ++_i) \
;         __builtin_amdgcn_global_load_lds((const unsigned*)((const char*)(gbase) + (voff)[_i]), (LAS unsigned*)(lds + (bufoff) + ldsw + _i * 8192), 16, 0, 0); } while (0)
; #define PG8_LDA(dst, b, h) do { _Pragma("unroll") for (int m = 0; m < 4; ++m) _Pragma("unroll") for (int k = 0; k < 2; ++k) dst[m][k] = *(const LAS bf16x8*)(lds + PG8_SA(b, h) + aoff + m * 2048 + k * 1024); } while (0)
; #define PG8_MMA(ai, bj, At, Bt) do { __builtin_amdgcn_s_setprio(1); _Pragma("unroll") for (int m = 0; m < 4; ++m) _Pragma("unroll") for (int n = 0; n < 2; ++n) _Pragma("unroll") for (int k = 0; k < 2; ++k) \
;         acc[ai][bj][m][n] = __builtin_amdgcn_mfma_f32_16x16x32_bf16(Bt[n][k], At[m][k], acc[ai][bj][m][n], 0, 0, 0); __builtin_amdgcn_s_setprio(0); } while (0)
; #define PG8_WAIT_V(n) asm volatile("s_waitcnt vmcnt(" #n ")" ::: "memory")
; #define PG8_WAIT_L(n) asm volatile("s_waitcnt lgkmcnt(" #n ")" ::: "memory")
; #define PG8_BAR __builtin_amdgcn_s_barrier()
; #define PG8_SCHED __builtin_amdgcn_sched_barrier(0)
; template <int GI>
; __device__ __forceinline__ void gemm_phase(LAS unsigned char* lds, unsigned char* ws, int G, int cblk) {
;     ...
;             PG8_WAIT_V(8); PG8_WAIT_L(0); PG8_BAR; PG8_MMA(0, 0, At, B0); PG8_MMA(0, 1, At, B1); PG8_BAR; PG8_SCHED;
;             PG8_LDA(At, 0, 1); PG8_STAGE(PG8_SB(0, 0), b2, voffB); PG8_STAGE(PG8_SB(0, 1), b2 + hstepB, voffB); PG8_STAGE(PG8_SA(0, 0), a2, voffA);
;             PG8_WAIT_V(8); PG8_WAIT_L(0); PG8_BAR; PG8_MMA(1, 0, At, B0); PG8_MMA(1, 1, At, B1); PG8_BAR; PG8_SCHED;
	s_waitcnt lgkmcnt(0)
	v_mfma_f32_16x16x32_bf16 v[124:127], v[154:157], v[196:199], v[124:127]
	v_mfma_f32_16x16x32_bf16 v[120:123], v[168:171], v[196:199], v[120:123]
	v_mfma_f32_16x16x32_bf16 v[116:119], v[154:157], v[204:207], v[116:119]
	v_mfma_f32_16x16x32_bf16 v[112:115], v[168:171], v[204:207], v[112:115]
	v_mfma_f32_16x16x32_bf16 v[100:103], v[154:157], v[212:215], v[100:103]
	v_mfma_f32_16x16x32_bf16 v[96:99], v[168:171], v[212:215], v[96:99]
	v_mfma_f32_16x16x32_bf16 v[84:87], v[154:157], v[220:223], v[84:87]
	v_mfma_f32_16x16x32_bf16 v[80:83], v[168:171], v[220:223], v[80:83]
	v_mfma_f32_16x16x32_bf16 v[124:127], v[164:167], v[200:203], v[124:127]
	v_mfma_f32_16x16x32_bf16 v[120:123], v[172:175], v[200:203], v[120:123]
	v_mfma_f32_16x16x32_bf16 v[116:119], v[164:167], v[208:211], v[116:119]
	v_mfma_f32_16x16x32_bf16 v[112:115], v[172:175], v[208:211], v[112:115]
	v_mfma_f32_16x16x32_bf16 v[100:103], v[164:167], v[216:219], v[100:103]
	v_mfma_f32_16x16x32_bf16 v[96:99], v[172:175], v[216:219], v[96:99]
	v_mfma_f32_16x16x32_bf16 v[84:87], v[164:167], v[224:227], v[84:87]
	v_mfma_f32_16x16x32_bf16 v[80:83], v[172:175], v[224:227], v[80:83]
	v_mfma_f32_16x16x32_bf16 v[108:111], v[176:179], v[196:199], v[108:111]
	v_mfma_f32_16x16x32_bf16 v[104:107], v[184:187], v[196:199], v[104:107]
	v_mfma_f32_16x16x32_bf16 v[92:95], v[176:179], v[204:207], v[92:95]
	v_mfma_f32_16x16x32_bf16 v[88:91], v[184:187], v[204:207], v[88:91]
	v_mfma_f32_16x16x32_bf16 v[76:79], v[176:179], v[212:215], v[76:79]
	v_mfma_f32_16x16x32_bf16 v[72:75], v[184:187], v[212:215], v[72:75]
	v_mfma_f32_16x16x32_bf16 v[68:71], v[176:179], v[220:223], v[68:71]
	v_mfma_f32_16x16x32_bf16 v[64:67], v[184:187], v[220:223], v[64:67]
	v_mfma_f32_16x16x32_bf16 v[108:111], v[180:183], v[200:203], v[108:111]
	v_mfma_f32_16x16x32_bf16 v[104:107], v[192:195], v[200:203], v[104:107]
	v_mfma_f32_16x16x32_bf16 v[92:95], v[180:183], v[208:211], v[92:95]
	v_mfma_f32_16x16x32_bf16 v[88:91], v[192:195], v[208:211], v[88:91]
	v_mfma_f32_16x16x32_bf16 v[76:79], v[180:183], v[216:219], v[76:79]
	v_mfma_f32_16x16x32_bf16 v[72:75], v[192:195], v[216:219], v[72:75]
	v_mfma_f32_16x16x32_bf16 v[68:71], v[180:183], v[224:227], v[68:71]
	v_mfma_f32_16x16x32_bf16 v[64:67], v[192:195], v[224:227], v[64:67]
	s_barrier
	s_add_i32 s34, s33, s0
	v_lshl_add_u64 v[158:159], s[48:49], 0, v[130:131]
	s_mov_b32 m0, s34
	ds_read_b128 v[196:199], v153 offset:16384
	ds_read_b128 v[200:203], v153 offset:17408
	ds_read_b128 v[204:207], v153 offset:18432
	ds_read_b128 v[208:211], v153 offset:19456
	ds_read_b128 v[212:215], v153 offset:20480
	ds_read_b128 v[216:219], v153 offset:21504
	ds_read_b128 v[220:223], v153 offset:22528
	ds_read_b128 v[224:227], v153 offset:23552
	global_load_lds_dwordx4 v[158:159], off
	s_add_i32 m0, s34, 0x2000
	s_add_u32 s54, s48, 0x80000
	v_lshl_add_u64 v[188:189], s[48:49], 0, v[134:135]
	s_addc_u32 s55, s49, 0
	s_add_i32 s34, s35, s0
	global_load_lds_dwordx4 v[188:189], off
	v_lshl_add_u64 v[228:229], s[54:55], 0, v[130:131]
	s_mov_b32 m0, s34
	v_lshl_add_u64 v[230:231], s[50:51], 0, v[132:133]
	global_load_lds_dwordx4 v[228:229], off
	v_lshl_add_u64 v[228:229], s[54:55], 0, v[134:135]
	s_add_i32 m0, s34, 0x2000
	s_nop 0
	global_load_lds_dwordx4 v[228:229], off
	v_lshl_add_u64 v[228:229], s[50:51], 0, v[128:129]
	s_mov_b32 m0, s16
	s_nop 0
	global_load_lds_dwordx4 v[228:229], off
	s_mov_b32 m0, s17
	s_nop 0
	global_load_lds_dwordx4 v[230:231], off
	s_waitcnt vmcnt(8)
	s_waitcnt lgkmcnt(0)
	s_barrier
	s_waitcnt lgkmcnt(0)
	v_mfma_f32_16x16x32_bf16 v[60:63], v[154:157], v[196:199], v[60:63]
	v_mfma_f32_16x16x32_bf16 v[56:59], v[168:171], v[196:199], v[56:59]
	v_mfma_f32_16x16x32_bf16 v[52:55], v[154:157], v[204:207], v[52:55]
	v_mfma_f32_16x16x32_bf16 v[48:51], v[168:171], v[204:207], v[48:51]
	v_mfma_f32_16x16x32_bf16 v[36:39], v[154:157], v[212:215], v[36:39]
	v_mfma_f32_16x16x32_bf16 v[32:35], v[168:171], v[212:215], v[32:35]
	v_mfma_f32_16x16x32_bf16 v[20:23], v[154:157], v[220:223], v[20:23]
	v_mfma_f32_16x16x32_bf16 v[16:19], v[168:171], v[220:223], v[16:19]
	v_mfma_f32_16x16x32_bf16 v[60:63], v[164:167], v[200:203], v[60:63]
	v_mfma_f32_16x16x32_bf16 v[56:59], v[172:175], v[200:203], v[56:59]
	v_mfma_f32_16x16x32_bf16 v[52:55], v[164:167], v[208:211], v[52:55]
	v_mfma_f32_16x16x32_bf16 v[48:51], v[172:175], v[208:211], v[48:51]
	v_mfma_f32_16x16x32_bf16 v[36:39], v[164:167], v[216:219], v[36:39]
	v_mfma_f32_16x16x32_bf16 v[32:35], v[172:175], v[216:219], v[32:35]
	v_mfma_f32_16x16x32_bf16 v[20:23], v[164:167], v[224:227], v[20:23]
	v_mfma_f32_16x16x32_bf16 v[16:19], v[172:175], v[224:227], v[16:19]
	v_mfma_f32_16x16x32_bf16 v[44:47], v[176:179], v[196:199], v[44:47]
	v_mfma_f32_16x16x32_bf16 v[40:43], v[184:187], v[196:199], v[40:43]
	v_mfma_f32_16x16x32_bf16 v[28:31], v[176:179], v[204:207], v[28:31]
	v_mfma_f32_16x16x32_bf16 v[24:27], v[184:187], v[204:207], v[24:27]
	v_mfma_f32_16x16x32_bf16 v[12:15], v[176:179], v[212:215], v[12:15]
	v_mfma_f32_16x16x32_bf16 v[8:11], v[184:187], v[212:215], v[8:11]
	v_mfma_f32_16x16x32_bf16 v[4:7], v[176:179], v[220:223], v[4:7]
	v_mfma_f32_16x16x32_bf16 v[0:3], v[184:187], v[220:223], v[0:3]
	v_mfma_f32_16x16x32_bf16 v[44:47], v[180:183], v[200:203], v[44:47]
	v_mfma_f32_16x16x32_bf16 v[40:43], v[192:195], v[200:203], v[40:43]
	v_mfma_f32_16x16x32_bf16 v[28:31], v[180:183], v[208:211], v[28:31]
	v_mfma_f32_16x16x32_bf16 v[24:27], v[192:195], v[208:211], v[24:27]
	v_mfma_f32_16x16x32_bf16 v[12:15], v[180:183], v[216:219], v[12:15]
	v_mfma_f32_16x16x32_bf16 v[8:11], v[192:195], v[216:219], v[8:11]
	v_mfma_f32_16x16x32_bf16 v[4:7], v[180:183], v[224:227], v[4:7]
	v_mfma_f32_16x16x32_bf16 v[0:3], v[192:195], v[224:227], v[0:3]
	s_barrier
; #define PG8_STAGE(bufoff, gbase, voff) do { _Pragma("unroll") for (int _i = 0; _i < 2; ++_i) \
;         __builtin_amdgcn_global_load_lds((const unsigned*)((const char*)(gbase) + (voff)[_i]), (LAS unsigned*)(lds + (bufoff) + ldsw + _i * 8192), 16, 0, 0); } while (0)
; #define PG8_LDA(dst, b, h) do { _Pragma("unroll") for (int m = 0; m < 4; ++m) _Pragma("unroll") for (int k = 0; k < 2; ++k) dst[m][k] = *(const LAS bf16x8*)(lds + PG8_SA(b, h) + aoff + m * 2048 + k * 1024); } while (0)
; #define PG8_LDB(dst, b, h) do { _Pragma("unroll") for (int n = 0; n < 2; ++n) _Pragma("unroll") for (int k = 0; k < 2; ++k) dst[n][k] = *(const LAS bf16x8*)(lds + PG8_SB(b, h) + boff + n * 2048 + k * 1024); } while (0)
; #define PG8_MMA(ai, bj, At, Bt) do { __builtin_amdgcn_s_setprio(1); _Pragma("unroll") for (int m = 0; m < 4; ++m) _Pragma("unroll") for (int n = 0; n < 2; ++n) _Pragma("unroll") for (int k = 0; k < 2; ++k) \
;         acc[ai][bj][m][n] = __builtin_amdgcn_mfma_f32_16x16x32_bf16(Bt[n][k], At[m][k], acc[ai][bj][m][n], 0, 0, 0); __builtin_amdgcn_s_setprio(0); } while (0)
; #define PG8_WAIT_V(n) asm volatile("s_waitcnt vmcnt(" #n ")" ::: "memory")
; #define PG8_WAIT_L(n) asm volatile("s_waitcnt lgkmcnt(" #n ")" ::: "memory")
; #define PG8_BAR __builtin_amdgcn_s_barrier()
; #define PG8_SCHED __builtin_amdgcn_sched_barrier(0)
; template <int GI>
; __device__ __forceinline__ void gemm_phase(LAS unsigned char* lds, unsigned char* ws, int G, int cblk) {
;     ...
;             PG8_LDB(B0, 1, 0); PG8_LDB(B1, 1, 1); PG8_SCHED; PG8_LDA(At, 1, 0); PG8_STAGE(PG8_SA(0, 1), a2 + hstepA, voffA);
;             PG8_WAIT_V(8); PG8_WAIT_L(0); PG8_BAR; PG8_MMA(0, 0, At, B0); PG8_MMA(0, 1, At, B1); PG8_BAR; PG8_SCHED;
;             PG8_LDA(At, 1, 1); PG8_STAGE(PG8_SB(1, 0), b3, voffB); PG8_STAGE(PG8_SB(1, 1), b3 + hstepB, voffB); PG8_STAGE(PG8_SA(1, 0), a3, voffA);
;             PG8_WAIT_V(8); PG8_WAIT_L(0); PG8_BAR; PG8_MMA(1, 0, At, B0); PG8_MMA(1, 1, At, B1); PG8_BAR; PG8_SCHED;
;         }
	s_add_i32 s34, 0, 0x18000
	v_add_u32_e32 v161, s34, v150
	s_add_i32 s53, 0, 0x1c000
	ds_read_b128 v[154:157], v161
	ds_read_b128 v[164:167], v161 offset:1024
	ds_read_b128 v[168:171], v161 offset:2048
	ds_read_b128 v[172:175], v161 offset:3072
	v_add_u32_e32 v161, s53, v150
	ds_read_b128 v[176:179], v161
	ds_read_b128 v[180:183], v161 offset:1024
	ds_read_b128 v[184:187], v161 offset:2048
	ds_read_b128 v[192:195], v161 offset:3072
	s_add_u32 s50, s50, 0x80000
	s_addc_u32 s51, s51, 0
	s_mov_b32 m0, s22
	v_lshl_add_u64 v[232:233], s[50:51], 0, v[128:129]
	ds_read_b128 v[196:199], v153 offset:32768
	ds_read_b128 v[200:203], v153 offset:33792
	ds_read_b128 v[204:207], v153 offset:34816
	ds_read_b128 v[208:211], v153 offset:35840
	ds_read_b128 v[212:215], v153 offset:36864
	ds_read_b128 v[216:219], v153 offset:37888
	ds_read_b128 v[220:223], v153 offset:38912
	ds_read_b128 v[224:227], v153 offset:39936
	global_load_lds_dwordx4 v[232:233], off
	v_lshl_add_u64 v[232:233], s[50:51], 0, v[132:133]
	s_mov_b32 m0, s23
	s_nop 0
	global_load_lds_dwordx4 v[232:233], off
	s_waitcnt vmcnt(8)
	s_waitcnt lgkmcnt(0)
	s_barrier
	s_waitcnt lgkmcnt(0)
	v_mfma_f32_16x16x32_bf16 v[124:127], v[154:157], v[196:199], v[124:127]
	v_mfma_f32_16x16x32_bf16 v[120:123], v[168:171], v[196:199], v[120:123]
	v_mfma_f32_16x16x32_bf16 v[116:119], v[154:157], v[204:207], v[116:119]
	v_mfma_f32_16x16x32_bf16 v[112:115], v[168:171], v[204:207], v[112:115]
	v_mfma_f32_16x16x32_bf16 v[100:103], v[154:157], v[212:215], v[100:103]
	v_mfma_f32_16x16x32_bf16 v[96:99], v[168:171], v[212:215], v[96:99]
	v_mfma_f32_16x16x32_bf16 v[84:87], v[154:157], v[220:223], v[84:87]
	v_mfma_f32_16x16x32_bf16 v[80:83], v[168:171], v[220:223], v[80:83]
	v_mfma_f32_16x16x32_bf16 v[124:127], v[164:167], v[200:203], v[124:127]
	v_mfma_f32_16x16x32_bf16 v[120:123], v[172:175], v[200:203], v[120:123]
	v_mfma_f32_16x16x32_bf16 v[116:119], v[164:167], v[208:211], v[116:119]
	v_mfma_f32_16x16x32_bf16 v[112:115], v[172:175], v[208:211], v[112:115]
	v_mfma_f32_16x16x32_bf16 v[100:103], v[164:167], v[216:219], v[100:103]
	v_mfma_f32_16x16x32_bf16 v[96:99], v[172:175], v[216:219], v[96:99]
	v_mfma_f32_16x16x32_bf16 v[84:87], v[164:167], v[224:227], v[84:87]
	v_mfma_f32_16x16x32_bf16 v[80:83], v[172:175], v[224:227], v[80:83]
	v_mfma_f32_16x16x32_bf16 v[108:111], v[176:179], v[196:199], v[108:111]
	v_mfma_f32_16x16x32_bf16 v[104:107], v[184:187], v[196:199], v[104:107]
	v_mfma_f32_16x16x32_bf16 v[92:95], v[176:179], v[204:207], v[92:95]
	v_mfma_f32_16x16x32_bf16 v[88:91], v[184:187], v[204:207], v[88:91]
	v_mfma_f32_16x16x32_bf16 v[76:79], v[176:179], v[212:215], v[76:79]
	v_mfma_f32_16x16x32_bf16 v[72:75], v[184:187], v[212:215], v[72:75]
	v_mfma_f32_16x16x32_bf16 v[68:71], v[176:179], v[220:223], v[68:71]
	v_mfma_f32_16x16x32_bf16 v[64:67], v[184:187], v[220:223], v[64:67]
	v_mfma_f32_16x16x32_bf16 v[108:111], v[180:183], v[200:203], v[108:111]
	v_mfma_f32_16x16x32_bf16 v[104:107], v[192:195], v[200:203], v[104:107]
	v_mfma_f32_16x16x32_bf16 v[92:95], v[180:183], v[208:211], v[92:95]
	v_mfma_f32_16x16x32_bf16 v[88:91], v[192:195], v[208:211], v[88:91]
	v_mfma_f32_16x16x32_bf16 v[76:79], v[180:183], v[216:219], v[76:79]
	v_mfma_f32_16x16x32_bf16 v[72:75], v[192:195], v[216:219], v[72:75]
	v_mfma_f32_16x16x32_bf16 v[68:71], v[180:183], v[224:227], v[68:71]
	v_mfma_f32_16x16x32_bf16 v[64:67], v[192:195], v[224:227], v[64:67]
	s_barrier
	s_add_i32 s34, s34, s0
	v_lshl_add_u64 v[158:159], v[158:159], 0, s[8:9]
	s_mov_b32 m0, s34
	ds_read_b128 v[196:199], v153 offset:49152
	ds_read_b128 v[200:203], v153 offset:50176
	ds_read_b128 v[204:207], v153 offset:51200
	ds_read_b128 v[208:211], v153 offset:52224
	ds_read_b128 v[212:215], v153 offset:53248
	ds_read_b128 v[216:219], v153 offset:54272
	ds_read_b128 v[220:223], v153 offset:55296
	ds_read_b128 v[224:227], v153 offset:56320
	global_load_lds_dwordx4 v[158:159], off
	s_add_i32 m0, s34, 0x2000
	s_add_u32 s48, s48, 0x80080
	v_lshl_add_u64 v[158:159], v[188:189], 0, s[8:9]
	s_addc_u32 s49, s49, 0
	s_add_i32 s34, s53, s0
	global_load_lds_dwordx4 v[158:159], off
	v_lshl_add_u64 v[158:159], s[48:49], 0, v[130:131]
	s_mov_b32 m0, s34
	s_nop 0
	global_load_lds_dwordx4 v[158:159], off
	v_lshl_add_u64 v[158:159], s[48:49], 0, v[134:135]
	s_add_i32 m0, s34, 0x2000
	s_nop 0
	global_load_lds_dwordx4 v[158:159], off
	v_lshl_add_u64 v[158:159], v[228:229], 0, s[8:9]
	s_mov_b32 m0, s26
	s_nop 0
	global_load_lds_dwordx4 v[158:159], off
	v_lshl_add_u64 v[158:159], v[230:231], 0, s[8:9]
	s_mov_b32 m0, s27
	s_nop 0
	global_load_lds_dwordx4 v[158:159], off
	s_waitcnt vmcnt(8)
	s_waitcnt lgkmcnt(0)
	s_barrier
	s_waitcnt lgkmcnt(0)
	v_mfma_f32_16x16x32_bf16 v[60:63], v[154:157], v[196:199], v[60:63]
	v_mfma_f32_16x16x32_bf16 v[56:59], v[168:171], v[196:199], v[56:59]
	v_mfma_f32_16x16x32_bf16 v[52:55], v[154:157], v[204:207], v[52:55]
	v_mfma_f32_16x16x32_bf16 v[48:51], v[168:171], v[204:207], v[48:51]
	v_mfma_f32_16x16x32_bf16 v[36:39], v[154:157], v[212:215], v[36:39]
	v_mfma_f32_16x16x32_bf16 v[32:35], v[168:171], v[212:215], v[32:35]
	v_mfma_f32_16x16x32_bf16 v[20:23], v[154:157], v[220:223], v[20:23]
	v_mfma_f32_16x16x32_bf16 v[16:19], v[168:171], v[220:223], v[16:19]
	v_mfma_f32_16x16x32_bf16 v[60:63], v[164:167], v[200:203], v[60:63]
	v_mfma_f32_16x16x32_bf16 v[56:59], v[172:175], v[200:203], v[56:59]
	v_mfma_f32_16x16x32_bf16 v[52:55], v[164:167], v[208:211], v[52:55]
	v_mfma_f32_16x16x32_bf16 v[48:51], v[172:175], v[208:211], v[48:51]
	v_mfma_f32_16x16x32_bf16 v[36:39], v[164:167], v[216:219], v[36:39]
	v_mfma_f32_16x16x32_bf16 v[32:35], v[172:175], v[216:219], v[32:35]
	v_mfma_f32_16x16x32_bf16 v[20:23], v[164:167], v[224:227], v[20:23]
	v_mfma_f32_16x16x32_bf16 v[16:19], v[172:175], v[224:227], v[16:19]
	v_mfma_f32_16x16x32_bf16 v[44:47], v[176:179], v[196:199], v[44:47]
	v_mfma_f32_16x16x32_bf16 v[40:43], v[184:187], v[196:199], v[40:43]
	v_mfma_f32_16x16x32_bf16 v[28:31], v[176:179], v[204:207], v[28:31]
	v_mfma_f32_16x16x32_bf16 v[24:27], v[184:187], v[204:207], v[24:27]
	v_mfma_f32_16x16x32_bf16 v[12:15], v[176:179], v[212:215], v[12:15]
	v_mfma_f32_16x16x32_bf16 v[8:11], v[184:187], v[212:215], v[8:11]
	v_mfma_f32_16x16x32_bf16 v[4:7], v[176:179], v[220:223], v[4:7]
	v_mfma_f32_16x16x32_bf16 v[0:3], v[184:187], v[220:223], v[0:3]
	v_mfma_f32_16x16x32_bf16 v[44:47], v[180:183], v[200:203], v[44:47]
	v_mfma_f32_16x16x32_bf16 v[40:43], v[192:195], v[200:203], v[40:43]
	v_mfma_f32_16x16x32_bf16 v[28:31], v[180:183], v[208:211], v[28:31]
	v_mfma_f32_16x16x32_bf16 v[24:27], v[192:195], v[208:211], v[24:27]
	v_mfma_f32_16x16x32_bf16 v[12:15], v[180:183], v[216:219], v[12:15]
	v_mfma_f32_16x16x32_bf16 v[8:11], v[192:195], v[216:219], v[8:11]
	v_mfma_f32_16x16x32_bf16 v[4:7], v[180:183], v[224:227], v[4:7]
	v_mfma_f32_16x16x32_bf16 v[0:3], v[192:195], v[224:227], v[0:3]
	s_barrier
	s_add_i32 s19, s19, 2
	s_add_u32 s46, s46, 0x100
	s_addc_u32 s47, s47, 0
	s_add_u32 s14, s14, 0x100
	s_addc_u32 s15, s15, 0
	s_cmp_gt_u32 s19, 29
	s_cbranch_scc0 .LBB0_400

; #define PG8_STAGE(bufoff, gbase, voff) do { _Pragma("unroll") for (int _i = 0; _i < 2; ++_i) \
;         __builtin_amdgcn_global_load_lds((const unsigned*)((const char*)(gbase) + (voff)[_i]), (LAS unsigned*)(lds + (bufoff) + ldsw + _i * 8192), 16, 0, 0); } while (0)
; #define PG8_LDA(dst, b, h) do { _Pragma("unroll") for (int m = 0; m < 4; ++m) _Pragma("unroll") for (int k = 0; k < 2; ++k) dst[m][k] = *(const LAS bf16x8*)(lds + PG8_SA(b, h) + aoff + m * 2048 + k * 1024); } while (0)
; #define PG8_LDB(dst, b, h) do { _Pragma("unroll") for (int n = 0; n < 2; ++n) _Pragma("unroll") for (int k = 0; k < 2; ++k) dst[n][k] = *(const LAS bf16x8*)(lds + PG8_SB(b, h) + boff + n * 2048 + k * 1024); } while (0)
; #define PG8_MMA(ai, bj, At, Bt) do { __builtin_amdgcn_s_setprio(1); _Pragma("unroll") for (int m = 0; m < 4; ++m) _Pragma("unroll") for (int n = 0; n < 2; ++n) _Pragma("unroll") for (int k = 0; k < 2; ++k) \
;         acc[ai][bj][m][n] = __builtin_amdgcn_mfma_f32_16x16x32_bf16(Bt[n][k], At[m][k], acc[ai][bj][m][n], 0, 0, 0); __builtin_amdgcn_s_setprio(0); } while (0)
; #define PG8_WAIT_V(n) asm volatile("s_waitcnt vmcnt(" #n ")" ::: "memory")
; #define PG8_WAIT_L(n) asm volatile("s_waitcnt lgkmcnt(" #n ")" ::: "memory")
; #define PG8_BAR __builtin_amdgcn_s_barrier()
; #define PG8_SCHED __builtin_amdgcn_sched_barrier(0)
; template <int GI>
; __device__ __forceinline__ void gemm_phase(LAS unsigned char* lds, unsigned char* ws, int G, int cblk) {
;     ...
;         for (int t = 0; t < nt; t += 2) {
;             const bool last = (t == nt - 2);
;             const char* a1 = cA + (size_t)(t + 1) * kstep;
;             const char* a2 = last ? nA : cA + (size_t)(t + 2) * kstep; const char* b2 = last ? nB : cB + (size_t)(t + 2) * kstep;
;             const char* a3 = a2 + kstep; const char* b3 = b2 + kstep;
;             PG8_LDB(B0, 0, 0); PG8_LDB(B1, 0, 1); PG8_SCHED; PG8_LDA(At, 0, 0); PG8_STAGE(PG8_SA(1, 1), a1 + hstepA, voffA);
;             PG8_WAIT_V(8); PG8_WAIT_L(0); PG8_BAR; PG8_MMA(0, 0, At, B0); PG8_MMA(0, 1, At, B1); PG8_BAR; PG8_SCHED;
;             PG8_LDA(At, 0, 1); PG8_STAGE(PG8_SB(0, 0), b2, voffB); PG8_STAGE(PG8_SB(0, 1), b2 + hstepB, voffB); PG8_STAGE(PG8_SA(0, 0), a2, voffA);
.LBB0_415:
	s_add_u32 s50, s50, 0x100080
	s_addc_u32 s51, s51, 0
	s_add_u32 s14, s52, 0x100
	s_addc_u32 s15, s53, 0
	s_mov_b32 s21, -2
	ds_read_b128 v[154:157], v151
	ds_read_b128 v[164:167], v151 offset:1024
	ds_read_b128 v[168:171], v151 offset:2048
	ds_read_b128 v[172:175], v151 offset:3072
	ds_read_b128 v[176:179], v152
	ds_read_b128 v[180:183], v152 offset:1024
	ds_read_b128 v[184:187], v152 offset:2048
	ds_read_b128 v[192:195], v152 offset:3072
	s_add_u32 s34, s50, 0xfff00080
	s_addc_u32 s52, s51, -1
	s_cmp_eq_u32 s21, 4
	s_cselect_b32 s55, s41, s52
	s_cselect_b32 s54, s40, s34
	s_cselect_b32 s53, s43, s15
	s_cselect_b32 s52, s42, s14
	v_lshl_add_u64 v[158:159], s[50:51], 0, v[138:139]
	s_add_i32 m0, s22, 0xc000
	ds_read_b128 v[196:199], v153
	ds_read_b128 v[200:203], v153 offset:1024
	ds_read_b128 v[204:207], v153 offset:2048
	ds_read_b128 v[208:211], v153 offset:3072
	ds_read_b128 v[212:215], v153 offset:4096
	ds_read_b128 v[216:219], v153 offset:5120
	ds_read_b128 v[220:223], v153 offset:6144
	ds_read_b128 v[224:227], v153 offset:7168
	global_load_lds_dwordx4 v[158:159], off
	v_lshl_add_u64 v[158:159], s[50:51], 0, v[140:141]
	s_add_i32 m0, s22, 0xe000
	s_nop 0
	global_load_lds_dwordx4 v[158:159], off
	s_waitcnt vmcnt(8)
	s_waitcnt lgkmcnt(0)
	s_barrier
	s_waitcnt lgkmcnt(0)
	v_mfma_f32_16x16x32_bf16 v[124:127], v[154:157], v[196:199], 0
	v_mfma_f32_16x16x32_bf16 v[120:123], v[168:171], v[196:199], 0
	v_mfma_f32_16x16x32_bf16 v[116:119], v[154:157], v[204:207], 0
	v_mfma_f32_16x16x32_bf16 v[108:111], v[168:171], v[204:207], 0
	v_mfma_f32_16x16x32_bf16 v[100:103], v[154:157], v[212:215], 0
	v_mfma_f32_16x16x32_bf16 v[92:95], v[168:171], v[212:215], 0
	v_mfma_f32_16x16x32_bf16 v[84:87], v[154:157], v[220:223], 0
	v_mfma_f32_16x16x32_bf16 v[76:79], v[168:171], v[220:223], 0
	v_mfma_f32_16x16x32_bf16 v[124:127], v[164:167], v[200:203], v[124:127]
	v_mfma_f32_16x16x32_bf16 v[120:123], v[172:175], v[200:203], v[120:123]
	v_mfma_f32_16x16x32_bf16 v[116:119], v[164:167], v[208:211], v[116:119]
	v_mfma_f32_16x16x32_bf16 v[108:111], v[172:175], v[208:211], v[108:111]
	v_mfma_f32_16x16x32_bf16 v[100:103], v[164:167], v[216:219], v[100:103]
	v_mfma_f32_16x16x32_bf16 v[92:95], v[172:175], v[216:219], v[92:95]
	v_mfma_f32_16x16x32_bf16 v[84:87], v[164:167], v[224:227], v[84:87]
	v_mfma_f32_16x16x32_bf16 v[76:79], v[172:175], v[224:227], v[76:79]
	v_mfma_f32_16x16x32_bf16 v[112:115], v[176:179], v[196:199], 0
	v_mfma_f32_16x16x32_bf16 v[104:107], v[184:187], v[196:199], 0
	v_mfma_f32_16x16x32_bf16 v[96:99], v[176:179], v[204:207], 0
	v_mfma_f32_16x16x32_bf16 v[88:91], v[184:187], v[204:207], 0
	v_mfma_f32_16x16x32_bf16 v[80:83], v[176:179], v[212:215], 0
	v_mfma_f32_16x16x32_bf16 v[72:75], v[184:187], v[212:215], 0
	v_mfma_f32_16x16x32_bf16 v[68:71], v[176:179], v[220:223], 0
	v_mfma_f32_16x16x32_bf16 v[64:67], v[184:187], v[220:223], 0
	v_mfma_f32_16x16x32_bf16 v[112:115], v[180:183], v[200:203], v[112:115]
	v_mfma_f32_16x16x32_bf16 v[104:107], v[192:195], v[200:203], v[104:107]
	v_mfma_f32_16x16x32_bf16 v[96:99], v[180:183], v[208:211], v[96:99]
	v_mfma_f32_16x16x32_bf16 v[88:91], v[192:195], v[208:211], v[88:91]
	v_mfma_f32_16x16x32_bf16 v[80:83], v[180:183], v[216:219], v[80:83]
	v_mfma_f32_16x16x32_bf16 v[72:75], v[192:195], v[216:219], v[72:75]
	v_mfma_f32_16x16x32_bf16 v[68:71], v[180:183], v[224:227], v[68:71]
	v_mfma_f32_16x16x32_bf16 v[64:67], v[192:195], v[224:227], v[64:67]
	s_barrier
	s_add_i32 s34, s39, s0
	v_lshl_add_u64 v[158:159], s[52:53], 0, v[132:133]
	s_mov_b32 m0, s34
	ds_read_b128 v[196:199], v153 offset:16384
	ds_read_b128 v[200:203], v153 offset:17408
	ds_read_b128 v[204:207], v153 offset:18432
	ds_read_b128 v[208:211], v153 offset:19456
	ds_read_b128 v[212:215], v153 offset:20480
	ds_read_b128 v[216:219], v153 offset:21504
	ds_read_b128 v[220:223], v153 offset:22528
	ds_read_b128 v[224:227], v153 offset:23552
	global_load_lds_dwordx4 v[158:159], off
	s_add_i32 m0, s34, 0x2000
	s_add_u32 s58, s52, 0x80000
	v_lshl_add_u64 v[188:189], s[52:53], 0, v[128:129]
	s_addc_u32 s59, s53, 0
	s_add_i32 s34, s56, s0
	global_load_lds_dwordx4 v[188:189], off
	v_lshl_add_u64 v[228:229], s[58:59], 0, v[132:133]
	s_mov_b32 m0, s34
	v_lshl_add_u64 v[230:231], s[54:55], 0, v[130:131]
	global_load_lds_dwordx4 v[228:229], off
	v_lshl_add_u64 v[228:229], s[58:59], 0, v[128:129]
	s_add_i32 m0, s34, 0x2000
	s_nop 0
	global_load_lds_dwordx4 v[228:229], off
	v_lshl_add_u64 v[228:229], s[54:55], 0, v[134:135]
	s_mov_b32 m0, s22
	s_nop 0
	global_load_lds_dwordx4 v[228:229], off
	s_mov_b32 m0, s23
	s_nop 0
	global_load_lds_dwordx4 v[230:231], off
	s_waitcnt vmcnt(8)
	s_waitcnt lgkmcnt(0)
	s_barrier
; #define PG8_STAGE(bufoff, gbase, voff) do { _Pragma("unroll") for (int _i = 0; _i < 2; ++_i) \
;         __builtin_amdgcn_global_load_lds((const unsigned*)((const char*)(gbase) + (voff)[_i]), (LAS unsigned*)(lds + (bufoff) + ldsw + _i * 8192), 16, 0, 0); } while (0)
; #define PG8_LDA(dst, b, h) do { _Pragma("unroll") for (int m = 0; m < 4; ++m) _Pragma("unroll") for (int k = 0; k < 2; ++k) dst[m][k] = *(const LAS bf16x8*)(lds + PG8_SA(b, h) + aoff + m * 2048 + k * 1024); } while (0)
; #define PG8_LDB(dst, b, h) do { _Pragma("unroll") for (int n = 0; n < 2; ++n) _Pragma("unroll") for (int k = 0; k < 2; ++k) dst[n][k] = *(const LAS bf16x8*)(lds + PG8_SB(b, h) + boff + n * 2048 + k * 1024); } while (0)
; #define PG8_MMA(ai, bj, At, Bt) do { __builtin_amdgcn_s_setprio(1); _Pragma("unroll") for (int m = 0; m < 4; ++m) _Pragma("unroll") for (int n = 0; n < 2; ++n) _Pragma("unroll") for (int k = 0; k < 2; ++k) \
;         acc[ai][bj][m][n] = __builtin_amdgcn_mfma_f32_16x16x32_bf16(Bt[n][k], At[m][k], acc[ai][bj][m][n], 0, 0, 0); __builtin_amdgcn_s_setprio(0); } while (0)
; #define PG8_WAIT_V(n) asm volatile("s_waitcnt vmcnt(" #n ")" ::: "memory")
; #define PG8_WAIT_L(n) asm volatile("s_waitcnt lgkmcnt(" #n ")" ::: "memory")
; #define PG8_BAR __builtin_amdgcn_s_barrier()
; #define PG8_SCHED __builtin_amdgcn_sched_barrier(0)
; template <int GI>
; __device__ __forceinline__ void gemm_phase(LAS unsigned char* lds, unsigned char* ws, int G, int cblk) {
;     ...
;             PG8_WAIT_V(8); PG8_WAIT_L(0); PG8_BAR; PG8_MMA(0, 0, At, B0); PG8_MMA(0, 1, At, B1); PG8_BAR; PG8_SCHED;
;             PG8_LDA(At, 0, 1); PG8_STAGE(PG8_SB(0, 0), b2, voffB); PG8_STAGE(PG8_SB(0, 1), b2 + hstepB, voffB); PG8_STAGE(PG8_SA(0, 0), a2, voffA);
;             PG8_WAIT_V(8); PG8_WAIT_L(0); PG8_BAR; PG8_MMA(1, 0, At, B0); PG8_MMA(1, 1, At, B1); PG8_BAR; PG8_SCHED;
;             PG8_LDB(B0, 1, 0); PG8_LDB(B1, 1, 1); PG8_SCHED; PG8_LDA(At, 1, 0); PG8_STAGE(PG8_SA(0, 1), a2 + hstepA, voffA);
;             PG8_WAIT_V(8); PG8_WAIT_L(0); PG8_BAR; PG8_MMA(0, 0, At, B0); PG8_MMA(0, 1, At, B1); PG8_BAR; PG8_SCHED;
	s_waitcnt lgkmcnt(0)
	v_mfma_f32_16x16x32_bf16 v[60:63], v[154:157], v[196:199], 0
	v_mfma_f32_16x16x32_bf16 v[56:59], v[168:171], v[196:199], 0
	v_mfma_f32_16x16x32_bf16 v[52:55], v[154:157], v[204:207], 0
	v_mfma_f32_16x16x32_bf16 v[44:47], v[168:171], v[204:207], 0
	v_mfma_f32_16x16x32_bf16 v[36:39], v[154:157], v[212:215], 0
	v_mfma_f32_16x16x32_bf16 v[28:31], v[168:171], v[212:215], 0
	v_mfma_f32_16x16x32_bf16 v[20:23], v[154:157], v[220:223], 0
	v_mfma_f32_16x16x32_bf16 v[12:15], v[168:171], v[220:223], 0
	v_mfma_f32_16x16x32_bf16 v[60:63], v[164:167], v[200:203], v[60:63]
	v_mfma_f32_16x16x32_bf16 v[56:59], v[172:175], v[200:203], v[56:59]
	v_mfma_f32_16x16x32_bf16 v[52:55], v[164:167], v[208:211], v[52:55]
	v_mfma_f32_16x16x32_bf16 v[44:47], v[172:175], v[208:211], v[44:47]
	v_mfma_f32_16x16x32_bf16 v[36:39], v[164:167], v[216:219], v[36:39]
	v_mfma_f32_16x16x32_bf16 v[28:31], v[172:175], v[216:219], v[28:31]
	v_mfma_f32_16x16x32_bf16 v[20:23], v[164:167], v[224:227], v[20:23]
	v_mfma_f32_16x16x32_bf16 v[12:15], v[172:175], v[224:227], v[12:15]
	v_mfma_f32_16x16x32_bf16 v[48:51], v[176:179], v[196:199], 0
	v_mfma_f32_16x16x32_bf16 v[40:43], v[184:187], v[196:199], 0
	v_mfma_f32_16x16x32_bf16 v[32:35], v[176:179], v[204:207], 0
	v_mfma_f32_16x16x32_bf16 v[24:27], v[184:187], v[204:207], 0
	v_mfma_f32_16x16x32_bf16 v[16:19], v[176:179], v[212:215], 0
	v_mfma_f32_16x16x32_bf16 v[8:11], v[184:187], v[212:215], 0
	v_mfma_f32_16x16x32_bf16 v[4:7], v[176:179], v[220:223], 0
	v_mfma_f32_16x16x32_bf16 v[0:3], v[184:187], v[220:223], 0
	v_mfma_f32_16x16x32_bf16 v[48:51], v[180:183], v[200:203], v[48:51]
	v_mfma_f32_16x16x32_bf16 v[40:43], v[192:195], v[200:203], v[40:43]
	v_mfma_f32_16x16x32_bf16 v[32:35], v[180:183], v[208:211], v[32:35]
	v_mfma_f32_16x16x32_bf16 v[24:27], v[192:195], v[208:211], v[24:27]
	v_mfma_f32_16x16x32_bf16 v[16:19], v[180:183], v[216:219], v[16:19]
	v_mfma_f32_16x16x32_bf16 v[8:11], v[192:195], v[216:219], v[8:11]
	v_mfma_f32_16x16x32_bf16 v[4:7], v[180:183], v[224:227], v[4:7]
	v_mfma_f32_16x16x32_bf16 v[0:3], v[192:195], v[224:227], v[0:3]
	s_barrier
	s_add_i32 s34, 0, 0x18000
	v_add_u32_e32 v161, s34, v150
	s_add_i32 s58, 0, 0x1c000
	ds_read_b128 v[154:157], v161
	ds_read_b128 v[164:167], v161 offset:1024
	ds_read_b128 v[168:171], v161 offset:2048
	ds_read_b128 v[172:175], v161 offset:3072
	v_add_u32_e32 v161, s58, v150
	ds_read_b128 v[176:179], v161
	ds_read_b128 v[180:183], v161 offset:1024
	ds_read_b128 v[184:187], v161 offset:2048
	ds_read_b128 v[192:195], v161 offset:3072
	s_add_u32 s54, s54, 0x100000
	s_addc_u32 s55, s55, 0
	s_mov_b32 m0, s24
	v_lshl_add_u64 v[232:233], s[54:55], 0, v[134:135]
	ds_read_b128 v[196:199], v153 offset:32768
	ds_read_b128 v[200:203], v153 offset:33792
	ds_read_b128 v[204:207], v153 offset:34816
	ds_read_b128 v[208:211], v153 offset:35840
	ds_read_b128 v[212:215], v153 offset:36864
	ds_read_b128 v[216:219], v153 offset:37888
	ds_read_b128 v[220:223], v153 offset:38912
	ds_read_b128 v[224:227], v153 offset:39936
	global_load_lds_dwordx4 v[232:233], off
	v_lshl_add_u64 v[232:233], s[54:55], 0, v[130:131]
	s_mov_b32 m0, s25
	s_nop 0
	global_load_lds_dwordx4 v[232:233], off
	s_waitcnt vmcnt(8)
	s_waitcnt lgkmcnt(0)
	s_barrier
	s_waitcnt lgkmcnt(0)
	v_mfma_f32_16x16x32_bf16 v[124:127], v[154:157], v[196:199], v[124:127]
	v_mfma_f32_16x16x32_bf16 v[120:123], v[168:171], v[196:199], v[120:123]
	v_mfma_f32_16x16x32_bf16 v[116:119], v[154:157], v[204:207], v[116:119]
	v_mfma_f32_16x16x32_bf16 v[108:111], v[168:171], v[204:207], v[108:111]
	v_mfma_f32_16x16x32_bf16 v[100:103], v[154:157], v[212:215], v[100:103]
	v_mfma_f32_16x16x32_bf16 v[92:95], v[168:171], v[212:215], v[92:95]
	v_mfma_f32_16x16x32_bf16 v[84:87], v[154:157], v[220:223], v[84:87]
	v_mfma_f32_16x16x32_bf16 v[76:79], v[168:171], v[220:223], v[76:79]
	v_mfma_f32_16x16x32_bf16 v[124:127], v[164:167], v[200:203], v[124:127]
	v_mfma_f32_16x16x32_bf16 v[120:123], v[172:175], v[200:203], v[120:123]
	v_mfma_f32_16x16x32_bf16 v[116:119], v[164:167], v[208:211], v[116:119]
	v_mfma_f32_16x16x32_bf16 v[108:111], v[172:175], v[208:211], v[108:111]
	v_mfma_f32_16x16x32_bf16 v[100:103], v[164:167], v[216:219], v[100:103]
	v_mfma_f32_16x16x32_bf16 v[92:95], v[172:175], v[216:219], v[92:95]
	v_mfma_f32_16x16x32_bf16 v[84:87], v[164:167], v[224:227], v[84:87]
	v_mfma_f32_16x16x32_bf16 v[76:79], v[172:175], v[224:227], v[76:79]
	v_mfma_f32_16x16x32_bf16 v[112:115], v[176:179], v[196:199], v[112:115]
	v_mfma_f32_16x16x32_bf16 v[104:107], v[184:187], v[196:199], v[104:107]
	v_mfma_f32_16x16x32_bf16 v[96:99], v[176:179], v[204:207], v[96:99]
	v_mfma_f32_16x16x32_bf16 v[88:91], v[184:187], v[204:207], v[88:91]
	v_mfma_f32_16x16x32_bf16 v[80:83], v[176:179], v[212:215], v[80:83]
	v_mfma_f32_16x16x32_bf16 v[72:75], v[184:187], v[212:215], v[72:75]
	v_mfma_f32_16x16x32_bf16 v[68:71], v[176:179], v[220:223], v[68:71]
	v_mfma_f32_16x16x32_bf16 v[64:67], v[184:187], v[220:223], v[64:67]
	v_mfma_f32_16x16x32_bf16 v[112:115], v[180:183], v[200:203], v[112:115]
	v_mfma_f32_16x16x32_bf16 v[104:107], v[192:195], v[200:203], v[104:107]
	v_mfma_f32_16x16x32_bf16 v[96:99], v[180:183], v[208:211], v[96:99]
	v_mfma_f32_16x16x32_bf16 v[88:91], v[192:195], v[208:211], v[88:91]
	v_mfma_f32_16x16x32_bf16 v[80:83], v[180:183], v[216:219], v[80:83]
	v_mfma_f32_16x16x32_bf16 v[72:75], v[192:195], v[216:219], v[72:75]
	v_mfma_f32_16x16x32_bf16 v[68:71], v[180:183], v[224:227], v[68:71]
	v_mfma_f32_16x16x32_bf16 v[64:67], v[192:195], v[224:227], v[64:67]
	s_barrier
; #define PG8_STAGE(bufoff, gbase, voff) do { _Pragma("unroll") for (int _i = 0; _i < 2; ++_i) \
;         __builtin_amdgcn_global_load_lds((const unsigned*)((const char*)(gbase) + (voff)[_i]), (LAS unsigned*)(lds + (bufoff) + ldsw + _i * 8192), 16, 0, 0); } while (0)
; #define PG8_LDA(dst, b, h) do { _Pragma("unroll") for (int m = 0; m < 4; ++m) _Pragma("unroll") for (int k = 0; k < 2; ++k) dst[m][k] = *(const LAS bf16x8*)(lds + PG8_SA(b, h) + aoff + m * 2048 + k * 1024); } while (0)
; #define PG8_LDB(dst, b, h) do { _Pragma("unroll") for (int n = 0; n < 2; ++n) _Pragma("unroll") for (int k = 0; k < 2; ++k) dst[n][k] = *(const LAS bf16x8*)(lds + PG8_SB(b, h) + boff + n * 2048 + k * 1024); } while (0)
; #define PG8_WAIT_V(n) asm volatile("s_waitcnt vmcnt(" #n ")" ::: "memory")
; #define PG8_WAIT_L(n) asm volatile("s_waitcnt lgkmcnt(" #n ")" ::: "memory")
; template <int GI>
; __device__ __forceinline__ void gemm_phase(LAS unsigned char* lds, unsigned char* ws, int G, int cblk) {
;     ...
;         for (int t = 0; t < nt; t += 2) {
;             const bool last = (t == nt - 2);
;             const char* a1 = cA + (size_t)(t + 1) * kstep;
;             const char* a2 = last ? nA : cA + (size_t)(t + 2) * kstep; const char* b2 = last ? nB : cB + (size_t)(t + 2) * kstep;
;             const char* a3 = a2 + kstep; const char* b3 = b2 + kstep;
;             PG8_LDB(B0, 0, 0); PG8_LDB(B1, 0, 1); PG8_SCHED; PG8_LDA(At, 0, 0); PG8_STAGE(PG8_SA(1, 1), a1 + hstepA, voffA);
;             PG8_WAIT_V(8); PG8_WAIT_L(0); PG8_BAR; PG8_MMA(0, 0, At, B0); PG8_MMA(0, 1, At, B1); PG8_BAR; PG8_SCHED;
;             PG8_LDA(At, 0, 1); PG8_STAGE(PG8_SB(0, 0), b2, voffB); PG8_STAGE(PG8_SB(0, 1), b2 + hstepB, voffB); PG8_STAGE(PG8_SA(0, 0), a2, voffA);
;             PG8_WAIT_V(8); PG8_WAIT_L(0); PG8_BAR; PG8_MMA(1, 0, At, B0); PG8_MMA(1, 1, At, B1); PG8_BAR; PG8_SCHED;
;             PG8_LDB(B0, 1, 0); PG8_LDB(B1, 1, 1); PG8_SCHED; PG8_LDA(At, 1, 0); PG8_STAGE(PG8_SA(0, 1), a2 + hstepA, voffA);
;             PG8_WAIT_V(8); PG8_WAIT_L(0); PG8_BAR; PG8_MMA(0, 0, At, B0); PG8_MMA(0, 1, At, B1); PG8_BAR; PG8_SCHED;
;             PG8_LDA(At, 1, 1); PG8_STAGE(PG8_SB(1, 0), b3, voffB); PG8_STAGE(PG8_SB(1, 1), b3 + hstepB, voffB); PG8_STAGE(PG8_SA(1, 0), a3, voffA);
;             PG8_WAIT_V(8); PG8_WAIT_L(0); PG8_BAR; PG8_MMA(1, 0, At, B0); PG8_MMA(1, 1, At, B1); PG8_BAR; PG8_SCHED;
	s_add_i32 s34, s34, s0
	v_lshl_add_u64 v[158:159], v[158:159], 0, s[12:13]
	s_mov_b32 m0, s34
	ds_read_b128 v[196:199], v153 offset:49152
	ds_read_b128 v[200:203], v153 offset:50176
	ds_read_b128 v[204:207], v153 offset:51200
	ds_read_b128 v[208:211], v153 offset:52224
	ds_read_b128 v[212:215], v153 offset:53248
	ds_read_b128 v[216:219], v153 offset:54272
	ds_read_b128 v[220:223], v153 offset:55296
	ds_read_b128 v[224:227], v153 offset:56320
	global_load_lds_dwordx4 v[158:159], off
	s_add_i32 m0, s34, 0x2000
	s_add_u32 s52, s52, 0x80080
	v_lshl_add_u64 v[158:159], v[188:189], 0, s[12:13]
	s_addc_u32 s53, s53, 0
	s_add_i32 s34, s58, s0
	global_load_lds_dwordx4 v[158:159], off
	v_lshl_add_u64 v[158:159], s[52:53], 0, v[132:133]
	s_mov_b32 m0, s34
	s_nop 0
	global_load_lds_dwordx4 v[158:159], off
	v_lshl_add_u64 v[158:159], s[52:53], 0, v[128:129]
	s_add_i32 m0, s34, 0x2000
	s_nop 0
	global_load_lds_dwordx4 v[158:159], off
	v_lshl_add_u64 v[158:159], v[228:229], 0, s[12:13]
	s_mov_b32 m0, s33
	s_nop 0
	global_load_lds_dwordx4 v[158:159], off
	v_lshl_add_u64 v[158:159], v[230:231], 0, s[12:13]
	s_mov_b32 m0, s35
	s_nop 0
	global_load_lds_dwordx4 v[158:159], off
	s_waitcnt vmcnt(8)
	s_waitcnt lgkmcnt(0)
	s_barrier
	s_waitcnt lgkmcnt(0)
	v_mfma_f32_16x16x32_bf16 v[60:63], v[154:157], v[196:199], v[60:63]
	v_mfma_f32_16x16x32_bf16 v[56:59], v[168:171], v[196:199], v[56:59]
	v_mfma_f32_16x16x32_bf16 v[52:55], v[154:157], v[204:207], v[52:55]
	v_mfma_f32_16x16x32_bf16 v[44:47], v[168:171], v[204:207], v[44:47]
	v_mfma_f32_16x16x32_bf16 v[36:39], v[154:157], v[212:215], v[36:39]
	v_mfma_f32_16x16x32_bf16 v[28:31], v[168:171], v[212:215], v[28:31]
	v_mfma_f32_16x16x32_bf16 v[20:23], v[154:157], v[220:223], v[20:23]
	v_mfma_f32_16x16x32_bf16 v[12:15], v[168:171], v[220:223], v[12:15]
	v_mfma_f32_16x16x32_bf16 v[60:63], v[164:167], v[200:203], v[60:63]
	v_mfma_f32_16x16x32_bf16 v[56:59], v[172:175], v[200:203], v[56:59]
	v_mfma_f32_16x16x32_bf16 v[52:55], v[164:167], v[208:211], v[52:55]
	v_mfma_f32_16x16x32_bf16 v[44:47], v[172:175], v[208:211], v[44:47]
	v_mfma_f32_16x16x32_bf16 v[36:39], v[164:167], v[216:219], v[36:39]
	v_mfma_f32_16x16x32_bf16 v[28:31], v[172:175], v[216:219], v[28:31]
	v_mfma_f32_16x16x32_bf16 v[20:23], v[164:167], v[224:227], v[20:23]
	v_mfma_f32_16x16x32_bf16 v[12:15], v[172:175], v[224:227], v[12:15]
	v_mfma_f32_16x16x32_bf16 v[48:51], v[176:179], v[196:199], v[48:51]
	v_mfma_f32_16x16x32_bf16 v[40:43], v[184:187], v[196:199], v[40:43]
	v_mfma_f32_16x16x32_bf16 v[32:35], v[176:179], v[204:207], v[32:35]
	v_mfma_f32_16x16x32_bf16 v[24:27], v[184:187], v[204:207], v[24:27]
	v_mfma_f32_16x16x32_bf16 v[16:19], v[176:179], v[212:215], v[16:19]
	v_mfma_f32_16x16x32_bf16 v[8:11], v[184:187], v[212:215], v[8:11]
	v_mfma_f32_16x16x32_bf16 v[4:7], v[176:179], v[220:223], v[4:7]
	v_mfma_f32_16x16x32_bf16 v[0:3], v[184:187], v[220:223], v[0:3]
	v_mfma_f32_16x16x32_bf16 v[48:51], v[180:183], v[200:203], v[48:51]
	v_mfma_f32_16x16x32_bf16 v[40:43], v[192:195], v[200:203], v[40:43]
	v_mfma_f32_16x16x32_bf16 v[32:35], v[180:183], v[208:211], v[32:35]
	v_mfma_f32_16x16x32_bf16 v[24:27], v[192:195], v[208:211], v[24:27]
	v_mfma_f32_16x16x32_bf16 v[16:19], v[180:183], v[216:219], v[16:19]
	v_mfma_f32_16x16x32_bf16 v[8:11], v[192:195], v[216:219], v[8:11]
	v_mfma_f32_16x16x32_bf16 v[4:7], v[180:183], v[224:227], v[4:7]
	v_mfma_f32_16x16x32_bf16 v[0:3], v[192:195], v[224:227], v[0:3]
	s_barrier
	s_add_i32 s21, s21, 2
	s_add_u32 s50, s50, 0x100
	s_addc_u32 s51, s51, 0
	s_add_u32 s14, s14, 0x100
	s_addc_u32 s15, s15, 0
	s_cmp_gt_u32 s21, 5
	s_cbranch_scc0 .LBB0_416
	s_branch .Lpeel_exit_4
.LBB0_416:
	ds_read_b128 v[154:157], v151
	ds_read_b128 v[164:167], v151 offset:1024
	ds_read_b128 v[168:171], v151 offset:2048
	ds_read_b128 v[172:175], v151 offset:3072
	ds_read_b128 v[176:179], v152
	ds_read_b128 v[180:183], v152 offset:1024
	ds_read_b128 v[184:187], v152 offset:2048
	ds_read_b128 v[192:195], v152 offset:3072
	s_add_u32 s34, s50, 0xfff00080
	s_addc_u32 s52, s51, -1
	s_cmp_eq_u32 s21, 4
	s_cselect_b32 s55, s41, s52
	s_cselect_b32 s54, s40, s34
	s_cselect_b32 s53, s43, s15
	s_cselect_b32 s52, s42, s14
	v_lshl_add_u64 v[158:159], s[50:51], 0, v[138:139]
	s_add_i32 m0, s22, 0xc000
	ds_read_b128 v[196:199], v153
	ds_read_b128 v[200:203], v153 offset:1024
	ds_read_b128 v[204:207], v153 offset:2048
	ds_read_b128 v[208:211], v153 offset:3072
	ds_read_b128 v[212:215], v153 offset:4096
	ds_read_b128 v[216:219], v153 offset:5120
	ds_read_b128 v[220:223], v153 offset:6144
	ds_read_b128 v[224:227], v153 offset:7168
	global_load_lds_dwordx4 v[158:159], off
	v_lshl_add_u64 v[158:159], s[50:51], 0, v[140:141]
	s_add_i32 m0, s22, 0xe000
	s_nop 0
	global_load_lds_dwordx4 v[158:159], off
	s_waitcnt vmcnt(8)
	s_waitcnt lgkmcnt(0)
	s_barrier
; #define PG8_STAGE(bufoff, gbase, voff) do { _Pragma("unroll") for (int _i = 0; _i < 2; ++_i) \
;         __builtin_amdgcn_global_load_lds((const unsigned*)((const char*)(gbase) + (voff)[_i]), (LAS unsigned*)(lds + (bufoff) + ldsw + _i * 8192), 16, 0, 0); } while (0)
; #define PG8_LDA(dst, b, h) do { _Pragma("unroll") for (int m = 0; m < 4; ++m) _Pragma("unroll") for (int k = 0; k < 2; ++k) dst[m][k] = *(const LAS bf16x8*)(lds + PG8_SA(b, h) + aoff + m * 2048 + k * 1024); } while (0)
; #define PG8_MMA(ai, bj, At, Bt) do { __builtin_amdgcn_s_setprio(1); _Pragma("unroll") for (int m = 0; m < 4; ++m) _Pragma("unroll") for (int n = 0; n < 2; ++n) _Pragma("unroll") for (int k = 0; k < 2; ++k) \
;         acc[ai][bj][m][n] = __builtin_amdgcn_mfma_f32_16x16x32_bf16(Bt[n][k], At[m][k], acc[ai][bj][m][n], 0, 0, 0); __builtin_amdgcn_s_setprio(0); } while (0)
; #define PG8_WAIT_V(n) asm volatile("s_waitcnt vmcnt(" #n ")" ::: "memory")
; #define PG8_WAIT_L(n) asm volatile("s_waitcnt lgkmcnt(" #n ")" ::: "memory")
; #define PG8_BAR __builtin_amdgcn_s_barrier()
; #define PG8_SCHED __builtin_amdgcn_sched_barrier(0)
; template <int GI>
; __device__ __forceinline__ void gemm_phase(LAS unsigned char* lds, unsigned char* ws, int G, int cblk) {
;     ...
;             PG8_WAIT_V(8); PG8_WAIT_L(0); PG8_BAR; PG8_MMA(0, 0, At, B0); PG8_MMA(0, 1, At, B1); PG8_BAR; PG8_SCHED;
;             PG8_LDA(At, 0, 1); PG8_STAGE(PG8_SB(0, 0), b2, voffB); PG8_STAGE(PG8_SB(0, 1), b2 + hstepB, voffB); PG8_STAGE(PG8_SA(0, 0), a2, voffA);
;             PG8_WAIT_V(8); PG8_WAIT_L(0); PG8_BAR; PG8_MMA(1, 0, At, B0); PG8_MMA(1, 1, At, B1); PG8_BAR; PG8_SCHED;
	s_waitcnt lgkmcnt(0)
	v_mfma_f32_16x16x32_bf16 v[124:127], v[154:157], v[196:199], v[124:127]
	v_mfma_f32_16x16x32_bf16 v[120:123], v[168:171], v[196:199], v[120:123]
	v_mfma_f32_16x16x32_bf16 v[116:119], v[154:157], v[204:207], v[116:119]
	v_mfma_f32_16x16x32_bf16 v[108:111], v[168:171], v[204:207], v[108:111]
	v_mfma_f32_16x16x32_bf16 v[100:103], v[154:157], v[212:215], v[100:103]
	v_mfma_f32_16x16x32_bf16 v[92:95], v[168:171], v[212:215], v[92:95]
	v_mfma_f32_16x16x32_bf16 v[84:87], v[154:157], v[220:223], v[84:87]
	v_mfma_f32_16x16x32_bf16 v[76:79], v[168:171], v[220:223], v[76:79]
	v_mfma_f32_16x16x32_bf16 v[124:127], v[164:167], v[200:203], v[124:127]
	v_mfma_f32_16x16x32_bf16 v[120:123], v[172:175], v[200:203], v[120:123]
	v_mfma_f32_16x16x32_bf16 v[116:119], v[164:167], v[208:211], v[116:119]
	v_mfma_f32_16x16x32_bf16 v[108:111], v[172:175], v[208:211], v[108:111]
	v_mfma_f32_16x16x32_bf16 v[100:103], v[164:167], v[216:219], v[100:103]
	v_mfma_f32_16x16x32_bf16 v[92:95], v[172:175], v[216:219], v[92:95]
	v_mfma_f32_16x16x32_bf16 v[84:87], v[164:167], v[224:227], v[84:87]
	v_mfma_f32_16x16x32_bf16 v[76:79], v[172:175], v[224:227], v[76:79]
	v_mfma_f32_16x16x32_bf16 v[112:115], v[176:179], v[196:199], v[112:115]
	v_mfma_f32_16x16x32_bf16 v[104:107], v[184:187], v[196:199], v[104:107]
	v_mfma_f32_16x16x32_bf16 v[96:99], v[176:179], v[204:207], v[96:99]
	v_mfma_f32_16x16x32_bf16 v[88:91], v[184:187], v[204:207], v[88:91]
	v_mfma_f32_16x16x32_bf16 v[80:83], v[176:179], v[212:215], v[80:83]
	v_mfma_f32_16x16x32_bf16 v[72:75], v[184:187], v[212:215], v[72:75]
	v_mfma_f32_16x16x32_bf16 v[68:71], v[176:179], v[220:223], v[68:71]
	v_mfma_f32_16x16x32_bf16 v[64:67], v[184:187], v[220:223], v[64:67]
	v_mfma_f32_16x16x32_bf16 v[112:115], v[180:183], v[200:203], v[112:115]
	v_mfma_f32_16x16x32_bf16 v[104:107], v[192:195], v[200:203], v[104:107]
	v_mfma_f32_16x16x32_bf16 v[96:99], v[180:183], v[208:211], v[96:99]
	v_mfma_f32_16x16x32_bf16 v[88:91], v[192:195], v[208:211], v[88:91]
	v_mfma_f32_16x16x32_bf16 v[80:83], v[180:183], v[216:219], v[80:83]
	v_mfma_f32_16x16x32_bf16 v[72:75], v[192:195], v[216:219], v[72:75]
	v_mfma_f32_16x16x32_bf16 v[68:71], v[180:183], v[224:227], v[68:71]
	v_mfma_f32_16x16x32_bf16 v[64:67], v[192:195], v[224:227], v[64:67]
	s_barrier
	s_add_i32 s34, s39, s0
	v_lshl_add_u64 v[158:159], s[52:53], 0, v[132:133]
	s_mov_b32 m0, s34
	ds_read_b128 v[196:199], v153 offset:16384
	ds_read_b128 v[200:203], v153 offset:17408
	ds_read_b128 v[204:207], v153 offset:18432
	ds_read_b128 v[208:211], v153 offset:19456
	ds_read_b128 v[212:215], v153 offset:20480
	ds_read_b128 v[216:219], v153 offset:21504
	ds_read_b128 v[220:223], v153 offset:22528
	ds_read_b128 v[224:227], v153 offset:23552
	global_load_lds_dwordx4 v[158:159], off
	s_add_i32 m0, s34, 0x2000
	s_add_u32 s58, s52, 0x80000
	v_lshl_add_u64 v[188:189], s[52:53], 0, v[128:129]
	s_addc_u32 s59, s53, 0
	s_add_i32 s34, s56, s0
	global_load_lds_dwordx4 v[188:189], off
	v_lshl_add_u64 v[228:229], s[58:59], 0, v[132:133]
	s_mov_b32 m0, s34
	v_lshl_add_u64 v[230:231], s[54:55], 0, v[130:131]
	global_load_lds_dwordx4 v[228:229], off
	v_lshl_add_u64 v[228:229], s[58:59], 0, v[128:129]
	s_add_i32 m0, s34, 0x2000
	s_nop 0
	global_load_lds_dwordx4 v[228:229], off
	v_lshl_add_u64 v[228:229], s[54:55], 0, v[134:135]
	s_mov_b32 m0, s22
	s_nop 0
	global_load_lds_dwordx4 v[228:229], off
	s_mov_b32 m0, s23
	s_nop 0
	global_load_lds_dwordx4 v[230:231], off
	s_waitcnt vmcnt(8)
	s_waitcnt lgkmcnt(0)
	s_barrier
	s_waitcnt lgkmcnt(0)
	v_mfma_f32_16x16x32_bf16 v[60:63], v[154:157], v[196:199], v[60:63]
	v_mfma_f32_16x16x32_bf16 v[56:59], v[168:171], v[196:199], v[56:59]
	v_mfma_f32_16x16x32_bf16 v[52:55], v[154:157], v[204:207], v[52:55]
	v_mfma_f32_16x16x32_bf16 v[44:47], v[168:171], v[204:207], v[44:47]
	v_mfma_f32_16x16x32_bf16 v[36:39], v[154:157], v[212:215], v[36:39]
	v_mfma_f32_16x16x32_bf16 v[28:31], v[168:171], v[212:215], v[28:31]
	v_mfma_f32_16x16x32_bf16 v[20:23], v[154:157], v[220:223], v[20:23]
	v_mfma_f32_16x16x32_bf16 v[12:15], v[168:171], v[220:223], v[12:15]
	v_mfma_f32_16x16x32_bf16 v[60:63], v[164:167], v[200:203], v[60:63]
	v_mfma_f32_16x16x32_bf16 v[56:59], v[172:175], v[200:203], v[56:59]
	v_mfma_f32_16x16x32_bf16 v[52:55], v[164:167], v[208:211], v[52:55]
	v_mfma_f32_16x16x32_bf16 v[44:47], v[172:175], v[208:211], v[44:47]
	v_mfma_f32_16x16x32_bf16 v[36:39], v[164:167], v[216:219], v[36:39]
	v_mfma_f32_16x16x32_bf16 v[28:31], v[172:175], v[216:219], v[28:31]
	v_mfma_f32_16x16x32_bf16 v[20:23], v[164:167], v[224:227], v[20:23]
	v_mfma_f32_16x16x32_bf16 v[12:15], v[172:175], v[224:227], v[12:15]
	v_mfma_f32_16x16x32_bf16 v[48:51], v[176:179], v[196:199], v[48:51]
	v_mfma_f32_16x16x32_bf16 v[40:43], v[184:187], v[196:199], v[40:43]
	v_mfma_f32_16x16x32_bf16 v[32:35], v[176:179], v[204:207], v[32:35]
	v_mfma_f32_16x16x32_bf16 v[24:27], v[184:187], v[204:207], v[24:27]
	v_mfma_f32_16x16x32_bf16 v[16:19], v[176:179], v[212:215], v[16:19]
	v_mfma_f32_16x16x32_bf16 v[8:11], v[184:187], v[212:215], v[8:11]
	v_mfma_f32_16x16x32_bf16 v[4:7], v[176:179], v[220:223], v[4:7]
	v_mfma_f32_16x16x32_bf16 v[0:3], v[184:187], v[220:223], v[0:3]
	v_mfma_f32_16x16x32_bf16 v[48:51], v[180:183], v[200:203], v[48:51]
	v_mfma_f32_16x16x32_bf16 v[40:43], v[192:195], v[200:203], v[40:43]
	v_mfma_f32_16x16x32_bf16 v[32:35], v[180:183], v[208:211], v[32:35]
	v_mfma_f32_16x16x32_bf16 v[24:27], v[192:195], v[208:211], v[24:27]
	v_mfma_f32_16x16x32_bf16 v[16:19], v[180:183], v[216:219], v[16:19]
	v_mfma_f32_16x16x32_bf16 v[8:11], v[192:195], v[216:219], v[8:11]
	v_mfma_f32_16x16x32_bf16 v[4:7], v[180:183], v[224:227], v[4:7]
	v_mfma_f32_16x16x32_bf16 v[0:3], v[192:195], v[224:227], v[0:3]
	s_barrier
; #define PG8_STAGE(bufoff, gbase, voff) do { _Pragma("unroll") for (int _i = 0; _i < 2; ++_i) \
;         __builtin_amdgcn_global_load_lds((const unsigned*)((const char*)(gbase) + (voff)[_i]), (LAS unsigned*)(lds + (bufoff) + ldsw + _i * 8192), 16, 0, 0); } while (0)
; #define PG8_LDA(dst, b, h) do { _Pragma("unroll") for (int m = 0; m < 4; ++m) _Pragma("unroll") for (int k = 0; k < 2; ++k) dst[m][k] = *(const LAS bf16x8*)(lds + PG8_SA(b, h) + aoff + m * 2048 + k * 1024); } while (0)
; #define PG8_LDB(dst, b, h) do { _Pragma("unroll") for (int n = 0; n < 2; ++n) _Pragma("unroll") for (int k = 0; k < 2; ++k) dst[n][k] = *(const LAS bf16x8*)(lds + PG8_SB(b, h) + boff + n * 2048 + k * 1024); } while (0)
; #define PG8_MMA(ai, bj, At, Bt) do { __builtin_amdgcn_s_setprio(1); _Pragma("unroll") for (int m = 0; m < 4; ++m) _Pragma("unroll") for (int n = 0; n < 2; ++n) _Pragma("unroll") for (int k = 0; k < 2; ++k) \
;         acc[ai][bj][m][n] = __builtin_amdgcn_mfma_f32_16x16x32_bf16(Bt[n][k], At[m][k], acc[ai][bj][m][n], 0, 0, 0); __builtin_amdgcn_s_setprio(0); } while (0)
; #define PG8_WAIT_V(n) asm volatile("s_waitcnt vmcnt(" #n ")" ::: "memory")
; #define PG8_WAIT_L(n) asm volatile("s_waitcnt lgkmcnt(" #n ")" ::: "memory")
; #define PG8_BAR __builtin_amdgcn_s_barrier()
; #define PG8_SCHED __builtin_amdgcn_sched_barrier(0)
; template <int GI>
; __device__ __forceinline__ void gemm_phase(LAS unsigned char* lds, unsigned char* ws, int G, int cblk) {
;     ...
;             PG8_LDB(B0, 1, 0); PG8_LDB(B1, 1, 1); PG8_SCHED; PG8_LDA(At, 1, 0); PG8_STAGE(PG8_SA(0, 1), a2 + hstepA, voffA);
;             PG8_WAIT_V(8); PG8_WAIT_L(0); PG8_BAR; PG8_MMA(0, 0, At, B0); PG8_MMA(0, 1, At, B1); PG8_BAR; PG8_SCHED;
;             PG8_LDA(At, 1, 1); PG8_STAGE(PG8_SB(1, 0), b3, voffB); PG8_STAGE(PG8_SB(1, 1), b3 + hstepB, voffB); PG8_STAGE(PG8_SA(1, 0), a3, voffA);
;             PG8_WAIT_V(8); PG8_WAIT_L(0); PG8_BAR; PG8_MMA(1, 0, At, B0); PG8_MMA(1, 1, At, B1); PG8_BAR; PG8_SCHED;
;         }
	s_add_i32 s34, 0, 0x18000
	v_add_u32_e32 v161, s34, v150
	s_add_i32 s58, 0, 0x1c000
	ds_read_b128 v[154:157], v161
	ds_read_b128 v[164:167], v161 offset:1024
	ds_read_b128 v[168:171], v161 offset:2048
	ds_read_b128 v[172:175], v161 offset:3072
	v_add_u32_e32 v161, s58, v150
	ds_read_b128 v[176:179], v161
	ds_read_b128 v[180:183], v161 offset:1024
	ds_read_b128 v[184:187], v161 offset:2048
	ds_read_b128 v[192:195], v161 offset:3072
	s_add_u32 s54, s54, 0x100000
	s_addc_u32 s55, s55, 0
	s_mov_b32 m0, s24
	v_lshl_add_u64 v[232:233], s[54:55], 0, v[134:135]
	ds_read_b128 v[196:199], v153 offset:32768
	ds_read_b128 v[200:203], v153 offset:33792
	ds_read_b128 v[204:207], v153 offset:34816
	ds_read_b128 v[208:211], v153 offset:35840
	ds_read_b128 v[212:215], v153 offset:36864
	ds_read_b128 v[216:219], v153 offset:37888
	ds_read_b128 v[220:223], v153 offset:38912
	ds_read_b128 v[224:227], v153 offset:39936
	global_load_lds_dwordx4 v[232:233], off
	v_lshl_add_u64 v[232:233], s[54:55], 0, v[130:131]
	s_mov_b32 m0, s25
	s_nop 0
	global_load_lds_dwordx4 v[232:233], off
	s_waitcnt vmcnt(8)
	s_waitcnt lgkmcnt(0)
	s_barrier
	s_waitcnt lgkmcnt(0)
	v_mfma_f32_16x16x32_bf16 v[124:127], v[154:157], v[196:199], v[124:127]
	v_mfma_f32_16x16x32_bf16 v[120:123], v[168:171], v[196:199], v[120:123]
	v_mfma_f32_16x16x32_bf16 v[116:119], v[154:157], v[204:207], v[116:119]
	v_mfma_f32_16x16x32_bf16 v[108:111], v[168:171], v[204:207], v[108:111]
	v_mfma_f32_16x16x32_bf16 v[100:103], v[154:157], v[212:215], v[100:103]
	v_mfma_f32_16x16x32_bf16 v[92:95], v[168:171], v[212:215], v[92:95]
	v_mfma_f32_16x16x32_bf16 v[84:87], v[154:157], v[220:223], v[84:87]
	v_mfma_f32_16x16x32_bf16 v[76:79], v[168:171], v[220:223], v[76:79]
	v_mfma_f32_16x16x32_bf16 v[124:127], v[164:167], v[200:203], v[124:127]
	v_mfma_f32_16x16x32_bf16 v[120:123], v[172:175], v[200:203], v[120:123]
	v_mfma_f32_16x16x32_bf16 v[116:119], v[164:167], v[208:211], v[116:119]
	v_mfma_f32_16x16x32_bf16 v[108:111], v[172:175], v[208:211], v[108:111]
	v_mfma_f32_16x16x32_bf16 v[100:103], v[164:167], v[216:219], v[100:103]
	v_mfma_f32_16x16x32_bf16 v[92:95], v[172:175], v[216:219], v[92:95]
	v_mfma_f32_16x16x32_bf16 v[84:87], v[164:167], v[224:227], v[84:87]
	v_mfma_f32_16x16x32_bf16 v[76:79], v[172:175], v[224:227], v[76:79]
	v_mfma_f32_16x16x32_bf16 v[112:115], v[176:179], v[196:199], v[112:115]
	v_mfma_f32_16x16x32_bf16 v[104:107], v[184:187], v[196:199], v[104:107]
	v_mfma_f32_16x16x32_bf16 v[96:99], v[176:179], v[204:207], v[96:99]
	v_mfma_f32_16x16x32_bf16 v[88:91], v[184:187], v[204:207], v[88:91]
	v_mfma_f32_16x16x32_bf16 v[80:83], v[176:179], v[212:215], v[80:83]
	v_mfma_f32_16x16x32_bf16 v[72:75], v[184:187], v[212:215], v[72:75]
	v_mfma_f32_16x16x32_bf16 v[68:71], v[176:179], v[220:223], v[68:71]
	v_mfma_f32_16x16x32_bf16 v[64:67], v[184:187], v[220:223], v[64:67]
	v_mfma_f32_16x16x32_bf16 v[112:115], v[180:183], v[200:203], v[112:115]
	v_mfma_f32_16x16x32_bf16 v[104:107], v[192:195], v[200:203], v[104:107]
	v_mfma_f32_16x16x32_bf16 v[96:99], v[180:183], v[208:211], v[96:99]
	v_mfma_f32_16x16x32_bf16 v[88:91], v[192:195], v[208:211], v[88:91]
	v_mfma_f32_16x16x32_bf16 v[80:83], v[180:183], v[216:219], v[80:83]
	v_mfma_f32_16x16x32_bf16 v[72:75], v[192:195], v[216:219], v[72:75]
	v_mfma_f32_16x16x32_bf16 v[68:71], v[180:183], v[224:227], v[68:71]
	v_mfma_f32_16x16x32_bf16 v[64:67], v[192:195], v[224:227], v[64:67]
	s_barrier
	s_add_i32 s34, s34, s0
	v_lshl_add_u64 v[158:159], v[158:159], 0, s[12:13]
	s_mov_b32 m0, s34
	ds_read_b128 v[196:199], v153 offset:49152
	ds_read_b128 v[200:203], v153 offset:50176
	ds_read_b128 v[204:207], v153 offset:51200
	ds_read_b128 v[208:211], v153 offset:52224
	ds_read_b128 v[212:215], v153 offset:53248
	ds_read_b128 v[216:219], v153 offset:54272
	ds_read_b128 v[220:223], v153 offset:55296
	ds_read_b128 v[224:227], v153 offset:56320
	global_load_lds_dwordx4 v[158:159], off
	s_add_i32 m0, s34, 0x2000
	s_add_u32 s52, s52, 0x80080
	v_lshl_add_u64 v[158:159], v[188:189], 0, s[12:13]
	s_addc_u32 s53, s53, 0
	s_add_i32 s34, s58, s0
	global_load_lds_dwordx4 v[158:159], off
	v_lshl_add_u64 v[158:159], s[52:53], 0, v[132:133]
	s_mov_b32 m0, s34
	s_nop 0
	global_load_lds_dwordx4 v[158:159], off
	v_lshl_add_u64 v[158:159], s[52:53], 0, v[128:129]
	s_add_i32 m0, s34, 0x2000
	s_nop 0
	global_load_lds_dwordx4 v[158:159], off
	v_lshl_add_u64 v[158:159], v[228:229], 0, s[12:13]
	s_mov_b32 m0, s33
	s_nop 0
	global_load_lds_dwordx4 v[158:159], off
	v_lshl_add_u64 v[158:159], v[230:231], 0, s[12:13]
	s_mov_b32 m0, s35
	s_nop 0
	global_load_lds_dwordx4 v[158:159], off
	s_waitcnt vmcnt(8)
	s_waitcnt lgkmcnt(0)
	s_barrier
	s_waitcnt lgkmcnt(0)
	v_mfma_f32_16x16x32_bf16 v[60:63], v[154:157], v[196:199], v[60:63]
	v_mfma_f32_16x16x32_bf16 v[56:59], v[168:171], v[196:199], v[56:59]
	v_mfma_f32_16x16x32_bf16 v[52:55], v[154:157], v[204:207], v[52:55]
	v_mfma_f32_16x16x32_bf16 v[44:47], v[168:171], v[204:207], v[44:47]
	v_mfma_f32_16x16x32_bf16 v[36:39], v[154:157], v[212:215], v[36:39]
	v_mfma_f32_16x16x32_bf16 v[28:31], v[168:171], v[212:215], v[28:31]
	v_mfma_f32_16x16x32_bf16 v[20:23], v[154:157], v[220:223], v[20:23]
	v_mfma_f32_16x16x32_bf16 v[12:15], v[168:171], v[220:223], v[12:15]
	v_mfma_f32_16x16x32_bf16 v[60:63], v[164:167], v[200:203], v[60:63]
	v_mfma_f32_16x16x32_bf16 v[56:59], v[172:175], v[200:203], v[56:59]
	v_mfma_f32_16x16x32_bf16 v[52:55], v[164:167], v[208:211], v[52:55]
	v_mfma_f32_16x16x32_bf16 v[44:47], v[172:175], v[208:211], v[44:47]
	v_mfma_f32_16x16x32_bf16 v[36:39], v[164:167], v[216:219], v[36:39]
	v_mfma_f32_16x16x32_bf16 v[28:31], v[172:175], v[216:219], v[28:31]
	v_mfma_f32_16x16x32_bf16 v[20:23], v[164:167], v[224:227], v[20:23]
	v_mfma_f32_16x16x32_bf16 v[12:15], v[172:175], v[224:227], v[12:15]
	v_mfma_f32_16x16x32_bf16 v[48:51], v[176:179], v[196:199], v[48:51]
	v_mfma_f32_16x16x32_bf16 v[40:43], v[184:187], v[196:199], v[40:43]
	v_mfma_f32_16x16x32_bf16 v[32:35], v[176:179], v[204:207], v[32:35]
	v_mfma_f32_16x16x32_bf16 v[24:27], v[184:187], v[204:207], v[24:27]
	v_mfma_f32_16x16x32_bf16 v[16:19], v[176:179], v[212:215], v[16:19]
	v_mfma_f32_16x16x32_bf16 v[8:11], v[184:187], v[212:215], v[8:11]
	v_mfma_f32_16x16x32_bf16 v[4:7], v[176:179], v[220:223], v[4:7]
	v_mfma_f32_16x16x32_bf16 v[0:3], v[184:187], v[220:223], v[0:3]
	v_mfma_f32_16x16x32_bf16 v[48:51], v[180:183], v[200:203], v[48:51]
	v_mfma_f32_16x16x32_bf16 v[40:43], v[192:195], v[200:203], v[40:43]
	v_mfma_f32_16x16x32_bf16 v[32:35], v[180:183], v[208:211], v[32:35]
	v_mfma_f32_16x16x32_bf16 v[24:27], v[192:195], v[208:211], v[24:27]
	v_mfma_f32_16x16x32_bf16 v[16:19], v[180:183], v[216:219], v[16:19]
	v_mfma_f32_16x16x32_bf16 v[8:11], v[192:195], v[216:219], v[8:11]
	v_mfma_f32_16x16x32_bf16 v[4:7], v[180:183], v[224:227], v[4:7]
	v_mfma_f32_16x16x32_bf16 v[0:3], v[192:195], v[224:227], v[0:3]
	s_barrier
	s_add_i32 s21, s21, 2
	s_add_u32 s50, s50, 0x100
	s_addc_u32 s51, s51, 0
	s_add_u32 s14, s14, 0x100
	s_addc_u32 s15, s15, 0
	s_cmp_gt_u32 s21, 5
	s_cbranch_scc0 .LBB0_416

; #define PG8_STAGE(bufoff, gbase, voff) do { _Pragma("unroll") for (int _i = 0; _i < 2; ++_i) \
;         __builtin_amdgcn_global_load_lds((const unsigned*)((const char*)(gbase) + (voff)[_i]), (LAS unsigned*)(lds + (bufoff) + ldsw + _i * 8192), 16, 0, 0); } while (0)
; #define PG8_LDA(dst, b, h) do { _Pragma("unroll") for (int m = 0; m < 4; ++m) _Pragma("unroll") for (int k = 0; k < 2; ++k) dst[m][k] = *(const LAS bf16x8*)(lds + PG8_SA(b, h) + aoff + m * 2048 + k * 1024); } while (0)
; #define PG8_LDB(dst, b, h) do { _Pragma("unroll") for (int n = 0; n < 2; ++n) _Pragma("unroll") for (int k = 0; k < 2; ++k) dst[n][k] = *(const LAS bf16x8*)(lds + PG8_SB(b, h) + boff + n * 2048 + k * 1024); } while (0)
; #define PG8_MMA(ai, bj, At, Bt) do { __builtin_amdgcn_s_setprio(1); _Pragma("unroll") for (int m = 0; m < 4; ++m) _Pragma("unroll") for (int n = 0; n < 2; ++n) _Pragma("unroll") for (int k = 0; k < 2; ++k) \
;         acc[ai][bj][m][n] = __builtin_amdgcn_mfma_f32_16x16x32_bf16(Bt[n][k], At[m][k], acc[ai][bj][m][n], 0, 0, 0); __builtin_amdgcn_s_setprio(0); } while (0)
; #define PG8_WAIT_V(n) asm volatile("s_waitcnt vmcnt(" #n ")" ::: "memory")
; #define PG8_WAIT_L(n) asm volatile("s_waitcnt lgkmcnt(" #n ")" ::: "memory")
; #define PG8_BAR __builtin_amdgcn_s_barrier()
; #define PG8_SCHED __builtin_amdgcn_sched_barrier(0)
; template <int GI>
; __device__ __forceinline__ void gemm_phase(LAS unsigned char* lds, unsigned char* ws, int G, int cblk) {
;     ...
;         for (int t = 0; t < nt; t += 2) {
;             const bool last = (t == nt - 2);
;             const char* a1 = cA + (size_t)(t + 1) * kstep;
;             const char* a2 = last ? nA : cA + (size_t)(t + 2) * kstep; const char* b2 = last ? nB : cB + (size_t)(t + 2) * kstep;
;             const char* a3 = a2 + kstep; const char* b3 = b2 + kstep;
;             PG8_LDB(B0, 0, 0); PG8_LDB(B1, 0, 1); PG8_SCHED; PG8_LDA(At, 0, 0); PG8_STAGE(PG8_SA(1, 1), a1 + hstepA, voffA);
;             PG8_WAIT_V(8); PG8_WAIT_L(0); PG8_BAR; PG8_MMA(0, 0, At, B0); PG8_MMA(0, 1, At, B1); PG8_BAR; PG8_SCHED;
;             PG8_LDA(At, 0, 1); PG8_STAGE(PG8_SB(0, 0), b2, voffB); PG8_STAGE(PG8_SB(0, 1), b2 + hstepB, voffB); PG8_STAGE(PG8_SA(0, 0), a2, voffA);
.LBB0_431:
	s_add_u32 s46, s46, 0x80080
	s_addc_u32 s47, s47, 0
	s_add_u32 s14, s48, 0x100
	s_addc_u32 s15, s49, 0
	s_mov_b32 s19, -2
	ds_read_b128 v[154:157], v151
	ds_read_b128 v[164:167], v151 offset:1024
	ds_read_b128 v[168:171], v151 offset:2048
	ds_read_b128 v[172:175], v151 offset:3072
	ds_read_b128 v[176:179], v152
	ds_read_b128 v[180:183], v152 offset:1024
	ds_read_b128 v[184:187], v152 offset:2048
	ds_read_b128 v[192:195], v152 offset:3072
	s_add_u32 s34, s46, 0xfff80080
	s_addc_u32 s48, s47, -1
	s_cmp_eq_u32 s19, 4
	s_cselect_b32 s51, s39, s48
	s_cselect_b32 s50, s38, s34
	s_cselect_b32 s49, s41, s15
	s_cselect_b32 s48, s40, s14
	v_lshl_add_u64 v[158:159], s[46:47], 0, v[138:139]
	s_add_i32 m0, s16, 0xc000
	ds_read_b128 v[196:199], v153
	ds_read_b128 v[200:203], v153 offset:1024
	ds_read_b128 v[204:207], v153 offset:2048
	ds_read_b128 v[208:211], v153 offset:3072
	ds_read_b128 v[212:215], v153 offset:4096
	ds_read_b128 v[216:219], v153 offset:5120
	ds_read_b128 v[220:223], v153 offset:6144
	ds_read_b128 v[224:227], v153 offset:7168
	global_load_lds_dwordx4 v[158:159], off
	v_lshl_add_u64 v[158:159], s[46:47], 0, v[140:141]
	s_add_i32 m0, s16, 0xe000
	s_nop 0
	global_load_lds_dwordx4 v[158:159], off
	s_waitcnt vmcnt(8)
	s_waitcnt lgkmcnt(0)
	s_barrier
	s_waitcnt lgkmcnt(0)
	v_mfma_f32_16x16x32_bf16 v[124:127], v[154:157], v[196:199], 0
	v_mfma_f32_16x16x32_bf16 v[120:123], v[168:171], v[196:199], 0
	v_mfma_f32_16x16x32_bf16 v[116:119], v[154:157], v[204:207], 0
	v_mfma_f32_16x16x32_bf16 v[112:115], v[168:171], v[204:207], 0
	v_mfma_f32_16x16x32_bf16 v[100:103], v[154:157], v[212:215], 0
	v_mfma_f32_16x16x32_bf16 v[96:99], v[168:171], v[212:215], 0
	v_mfma_f32_16x16x32_bf16 v[84:87], v[154:157], v[220:223], 0
	v_mfma_f32_16x16x32_bf16 v[80:83], v[168:171], v[220:223], 0
	v_mfma_f32_16x16x32_bf16 v[124:127], v[164:167], v[200:203], v[124:127]
	v_mfma_f32_16x16x32_bf16 v[120:123], v[172:175], v[200:203], v[120:123]
	v_mfma_f32_16x16x32_bf16 v[116:119], v[164:167], v[208:211], v[116:119]
	v_mfma_f32_16x16x32_bf16 v[112:115], v[172:175], v[208:211], v[112:115]
	v_mfma_f32_16x16x32_bf16 v[100:103], v[164:167], v[216:219], v[100:103]
	v_mfma_f32_16x16x32_bf16 v[96:99], v[172:175], v[216:219], v[96:99]
	v_mfma_f32_16x16x32_bf16 v[84:87], v[164:167], v[224:227], v[84:87]
	v_mfma_f32_16x16x32_bf16 v[80:83], v[172:175], v[224:227], v[80:83]
	v_mfma_f32_16x16x32_bf16 v[108:111], v[176:179], v[196:199], 0
	v_mfma_f32_16x16x32_bf16 v[104:107], v[184:187], v[196:199], 0
	v_mfma_f32_16x16x32_bf16 v[92:95], v[176:179], v[204:207], 0
	v_mfma_f32_16x16x32_bf16 v[88:91], v[184:187], v[204:207], 0
	v_mfma_f32_16x16x32_bf16 v[76:79], v[176:179], v[212:215], 0
	v_mfma_f32_16x16x32_bf16 v[72:75], v[184:187], v[212:215], 0
	v_mfma_f32_16x16x32_bf16 v[68:71], v[176:179], v[220:223], 0
	v_mfma_f32_16x16x32_bf16 v[64:67], v[184:187], v[220:223], 0
	v_mfma_f32_16x16x32_bf16 v[108:111], v[180:183], v[200:203], v[108:111]
	v_mfma_f32_16x16x32_bf16 v[104:107], v[192:195], v[200:203], v[104:107]
	v_mfma_f32_16x16x32_bf16 v[92:95], v[180:183], v[208:211], v[92:95]
	v_mfma_f32_16x16x32_bf16 v[88:91], v[192:195], v[208:211], v[88:91]
	v_mfma_f32_16x16x32_bf16 v[76:79], v[180:183], v[216:219], v[76:79]
	v_mfma_f32_16x16x32_bf16 v[72:75], v[192:195], v[216:219], v[72:75]
	v_mfma_f32_16x16x32_bf16 v[68:71], v[180:183], v[224:227], v[68:71]
	v_mfma_f32_16x16x32_bf16 v[64:67], v[192:195], v[224:227], v[64:67]
	s_barrier
	s_add_i32 s34, s33, s0
	v_lshl_add_u64 v[158:159], s[48:49], 0, v[132:133]
	s_mov_b32 m0, s34
	ds_read_b128 v[196:199], v153 offset:16384
	ds_read_b128 v[200:203], v153 offset:17408
	ds_read_b128 v[204:207], v153 offset:18432
	ds_read_b128 v[208:211], v153 offset:19456
	ds_read_b128 v[212:215], v153 offset:20480
	ds_read_b128 v[216:219], v153 offset:21504
	ds_read_b128 v[220:223], v153 offset:22528
	ds_read_b128 v[224:227], v153 offset:23552
	global_load_lds_dwordx4 v[158:159], off
	s_add_i32 m0, s34, 0x2000
	s_add_u32 s54, s48, 0x100000
	v_lshl_add_u64 v[188:189], s[48:49], 0, v[128:129]
	s_addc_u32 s55, s49, 0
	s_add_i32 s34, s35, s0
	global_load_lds_dwordx4 v[188:189], off
	v_lshl_add_u64 v[228:229], s[54:55], 0, v[132:133]
	s_mov_b32 m0, s34
	v_lshl_add_u64 v[230:231], s[50:51], 0, v[130:131]
	global_load_lds_dwordx4 v[228:229], off
	v_lshl_add_u64 v[228:229], s[54:55], 0, v[128:129]
	s_add_i32 m0, s34, 0x2000
	s_nop 0
	global_load_lds_dwordx4 v[228:229], off
	v_lshl_add_u64 v[228:229], s[50:51], 0, v[134:135]
	s_mov_b32 m0, s16
	s_nop 0
	global_load_lds_dwordx4 v[228:229], off
	s_mov_b32 m0, s17
	s_nop 0
	global_load_lds_dwordx4 v[230:231], off
	s_waitcnt vmcnt(8)
	s_waitcnt lgkmcnt(0)
	s_barrier
; #define PG8_STAGE(bufoff, gbase, voff) do { _Pragma("unroll") for (int _i = 0; _i < 2; ++_i) \
;         __builtin_amdgcn_global_load_lds((const unsigned*)((const char*)(gbase) + (voff)[_i]), (LAS unsigned*)(lds + (bufoff) + ldsw + _i * 8192), 16, 0, 0); } while (0)
; #define PG8_LDA(dst, b, h) do { _Pragma("unroll") for (int m = 0; m < 4; ++m) _Pragma("unroll") for (int k = 0; k < 2; ++k) dst[m][k] = *(const LAS bf16x8*)(lds + PG8_SA(b, h) + aoff + m * 2048 + k * 1024); } while (0)
; #define PG8_LDB(dst, b, h) do { _Pragma("unroll") for (int n = 0; n < 2; ++n) _Pragma("unroll") for (int k = 0; k < 2; ++k) dst[n][k] = *(const LAS bf16x8*)(lds + PG8_SB(b, h) + boff + n * 2048 + k * 1024); } while (0)
; #define PG8_MMA(ai, bj, At, Bt) do { __builtin_amdgcn_s_setprio(1); _Pragma("unroll") for (int m = 0; m < 4; ++m) _Pragma("unroll") for (int n = 0; n < 2; ++n) _Pragma("unroll") for (int k = 0; k < 2; ++k) \
;         acc[ai][bj][m][n] = __builtin_amdgcn_mfma_f32_16x16x32_bf16(Bt[n][k], At[m][k], acc[ai][bj][m][n], 0, 0, 0); __builtin_amdgcn_s_setprio(0); } while (0)
; #define PG8_WAIT_V(n) asm volatile("s_waitcnt vmcnt(" #n ")" ::: "memory")
; #define PG8_WAIT_L(n) asm volatile("s_waitcnt lgkmcnt(" #n ")" ::: "memory")
; #define PG8_BAR __builtin_amdgcn_s_barrier()
; #define PG8_SCHED __builtin_amdgcn_sched_barrier(0)
; template <int GI>
; __device__ __forceinline__ void gemm_phase(LAS unsigned char* lds, unsigned char* ws, int G, int cblk) {
;     ...
;             PG8_WAIT_V(8); PG8_WAIT_L(0); PG8_BAR; PG8_MMA(0, 0, At, B0); PG8_MMA(0, 1, At, B1); PG8_BAR; PG8_SCHED;
;             PG8_LDA(At, 0, 1); PG8_STAGE(PG8_SB(0, 0), b2, voffB); PG8_STAGE(PG8_SB(0, 1), b2 + hstepB, voffB); PG8_STAGE(PG8_SA(0, 0), a2, voffA);
;             PG8_WAIT_V(8); PG8_WAIT_L(0); PG8_BAR; PG8_MMA(1, 0, At, B0); PG8_MMA(1, 1, At, B1); PG8_BAR; PG8_SCHED;
;             PG8_LDB(B0, 1, 0); PG8_LDB(B1, 1, 1); PG8_SCHED; PG8_LDA(At, 1, 0); PG8_STAGE(PG8_SA(0, 1), a2 + hstepA, voffA);
;             PG8_WAIT_V(8); PG8_WAIT_L(0); PG8_BAR; PG8_MMA(0, 0, At, B0); PG8_MMA(0, 1, At, B1); PG8_BAR; PG8_SCHED;
	s_waitcnt lgkmcnt(0)
	v_mfma_f32_16x16x32_bf16 v[60:63], v[154:157], v[196:199], 0
	v_mfma_f32_16x16x32_bf16 v[56:59], v[168:171], v[196:199], 0
	v_mfma_f32_16x16x32_bf16 v[52:55], v[154:157], v[204:207], 0
	v_mfma_f32_16x16x32_bf16 v[48:51], v[168:171], v[204:207], 0
	v_mfma_f32_16x16x32_bf16 v[36:39], v[154:157], v[212:215], 0
	v_mfma_f32_16x16x32_bf16 v[32:35], v[168:171], v[212:215], 0
	v_mfma_f32_16x16x32_bf16 v[20:23], v[154:157], v[220:223], 0
	v_mfma_f32_16x16x32_bf16 v[16:19], v[168:171], v[220:223], 0
	v_mfma_f32_16x16x32_bf16 v[60:63], v[164:167], v[200:203], v[60:63]
	v_mfma_f32_16x16x32_bf16 v[56:59], v[172:175], v[200:203], v[56:59]
	v_mfma_f32_16x16x32_bf16 v[52:55], v[164:167], v[208:211], v[52:55]
	v_mfma_f32_16x16x32_bf16 v[48:51], v[172:175], v[208:211], v[48:51]
	v_mfma_f32_16x16x32_bf16 v[36:39], v[164:167], v[216:219], v[36:39]
	v_mfma_f32_16x16x32_bf16 v[32:35], v[172:175], v[216:219], v[32:35]
	v_mfma_f32_16x16x32_bf16 v[20:23], v[164:167], v[224:227], v[20:23]
	v_mfma_f32_16x16x32_bf16 v[16:19], v[172:175], v[224:227], v[16:19]
	v_mfma_f32_16x16x32_bf16 v[44:47], v[176:179], v[196:199], 0
	v_mfma_f32_16x16x32_bf16 v[40:43], v[184:187], v[196:199], 0
	v_mfma_f32_16x16x32_bf16 v[28:31], v[176:179], v[204:207], 0
	v_mfma_f32_16x16x32_bf16 v[24:27], v[184:187], v[204:207], 0
	v_mfma_f32_16x16x32_bf16 v[12:15], v[176:179], v[212:215], 0
	v_mfma_f32_16x16x32_bf16 v[8:11], v[184:187], v[212:215], 0
	v_mfma_f32_16x16x32_bf16 v[4:7], v[176:179], v[220:223], 0
	v_mfma_f32_16x16x32_bf16 v[0:3], v[184:187], v[220:223], 0
	v_mfma_f32_16x16x32_bf16 v[44:47], v[180:183], v[200:203], v[44:47]
	v_mfma_f32_16x16x32_bf16 v[40:43], v[192:195], v[200:203], v[40:43]
	v_mfma_f32_16x16x32_bf16 v[28:31], v[180:183], v[208:211], v[28:31]
	v_mfma_f32_16x16x32_bf16 v[24:27], v[192:195], v[208:211], v[24:27]
	v_mfma_f32_16x16x32_bf16 v[12:15], v[180:183], v[216:219], v[12:15]
	v_mfma_f32_16x16x32_bf16 v[8:11], v[192:195], v[216:219], v[8:11]
	v_mfma_f32_16x16x32_bf16 v[4:7], v[180:183], v[224:227], v[4:7]
	v_mfma_f32_16x16x32_bf16 v[0:3], v[192:195], v[224:227], v[0:3]
	s_barrier
	s_add_i32 s34, 0, 0x18000
	v_add_u32_e32 v161, s34, v150
	s_add_i32 s53, 0, 0x1c000
	ds_read_b128 v[154:157], v161
	ds_read_b128 v[164:167], v161 offset:1024
	ds_read_b128 v[168:171], v161 offset:2048
	ds_read_b128 v[172:175], v161 offset:3072
	v_add_u32_e32 v161, s53, v150
	ds_read_b128 v[176:179], v161
	ds_read_b128 v[180:183], v161 offset:1024
	ds_read_b128 v[184:187], v161 offset:2048
	ds_read_b128 v[192:195], v161 offset:3072
	s_add_u32 s50, s50, 0x80000
	s_addc_u32 s51, s51, 0
	s_mov_b32 m0, s22
	v_lshl_add_u64 v[232:233], s[50:51], 0, v[134:135]
	ds_read_b128 v[196:199], v153 offset:32768
	ds_read_b128 v[200:203], v153 offset:33792
	ds_read_b128 v[204:207], v153 offset:34816
	ds_read_b128 v[208:211], v153 offset:35840
	ds_read_b128 v[212:215], v153 offset:36864
	ds_read_b128 v[216:219], v153 offset:37888
	ds_read_b128 v[220:223], v153 offset:38912
	ds_read_b128 v[224:227], v153 offset:39936
	global_load_lds_dwordx4 v[232:233], off
	v_lshl_add_u64 v[232:233], s[50:51], 0, v[130:131]
	s_mov_b32 m0, s23
	s_nop 0
	global_load_lds_dwordx4 v[232:233], off
	s_waitcnt vmcnt(8)
	s_waitcnt lgkmcnt(0)
	s_barrier
	s_waitcnt lgkmcnt(0)
	v_mfma_f32_16x16x32_bf16 v[124:127], v[154:157], v[196:199], v[124:127]
	v_mfma_f32_16x16x32_bf16 v[120:123], v[168:171], v[196:199], v[120:123]
	v_mfma_f32_16x16x32_bf16 v[116:119], v[154:157], v[204:207], v[116:119]
	v_mfma_f32_16x16x32_bf16 v[112:115], v[168:171], v[204:207], v[112:115]
	v_mfma_f32_16x16x32_bf16 v[100:103], v[154:157], v[212:215], v[100:103]
	v_mfma_f32_16x16x32_bf16 v[96:99], v[168:171], v[212:215], v[96:99]
	v_mfma_f32_16x16x32_bf16 v[84:87], v[154:157], v[220:223], v[84:87]
	v_mfma_f32_16x16x32_bf16 v[80:83], v[168:171], v[220:223], v[80:83]
	v_mfma_f32_16x16x32_bf16 v[124:127], v[164:167], v[200:203], v[124:127]
	v_mfma_f32_16x16x32_bf16 v[120:123], v[172:175], v[200:203], v[120:123]
	v_mfma_f32_16x16x32_bf16 v[116:119], v[164:167], v[208:211], v[116:119]
	v_mfma_f32_16x16x32_bf16 v[112:115], v[172:175], v[208:211], v[112:115]
	v_mfma_f32_16x16x32_bf16 v[100:103], v[164:167], v[216:219], v[100:103]
	v_mfma_f32_16x16x32_bf16 v[96:99], v[172:175], v[216:219], v[96:99]
	v_mfma_f32_16x16x32_bf16 v[84:87], v[164:167], v[224:227], v[84:87]
	v_mfma_f32_16x16x32_bf16 v[80:83], v[172:175], v[224:227], v[80:83]
	v_mfma_f32_16x16x32_bf16 v[108:111], v[176:179], v[196:199], v[108:111]
	v_mfma_f32_16x16x32_bf16 v[104:107], v[184:187], v[196:199], v[104:107]
	v_mfma_f32_16x16x32_bf16 v[92:95], v[176:179], v[204:207], v[92:95]
	v_mfma_f32_16x16x32_bf16 v[88:91], v[184:187], v[204:207], v[88:91]
	v_mfma_f32_16x16x32_bf16 v[76:79], v[176:179], v[212:215], v[76:79]
	v_mfma_f32_16x16x32_bf16 v[72:75], v[184:187], v[212:215], v[72:75]
	v_mfma_f32_16x16x32_bf16 v[68:71], v[176:179], v[220:223], v[68:71]
	v_mfma_f32_16x16x32_bf16 v[64:67], v[184:187], v[220:223], v[64:67]
	v_mfma_f32_16x16x32_bf16 v[108:111], v[180:183], v[200:203], v[108:111]
	v_mfma_f32_16x16x32_bf16 v[104:107], v[192:195], v[200:203], v[104:107]
	v_mfma_f32_16x16x32_bf16 v[92:95], v[180:183], v[208:211], v[92:95]
	v_mfma_f32_16x16x32_bf16 v[88:91], v[192:195], v[208:211], v[88:91]
	v_mfma_f32_16x16x32_bf16 v[76:79], v[180:183], v[216:219], v[76:79]
	v_mfma_f32_16x16x32_bf16 v[72:75], v[192:195], v[216:219], v[72:75]
	v_mfma_f32_16x16x32_bf16 v[68:71], v[180:183], v[224:227], v[68:71]
	v_mfma_f32_16x16x32_bf16 v[64:67], v[192:195], v[224:227], v[64:67]
	s_barrier
; #define PG8_STAGE(bufoff, gbase, voff) do { _Pragma("unroll") for (int _i = 0; _i < 2; ++_i) \
;         __builtin_amdgcn_global_load_lds((const unsigned*)((const char*)(gbase) + (voff)[_i]), (LAS unsigned*)(lds + (bufoff) + ldsw + _i * 8192), 16, 0, 0); } while (0)
; #define PG8_LDA(dst, b, h) do { _Pragma("unroll") for (int m = 0; m < 4; ++m) _Pragma("unroll") for (int k = 0; k < 2; ++k) dst[m][k] = *(const LAS bf16x8*)(lds + PG8_SA(b, h) + aoff + m * 2048 + k * 1024); } while (0)
; #define PG8_LDB(dst, b, h) do { _Pragma("unroll") for (int n = 0; n < 2; ++n) _Pragma("unroll") for (int k = 0; k < 2; ++k) dst[n][k] = *(const LAS bf16x8*)(lds + PG8_SB(b, h) + boff + n * 2048 + k * 1024); } while (0)
; #define PG8_WAIT_V(n) asm volatile("s_waitcnt vmcnt(" #n ")" ::: "memory")
; #define PG8_WAIT_L(n) asm volatile("s_waitcnt lgkmcnt(" #n ")" ::: "memory")
; template <int GI>
; __device__ __forceinline__ void gemm_phase(LAS unsigned char* lds, unsigned char* ws, int G, int cblk) {
;     ...
;         for (int t = 0; t < nt; t += 2) {
;             const bool last = (t == nt - 2);
;             const char* a1 = cA + (size_t)(t + 1) * kstep;
;             const char* a2 = last ? nA : cA + (size_t)(t + 2) * kstep; const char* b2 = last ? nB : cB + (size_t)(t + 2) * kstep;
;             const char* a3 = a2 + kstep; const char* b3 = b2 + kstep;
;             PG8_LDB(B0, 0, 0); PG8_LDB(B1, 0, 1); PG8_SCHED; PG8_LDA(At, 0, 0); PG8_STAGE(PG8_SA(1, 1), a1 + hstepA, voffA);
;             PG8_WAIT_V(8); PG8_WAIT_L(0); PG8_BAR; PG8_MMA(0, 0, At, B0); PG8_MMA(0, 1, At, B1); PG8_BAR; PG8_SCHED;
;             PG8_LDA(At, 0, 1); PG8_STAGE(PG8_SB(0, 0), b2, voffB); PG8_STAGE(PG8_SB(0, 1), b2 + hstepB, voffB); PG8_STAGE(PG8_SA(0, 0), a2, voffA);
;             PG8_WAIT_V(8); PG8_WAIT_L(0); PG8_BAR; PG8_MMA(1, 0, At, B0); PG8_MMA(1, 1, At, B1); PG8_BAR; PG8_SCHED;
;             PG8_LDB(B0, 1, 0); PG8_LDB(B1, 1, 1); PG8_SCHED; PG8_LDA(At, 1, 0); PG8_STAGE(PG8_SA(0, 1), a2 + hstepA, voffA);
;             PG8_WAIT_V(8); PG8_WAIT_L(0); PG8_BAR; PG8_MMA(0, 0, At, B0); PG8_MMA(0, 1, At, B1); PG8_BAR; PG8_SCHED;
;             PG8_LDA(At, 1, 1); PG8_STAGE(PG8_SB(1, 0), b3, voffB); PG8_STAGE(PG8_SB(1, 1), b3 + hstepB, voffB); PG8_STAGE(PG8_SA(1, 0), a3, voffA);
;             PG8_WAIT_V(8); PG8_WAIT_L(0); PG8_BAR; PG8_MMA(1, 0, At, B0); PG8_MMA(1, 1, At, B1); PG8_BAR; PG8_SCHED;
	s_add_i32 s34, s34, s0
	v_lshl_add_u64 v[158:159], v[158:159], 0, s[8:9]
	s_mov_b32 m0, s34
	ds_read_b128 v[196:199], v153 offset:49152
	ds_read_b128 v[200:203], v153 offset:50176
	ds_read_b128 v[204:207], v153 offset:51200
	ds_read_b128 v[208:211], v153 offset:52224
	ds_read_b128 v[212:215], v153 offset:53248
	ds_read_b128 v[216:219], v153 offset:54272
	ds_read_b128 v[220:223], v153 offset:55296
	ds_read_b128 v[224:227], v153 offset:56320
	global_load_lds_dwordx4 v[158:159], off
	s_add_i32 m0, s34, 0x2000
	s_add_u32 s48, s48, 0x100080
	v_lshl_add_u64 v[158:159], v[188:189], 0, s[8:9]
	s_addc_u32 s49, s49, 0
	s_add_i32 s34, s53, s0
	global_load_lds_dwordx4 v[158:159], off
	v_lshl_add_u64 v[158:159], s[48:49], 0, v[132:133]
	s_mov_b32 m0, s34
	s_nop 0
	global_load_lds_dwordx4 v[158:159], off
	v_lshl_add_u64 v[158:159], s[48:49], 0, v[128:129]
	s_add_i32 m0, s34, 0x2000
	s_nop 0
	global_load_lds_dwordx4 v[158:159], off
	v_lshl_add_u64 v[158:159], v[228:229], 0, s[8:9]
	s_mov_b32 m0, s26
	s_nop 0
	global_load_lds_dwordx4 v[158:159], off
	v_lshl_add_u64 v[158:159], v[230:231], 0, s[8:9]
	s_mov_b32 m0, s27
	s_nop 0
	global_load_lds_dwordx4 v[158:159], off
	s_waitcnt vmcnt(8)
	s_waitcnt lgkmcnt(0)
	s_barrier
	s_waitcnt lgkmcnt(0)
	v_mfma_f32_16x16x32_bf16 v[60:63], v[154:157], v[196:199], v[60:63]
	v_mfma_f32_16x16x32_bf16 v[56:59], v[168:171], v[196:199], v[56:59]
	v_mfma_f32_16x16x32_bf16 v[52:55], v[154:157], v[204:207], v[52:55]
	v_mfma_f32_16x16x32_bf16 v[48:51], v[168:171], v[204:207], v[48:51]
	v_mfma_f32_16x16x32_bf16 v[36:39], v[154:157], v[212:215], v[36:39]
	v_mfma_f32_16x16x32_bf16 v[32:35], v[168:171], v[212:215], v[32:35]
	v_mfma_f32_16x16x32_bf16 v[20:23], v[154:157], v[220:223], v[20:23]
	v_mfma_f32_16x16x32_bf16 v[16:19], v[168:171], v[220:223], v[16:19]
	v_mfma_f32_16x16x32_bf16 v[60:63], v[164:167], v[200:203], v[60:63]
	v_mfma_f32_16x16x32_bf16 v[56:59], v[172:175], v[200:203], v[56:59]
	v_mfma_f32_16x16x32_bf16 v[52:55], v[164:167], v[208:211], v[52:55]
	v_mfma_f32_16x16x32_bf16 v[48:51], v[172:175], v[208:211], v[48:51]
	v_mfma_f32_16x16x32_bf16 v[36:39], v[164:167], v[216:219], v[36:39]
	v_mfma_f32_16x16x32_bf16 v[32:35], v[172:175], v[216:219], v[32:35]
	v_mfma_f32_16x16x32_bf16 v[20:23], v[164:167], v[224:227], v[20:23]
	v_mfma_f32_16x16x32_bf16 v[16:19], v[172:175], v[224:227], v[16:19]
	v_mfma_f32_16x16x32_bf16 v[44:47], v[176:179], v[196:199], v[44:47]
	v_mfma_f32_16x16x32_bf16 v[40:43], v[184:187], v[196:199], v[40:43]
	v_mfma_f32_16x16x32_bf16 v[28:31], v[176:179], v[204:207], v[28:31]
	v_mfma_f32_16x16x32_bf16 v[24:27], v[184:187], v[204:207], v[24:27]
	v_mfma_f32_16x16x32_bf16 v[12:15], v[176:179], v[212:215], v[12:15]
	v_mfma_f32_16x16x32_bf16 v[8:11], v[184:187], v[212:215], v[8:11]
	v_mfma_f32_16x16x32_bf16 v[4:7], v[176:179], v[220:223], v[4:7]
	v_mfma_f32_16x16x32_bf16 v[0:3], v[184:187], v[220:223], v[0:3]
	v_mfma_f32_16x16x32_bf16 v[44:47], v[180:183], v[200:203], v[44:47]
	v_mfma_f32_16x16x32_bf16 v[40:43], v[192:195], v[200:203], v[40:43]
	v_mfma_f32_16x16x32_bf16 v[28:31], v[180:183], v[208:211], v[28:31]
	v_mfma_f32_16x16x32_bf16 v[24:27], v[192:195], v[208:211], v[24:27]
	v_mfma_f32_16x16x32_bf16 v[12:15], v[180:183], v[216:219], v[12:15]
	v_mfma_f32_16x16x32_bf16 v[8:11], v[192:195], v[216:219], v[8:11]
	v_mfma_f32_16x16x32_bf16 v[4:7], v[180:183], v[224:227], v[4:7]
	v_mfma_f32_16x16x32_bf16 v[0:3], v[192:195], v[224:227], v[0:3]
	s_barrier
	s_add_i32 s19, s19, 2
	s_add_u32 s46, s46, 0x100
	s_addc_u32 s47, s47, 0
	s_add_u32 s14, s14, 0x100
	s_addc_u32 s15, s15, 0
	s_cmp_gt_u32 s19, 5
	s_cbranch_scc0 .LBB0_432
	s_branch .Lpeel_exit_5
.LBB0_432:
	ds_read_b128 v[154:157], v151
	ds_read_b128 v[164:167], v151 offset:1024
	ds_read_b128 v[168:171], v151 offset:2048
	ds_read_b128 v[172:175], v151 offset:3072
	ds_read_b128 v[176:179], v152
	ds_read_b128 v[180:183], v152 offset:1024
	ds_read_b128 v[184:187], v152 offset:2048
	ds_read_b128 v[192:195], v152 offset:3072
	s_add_u32 s34, s46, 0xfff80080
	s_addc_u32 s48, s47, -1
	s_cmp_eq_u32 s19, 4
	s_cselect_b32 s51, s39, s48
	s_cselect_b32 s50, s38, s34
	s_cselect_b32 s49, s41, s15
	s_cselect_b32 s48, s40, s14
	v_lshl_add_u64 v[158:159], s[46:47], 0, v[138:139]
	s_add_i32 m0, s16, 0xc000
	ds_read_b128 v[196:199], v153
	ds_read_b128 v[200:203], v153 offset:1024
	ds_read_b128 v[204:207], v153 offset:2048
	ds_read_b128 v[208:211], v153 offset:3072
	ds_read_b128 v[212:215], v153 offset:4096
	ds_read_b128 v[216:219], v153 offset:5120
	ds_read_b128 v[220:223], v153 offset:6144
	ds_read_b128 v[224:227], v153 offset:7168
	global_load_lds_dwordx4 v[158:159], off
	v_lshl_add_u64 v[158:159], s[46:47], 0, v[140:141]
	s_add_i32 m0, s16, 0xe000
	s_nop 0
	global_load_lds_dwordx4 v[158:159], off
	s_waitcnt vmcnt(8)
	s_waitcnt lgkmcnt(0)
	s_barrier
; #define PG8_STAGE(bufoff, gbase, voff) do { _Pragma("unroll") for (int _i = 0; _i < 2; ++_i) \
;         __builtin_amdgcn_global_load_lds((const unsigned*)((const char*)(gbase) + (voff)[_i]), (LAS unsigned*)(lds + (bufoff) + ldsw + _i * 8192), 16, 0, 0); } while (0)
; #define PG8_LDA(dst, b, h) do { _Pragma("unroll") for (int m = 0; m < 4; ++m) _Pragma("unroll") for (int k = 0; k < 2; ++k) dst[m][k] = *(const LAS bf16x8*)(lds + PG8_SA(b, h) + aoff + m * 2048 + k * 1024); } while (0)
; #define PG8_MMA(ai, bj, At, Bt) do { __builtin_amdgcn_s_setprio(1); _Pragma("unroll") for (int m = 0; m < 4; ++m) _Pragma("unroll") for (int n = 0; n < 2; ++n) _Pragma("unroll") for (int k = 0; k < 2; ++k) \
;         acc[ai][bj][m][n] = __builtin_amdgcn_mfma_f32_16x16x32_bf16(Bt[n][k], At[m][k], acc[ai][bj][m][n], 0, 0, 0); __builtin_amdgcn_s_setprio(0); } while (0)
; #define PG8_WAIT_V(n) asm volatile("s_waitcnt vmcnt(" #n ")" ::: "memory")
; #define PG8_WAIT_L(n) asm volatile("s_waitcnt lgkmcnt(" #n ")" ::: "memory")
; #define PG8_BAR __builtin_amdgcn_s_barrier()
; #define PG8_SCHED __builtin_amdgcn_sched_barrier(0)
; template <int GI>
; __device__ __forceinline__ void gemm_phase(LAS unsigned char* lds, unsigned char* ws, int G, int cblk) {
;     ...
;             PG8_WAIT_V(8); PG8_WAIT_L(0); PG8_BAR; PG8_MMA(0, 0, At, B0); PG8_MMA(0, 1, At, B1); PG8_BAR; PG8_SCHED;
;             PG8_LDA(At, 0, 1); PG8_STAGE(PG8_SB(0, 0), b2, voffB); PG8_STAGE(PG8_SB(0, 1), b2 + hstepB, voffB); PG8_STAGE(PG8_SA(0, 0), a2, voffA);
;             PG8_WAIT_V(8); PG8_WAIT_L(0); PG8_BAR; PG8_MMA(1, 0, At, B0); PG8_MMA(1, 1, At, B1); PG8_BAR; PG8_SCHED;
	s_waitcnt lgkmcnt(0)
	v_mfma_f32_16x16x32_bf16 v[124:127], v[154:157], v[196:199], v[124:127]
	v_mfma_f32_16x16x32_bf16 v[120:123], v[168:171], v[196:199], v[120:123]
	v_mfma_f32_16x16x32_bf16 v[116:119], v[154:157], v[204:207], v[116:119]
	v_mfma_f32_16x16x32_bf16 v[112:115], v[168:171], v[204:207], v[112:115]
	v_mfma_f32_16x16x32_bf16 v[100:103], v[154:157], v[212:215], v[100:103]
	v_mfma_f32_16x16x32_bf16 v[96:99], v[168:171], v[212:215], v[96:99]
	v_mfma_f32_16x16x32_bf16 v[84:87], v[154:157], v[220:223], v[84:87]
	v_mfma_f32_16x16x32_bf16 v[80:83], v[168:171], v[220:223], v[80:83]
	v_mfma_f32_16x16x32_bf16 v[124:127], v[164:167], v[200:203], v[124:127]
	v_mfma_f32_16x16x32_bf16 v[120:123], v[172:175], v[200:203], v[120:123]
	v_mfma_f32_16x16x32_bf16 v[116:119], v[164:167], v[208:211], v[116:119]
	v_mfma_f32_16x16x32_bf16 v[112:115], v[172:175], v[208:211], v[112:115]
	v_mfma_f32_16x16x32_bf16 v[100:103], v[164:167], v[216:219], v[100:103]
	v_mfma_f32_16x16x32_bf16 v[96:99], v[172:175], v[216:219], v[96:99]
	v_mfma_f32_16x16x32_bf16 v[84:87], v[164:167], v[224:227], v[84:87]
	v_mfma_f32_16x16x32_bf16 v[80:83], v[172:175], v[224:227], v[80:83]
	v_mfma_f32_16x16x32_bf16 v[108:111], v[176:179], v[196:199], v[108:111]
	v_mfma_f32_16x16x32_bf16 v[104:107], v[184:187], v[196:199], v[104:107]
	v_mfma_f32_16x16x32_bf16 v[92:95], v[176:179], v[204:207], v[92:95]
	v_mfma_f32_16x16x32_bf16 v[88:91], v[184:187], v[204:207], v[88:91]
	v_mfma_f32_16x16x32_bf16 v[76:79], v[176:179], v[212:215], v[76:79]
	v_mfma_f32_16x16x32_bf16 v[72:75], v[184:187], v[212:215], v[72:75]
	v_mfma_f32_16x16x32_bf16 v[68:71], v[176:179], v[220:223], v[68:71]
	v_mfma_f32_16x16x32_bf16 v[64:67], v[184:187], v[220:223], v[64:67]
	v_mfma_f32_16x16x32_bf16 v[108:111], v[180:183], v[200:203], v[108:111]
	v_mfma_f32_16x16x32_bf16 v[104:107], v[192:195], v[200:203], v[104:107]
	v_mfma_f32_16x16x32_bf16 v[92:95], v[180:183], v[208:211], v[92:95]
	v_mfma_f32_16x16x32_bf16 v[88:91], v[192:195], v[208:211], v[88:91]
	v_mfma_f32_16x16x32_bf16 v[76:79], v[180:183], v[216:219], v[76:79]
	v_mfma_f32_16x16x32_bf16 v[72:75], v[192:195], v[216:219], v[72:75]
	v_mfma_f32_16x16x32_bf16 v[68:71], v[180:183], v[224:227], v[68:71]
	v_mfma_f32_16x16x32_bf16 v[64:67], v[192:195], v[224:227], v[64:67]
	s_barrier
	s_add_i32 s34, s33, s0
	v_lshl_add_u64 v[158:159], s[48:49], 0, v[132:133]
	s_mov_b32 m0, s34
	ds_read_b128 v[196:199], v153 offset:16384
	ds_read_b128 v[200:203], v153 offset:17408
	ds_read_b128 v[204:207], v153 offset:18432
	ds_read_b128 v[208:211], v153 offset:19456
	ds_read_b128 v[212:215], v153 offset:20480
	ds_read_b128 v[216:219], v153 offset:21504
	ds_read_b128 v[220:223], v153 offset:22528
	ds_read_b128 v[224:227], v153 offset:23552
	global_load_lds_dwordx4 v[158:159], off
	s_add_i32 m0, s34, 0x2000
	s_add_u32 s54, s48, 0x100000
	v_lshl_add_u64 v[188:189], s[48:49], 0, v[128:129]
	s_addc_u32 s55, s49, 0
	s_add_i32 s34, s35, s0
	global_load_lds_dwordx4 v[188:189], off
	v_lshl_add_u64 v[228:229], s[54:55], 0, v[132:133]
	s_mov_b32 m0, s34
	v_lshl_add_u64 v[230:231], s[50:51], 0, v[130:131]
	global_load_lds_dwordx4 v[228:229], off
	v_lshl_add_u64 v[228:229], s[54:55], 0, v[128:129]
	s_add_i32 m0, s34, 0x2000
	s_nop 0
	global_load_lds_dwordx4 v[228:229], off
	v_lshl_add_u64 v[228:229], s[50:51], 0, v[134:135]
	s_mov_b32 m0, s16
	s_nop 0
	global_load_lds_dwordx4 v[228:229], off
	s_mov_b32 m0, s17
	s_nop 0
	global_load_lds_dwordx4 v[230:231], off
	s_waitcnt vmcnt(8)
	s_waitcnt lgkmcnt(0)
	s_barrier
	s_waitcnt lgkmcnt(0)
	v_mfma_f32_16x16x32_bf16 v[60:63], v[154:157], v[196:199], v[60:63]
	v_mfma_f32_16x16x32_bf16 v[56:59], v[168:171], v[196:199], v[56:59]
	v_mfma_f32_16x16x32_bf16 v[52:55], v[154:157], v[204:207], v[52:55]
	v_mfma_f32_16x16x32_bf16 v[48:51], v[168:171], v[204:207], v[48:51]
	v_mfma_f32_16x16x32_bf16 v[36:39], v[154:157], v[212:215], v[36:39]
	v_mfma_f32_16x16x32_bf16 v[32:35], v[168:171], v[212:215], v[32:35]
	v_mfma_f32_16x16x32_bf16 v[20:23], v[154:157], v[220:223], v[20:23]
	v_mfma_f32_16x16x32_bf16 v[16:19], v[168:171], v[220:223], v[16:19]
	v_mfma_f32_16x16x32_bf16 v[60:63], v[164:167], v[200:203], v[60:63]
	v_mfma_f32_16x16x32_bf16 v[56:59], v[172:175], v[200:203], v[56:59]
	v_mfma_f32_16x16x32_bf16 v[52:55], v[164:167], v[208:211], v[52:55]
	v_mfma_f32_16x16x32_bf16 v[48:51], v[172:175], v[208:211], v[48:51]
	v_mfma_f32_16x16x32_bf16 v[36:39], v[164:167], v[216:219], v[36:39]
	v_mfma_f32_16x16x32_bf16 v[32:35], v[172:175], v[216:219], v[32:35]
	v_mfma_f32_16x16x32_bf16 v[20:23], v[164:167], v[224:227], v[20:23]
	v_mfma_f32_16x16x32_bf16 v[16:19], v[172:175], v[224:227], v[16:19]
	v_mfma_f32_16x16x32_bf16 v[44:47], v[176:179], v[196:199], v[44:47]
	v_mfma_f32_16x16x32_bf16 v[40:43], v[184:187], v[196:199], v[40:43]
	v_mfma_f32_16x16x32_bf16 v[28:31], v[176:179], v[204:207], v[28:31]
	v_mfma_f32_16x16x32_bf16 v[24:27], v[184:187], v[204:207], v[24:27]
	v_mfma_f32_16x16x32_bf16 v[12:15], v[176:179], v[212:215], v[12:15]
	v_mfma_f32_16x16x32_bf16 v[8:11], v[184:187], v[212:215], v[8:11]
	v_mfma_f32_16x16x32_bf16 v[4:7], v[176:179], v[220:223], v[4:7]
	v_mfma_f32_16x16x32_bf16 v[0:3], v[184:187], v[220:223], v[0:3]
	v_mfma_f32_16x16x32_bf16 v[44:47], v[180:183], v[200:203], v[44:47]
	v_mfma_f32_16x16x32_bf16 v[40:43], v[192:195], v[200:203], v[40:43]
	v_mfma_f32_16x16x32_bf16 v[28:31], v[180:183], v[208:211], v[28:31]
	v_mfma_f32_16x16x32_bf16 v[24:27], v[192:195], v[208:211], v[24:27]
	v_mfma_f32_16x16x32_bf16 v[12:15], v[180:183], v[216:219], v[12:15]
	v_mfma_f32_16x16x32_bf16 v[8:11], v[192:195], v[216:219], v[8:11]
	v_mfma_f32_16x16x32_bf16 v[4:7], v[180:183], v[224:227], v[4:7]
	v_mfma_f32_16x16x32_bf16 v[0:3], v[192:195], v[224:227], v[0:3]
	s_barrier
; #define PG8_STAGE(bufoff, gbase, voff) do { _Pragma("unroll") for (int _i = 0; _i < 2; ++_i) \
;         __builtin_amdgcn_global_load_lds((const unsigned*)((const char*)(gbase) + (voff)[_i]), (LAS unsigned*)(lds + (bufoff) + ldsw + _i * 8192), 16, 0, 0); } while (0)
; #define PG8_LDA(dst, b, h) do { _Pragma("unroll") for (int m = 0; m < 4; ++m) _Pragma("unroll") for (int k = 0; k < 2; ++k) dst[m][k] = *(const LAS bf16x8*)(lds + PG8_SA(b, h) + aoff + m * 2048 + k * 1024); } while (0)
; #define PG8_LDB(dst, b, h) do { _Pragma("unroll") for (int n = 0; n < 2; ++n) _Pragma("unroll") for (int k = 0; k < 2; ++k) dst[n][k] = *(const LAS bf16x8*)(lds + PG8_SB(b, h) + boff + n * 2048 + k * 1024); } while (0)
; #define PG8_MMA(ai, bj, At, Bt) do { __builtin_amdgcn_s_setprio(1); _Pragma("unroll") for (int m = 0; m < 4; ++m) _Pragma("unroll") for (int n = 0; n < 2; ++n) _Pragma("unroll") for (int k = 0; k < 2; ++k) \
;         acc[ai][bj][m][n] = __builtin_amdgcn_mfma_f32_16x16x32_bf16(Bt[n][k], At[m][k], acc[ai][bj][m][n], 0, 0, 0); __builtin_amdgcn_s_setprio(0); } while (0)
; #define PG8_WAIT_V(n) asm volatile("s_waitcnt vmcnt(" #n ")" ::: "memory")
; #define PG8_WAIT_L(n) asm volatile("s_waitcnt lgkmcnt(" #n ")" ::: "memory")
; #define PG8_BAR __builtin_amdgcn_s_barrier()
; #define PG8_SCHED __builtin_amdgcn_sched_barrier(0)
; template <int GI>
; __device__ __forceinline__ void gemm_phase(LAS unsigned char* lds, unsigned char* ws, int G, int cblk) {
;     ...
;             PG8_LDB(B0, 1, 0); PG8_LDB(B1, 1, 1); PG8_SCHED; PG8_LDA(At, 1, 0); PG8_STAGE(PG8_SA(0, 1), a2 + hstepA, voffA);
;             PG8_WAIT_V(8); PG8_WAIT_L(0); PG8_BAR; PG8_MMA(0, 0, At, B0); PG8_MMA(0, 1, At, B1); PG8_BAR; PG8_SCHED;
;             PG8_LDA(At, 1, 1); PG8_STAGE(PG8_SB(1, 0), b3, voffB); PG8_STAGE(PG8_SB(1, 1), b3 + hstepB, voffB); PG8_STAGE(PG8_SA(1, 0), a3, voffA);
;             PG8_WAIT_V(8); PG8_WAIT_L(0); PG8_BAR; PG8_MMA(1, 0, At, B0); PG8_MMA(1, 1, At, B1); PG8_BAR; PG8_SCHED;
;         }
	s_add_i32 s34, 0, 0x18000
	v_add_u32_e32 v161, s34, v150
	s_add_i32 s53, 0, 0x1c000
	ds_read_b128 v[154:157], v161
	ds_read_b128 v[164:167], v161 offset:1024
	ds_read_b128 v[168:171], v161 offset:2048
	ds_read_b128 v[172:175], v161 offset:3072
	v_add_u32_e32 v161, s53, v150
	ds_read_b128 v[176:179], v161
	ds_read_b128 v[180:183], v161 offset:1024
	ds_read_b128 v[184:187], v161 offset:2048
	ds_read_b128 v[192:195], v161 offset:3072
	s_add_u32 s50, s50, 0x80000
	s_addc_u32 s51, s51, 0
	s_mov_b32 m0, s22
	v_lshl_add_u64 v[232:233], s[50:51], 0, v[134:135]
	ds_read_b128 v[196:199], v153 offset:32768
	ds_read_b128 v[200:203], v153 offset:33792
	ds_read_b128 v[204:207], v153 offset:34816
	ds_read_b128 v[208:211], v153 offset:35840
	ds_read_b128 v[212:215], v153 offset:36864
	ds_read_b128 v[216:219], v153 offset:37888
	ds_read_b128 v[220:223], v153 offset:38912
	ds_read_b128 v[224:227], v153 offset:39936
	global_load_lds_dwordx4 v[232:233], off
	v_lshl_add_u64 v[232:233], s[50:51], 0, v[130:131]
	s_mov_b32 m0, s23
	s_nop 0
	global_load_lds_dwordx4 v[232:233], off
	s_waitcnt vmcnt(8)
	s_waitcnt lgkmcnt(0)
	s_barrier
	s_waitcnt lgkmcnt(0)
	v_mfma_f32_16x16x32_bf16 v[124:127], v[154:157], v[196:199], v[124:127]
	v_mfma_f32_16x16x32_bf16 v[120:123], v[168:171], v[196:199], v[120:123]
	v_mfma_f32_16x16x32_bf16 v[116:119], v[154:157], v[204:207], v[116:119]
	v_mfma_f32_16x16x32_bf16 v[112:115], v[168:171], v[204:207], v[112:115]
	v_mfma_f32_16x16x32_bf16 v[100:103], v[154:157], v[212:215], v[100:103]
	v_mfma_f32_16x16x32_bf16 v[96:99], v[168:171], v[212:215], v[96:99]
	v_mfma_f32_16x16x32_bf16 v[84:87], v[154:157], v[220:223], v[84:87]
	v_mfma_f32_16x16x32_bf16 v[80:83], v[168:171], v[220:223], v[80:83]
	v_mfma_f32_16x16x32_bf16 v[124:127], v[164:167], v[200:203], v[124:127]
	v_mfma_f32_16x16x32_bf16 v[120:123], v[172:175], v[200:203], v[120:123]
	v_mfma_f32_16x16x32_bf16 v[116:119], v[164:167], v[208:211], v[116:119]
	v_mfma_f32_16x16x32_bf16 v[112:115], v[172:175], v[208:211], v[112:115]
	v_mfma_f32_16x16x32_bf16 v[100:103], v[164:167], v[216:219], v[100:103]
	v_mfma_f32_16x16x32_bf16 v[96:99], v[172:175], v[216:219], v[96:99]
	v_mfma_f32_16x16x32_bf16 v[84:87], v[164:167], v[224:227], v[84:87]
	v_mfma_f32_16x16x32_bf16 v[80:83], v[172:175], v[224:227], v[80:83]
	v_mfma_f32_16x16x32_bf16 v[108:111], v[176:179], v[196:199], v[108:111]
	v_mfma_f32_16x16x32_bf16 v[104:107], v[184:187], v[196:199], v[104:107]
	v_mfma_f32_16x16x32_bf16 v[92:95], v[176:179], v[204:207], v[92:95]
	v_mfma_f32_16x16x32_bf16 v[88:91], v[184:187], v[204:207], v[88:91]
	v_mfma_f32_16x16x32_bf16 v[76:79], v[176:179], v[212:215], v[76:79]
	v_mfma_f32_16x16x32_bf16 v[72:75], v[184:187], v[212:215], v[72:75]
	v_mfma_f32_16x16x32_bf16 v[68:71], v[176:179], v[220:223], v[68:71]
	v_mfma_f32_16x16x32_bf16 v[64:67], v[184:187], v[220:223], v[64:67]
	v_mfma_f32_16x16x32_bf16 v[108:111], v[180:183], v[200:203], v[108:111]
	v_mfma_f32_16x16x32_bf16 v[104:107], v[192:195], v[200:203], v[104:107]
	v_mfma_f32_16x16x32_bf16 v[92:95], v[180:183], v[208:211], v[92:95]
	v_mfma_f32_16x16x32_bf16 v[88:91], v[192:195], v[208:211], v[88:91]
	v_mfma_f32_16x16x32_bf16 v[76:79], v[180:183], v[216:219], v[76:79]
	v_mfma_f32_16x16x32_bf16 v[72:75], v[192:195], v[216:219], v[72:75]
	v_mfma_f32_16x16x32_bf16 v[68:71], v[180:183], v[224:227], v[68:71]
	v_mfma_f32_16x16x32_bf16 v[64:67], v[192:195], v[224:227], v[64:67]
	s_barrier
	s_add_i32 s34, s34, s0
	v_lshl_add_u64 v[158:159], v[158:159], 0, s[8:9]
	s_mov_b32 m0, s34
	ds_read_b128 v[196:199], v153 offset:49152
	ds_read_b128 v[200:203], v153 offset:50176
	ds_read_b128 v[204:207], v153 offset:51200
	ds_read_b128 v[208:211], v153 offset:52224
	ds_read_b128 v[212:215], v153 offset:53248
	ds_read_b128 v[216:219], v153 offset:54272
	ds_read_b128 v[220:223], v153 offset:55296
	ds_read_b128 v[224:227], v153 offset:56320
	global_load_lds_dwordx4 v[158:159], off
	s_add_i32 m0, s34, 0x2000
	s_add_u32 s48, s48, 0x100080
	v_lshl_add_u64 v[158:159], v[188:189], 0, s[8:9]
	s_addc_u32 s49, s49, 0
	s_add_i32 s34, s53, s0
	global_load_lds_dwordx4 v[158:159], off
	v_lshl_add_u64 v[158:159], s[48:49], 0, v[132:133]
	s_mov_b32 m0, s34
	s_nop 0
	global_load_lds_dwordx4 v[158:159], off
	v_lshl_add_u64 v[158:159], s[48:49], 0, v[128:129]
	s_add_i32 m0, s34, 0x2000
	s_nop 0
	global_load_lds_dwordx4 v[158:159], off
	v_lshl_add_u64 v[158:159], v[228:229], 0, s[8:9]
	s_mov_b32 m0, s26
	s_nop 0
	global_load_lds_dwordx4 v[158:159], off
	v_lshl_add_u64 v[158:159], v[230:231], 0, s[8:9]
	s_mov_b32 m0, s27
	s_nop 0
	global_load_lds_dwordx4 v[158:159], off
	s_waitcnt vmcnt(8)
	s_waitcnt lgkmcnt(0)
	s_barrier
	s_waitcnt lgkmcnt(0)
	v_mfma_f32_16x16x32_bf16 v[60:63], v[154:157], v[196:199], v[60:63]
	v_mfma_f32_16x16x32_bf16 v[56:59], v[168:171], v[196:199], v[56:59]
	v_mfma_f32_16x16x32_bf16 v[52:55], v[154:157], v[204:207], v[52:55]
	v_mfma_f32_16x16x32_bf16 v[48:51], v[168:171], v[204:207], v[48:51]
	v_mfma_f32_16x16x32_bf16 v[36:39], v[154:157], v[212:215], v[36:39]
	v_mfma_f32_16x16x32_bf16 v[32:35], v[168:171], v[212:215], v[32:35]
	v_mfma_f32_16x16x32_bf16 v[20:23], v[154:157], v[220:223], v[20:23]
	v_mfma_f32_16x16x32_bf16 v[16:19], v[168:171], v[220:223], v[16:19]
	v_mfma_f32_16x16x32_bf16 v[60:63], v[164:167], v[200:203], v[60:63]
	v_mfma_f32_16x16x32_bf16 v[56:59], v[172:175], v[200:203], v[56:59]
	v_mfma_f32_16x16x32_bf16 v[52:55], v[164:167], v[208:211], v[52:55]
	v_mfma_f32_16x16x32_bf16 v[48:51], v[172:175], v[208:211], v[48:51]
	v_mfma_f32_16x16x32_bf16 v[36:39], v[164:167], v[216:219], v[36:39]
	v_mfma_f32_16x16x32_bf16 v[32:35], v[172:175], v[216:219], v[32:35]
	v_mfma_f32_16x16x32_bf16 v[20:23], v[164:167], v[224:227], v[20:23]
	v_mfma_f32_16x16x32_bf16 v[16:19], v[172:175], v[224:227], v[16:19]
	v_mfma_f32_16x16x32_bf16 v[44:47], v[176:179], v[196:199], v[44:47]
	v_mfma_f32_16x16x32_bf16 v[40:43], v[184:187], v[196:199], v[40:43]
	v_mfma_f32_16x16x32_bf16 v[28:31], v[176:179], v[204:207], v[28:31]
	v_mfma_f32_16x16x32_bf16 v[24:27], v[184:187], v[204:207], v[24:27]
	v_mfma_f32_16x16x32_bf16 v[12:15], v[176:179], v[212:215], v[12:15]
	v_mfma_f32_16x16x32_bf16 v[8:11], v[184:187], v[212:215], v[8:11]
	v_mfma_f32_16x16x32_bf16 v[4:7], v[176:179], v[220:223], v[4:7]
	v_mfma_f32_16x16x32_bf16 v[0:3], v[184:187], v[220:223], v[0:3]
	v_mfma_f32_16x16x32_bf16 v[44:47], v[180:183], v[200:203], v[44:47]
	v_mfma_f32_16x16x32_bf16 v[40:43], v[192:195], v[200:203], v[40:43]
	v_mfma_f32_16x16x32_bf16 v[28:31], v[180:183], v[208:211], v[28:31]
	v_mfma_f32_16x16x32_bf16 v[24:27], v[192:195], v[208:211], v[24:27]
	v_mfma_f32_16x16x32_bf16 v[12:15], v[180:183], v[216:219], v[12:15]
	v_mfma_f32_16x16x32_bf16 v[8:11], v[192:195], v[216:219], v[8:11]
	v_mfma_f32_16x16x32_bf16 v[4:7], v[180:183], v[224:227], v[4:7]
	v_mfma_f32_16x16x32_bf16 v[0:3], v[192:195], v[224:227], v[0:3]
	s_barrier
	s_add_i32 s19, s19, 2
	s_add_u32 s46, s46, 0x100
	s_addc_u32 s47, s47, 0
	s_add_u32 s14, s14, 0x100
	s_addc_u32 s15, s15, 0
	s_cmp_gt_u32 s19, 5
	s_cbranch_scc0 .LBB0_432

; #define PG8_STAGE(bufoff, gbase, voff) do { _Pragma("unroll") for (int _i = 0; _i < 2; ++_i) \
;         __builtin_amdgcn_global_load_lds((const unsigned*)((const char*)(gbase) + (voff)[_i]), (LAS unsigned*)(lds + (bufoff) + ldsw + _i * 8192), 16, 0, 0); } while (0)
; #define PG8_LDA(dst, b, h) do { _Pragma("unroll") for (int m = 0; m < 4; ++m) _Pragma("unroll") for (int k = 0; k < 2; ++k) dst[m][k] = *(const LAS bf16x8*)(lds + PG8_SA(b, h) + aoff + m * 2048 + k * 1024); } while (0)
; #define PG8_LDB(dst, b, h) do { _Pragma("unroll") for (int n = 0; n < 2; ++n) _Pragma("unroll") for (int k = 0; k < 2; ++k) dst[n][k] = *(const LAS bf16x8*)(lds + PG8_SB(b, h) + boff + n * 2048 + k * 1024); } while (0)
; #define PG8_MMA(ai, bj, At, Bt) do { __builtin_amdgcn_s_setprio(1); _Pragma("unroll") for (int m = 0; m < 4; ++m) _Pragma("unroll") for (int n = 0; n < 2; ++n) _Pragma("unroll") for (int k = 0; k < 2; ++k) \
;         acc[ai][bj][m][n] = __builtin_amdgcn_mfma_f32_16x16x32_bf16(Bt[n][k], At[m][k], acc[ai][bj][m][n], 0, 0, 0); __builtin_amdgcn_s_setprio(0); } while (0)
; #define PG8_WAIT_V(n) asm volatile("s_waitcnt vmcnt(" #n ")" ::: "memory")
; #define PG8_WAIT_L(n) asm volatile("s_waitcnt lgkmcnt(" #n ")" ::: "memory")
; #define PG8_BAR __builtin_amdgcn_s_barrier()
; #define PG8_SCHED __builtin_amdgcn_sched_barrier(0)
; template <int GI>
; __device__ __forceinline__ void gemm_phase(LAS unsigned char* lds, unsigned char* ws, int G, int cblk) {
;     ...
;         for (int t = 0; t < nt; t += 2) {
;             const bool last = (t == nt - 2);
;             const char* a1 = cA + (size_t)(t + 1) * kstep;
;             const char* a2 = last ? nA : cA + (size_t)(t + 2) * kstep; const char* b2 = last ? nB : cB + (size_t)(t + 2) * kstep;
;             const char* a3 = a2 + kstep; const char* b3 = b2 + kstep;
;             PG8_LDB(B0, 0, 0); PG8_LDB(B1, 0, 1); PG8_SCHED; PG8_LDA(At, 0, 0); PG8_STAGE(PG8_SA(1, 1), a1 + hstepA, voffA);
;             PG8_WAIT_V(8); PG8_WAIT_L(0); PG8_BAR; PG8_MMA(0, 0, At, B0); PG8_MMA(0, 1, At, B1); PG8_BAR; PG8_SCHED;
;             PG8_LDA(At, 0, 1); PG8_STAGE(PG8_SB(0, 0), b2, voffB); PG8_STAGE(PG8_SB(0, 1), b2 + hstepB, voffB); PG8_STAGE(PG8_SA(0, 0), a2, voffA);
.LBB0_564:
	s_add_u32 s48, s48, 0x80080
	s_addc_u32 s49, s49, 0
	s_add_u32 s0, s50, 0x100
	s_addc_u32 s1, s51, 0
	s_mov_b32 s16, -2
	ds_read_b128 v[152:155], v167
	ds_read_b128 v[156:159], v167 offset:1024
	ds_read_b128 v[172:175], v167 offset:2048
	ds_read_b128 v[176:179], v167 offset:3072
	ds_read_b128 v[180:183], v168
	ds_read_b128 v[184:187], v168 offset:1024
	ds_read_b128 v[192:195], v168 offset:2048
	ds_read_b128 v[196:199], v168 offset:3072
	s_add_u32 s17, s48, 0xfff80080
	s_addc_u32 s33, s49, -1
	s_cmp_eq_u32 s16, 28
	s_cselect_b32 s53, s41, s33
	s_cselect_b32 s52, s40, s17
	s_cselect_b32 s51, s43, s1
	s_cselect_b32 s50, s42, s0
	v_lshl_add_u64 v[164:165], s[48:49], 0, v[148:149]
	s_add_i32 m0, s23, 0xc000
	ds_read_b128 v[200:203], v169
	ds_read_b128 v[204:207], v169 offset:1024
	ds_read_b128 v[208:211], v169 offset:2048
	ds_read_b128 v[212:215], v169 offset:3072
	ds_read_b128 v[216:219], v169 offset:4096
	ds_read_b128 v[220:223], v169 offset:5120
	ds_read_b128 v[224:227], v169 offset:6144
	ds_read_b128 v[228:231], v169 offset:7168
	global_load_lds_dwordx4 v[164:165], off
	v_lshl_add_u64 v[164:165], s[48:49], 0, v[150:151]
	s_add_i32 m0, s23, 0xe000
	s_nop 0
	global_load_lds_dwordx4 v[164:165], off
	s_waitcnt vmcnt(8)
	s_waitcnt lgkmcnt(0)
	s_barrier
	s_waitcnt lgkmcnt(0)
	v_mfma_f32_16x16x32_bf16 v[124:127], v[152:155], v[200:203], 0
	v_mfma_f32_16x16x32_bf16 v[120:123], v[172:175], v[200:203], 0
	v_mfma_f32_16x16x32_bf16 v[108:111], v[152:155], v[208:211], 0
	v_mfma_f32_16x16x32_bf16 v[104:107], v[172:175], v[208:211], 0
	v_mfma_f32_16x16x32_bf16 v[92:95], v[152:155], v[216:219], 0
	v_mfma_f32_16x16x32_bf16 v[88:91], v[172:175], v[216:219], 0
	v_mfma_f32_16x16x32_bf16 v[76:79], v[152:155], v[224:227], 0
	v_mfma_f32_16x16x32_bf16 v[72:75], v[172:175], v[224:227], 0
	v_mfma_f32_16x16x32_bf16 v[124:127], v[156:159], v[204:207], v[124:127]
	v_mfma_f32_16x16x32_bf16 v[120:123], v[176:179], v[204:207], v[120:123]
	v_mfma_f32_16x16x32_bf16 v[108:111], v[156:159], v[212:215], v[108:111]
	v_mfma_f32_16x16x32_bf16 v[104:107], v[176:179], v[212:215], v[104:107]
	v_mfma_f32_16x16x32_bf16 v[92:95], v[156:159], v[220:223], v[92:95]
	v_mfma_f32_16x16x32_bf16 v[88:91], v[176:179], v[220:223], v[88:91]
	v_mfma_f32_16x16x32_bf16 v[76:79], v[156:159], v[228:231], v[76:79]
	v_mfma_f32_16x16x32_bf16 v[72:75], v[176:179], v[228:231], v[72:75]
	v_mfma_f32_16x16x32_bf16 v[116:119], v[180:183], v[200:203], 0
	v_mfma_f32_16x16x32_bf16 v[112:115], v[192:195], v[200:203], 0
	v_mfma_f32_16x16x32_bf16 v[100:103], v[180:183], v[208:211], 0
	v_mfma_f32_16x16x32_bf16 v[96:99], v[192:195], v[208:211], 0
	v_mfma_f32_16x16x32_bf16 v[84:87], v[180:183], v[216:219], 0
	v_mfma_f32_16x16x32_bf16 v[80:83], v[192:195], v[216:219], 0
	v_mfma_f32_16x16x32_bf16 v[68:71], v[180:183], v[224:227], 0
	v_mfma_f32_16x16x32_bf16 v[64:67], v[192:195], v[224:227], 0
	v_mfma_f32_16x16x32_bf16 v[116:119], v[184:187], v[204:207], v[116:119]
	v_mfma_f32_16x16x32_bf16 v[112:115], v[196:199], v[204:207], v[112:115]
	v_mfma_f32_16x16x32_bf16 v[100:103], v[184:187], v[212:215], v[100:103]
	v_mfma_f32_16x16x32_bf16 v[96:99], v[196:199], v[212:215], v[96:99]
	v_mfma_f32_16x16x32_bf16 v[84:87], v[184:187], v[220:223], v[84:87]
	v_mfma_f32_16x16x32_bf16 v[80:83], v[196:199], v[220:223], v[80:83]
	v_mfma_f32_16x16x32_bf16 v[68:71], v[184:187], v[228:231], v[68:71]
	v_mfma_f32_16x16x32_bf16 v[64:67], v[196:199], v[228:231], v[64:67]
	s_barrier
	s_add_i32 s17, s60, s22
	v_lshl_add_u64 v[164:165], s[50:51], 0, v[132:133]
	s_mov_b32 m0, s17
	ds_read_b128 v[200:203], v169 offset:16384
	ds_read_b128 v[204:207], v169 offset:17408
	ds_read_b128 v[208:211], v169 offset:18432
	ds_read_b128 v[212:215], v169 offset:19456
	ds_read_b128 v[216:219], v169 offset:20480
	ds_read_b128 v[220:223], v169 offset:21504
	ds_read_b128 v[224:227], v169 offset:22528
	ds_read_b128 v[228:231], v169 offset:23552
	global_load_lds_dwordx4 v[164:165], off
	s_add_i32 m0, s17, 0x2000
	s_add_u32 s64, s50, 0x80000
	v_lshl_add_u64 v[188:189], s[50:51], 0, v[136:137]
	s_addc_u32 s65, s51, 0
	s_add_i32 s17, s61, s22
	global_load_lds_dwordx4 v[188:189], off
	v_lshl_add_u64 v[232:233], s[64:65], 0, v[132:133]
	s_mov_b32 m0, s17
	v_lshl_add_u64 v[234:235], s[52:53], 0, v[134:135]
	global_load_lds_dwordx4 v[232:233], off
	v_lshl_add_u64 v[232:233], s[64:65], 0, v[136:137]
	s_add_i32 m0, s17, 0x2000
	s_nop 0
	global_load_lds_dwordx4 v[232:233], off
	v_lshl_add_u64 v[232:233], s[52:53], 0, v[130:131]
	s_mov_b32 m0, s23
	s_nop 0
	global_load_lds_dwordx4 v[232:233], off
	s_mov_b32 m0, s24
	s_nop 0
	global_load_lds_dwordx4 v[234:235], off
	s_waitcnt vmcnt(8)
	s_waitcnt lgkmcnt(0)
	s_barrier
; #define PG8_STAGE(bufoff, gbase, voff) do { _Pragma("unroll") for (int _i = 0; _i < 2; ++_i) \
;         __builtin_amdgcn_global_load_lds((const unsigned*)((const char*)(gbase) + (voff)[_i]), (LAS unsigned*)(lds + (bufoff) + ldsw + _i * 8192), 16, 0, 0); } while (0)
; #define PG8_LDA(dst, b, h) do { _Pragma("unroll") for (int m = 0; m < 4; ++m) _Pragma("unroll") for (int k = 0; k < 2; ++k) dst[m][k] = *(const LAS bf16x8*)(lds + PG8_SA(b, h) + aoff + m * 2048 + k * 1024); } while (0)
; #define PG8_LDB(dst, b, h) do { _Pragma("unroll") for (int n = 0; n < 2; ++n) _Pragma("unroll") for (int k = 0; k < 2; ++k) dst[n][k] = *(const LAS bf16x8*)(lds + PG8_SB(b, h) + boff + n * 2048 + k * 1024); } while (0)
; #define PG8_MMA(ai, bj, At, Bt) do { __builtin_amdgcn_s_setprio(1); _Pragma("unroll") for (int m = 0; m < 4; ++m) _Pragma("unroll") for (int n = 0; n < 2; ++n) _Pragma("unroll") for (int k = 0; k < 2; ++k) \
;         acc[ai][bj][m][n] = __builtin_amdgcn_mfma_f32_16x16x32_bf16(Bt[n][k], At[m][k], acc[ai][bj][m][n], 0, 0, 0); __builtin_amdgcn_s_setprio(0); } while (0)
; #define PG8_WAIT_V(n) asm volatile("s_waitcnt vmcnt(" #n ")" ::: "memory")
; #define PG8_WAIT_L(n) asm volatile("s_waitcnt lgkmcnt(" #n ")" ::: "memory")
; #define PG8_BAR __builtin_amdgcn_s_barrier()
; #define PG8_SCHED __builtin_amdgcn_sched_barrier(0)
; template <int GI>
; __device__ __forceinline__ void gemm_phase(LAS unsigned char* lds, unsigned char* ws, int G, int cblk) {
;     ...
;             PG8_WAIT_V(8); PG8_WAIT_L(0); PG8_BAR; PG8_MMA(0, 0, At, B0); PG8_MMA(0, 1, At, B1); PG8_BAR; PG8_SCHED;
;             PG8_LDA(At, 0, 1); PG8_STAGE(PG8_SB(0, 0), b2, voffB); PG8_STAGE(PG8_SB(0, 1), b2 + hstepB, voffB); PG8_STAGE(PG8_SA(0, 0), a2, voffA);
;             PG8_WAIT_V(8); PG8_WAIT_L(0); PG8_BAR; PG8_MMA(1, 0, At, B0); PG8_MMA(1, 1, At, B1); PG8_BAR; PG8_SCHED;
;             PG8_LDB(B0, 1, 0); PG8_LDB(B1, 1, 1); PG8_SCHED; PG8_LDA(At, 1, 0); PG8_STAGE(PG8_SA(0, 1), a2 + hstepA, voffA);
;             PG8_WAIT_V(8); PG8_WAIT_L(0); PG8_BAR; PG8_MMA(0, 0, At, B0); PG8_MMA(0, 1, At, B1); PG8_BAR; PG8_SCHED;
	s_waitcnt lgkmcnt(0)
	v_mfma_f32_16x16x32_bf16 v[60:63], v[152:155], v[200:203], 0
	v_mfma_f32_16x16x32_bf16 v[56:59], v[172:175], v[200:203], 0
	v_mfma_f32_16x16x32_bf16 v[44:47], v[152:155], v[208:211], 0
	v_mfma_f32_16x16x32_bf16 v[40:43], v[172:175], v[208:211], 0
	v_mfma_f32_16x16x32_bf16 v[28:31], v[152:155], v[216:219], 0
	v_mfma_f32_16x16x32_bf16 v[24:27], v[172:175], v[216:219], 0
	v_mfma_f32_16x16x32_bf16 v[12:15], v[152:155], v[224:227], 0
	v_mfma_f32_16x16x32_bf16 v[8:11], v[172:175], v[224:227], 0
	v_mfma_f32_16x16x32_bf16 v[60:63], v[156:159], v[204:207], v[60:63]
	v_mfma_f32_16x16x32_bf16 v[56:59], v[176:179], v[204:207], v[56:59]
	v_mfma_f32_16x16x32_bf16 v[44:47], v[156:159], v[212:215], v[44:47]
	v_mfma_f32_16x16x32_bf16 v[40:43], v[176:179], v[212:215], v[40:43]
	v_mfma_f32_16x16x32_bf16 v[28:31], v[156:159], v[220:223], v[28:31]
	v_mfma_f32_16x16x32_bf16 v[24:27], v[176:179], v[220:223], v[24:27]
	v_mfma_f32_16x16x32_bf16 v[12:15], v[156:159], v[228:231], v[12:15]
	v_mfma_f32_16x16x32_bf16 v[8:11], v[176:179], v[228:231], v[8:11]
	v_mfma_f32_16x16x32_bf16 v[52:55], v[180:183], v[200:203], 0
	v_mfma_f32_16x16x32_bf16 v[48:51], v[192:195], v[200:203], 0
	v_mfma_f32_16x16x32_bf16 v[36:39], v[180:183], v[208:211], 0
	v_mfma_f32_16x16x32_bf16 v[32:35], v[192:195], v[208:211], 0
	v_mfma_f32_16x16x32_bf16 v[20:23], v[180:183], v[216:219], 0
	v_mfma_f32_16x16x32_bf16 v[16:19], v[192:195], v[216:219], 0
	v_mfma_f32_16x16x32_bf16 v[4:7], v[180:183], v[224:227], 0
	v_mfma_f32_16x16x32_bf16 v[0:3], v[192:195], v[224:227], 0
	v_mfma_f32_16x16x32_bf16 v[52:55], v[184:187], v[204:207], v[52:55]
	v_mfma_f32_16x16x32_bf16 v[48:51], v[196:199], v[204:207], v[48:51]
	v_mfma_f32_16x16x32_bf16 v[36:39], v[184:187], v[212:215], v[36:39]
	v_mfma_f32_16x16x32_bf16 v[32:35], v[196:199], v[212:215], v[32:35]
	v_mfma_f32_16x16x32_bf16 v[20:23], v[184:187], v[220:223], v[20:23]
	v_mfma_f32_16x16x32_bf16 v[16:19], v[196:199], v[220:223], v[16:19]
	v_mfma_f32_16x16x32_bf16 v[4:7], v[184:187], v[228:231], v[4:7]
	v_mfma_f32_16x16x32_bf16 v[0:3], v[196:199], v[228:231], v[0:3]
	s_barrier
	s_add_i32 s17, 0, 0x18000
	s_add_i32 s33, 0, 0x1c000
	v_add_u32_e32 v176, s17, v161
	v_add_u32_e32 v191, s33, v161
	ds_read_b128 v[152:155], v176
	ds_read_b128 v[156:159], v176 offset:1024
	ds_read_b128 v[172:175], v176 offset:2048
	ds_read_b128 v[176:179], v176 offset:3072
	ds_read_b128 v[180:183], v191
	ds_read_b128 v[184:187], v191 offset:1024
	ds_read_b128 v[192:195], v191 offset:2048
	ds_read_b128 v[196:199], v191 offset:3072
	s_add_u32 s52, s52, 0x80000
	s_addc_u32 s53, s53, 0
	s_mov_b32 m0, s25
	v_lshl_add_u64 v[236:237], s[52:53], 0, v[130:131]
	ds_read_b128 v[200:203], v169 offset:32768
	ds_read_b128 v[204:207], v169 offset:33792
	ds_read_b128 v[208:211], v169 offset:34816
	ds_read_b128 v[212:215], v169 offset:35840
	ds_read_b128 v[216:219], v169 offset:36864
	ds_read_b128 v[220:223], v169 offset:37888
	ds_read_b128 v[224:227], v169 offset:38912
	ds_read_b128 v[228:231], v169 offset:39936
	global_load_lds_dwordx4 v[236:237], off
	v_lshl_add_u64 v[236:237], s[52:53], 0, v[134:135]
	s_mov_b32 m0, s26
	s_nop 0
	global_load_lds_dwordx4 v[236:237], off
	s_waitcnt vmcnt(8)
	s_waitcnt lgkmcnt(0)
	s_barrier
	s_waitcnt lgkmcnt(0)
	v_mfma_f32_16x16x32_bf16 v[124:127], v[152:155], v[200:203], v[124:127]
	v_mfma_f32_16x16x32_bf16 v[120:123], v[172:175], v[200:203], v[120:123]
	v_mfma_f32_16x16x32_bf16 v[108:111], v[152:155], v[208:211], v[108:111]
	v_mfma_f32_16x16x32_bf16 v[104:107], v[172:175], v[208:211], v[104:107]
	v_mfma_f32_16x16x32_bf16 v[92:95], v[152:155], v[216:219], v[92:95]
	v_mfma_f32_16x16x32_bf16 v[88:91], v[172:175], v[216:219], v[88:91]
	v_mfma_f32_16x16x32_bf16 v[76:79], v[152:155], v[224:227], v[76:79]
	v_mfma_f32_16x16x32_bf16 v[72:75], v[172:175], v[224:227], v[72:75]
	v_mfma_f32_16x16x32_bf16 v[124:127], v[156:159], v[204:207], v[124:127]
	v_mfma_f32_16x16x32_bf16 v[120:123], v[176:179], v[204:207], v[120:123]
	v_mfma_f32_16x16x32_bf16 v[108:111], v[156:159], v[212:215], v[108:111]
	v_mfma_f32_16x16x32_bf16 v[104:107], v[176:179], v[212:215], v[104:107]
	v_mfma_f32_16x16x32_bf16 v[92:95], v[156:159], v[220:223], v[92:95]
	v_mfma_f32_16x16x32_bf16 v[88:91], v[176:179], v[220:223], v[88:91]
	v_mfma_f32_16x16x32_bf16 v[76:79], v[156:159], v[228:231], v[76:79]
	v_mfma_f32_16x16x32_bf16 v[72:75], v[176:179], v[228:231], v[72:75]
	v_mfma_f32_16x16x32_bf16 v[116:119], v[180:183], v[200:203], v[116:119]
	v_mfma_f32_16x16x32_bf16 v[112:115], v[192:195], v[200:203], v[112:115]
	v_mfma_f32_16x16x32_bf16 v[100:103], v[180:183], v[208:211], v[100:103]
	v_mfma_f32_16x16x32_bf16 v[96:99], v[192:195], v[208:211], v[96:99]
	v_mfma_f32_16x16x32_bf16 v[84:87], v[180:183], v[216:219], v[84:87]
	v_mfma_f32_16x16x32_bf16 v[80:83], v[192:195], v[216:219], v[80:83]
	v_mfma_f32_16x16x32_bf16 v[68:71], v[180:183], v[224:227], v[68:71]
	v_mfma_f32_16x16x32_bf16 v[64:67], v[192:195], v[224:227], v[64:67]
	v_mfma_f32_16x16x32_bf16 v[116:119], v[184:187], v[204:207], v[116:119]
	v_mfma_f32_16x16x32_bf16 v[112:115], v[196:199], v[204:207], v[112:115]
	v_mfma_f32_16x16x32_bf16 v[100:103], v[184:187], v[212:215], v[100:103]
	v_mfma_f32_16x16x32_bf16 v[96:99], v[196:199], v[212:215], v[96:99]
	v_mfma_f32_16x16x32_bf16 v[84:87], v[184:187], v[220:223], v[84:87]
	v_mfma_f32_16x16x32_bf16 v[80:83], v[196:199], v[220:223], v[80:83]
	v_mfma_f32_16x16x32_bf16 v[68:71], v[184:187], v[228:231], v[68:71]
	v_mfma_f32_16x16x32_bf16 v[64:67], v[196:199], v[228:231], v[64:67]
	s_barrier
; #define PG8_STAGE(bufoff, gbase, voff) do { _Pragma("unroll") for (int _i = 0; _i < 2; ++_i) \
;         __builtin_amdgcn_global_load_lds((const unsigned*)((const char*)(gbase) + (voff)[_i]), (LAS unsigned*)(lds + (bufoff) + ldsw + _i * 8192), 16, 0, 0); } while (0)
; #define PG8_LDA(dst, b, h) do { _Pragma("unroll") for (int m = 0; m < 4; ++m) _Pragma("unroll") for (int k = 0; k < 2; ++k) dst[m][k] = *(const LAS bf16x8*)(lds + PG8_SA(b, h) + aoff + m * 2048 + k * 1024); } while (0)
; #define PG8_LDB(dst, b, h) do { _Pragma("unroll") for (int n = 0; n < 2; ++n) _Pragma("unroll") for (int k = 0; k < 2; ++k) dst[n][k] = *(const LAS bf16x8*)(lds + PG8_SB(b, h) + boff + n * 2048 + k * 1024); } while (0)
; #define PG8_WAIT_V(n) asm volatile("s_waitcnt vmcnt(" #n ")" ::: "memory")
; #define PG8_WAIT_L(n) asm volatile("s_waitcnt lgkmcnt(" #n ")" ::: "memory")
; template <int GI>
; __device__ __forceinline__ void gemm_phase(LAS unsigned char* lds, unsigned char* ws, int G, int cblk) {
;     ...
;         for (int t = 0; t < nt; t += 2) {
;             const bool last = (t == nt - 2);
;             const char* a1 = cA + (size_t)(t + 1) * kstep;
;             const char* a2 = last ? nA : cA + (size_t)(t + 2) * kstep; const char* b2 = last ? nB : cB + (size_t)(t + 2) * kstep;
;             const char* a3 = a2 + kstep; const char* b3 = b2 + kstep;
;             PG8_LDB(B0, 0, 0); PG8_LDB(B1, 0, 1); PG8_SCHED; PG8_LDA(At, 0, 0); PG8_STAGE(PG8_SA(1, 1), a1 + hstepA, voffA);
;             PG8_WAIT_V(8); PG8_WAIT_L(0); PG8_BAR; PG8_MMA(0, 0, At, B0); PG8_MMA(0, 1, At, B1); PG8_BAR; PG8_SCHED;
;             PG8_LDA(At, 0, 1); PG8_STAGE(PG8_SB(0, 0), b2, voffB); PG8_STAGE(PG8_SB(0, 1), b2 + hstepB, voffB); PG8_STAGE(PG8_SA(0, 0), a2, voffA);
;             PG8_WAIT_V(8); PG8_WAIT_L(0); PG8_BAR; PG8_MMA(1, 0, At, B0); PG8_MMA(1, 1, At, B1); PG8_BAR; PG8_SCHED;
;             PG8_LDB(B0, 1, 0); PG8_LDB(B1, 1, 1); PG8_SCHED; PG8_LDA(At, 1, 0); PG8_STAGE(PG8_SA(0, 1), a2 + hstepA, voffA);
;             PG8_WAIT_V(8); PG8_WAIT_L(0); PG8_BAR; PG8_MMA(0, 0, At, B0); PG8_MMA(0, 1, At, B1); PG8_BAR; PG8_SCHED;
;             PG8_LDA(At, 1, 1); PG8_STAGE(PG8_SB(1, 0), b3, voffB); PG8_STAGE(PG8_SB(1, 1), b3 + hstepB, voffB); PG8_STAGE(PG8_SA(1, 0), a3, voffA);
;             PG8_WAIT_V(8); PG8_WAIT_L(0); PG8_BAR; PG8_MMA(1, 0, At, B0); PG8_MMA(1, 1, At, B1); PG8_BAR; PG8_SCHED;
	s_add_i32 s17, s17, s22
	v_lshl_add_u64 v[164:165], v[164:165], 0, s[18:19]
	s_mov_b32 m0, s17
	ds_read_b128 v[200:203], v169 offset:49152
	ds_read_b128 v[204:207], v169 offset:50176
	ds_read_b128 v[208:211], v169 offset:51200
	ds_read_b128 v[212:215], v169 offset:52224
	ds_read_b128 v[216:219], v169 offset:53248
	ds_read_b128 v[220:223], v169 offset:54272
	ds_read_b128 v[224:227], v169 offset:55296
	ds_read_b128 v[228:231], v169 offset:56320
	global_load_lds_dwordx4 v[164:165], off
	s_add_i32 m0, s17, 0x2000
	s_add_u32 s50, s50, 0x80080
	v_lshl_add_u64 v[164:165], v[188:189], 0, s[18:19]
	s_addc_u32 s51, s51, 0
	s_add_i32 s17, s33, s22
	global_load_lds_dwordx4 v[164:165], off
	v_lshl_add_u64 v[164:165], s[50:51], 0, v[132:133]
	s_mov_b32 m0, s17
	s_nop 0
	global_load_lds_dwordx4 v[164:165], off
	v_lshl_add_u64 v[164:165], s[50:51], 0, v[136:137]
	s_add_i32 m0, s17, 0x2000
	s_nop 0
	global_load_lds_dwordx4 v[164:165], off
	v_lshl_add_u64 v[164:165], v[232:233], 0, s[18:19]
	s_mov_b32 m0, s35
	s_nop 0
	global_load_lds_dwordx4 v[164:165], off
	v_lshl_add_u64 v[164:165], v[234:235], 0, s[18:19]
	s_mov_b32 m0, s55
	s_nop 0
	global_load_lds_dwordx4 v[164:165], off
	s_waitcnt vmcnt(8)
	s_waitcnt lgkmcnt(0)
	s_barrier
	s_waitcnt lgkmcnt(0)
	v_mfma_f32_16x16x32_bf16 v[60:63], v[152:155], v[200:203], v[60:63]
	v_mfma_f32_16x16x32_bf16 v[56:59], v[172:175], v[200:203], v[56:59]
	v_mfma_f32_16x16x32_bf16 v[44:47], v[152:155], v[208:211], v[44:47]
	v_mfma_f32_16x16x32_bf16 v[40:43], v[172:175], v[208:211], v[40:43]
	v_mfma_f32_16x16x32_bf16 v[28:31], v[152:155], v[216:219], v[28:31]
	v_mfma_f32_16x16x32_bf16 v[24:27], v[172:175], v[216:219], v[24:27]
	v_mfma_f32_16x16x32_bf16 v[12:15], v[152:155], v[224:227], v[12:15]
	v_mfma_f32_16x16x32_bf16 v[8:11], v[172:175], v[224:227], v[8:11]
	v_mfma_f32_16x16x32_bf16 v[60:63], v[156:159], v[204:207], v[60:63]
	v_mfma_f32_16x16x32_bf16 v[56:59], v[176:179], v[204:207], v[56:59]
	v_mfma_f32_16x16x32_bf16 v[44:47], v[156:159], v[212:215], v[44:47]
	v_mfma_f32_16x16x32_bf16 v[40:43], v[176:179], v[212:215], v[40:43]
	v_mfma_f32_16x16x32_bf16 v[28:31], v[156:159], v[220:223], v[28:31]
	v_mfma_f32_16x16x32_bf16 v[24:27], v[176:179], v[220:223], v[24:27]
	v_mfma_f32_16x16x32_bf16 v[12:15], v[156:159], v[228:231], v[12:15]
	v_mfma_f32_16x16x32_bf16 v[8:11], v[176:179], v[228:231], v[8:11]
	v_mfma_f32_16x16x32_bf16 v[52:55], v[180:183], v[200:203], v[52:55]
	v_mfma_f32_16x16x32_bf16 v[48:51], v[192:195], v[200:203], v[48:51]
	v_mfma_f32_16x16x32_bf16 v[36:39], v[180:183], v[208:211], v[36:39]
	v_mfma_f32_16x16x32_bf16 v[32:35], v[192:195], v[208:211], v[32:35]
	v_mfma_f32_16x16x32_bf16 v[20:23], v[180:183], v[216:219], v[20:23]
	v_mfma_f32_16x16x32_bf16 v[16:19], v[192:195], v[216:219], v[16:19]
	v_mfma_f32_16x16x32_bf16 v[4:7], v[180:183], v[224:227], v[4:7]
	v_mfma_f32_16x16x32_bf16 v[0:3], v[192:195], v[224:227], v[0:3]
	v_mfma_f32_16x16x32_bf16 v[52:55], v[184:187], v[204:207], v[52:55]
	v_mfma_f32_16x16x32_bf16 v[48:51], v[196:199], v[204:207], v[48:51]
	v_mfma_f32_16x16x32_bf16 v[36:39], v[184:187], v[212:215], v[36:39]
	v_mfma_f32_16x16x32_bf16 v[32:35], v[196:199], v[212:215], v[32:35]
	v_mfma_f32_16x16x32_bf16 v[20:23], v[184:187], v[220:223], v[20:23]
	v_mfma_f32_16x16x32_bf16 v[16:19], v[196:199], v[220:223], v[16:19]
	v_mfma_f32_16x16x32_bf16 v[4:7], v[184:187], v[228:231], v[4:7]
	v_mfma_f32_16x16x32_bf16 v[0:3], v[196:199], v[228:231], v[0:3]
	s_barrier
	s_add_i32 s16, s16, 2
	s_add_u32 s48, s48, 0x100
	s_addc_u32 s49, s49, 0
	s_add_u32 s0, s0, 0x100
	s_addc_u32 s1, s1, 0
	s_cmp_gt_u32 s16, 29
	s_cbranch_scc0 .LBB0_565
	s_branch .Lpeel_exit_6
.LBB0_565:
	ds_read_b128 v[152:155], v167
	ds_read_b128 v[156:159], v167 offset:1024
	ds_read_b128 v[172:175], v167 offset:2048
	ds_read_b128 v[176:179], v167 offset:3072
	ds_read_b128 v[180:183], v168
	ds_read_b128 v[184:187], v168 offset:1024
	ds_read_b128 v[192:195], v168 offset:2048
	ds_read_b128 v[196:199], v168 offset:3072
	s_add_u32 s17, s48, 0xfff80080
	s_addc_u32 s33, s49, -1
	s_cmp_eq_u32 s16, 28
	s_cselect_b32 s53, s41, s33
	s_cselect_b32 s52, s40, s17
	s_cselect_b32 s51, s43, s1
	s_cselect_b32 s50, s42, s0
	v_lshl_add_u64 v[164:165], s[48:49], 0, v[148:149]
	s_add_i32 m0, s23, 0xc000
	ds_read_b128 v[200:203], v169
	ds_read_b128 v[204:207], v169 offset:1024
	ds_read_b128 v[208:211], v169 offset:2048
	ds_read_b128 v[212:215], v169 offset:3072
	ds_read_b128 v[216:219], v169 offset:4096
	ds_read_b128 v[220:223], v169 offset:5120
	ds_read_b128 v[224:227], v169 offset:6144
	ds_read_b128 v[228:231], v169 offset:7168
	global_load_lds_dwordx4 v[164:165], off
	v_lshl_add_u64 v[164:165], s[48:49], 0, v[150:151]
	s_add_i32 m0, s23, 0xe000
	s_nop 0
	global_load_lds_dwordx4 v[164:165], off
	s_waitcnt vmcnt(8)
	s_waitcnt lgkmcnt(0)
	s_barrier
; #define PG8_STAGE(bufoff, gbase, voff) do { _Pragma("unroll") for (int _i = 0; _i < 2; ++_i) \
;         __builtin_amdgcn_global_load_lds((const unsigned*)((const char*)(gbase) + (voff)[_i]), (LAS unsigned*)(lds + (bufoff) + ldsw + _i * 8192), 16, 0, 0); } while (0)
; #define PG8_LDA(dst, b, h) do { _Pragma("unroll") for (int m = 0; m < 4; ++m) _Pragma("unroll") for (int k = 0; k < 2; ++k) dst[m][k] = *(const LAS bf16x8*)(lds + PG8_SA(b, h) + aoff + m * 2048 + k * 1024); } while (0)
; #define PG8_MMA(ai, bj, At, Bt) do { __builtin_amdgcn_s_setprio(1); _Pragma("unroll") for (int m = 0; m < 4; ++m) _Pragma("unroll") for (int n = 0; n < 2; ++n) _Pragma("unroll") for (int k = 0; k < 2; ++k) \
;         acc[ai][bj][m][n] = __builtin_amdgcn_mfma_f32_16x16x32_bf16(Bt[n][k], At[m][k], acc[ai][bj][m][n], 0, 0, 0); __builtin_amdgcn_s_setprio(0); } while (0)
; #define PG8_WAIT_V(n) asm volatile("s_waitcnt vmcnt(" #n ")" ::: "memory")
; #define PG8_WAIT_L(n) asm volatile("s_waitcnt lgkmcnt(" #n ")" ::: "memory")
; #define PG8_BAR __builtin_amdgcn_s_barrier()
; #define PG8_SCHED __builtin_amdgcn_sched_barrier(0)
; template <int GI>
; __device__ __forceinline__ void gemm_phase(LAS unsigned char* lds, unsigned char* ws, int G, int cblk) {
;     ...
;             PG8_WAIT_V(8); PG8_WAIT_L(0); PG8_BAR; PG8_MMA(0, 0, At, B0); PG8_MMA(0, 1, At, B1); PG8_BAR; PG8_SCHED;
;             PG8_LDA(At, 0, 1); PG8_STAGE(PG8_SB(0, 0), b2, voffB); PG8_STAGE(PG8_SB(0, 1), b2 + hstepB, voffB); PG8_STAGE(PG8_SA(0, 0), a2, voffA);
;             PG8_WAIT_V(8); PG8_WAIT_L(0); PG8_BAR; PG8_MMA(1, 0, At, B0); PG8_MMA(1, 1, At, B1); PG8_BAR; PG8_SCHED;
	s_waitcnt lgkmcnt(0)
	v_mfma_f32_16x16x32_bf16 v[124:127], v[152:155], v[200:203], v[124:127]
	v_mfma_f32_16x16x32_bf16 v[120:123], v[172:175], v[200:203], v[120:123]
	v_mfma_f32_16x16x32_bf16 v[108:111], v[152:155], v[208:211], v[108:111]
	v_mfma_f32_16x16x32_bf16 v[104:107], v[172:175], v[208:211], v[104:107]
	v_mfma_f32_16x16x32_bf16 v[92:95], v[152:155], v[216:219], v[92:95]
	v_mfma_f32_16x16x32_bf16 v[88:91], v[172:175], v[216:219], v[88:91]
	v_mfma_f32_16x16x32_bf16 v[76:79], v[152:155], v[224:227], v[76:79]
	v_mfma_f32_16x16x32_bf16 v[72:75], v[172:175], v[224:227], v[72:75]
	v_mfma_f32_16x16x32_bf16 v[124:127], v[156:159], v[204:207], v[124:127]
	v_mfma_f32_16x16x32_bf16 v[120:123], v[176:179], v[204:207], v[120:123]
	v_mfma_f32_16x16x32_bf16 v[108:111], v[156:159], v[212:215], v[108:111]
	v_mfma_f32_16x16x32_bf16 v[104:107], v[176:179], v[212:215], v[104:107]
	v_mfma_f32_16x16x32_bf16 v[92:95], v[156:159], v[220:223], v[92:95]
	v_mfma_f32_16x16x32_bf16 v[88:91], v[176:179], v[220:223], v[88:91]
	v_mfma_f32_16x16x32_bf16 v[76:79], v[156:159], v[228:231], v[76:79]
	v_mfma_f32_16x16x32_bf16 v[72:75], v[176:179], v[228:231], v[72:75]
	v_mfma_f32_16x16x32_bf16 v[116:119], v[180:183], v[200:203], v[116:119]
	v_mfma_f32_16x16x32_bf16 v[112:115], v[192:195], v[200:203], v[112:115]
	v_mfma_f32_16x16x32_bf16 v[100:103], v[180:183], v[208:211], v[100:103]
	v_mfma_f32_16x16x32_bf16 v[96:99], v[192:195], v[208:211], v[96:99]
	v_mfma_f32_16x16x32_bf16 v[84:87], v[180:183], v[216:219], v[84:87]
	v_mfma_f32_16x16x32_bf16 v[80:83], v[192:195], v[216:219], v[80:83]
	v_mfma_f32_16x16x32_bf16 v[68:71], v[180:183], v[224:227], v[68:71]
	v_mfma_f32_16x16x32_bf16 v[64:67], v[192:195], v[224:227], v[64:67]
	v_mfma_f32_16x16x32_bf16 v[116:119], v[184:187], v[204:207], v[116:119]
	v_mfma_f32_16x16x32_bf16 v[112:115], v[196:199], v[204:207], v[112:115]
	v_mfma_f32_16x16x32_bf16 v[100:103], v[184:187], v[212:215], v[100:103]
	v_mfma_f32_16x16x32_bf16 v[96:99], v[196:199], v[212:215], v[96:99]
	v_mfma_f32_16x16x32_bf16 v[84:87], v[184:187], v[220:223], v[84:87]
	v_mfma_f32_16x16x32_bf16 v[80:83], v[196:199], v[220:223], v[80:83]
	v_mfma_f32_16x16x32_bf16 v[68:71], v[184:187], v[228:231], v[68:71]
	v_mfma_f32_16x16x32_bf16 v[64:67], v[196:199], v[228:231], v[64:67]
	s_barrier
	s_add_i32 s17, s60, s22
	v_lshl_add_u64 v[164:165], s[50:51], 0, v[132:133]
	s_mov_b32 m0, s17
	ds_read_b128 v[200:203], v169 offset:16384
	ds_read_b128 v[204:207], v169 offset:17408
	ds_read_b128 v[208:211], v169 offset:18432
	ds_read_b128 v[212:215], v169 offset:19456
	ds_read_b128 v[216:219], v169 offset:20480
	ds_read_b128 v[220:223], v169 offset:21504
	ds_read_b128 v[224:227], v169 offset:22528
	ds_read_b128 v[228:231], v169 offset:23552
	global_load_lds_dwordx4 v[164:165], off
	s_add_i32 m0, s17, 0x2000
	s_add_u32 s64, s50, 0x80000
	v_lshl_add_u64 v[188:189], s[50:51], 0, v[136:137]
	s_addc_u32 s65, s51, 0
	s_add_i32 s17, s61, s22
	global_load_lds_dwordx4 v[188:189], off
	v_lshl_add_u64 v[232:233], s[64:65], 0, v[132:133]
	s_mov_b32 m0, s17
	v_lshl_add_u64 v[234:235], s[52:53], 0, v[134:135]
	global_load_lds_dwordx4 v[232:233], off
	v_lshl_add_u64 v[232:233], s[64:65], 0, v[136:137]
	s_add_i32 m0, s17, 0x2000
	s_nop 0
	global_load_lds_dwordx4 v[232:233], off
	v_lshl_add_u64 v[232:233], s[52:53], 0, v[130:131]
	s_mov_b32 m0, s23
	s_nop 0
	global_load_lds_dwordx4 v[232:233], off
	s_mov_b32 m0, s24
	s_nop 0
	global_load_lds_dwordx4 v[234:235], off
	s_waitcnt vmcnt(8)
	s_waitcnt lgkmcnt(0)
	s_barrier
	s_waitcnt lgkmcnt(0)
	v_mfma_f32_16x16x32_bf16 v[60:63], v[152:155], v[200:203], v[60:63]
	v_mfma_f32_16x16x32_bf16 v[56:59], v[172:175], v[200:203], v[56:59]
	v_mfma_f32_16x16x32_bf16 v[44:47], v[152:155], v[208:211], v[44:47]
	v_mfma_f32_16x16x32_bf16 v[40:43], v[172:175], v[208:211], v[40:43]
	v_mfma_f32_16x16x32_bf16 v[28:31], v[152:155], v[216:219], v[28:31]
	v_mfma_f32_16x16x32_bf16 v[24:27], v[172:175], v[216:219], v[24:27]
	v_mfma_f32_16x16x32_bf16 v[12:15], v[152:155], v[224:227], v[12:15]
	v_mfma_f32_16x16x32_bf16 v[8:11], v[172:175], v[224:227], v[8:11]
	v_mfma_f32_16x16x32_bf16 v[60:63], v[156:159], v[204:207], v[60:63]
	v_mfma_f32_16x16x32_bf16 v[56:59], v[176:179], v[204:207], v[56:59]
	v_mfma_f32_16x16x32_bf16 v[44:47], v[156:159], v[212:215], v[44:47]
	v_mfma_f32_16x16x32_bf16 v[40:43], v[176:179], v[212:215], v[40:43]
	v_mfma_f32_16x16x32_bf16 v[28:31], v[156:159], v[220:223], v[28:31]
	v_mfma_f32_16x16x32_bf16 v[24:27], v[176:179], v[220:223], v[24:27]
	v_mfma_f32_16x16x32_bf16 v[12:15], v[156:159], v[228:231], v[12:15]
	v_mfma_f32_16x16x32_bf16 v[8:11], v[176:179], v[228:231], v[8:11]
	v_mfma_f32_16x16x32_bf16 v[52:55], v[180:183], v[200:203], v[52:55]
	v_mfma_f32_16x16x32_bf16 v[48:51], v[192:195], v[200:203], v[48:51]
	v_mfma_f32_16x16x32_bf16 v[36:39], v[180:183], v[208:211], v[36:39]
	v_mfma_f32_16x16x32_bf16 v[32:35], v[192:195], v[208:211], v[32:35]
	v_mfma_f32_16x16x32_bf16 v[20:23], v[180:183], v[216:219], v[20:23]
	v_mfma_f32_16x16x32_bf16 v[16:19], v[192:195], v[216:219], v[16:19]
	v_mfma_f32_16x16x32_bf16 v[4:7], v[180:183], v[224:227], v[4:7]
	v_mfma_f32_16x16x32_bf16 v[0:3], v[192:195], v[224:227], v[0:3]
	v_mfma_f32_16x16x32_bf16 v[52:55], v[184:187], v[204:207], v[52:55]
	v_mfma_f32_16x16x32_bf16 v[48:51], v[196:199], v[204:207], v[48:51]
	v_mfma_f32_16x16x32_bf16 v[36:39], v[184:187], v[212:215], v[36:39]
	v_mfma_f32_16x16x32_bf16 v[32:35], v[196:199], v[212:215], v[32:35]
	v_mfma_f32_16x16x32_bf16 v[20:23], v[184:187], v[220:223], v[20:23]
	v_mfma_f32_16x16x32_bf16 v[16:19], v[196:199], v[220:223], v[16:19]
	v_mfma_f32_16x16x32_bf16 v[4:7], v[184:187], v[228:231], v[4:7]
	v_mfma_f32_16x16x32_bf16 v[0:3], v[196:199], v[228:231], v[0:3]
	s_barrier
; #define PG8_STAGE(bufoff, gbase, voff) do { _Pragma("unroll") for (int _i = 0; _i < 2; ++_i) \
;         __builtin_amdgcn_global_load_lds((const unsigned*)((const char*)(gbase) + (voff)[_i]), (LAS unsigned*)(lds + (bufoff) + ldsw + _i * 8192), 16, 0, 0); } while (0)
; #define PG8_LDA(dst, b, h) do { _Pragma("unroll") for (int m = 0; m < 4; ++m) _Pragma("unroll") for (int k = 0; k < 2; ++k) dst[m][k] = *(const LAS bf16x8*)(lds + PG8_SA(b, h) + aoff + m * 2048 + k * 1024); } while (0)
; #define PG8_LDB(dst, b, h) do { _Pragma("unroll") for (int n = 0; n < 2; ++n) _Pragma("unroll") for (int k = 0; k < 2; ++k) dst[n][k] = *(const LAS bf16x8*)(lds + PG8_SB(b, h) + boff + n * 2048 + k * 1024); } while (0)
; #define PG8_MMA(ai, bj, At, Bt) do { __builtin_amdgcn_s_setprio(1); _Pragma("unroll") for (int m = 0; m < 4; ++m) _Pragma("unroll") for (int n = 0; n < 2; ++n) _Pragma("unroll") for (int k = 0; k < 2; ++k) \
;         acc[ai][bj][m][n] = __builtin_amdgcn_mfma_f32_16x16x32_bf16(Bt[n][k], At[m][k], acc[ai][bj][m][n], 0, 0, 0); __builtin_amdgcn_s_setprio(0); } while (0)
; #define PG8_WAIT_V(n) asm volatile("s_waitcnt vmcnt(" #n ")" ::: "memory")
; #define PG8_WAIT_L(n) asm volatile("s_waitcnt lgkmcnt(" #n ")" ::: "memory")
; #define PG8_BAR __builtin_amdgcn_s_barrier()
; #define PG8_SCHED __builtin_amdgcn_sched_barrier(0)
; template <int GI>
; __device__ __forceinline__ void gemm_phase(LAS unsigned char* lds, unsigned char* ws, int G, int cblk) {
;     ...
;             PG8_LDB(B0, 1, 0); PG8_LDB(B1, 1, 1); PG8_SCHED; PG8_LDA(At, 1, 0); PG8_STAGE(PG8_SA(0, 1), a2 + hstepA, voffA);
;             PG8_WAIT_V(8); PG8_WAIT_L(0); PG8_BAR; PG8_MMA(0, 0, At, B0); PG8_MMA(0, 1, At, B1); PG8_BAR; PG8_SCHED;
;             PG8_LDA(At, 1, 1); PG8_STAGE(PG8_SB(1, 0), b3, voffB); PG8_STAGE(PG8_SB(1, 1), b3 + hstepB, voffB); PG8_STAGE(PG8_SA(1, 0), a3, voffA);
;             PG8_WAIT_V(8); PG8_WAIT_L(0); PG8_BAR; PG8_MMA(1, 0, At, B0); PG8_MMA(1, 1, At, B1); PG8_BAR; PG8_SCHED;
;         }
	s_add_i32 s17, 0, 0x18000
	s_add_i32 s33, 0, 0x1c000
	v_add_u32_e32 v176, s17, v161
	v_add_u32_e32 v191, s33, v161
	ds_read_b128 v[152:155], v176
	ds_read_b128 v[156:159], v176 offset:1024
	ds_read_b128 v[172:175], v176 offset:2048
	ds_read_b128 v[176:179], v176 offset:3072
	ds_read_b128 v[180:183], v191
	ds_read_b128 v[184:187], v191 offset:1024
	ds_read_b128 v[192:195], v191 offset:2048
	ds_read_b128 v[196:199], v191 offset:3072
	s_add_u32 s52, s52, 0x80000
	s_addc_u32 s53, s53, 0
	s_mov_b32 m0, s25
	v_lshl_add_u64 v[236:237], s[52:53], 0, v[130:131]
	ds_read_b128 v[200:203], v169 offset:32768
	ds_read_b128 v[204:207], v169 offset:33792
	ds_read_b128 v[208:211], v169 offset:34816
	ds_read_b128 v[212:215], v169 offset:35840
	ds_read_b128 v[216:219], v169 offset:36864
	ds_read_b128 v[220:223], v169 offset:37888
	ds_read_b128 v[224:227], v169 offset:38912
	ds_read_b128 v[228:231], v169 offset:39936
	global_load_lds_dwordx4 v[236:237], off
	v_lshl_add_u64 v[236:237], s[52:53], 0, v[134:135]
	s_mov_b32 m0, s26
	s_nop 0
	global_load_lds_dwordx4 v[236:237], off
	s_waitcnt vmcnt(8)
	s_waitcnt lgkmcnt(0)
	s_barrier
	s_waitcnt lgkmcnt(0)
	v_mfma_f32_16x16x32_bf16 v[124:127], v[152:155], v[200:203], v[124:127]
	v_mfma_f32_16x16x32_bf16 v[120:123], v[172:175], v[200:203], v[120:123]
	v_mfma_f32_16x16x32_bf16 v[108:111], v[152:155], v[208:211], v[108:111]
	v_mfma_f32_16x16x32_bf16 v[104:107], v[172:175], v[208:211], v[104:107]
	v_mfma_f32_16x16x32_bf16 v[92:95], v[152:155], v[216:219], v[92:95]
	v_mfma_f32_16x16x32_bf16 v[88:91], v[172:175], v[216:219], v[88:91]
	v_mfma_f32_16x16x32_bf16 v[76:79], v[152:155], v[224:227], v[76:79]
	v_mfma_f32_16x16x32_bf16 v[72:75], v[172:175], v[224:227], v[72:75]
	v_mfma_f32_16x16x32_bf16 v[124:127], v[156:159], v[204:207], v[124:127]
	v_mfma_f32_16x16x32_bf16 v[120:123], v[176:179], v[204:207], v[120:123]
	v_mfma_f32_16x16x32_bf16 v[108:111], v[156:159], v[212:215], v[108:111]
	v_mfma_f32_16x16x32_bf16 v[104:107], v[176:179], v[212:215], v[104:107]
	v_mfma_f32_16x16x32_bf16 v[92:95], v[156:159], v[220:223], v[92:95]
	v_mfma_f32_16x16x32_bf16 v[88:91], v[176:179], v[220:223], v[88:91]
	v_mfma_f32_16x16x32_bf16 v[76:79], v[156:159], v[228:231], v[76:79]
	v_mfma_f32_16x16x32_bf16 v[72:75], v[176:179], v[228:231], v[72:75]
	v_mfma_f32_16x16x32_bf16 v[116:119], v[180:183], v[200:203], v[116:119]
	v_mfma_f32_16x16x32_bf16 v[112:115], v[192:195], v[200:203], v[112:115]
	v_mfma_f32_16x16x32_bf16 v[100:103], v[180:183], v[208:211], v[100:103]
	v_mfma_f32_16x16x32_bf16 v[96:99], v[192:195], v[208:211], v[96:99]
	v_mfma_f32_16x16x32_bf16 v[84:87], v[180:183], v[216:219], v[84:87]
	v_mfma_f32_16x16x32_bf16 v[80:83], v[192:195], v[216:219], v[80:83]
	v_mfma_f32_16x16x32_bf16 v[68:71], v[180:183], v[224:227], v[68:71]
	v_mfma_f32_16x16x32_bf16 v[64:67], v[192:195], v[224:227], v[64:67]
	v_mfma_f32_16x16x32_bf16 v[116:119], v[184:187], v[204:207], v[116:119]
	v_mfma_f32_16x16x32_bf16 v[112:115], v[196:199], v[204:207], v[112:115]
	v_mfma_f32_16x16x32_bf16 v[100:103], v[184:187], v[212:215], v[100:103]
	v_mfma_f32_16x16x32_bf16 v[96:99], v[196:199], v[212:215], v[96:99]
	v_mfma_f32_16x16x32_bf16 v[84:87], v[184:187], v[220:223], v[84:87]
	v_mfma_f32_16x16x32_bf16 v[80:83], v[196:199], v[220:223], v[80:83]
	v_mfma_f32_16x16x32_bf16 v[68:71], v[184:187], v[228:231], v[68:71]
	v_mfma_f32_16x16x32_bf16 v[64:67], v[196:199], v[228:231], v[64:67]
	s_barrier
	s_add_i32 s17, s17, s22
	v_lshl_add_u64 v[164:165], v[164:165], 0, s[18:19]
	s_mov_b32 m0, s17
	ds_read_b128 v[200:203], v169 offset:49152
	ds_read_b128 v[204:207], v169 offset:50176
	ds_read_b128 v[208:211], v169 offset:51200
	ds_read_b128 v[212:215], v169 offset:52224
	ds_read_b128 v[216:219], v169 offset:53248
	ds_read_b128 v[220:223], v169 offset:54272
	ds_read_b128 v[224:227], v169 offset:55296
	ds_read_b128 v[228:231], v169 offset:56320
	global_load_lds_dwordx4 v[164:165], off
	s_add_i32 m0, s17, 0x2000
	s_add_u32 s50, s50, 0x80080
	v_lshl_add_u64 v[164:165], v[188:189], 0, s[18:19]
	s_addc_u32 s51, s51, 0
	s_add_i32 s17, s33, s22
	global_load_lds_dwordx4 v[164:165], off
	v_lshl_add_u64 v[164:165], s[50:51], 0, v[132:133]
	s_mov_b32 m0, s17
	s_nop 0
	global_load_lds_dwordx4 v[164:165], off
	v_lshl_add_u64 v[164:165], s[50:51], 0, v[136:137]
	s_add_i32 m0, s17, 0x2000
	s_nop 0
	global_load_lds_dwordx4 v[164:165], off
	v_lshl_add_u64 v[164:165], v[232:233], 0, s[18:19]
	s_mov_b32 m0, s35
	s_nop 0
	global_load_lds_dwordx4 v[164:165], off
	v_lshl_add_u64 v[164:165], v[234:235], 0, s[18:19]
	s_mov_b32 m0, s55
	s_nop 0
	global_load_lds_dwordx4 v[164:165], off
	s_waitcnt vmcnt(8)
	s_waitcnt lgkmcnt(0)
	s_barrier
	s_waitcnt lgkmcnt(0)
	v_mfma_f32_16x16x32_bf16 v[60:63], v[152:155], v[200:203], v[60:63]
	v_mfma_f32_16x16x32_bf16 v[56:59], v[172:175], v[200:203], v[56:59]
	v_mfma_f32_16x16x32_bf16 v[44:47], v[152:155], v[208:211], v[44:47]
	v_mfma_f32_16x16x32_bf16 v[40:43], v[172:175], v[208:211], v[40:43]
	v_mfma_f32_16x16x32_bf16 v[28:31], v[152:155], v[216:219], v[28:31]
	v_mfma_f32_16x16x32_bf16 v[24:27], v[172:175], v[216:219], v[24:27]
	v_mfma_f32_16x16x32_bf16 v[12:15], v[152:155], v[224:227], v[12:15]
	v_mfma_f32_16x16x32_bf16 v[8:11], v[172:175], v[224:227], v[8:11]
	v_mfma_f32_16x16x32_bf16 v[60:63], v[156:159], v[204:207], v[60:63]
	v_mfma_f32_16x16x32_bf16 v[56:59], v[176:179], v[204:207], v[56:59]
	v_mfma_f32_16x16x32_bf16 v[44:47], v[156:159], v[212:215], v[44:47]
	v_mfma_f32_16x16x32_bf16 v[40:43], v[176:179], v[212:215], v[40:43]
	v_mfma_f32_16x16x32_bf16 v[28:31], v[156:159], v[220:223], v[28:31]
	v_mfma_f32_16x16x32_bf16 v[24:27], v[176:179], v[220:223], v[24:27]
	v_mfma_f32_16x16x32_bf16 v[12:15], v[156:159], v[228:231], v[12:15]
	v_mfma_f32_16x16x32_bf16 v[8:11], v[176:179], v[228:231], v[8:11]
	v_mfma_f32_16x16x32_bf16 v[52:55], v[180:183], v[200:203], v[52:55]
	v_mfma_f32_16x16x32_bf16 v[48:51], v[192:195], v[200:203], v[48:51]
	v_mfma_f32_16x16x32_bf16 v[36:39], v[180:183], v[208:211], v[36:39]
	v_mfma_f32_16x16x32_bf16 v[32:35], v[192:195], v[208:211], v[32:35]
	v_mfma_f32_16x16x32_bf16 v[20:23], v[180:183], v[216:219], v[20:23]
	v_mfma_f32_16x16x32_bf16 v[16:19], v[192:195], v[216:219], v[16:19]
	v_mfma_f32_16x16x32_bf16 v[4:7], v[180:183], v[224:227], v[4:7]
	v_mfma_f32_16x16x32_bf16 v[0:3], v[192:195], v[224:227], v[0:3]
	v_mfma_f32_16x16x32_bf16 v[52:55], v[184:187], v[204:207], v[52:55]
	v_mfma_f32_16x16x32_bf16 v[48:51], v[196:199], v[204:207], v[48:51]
	v_mfma_f32_16x16x32_bf16 v[36:39], v[184:187], v[212:215], v[36:39]
	v_mfma_f32_16x16x32_bf16 v[32:35], v[196:199], v[212:215], v[32:35]
	v_mfma_f32_16x16x32_bf16 v[20:23], v[184:187], v[220:223], v[20:23]
	v_mfma_f32_16x16x32_bf16 v[16:19], v[196:199], v[220:223], v[16:19]
	v_mfma_f32_16x16x32_bf16 v[4:7], v[184:187], v[228:231], v[4:7]
	v_mfma_f32_16x16x32_bf16 v[0:3], v[196:199], v[228:231], v[0:3]
	s_barrier
	s_add_i32 s16, s16, 2
	s_add_u32 s48, s48, 0x100
	s_addc_u32 s49, s49, 0
	s_add_u32 s0, s0, 0x100
	s_addc_u32 s1, s1, 0
	s_cmp_gt_u32 s16, 29
	s_cbranch_scc0 .LBB0_565

; #define PG8_STAGE(bufoff, gbase, voff) do { _Pragma("unroll") for (int _i = 0; _i < 2; ++_i) \
;         __builtin_amdgcn_global_load_lds((const unsigned*)((const char*)(gbase) + (voff)[_i]), (LAS unsigned*)(lds + (bufoff) + ldsw + _i * 8192), 16, 0, 0); } while (0)
; #define PG8_LDA(dst, b, h) do { _Pragma("unroll") for (int m = 0; m < 4; ++m) _Pragma("unroll") for (int k = 0; k < 2; ++k) dst[m][k] = *(const LAS bf16x8*)(lds + PG8_SA(b, h) + aoff + m * 2048 + k * 1024); } while (0)
; #define PG8_LDB(dst, b, h) do { _Pragma("unroll") for (int n = 0; n < 2; ++n) _Pragma("unroll") for (int k = 0; k < 2; ++k) dst[n][k] = *(const LAS bf16x8*)(lds + PG8_SB(b, h) + boff + n * 2048 + k * 1024); } while (0)
; #define PG8_MMA(ai, bj, At, Bt) do { __builtin_amdgcn_s_setprio(1); _Pragma("unroll") for (int m = 0; m < 4; ++m) _Pragma("unroll") for (int n = 0; n < 2; ++n) _Pragma("unroll") for (int k = 0; k < 2; ++k) \
;         acc[ai][bj][m][n] = __builtin_amdgcn_mfma_f32_16x16x32_bf16(Bt[n][k], At[m][k], acc[ai][bj][m][n], 0, 0, 0); __builtin_amdgcn_s_setprio(0); } while (0)
; #define PG8_WAIT_V(n) asm volatile("s_waitcnt vmcnt(" #n ")" ::: "memory")
; #define PG8_WAIT_L(n) asm volatile("s_waitcnt lgkmcnt(" #n ")" ::: "memory")
; #define PG8_BAR __builtin_amdgcn_s_barrier()
; template <int GI>
; __device__ __forceinline__ void gemm_phase(LAS unsigned char* lds, unsigned char* ws, int G, int cblk) {
;     ...
;         const char* nA = has_next ? nxt.A : cA; const char* nB = has_next ? nxt.B : cB;
;         for (int t = 0; t < nt; t += 2) {
;             const bool last = (t == nt - 2);
;             const char* a1 = cA + (size_t)(t + 1) * kstep;
;             const char* a2 = last ? nA : cA + (size_t)(t + 2) * kstep; const char* b2 = last ? nB : cB + (size_t)(t + 2) * kstep;
;             const char* a3 = a2 + kstep; const char* b3 = b2 + kstep;
;             PG8_LDB(B0, 0, 0); PG8_LDB(B1, 0, 1); PG8_SCHED; PG8_LDA(At, 0, 0); PG8_STAGE(PG8_SA(1, 1), a1 + hstepA, voffA);
;             PG8_WAIT_V(8); PG8_WAIT_L(0); PG8_BAR; PG8_MMA(0, 0, At, B0); PG8_MMA(0, 1, At, B1); PG8_BAR; PG8_SCHED;
;             PG8_LDA(At, 0, 1); PG8_STAGE(PG8_SB(0, 0), b2, voffB); PG8_STAGE(PG8_SB(0, 1), b2 + hstepB, voffB); PG8_STAGE(PG8_SA(0, 0), a2, voffA);
;             PG8_WAIT_V(8); PG8_WAIT_L(0); PG8_BAR; PG8_MMA(1, 0, At, B0); PG8_MMA(1, 1, At, B1); PG8_BAR; PG8_SCHED;
.LBB0_696:
	s_add_u32 s44, s44, 0x40080
	s_addc_u32 s45, s45, 0
	s_add_u32 s16, s46, 0x100
	s_addc_u32 s17, s47, 0
	s_mov_b32 s19, -2
	ds_read_b128 v[156:159], v153
	ds_read_b128 v[164:167], v153 offset:1024
	ds_read_b128 v[168:171], v153 offset:2048
	ds_read_b128 v[172:175], v153 offset:3072
	ds_read_b128 v[176:179], v154
	ds_read_b128 v[180:183], v154 offset:1024
	ds_read_b128 v[184:187], v154 offset:2048
	ds_read_b128 v[192:195], v154 offset:3072
	s_add_u32 s34, s44, 0xfffc0080
	s_addc_u32 s46, s45, -1
	s_cmp_eq_u32 s19, 12
	s_cselect_b32 s49, s39, s46
	s_cselect_b32 s48, s38, s34
	s_cselect_b32 s47, s41, s17
	s_cselect_b32 s46, s40, s16
	v_lshl_add_u64 v[188:189], s[44:45], 0, v[140:141]
	s_add_i32 m0, s25, 0xc000
	ds_read_b128 v[196:199], v155
	ds_read_b128 v[200:203], v155 offset:1024
	ds_read_b128 v[204:207], v155 offset:2048
	ds_read_b128 v[208:211], v155 offset:3072
	ds_read_b128 v[212:215], v155 offset:4096
	ds_read_b128 v[216:219], v155 offset:5120
	ds_read_b128 v[220:223], v155 offset:6144
	ds_read_b128 v[224:227], v155 offset:7168
	global_load_lds_dwordx4 v[188:189], off
	v_lshl_add_u64 v[188:189], s[44:45], 0, v[142:143]
	s_add_i32 m0, s25, 0xe000
	s_nop 0
	global_load_lds_dwordx4 v[188:189], off
	s_waitcnt vmcnt(8)
	s_waitcnt lgkmcnt(0)
	s_barrier
	s_waitcnt lgkmcnt(0)
	v_mfma_f32_16x16x32_bf16 v[124:127], v[156:159], v[196:199], 0
	v_mfma_f32_16x16x32_bf16 v[120:123], v[168:171], v[196:199], 0
	v_mfma_f32_16x16x32_bf16 v[116:119], v[156:159], v[204:207], 0
	v_mfma_f32_16x16x32_bf16 v[112:115], v[168:171], v[204:207], 0
	v_mfma_f32_16x16x32_bf16 v[100:103], v[156:159], v[212:215], 0
	v_mfma_f32_16x16x32_bf16 v[96:99], v[168:171], v[212:215], 0
	v_mfma_f32_16x16x32_bf16 v[84:87], v[156:159], v[220:223], 0
	v_mfma_f32_16x16x32_bf16 v[80:83], v[168:171], v[220:223], 0
	v_mfma_f32_16x16x32_bf16 v[124:127], v[164:167], v[200:203], v[124:127]
	v_mfma_f32_16x16x32_bf16 v[120:123], v[172:175], v[200:203], v[120:123]
	v_mfma_f32_16x16x32_bf16 v[116:119], v[164:167], v[208:211], v[116:119]
	v_mfma_f32_16x16x32_bf16 v[112:115], v[172:175], v[208:211], v[112:115]
	v_mfma_f32_16x16x32_bf16 v[100:103], v[164:167], v[216:219], v[100:103]
	v_mfma_f32_16x16x32_bf16 v[96:99], v[172:175], v[216:219], v[96:99]
	v_mfma_f32_16x16x32_bf16 v[84:87], v[164:167], v[224:227], v[84:87]
	v_mfma_f32_16x16x32_bf16 v[80:83], v[172:175], v[224:227], v[80:83]
	v_mfma_f32_16x16x32_bf16 v[108:111], v[176:179], v[196:199], 0
	v_mfma_f32_16x16x32_bf16 v[104:107], v[184:187], v[196:199], 0
	v_mfma_f32_16x16x32_bf16 v[92:95], v[176:179], v[204:207], 0
	v_mfma_f32_16x16x32_bf16 v[88:91], v[184:187], v[204:207], 0
	v_mfma_f32_16x16x32_bf16 v[76:79], v[176:179], v[212:215], 0
	v_mfma_f32_16x16x32_bf16 v[72:75], v[184:187], v[212:215], 0
	v_mfma_f32_16x16x32_bf16 v[68:71], v[176:179], v[220:223], 0
	v_mfma_f32_16x16x32_bf16 v[64:67], v[184:187], v[220:223], 0
	v_mfma_f32_16x16x32_bf16 v[108:111], v[180:183], v[200:203], v[108:111]
	v_mfma_f32_16x16x32_bf16 v[104:107], v[192:195], v[200:203], v[104:107]
	v_mfma_f32_16x16x32_bf16 v[92:95], v[180:183], v[208:211], v[92:95]
	v_mfma_f32_16x16x32_bf16 v[88:91], v[192:195], v[208:211], v[88:91]
	v_mfma_f32_16x16x32_bf16 v[76:79], v[180:183], v[216:219], v[76:79]
	v_mfma_f32_16x16x32_bf16 v[72:75], v[192:195], v[216:219], v[72:75]
	v_mfma_f32_16x16x32_bf16 v[68:71], v[180:183], v[224:227], v[68:71]
	v_mfma_f32_16x16x32_bf16 v[64:67], v[192:195], v[224:227], v[64:67]
	s_barrier
	s_add_i32 s34, s53, s0
	v_lshl_add_u64 v[188:189], s[46:47], 0, v[132:133]
	s_mov_b32 m0, s34
	ds_read_b128 v[196:199], v155 offset:16384
	ds_read_b128 v[200:203], v155 offset:17408
	ds_read_b128 v[204:207], v155 offset:18432
	ds_read_b128 v[208:211], v155 offset:19456
	ds_read_b128 v[212:215], v155 offset:20480
	ds_read_b128 v[216:219], v155 offset:21504
	ds_read_b128 v[220:223], v155 offset:22528
	ds_read_b128 v[224:227], v155 offset:23552
	global_load_lds_dwordx4 v[188:189], off
	s_add_i32 m0, s34, 0x2000
	s_add_u32 s58, s46, 0x40000
	v_lshl_add_u64 v[228:229], s[46:47], 0, v[136:137]
	s_addc_u32 s59, s47, 0
	s_add_i32 s34, s55, s0
	global_load_lds_dwordx4 v[228:229], off
	v_lshl_add_u64 v[230:231], s[58:59], 0, v[132:133]
	s_mov_b32 m0, s34
	v_lshl_add_u64 v[232:233], s[48:49], 0, v[134:135]
	global_load_lds_dwordx4 v[230:231], off
	v_lshl_add_u64 v[230:231], s[58:59], 0, v[136:137]
	s_add_i32 m0, s34, 0x2000
	s_nop 0
	global_load_lds_dwordx4 v[230:231], off
	v_lshl_add_u64 v[230:231], s[48:49], 0, v[130:131]
	s_mov_b32 m0, s25
	s_nop 0
	global_load_lds_dwordx4 v[230:231], off
	s_mov_b32 m0, s26
	s_nop 0
	global_load_lds_dwordx4 v[232:233], off
	s_waitcnt vmcnt(8)
	s_waitcnt lgkmcnt(0)
	s_barrier
; #define PG8_STAGE(bufoff, gbase, voff) do { _Pragma("unroll") for (int _i = 0; _i < 2; ++_i) \
;         __builtin_amdgcn_global_load_lds((const unsigned*)((const char*)(gbase) + (voff)[_i]), (LAS unsigned*)(lds + (bufoff) + ldsw + _i * 8192), 16, 0, 0); } while (0)
; #define PG8_LDA(dst, b, h) do { _Pragma("unroll") for (int m = 0; m < 4; ++m) _Pragma("unroll") for (int k = 0; k < 2; ++k) dst[m][k] = *(const LAS bf16x8*)(lds + PG8_SA(b, h) + aoff + m * 2048 + k * 1024); } while (0)
; #define PG8_LDB(dst, b, h) do { _Pragma("unroll") for (int n = 0; n < 2; ++n) _Pragma("unroll") for (int k = 0; k < 2; ++k) dst[n][k] = *(const LAS bf16x8*)(lds + PG8_SB(b, h) + boff + n * 2048 + k * 1024); } while (0)
; #define PG8_MMA(ai, bj, At, Bt) do { __builtin_amdgcn_s_setprio(1); _Pragma("unroll") for (int m = 0; m < 4; ++m) _Pragma("unroll") for (int n = 0; n < 2; ++n) _Pragma("unroll") for (int k = 0; k < 2; ++k) \
;         acc[ai][bj][m][n] = __builtin_amdgcn_mfma_f32_16x16x32_bf16(Bt[n][k], At[m][k], acc[ai][bj][m][n], 0, 0, 0); __builtin_amdgcn_s_setprio(0); } while (0)
; #define PG8_WAIT_V(n) asm volatile("s_waitcnt vmcnt(" #n ")" ::: "memory")
; #define PG8_WAIT_L(n) asm volatile("s_waitcnt lgkmcnt(" #n ")" ::: "memory")
; #define PG8_BAR __builtin_amdgcn_s_barrier()
; #define PG8_SCHED __builtin_amdgcn_sched_barrier(0)
; template <int GI>
; __device__ __forceinline__ void gemm_phase(LAS unsigned char* lds, unsigned char* ws, int G, int cblk) {
;     ...
;             PG8_WAIT_V(8); PG8_WAIT_L(0); PG8_BAR; PG8_MMA(1, 0, At, B0); PG8_MMA(1, 1, At, B1); PG8_BAR; PG8_SCHED;
;             PG8_LDB(B0, 1, 0); PG8_LDB(B1, 1, 1); PG8_SCHED; PG8_LDA(At, 1, 0); PG8_STAGE(PG8_SA(0, 1), a2 + hstepA, voffA);
;             PG8_WAIT_V(8); PG8_WAIT_L(0); PG8_BAR; PG8_MMA(0, 0, At, B0); PG8_MMA(0, 1, At, B1); PG8_BAR; PG8_SCHED;
	s_waitcnt lgkmcnt(0)
	v_mfma_f32_16x16x32_bf16 v[60:63], v[156:159], v[196:199], 0
	v_mfma_f32_16x16x32_bf16 v[56:59], v[168:171], v[196:199], 0
	v_mfma_f32_16x16x32_bf16 v[52:55], v[156:159], v[204:207], 0
	v_mfma_f32_16x16x32_bf16 v[48:51], v[168:171], v[204:207], 0
	v_mfma_f32_16x16x32_bf16 v[36:39], v[156:159], v[212:215], 0
	v_mfma_f32_16x16x32_bf16 v[32:35], v[168:171], v[212:215], 0
	v_mfma_f32_16x16x32_bf16 v[20:23], v[156:159], v[220:223], 0
	v_mfma_f32_16x16x32_bf16 v[16:19], v[168:171], v[220:223], 0
	v_mfma_f32_16x16x32_bf16 v[60:63], v[164:167], v[200:203], v[60:63]
	v_mfma_f32_16x16x32_bf16 v[56:59], v[172:175], v[200:203], v[56:59]
	v_mfma_f32_16x16x32_bf16 v[52:55], v[164:167], v[208:211], v[52:55]
	v_mfma_f32_16x16x32_bf16 v[48:51], v[172:175], v[208:211], v[48:51]
	v_mfma_f32_16x16x32_bf16 v[36:39], v[164:167], v[216:219], v[36:39]
	v_mfma_f32_16x16x32_bf16 v[32:35], v[172:175], v[216:219], v[32:35]
	v_mfma_f32_16x16x32_bf16 v[20:23], v[164:167], v[224:227], v[20:23]
	v_mfma_f32_16x16x32_bf16 v[16:19], v[172:175], v[224:227], v[16:19]
	v_mfma_f32_16x16x32_bf16 v[44:47], v[176:179], v[196:199], 0
	v_mfma_f32_16x16x32_bf16 v[40:43], v[184:187], v[196:199], 0
	v_mfma_f32_16x16x32_bf16 v[28:31], v[176:179], v[204:207], 0
	v_mfma_f32_16x16x32_bf16 v[24:27], v[184:187], v[204:207], 0
	v_mfma_f32_16x16x32_bf16 v[12:15], v[176:179], v[212:215], 0
	v_mfma_f32_16x16x32_bf16 v[8:11], v[184:187], v[212:215], 0
	v_mfma_f32_16x16x32_bf16 v[4:7], v[176:179], v[220:223], 0
	v_mfma_f32_16x16x32_bf16 v[0:3], v[184:187], v[220:223], 0
	v_mfma_f32_16x16x32_bf16 v[44:47], v[180:183], v[200:203], v[44:47]
	v_mfma_f32_16x16x32_bf16 v[40:43], v[192:195], v[200:203], v[40:43]
	v_mfma_f32_16x16x32_bf16 v[28:31], v[180:183], v[208:211], v[28:31]
	v_mfma_f32_16x16x32_bf16 v[24:27], v[192:195], v[208:211], v[24:27]
	v_mfma_f32_16x16x32_bf16 v[12:15], v[180:183], v[216:219], v[12:15]
	v_mfma_f32_16x16x32_bf16 v[8:11], v[192:195], v[216:219], v[8:11]
	v_mfma_f32_16x16x32_bf16 v[4:7], v[180:183], v[224:227], v[4:7]
	v_mfma_f32_16x16x32_bf16 v[0:3], v[192:195], v[224:227], v[0:3]
	s_barrier
	s_add_i32 s34, 0, 0x18000
	v_add_u32_e32 v161, s34, v152
	s_add_i32 s57, 0, 0x1c000
	ds_read_b128 v[156:159], v161
	ds_read_b128 v[164:167], v161 offset:1024
	ds_read_b128 v[168:171], v161 offset:2048
	ds_read_b128 v[172:175], v161 offset:3072
	v_add_u32_e32 v161, s57, v152
	ds_read_b128 v[176:179], v161
	ds_read_b128 v[180:183], v161 offset:1024
	ds_read_b128 v[184:187], v161 offset:2048
	ds_read_b128 v[192:195], v161 offset:3072
	s_add_u32 s48, s48, 0x40000
	s_addc_u32 s49, s49, 0
	s_mov_b32 m0, s27
	v_lshl_add_u64 v[234:235], s[48:49], 0, v[130:131]
	ds_read_b128 v[196:199], v155 offset:32768
	ds_read_b128 v[200:203], v155 offset:33792
	ds_read_b128 v[204:207], v155 offset:34816
	ds_read_b128 v[208:211], v155 offset:35840
	ds_read_b128 v[212:215], v155 offset:36864
	ds_read_b128 v[216:219], v155 offset:37888
	ds_read_b128 v[220:223], v155 offset:38912
	ds_read_b128 v[224:227], v155 offset:39936
	global_load_lds_dwordx4 v[234:235], off
	v_lshl_add_u64 v[234:235], s[48:49], 0, v[134:135]
	s_mov_b32 m0, s33
	s_nop 0
	global_load_lds_dwordx4 v[234:235], off
	s_waitcnt vmcnt(8)
	s_waitcnt lgkmcnt(0)
	s_barrier
	s_waitcnt lgkmcnt(0)
	v_mfma_f32_16x16x32_bf16 v[124:127], v[156:159], v[196:199], v[124:127]
	v_mfma_f32_16x16x32_bf16 v[120:123], v[168:171], v[196:199], v[120:123]
	v_mfma_f32_16x16x32_bf16 v[116:119], v[156:159], v[204:207], v[116:119]
	v_mfma_f32_16x16x32_bf16 v[112:115], v[168:171], v[204:207], v[112:115]
	v_mfma_f32_16x16x32_bf16 v[100:103], v[156:159], v[212:215], v[100:103]
	v_mfma_f32_16x16x32_bf16 v[96:99], v[168:171], v[212:215], v[96:99]
	v_mfma_f32_16x16x32_bf16 v[84:87], v[156:159], v[220:223], v[84:87]
	v_mfma_f32_16x16x32_bf16 v[80:83], v[168:171], v[220:223], v[80:83]
	v_mfma_f32_16x16x32_bf16 v[124:127], v[164:167], v[200:203], v[124:127]
	v_mfma_f32_16x16x32_bf16 v[120:123], v[172:175], v[200:203], v[120:123]
	v_mfma_f32_16x16x32_bf16 v[116:119], v[164:167], v[208:211], v[116:119]
	v_mfma_f32_16x16x32_bf16 v[112:115], v[172:175], v[208:211], v[112:115]
	v_mfma_f32_16x16x32_bf16 v[100:103], v[164:167], v[216:219], v[100:103]
	v_mfma_f32_16x16x32_bf16 v[96:99], v[172:175], v[216:219], v[96:99]
	v_mfma_f32_16x16x32_bf16 v[84:87], v[164:167], v[224:227], v[84:87]
	v_mfma_f32_16x16x32_bf16 v[80:83], v[172:175], v[224:227], v[80:83]
	v_mfma_f32_16x16x32_bf16 v[108:111], v[176:179], v[196:199], v[108:111]
	v_mfma_f32_16x16x32_bf16 v[104:107], v[184:187], v[196:199], v[104:107]
	v_mfma_f32_16x16x32_bf16 v[92:95], v[176:179], v[204:207], v[92:95]
	v_mfma_f32_16x16x32_bf16 v[88:91], v[184:187], v[204:207], v[88:91]
	v_mfma_f32_16x16x32_bf16 v[76:79], v[176:179], v[212:215], v[76:79]
	v_mfma_f32_16x16x32_bf16 v[72:75], v[184:187], v[212:215], v[72:75]
	v_mfma_f32_16x16x32_bf16 v[68:71], v[176:179], v[220:223], v[68:71]
	v_mfma_f32_16x16x32_bf16 v[64:67], v[184:187], v[220:223], v[64:67]
	v_mfma_f32_16x16x32_bf16 v[108:111], v[180:183], v[200:203], v[108:111]
	v_mfma_f32_16x16x32_bf16 v[104:107], v[192:195], v[200:203], v[104:107]
	v_mfma_f32_16x16x32_bf16 v[92:95], v[180:183], v[208:211], v[92:95]
	v_mfma_f32_16x16x32_bf16 v[88:91], v[192:195], v[208:211], v[88:91]
	v_mfma_f32_16x16x32_bf16 v[76:79], v[180:183], v[216:219], v[76:79]
	v_mfma_f32_16x16x32_bf16 v[72:75], v[192:195], v[216:219], v[72:75]
	v_mfma_f32_16x16x32_bf16 v[68:71], v[180:183], v[224:227], v[68:71]
	v_mfma_f32_16x16x32_bf16 v[64:67], v[192:195], v[224:227], v[64:67]
	s_barrier
; #define PG8_STAGE(bufoff, gbase, voff) do { _Pragma("unroll") for (int _i = 0; _i < 2; ++_i) \
;         __builtin_amdgcn_global_load_lds((const unsigned*)((const char*)(gbase) + (voff)[_i]), (LAS unsigned*)(lds + (bufoff) + ldsw + _i * 8192), 16, 0, 0); } while (0)
; #define PG8_LDA(dst, b, h) do { _Pragma("unroll") for (int m = 0; m < 4; ++m) _Pragma("unroll") for (int k = 0; k < 2; ++k) dst[m][k] = *(const LAS bf16x8*)(lds + PG8_SA(b, h) + aoff + m * 2048 + k * 1024); } while (0)
; #define PG8_LDB(dst, b, h) do { _Pragma("unroll") for (int n = 0; n < 2; ++n) _Pragma("unroll") for (int k = 0; k < 2; ++k) dst[n][k] = *(const LAS bf16x8*)(lds + PG8_SB(b, h) + boff + n * 2048 + k * 1024); } while (0)
; #define PG8_MMA(ai, bj, At, Bt) do { __builtin_amdgcn_s_setprio(1); _Pragma("unroll") for (int m = 0; m < 4; ++m) _Pragma("unroll") for (int n = 0; n < 2; ++n) _Pragma("unroll") for (int k = 0; k < 2; ++k) \
;         acc[ai][bj][m][n] = __builtin_amdgcn_mfma_f32_16x16x32_bf16(Bt[n][k], At[m][k], acc[ai][bj][m][n], 0, 0, 0); __builtin_amdgcn_s_setprio(0); } while (0)
; #define PG8_WAIT_V(n) asm volatile("s_waitcnt vmcnt(" #n ")" ::: "memory")
; #define PG8_BAR __builtin_amdgcn_s_barrier()
; template <int GI>
; __device__ __forceinline__ void gemm_phase(LAS unsigned char* lds, unsigned char* ws, int G, int cblk) {
;     ...
;             PG8_LDB(B0, 0, 0); PG8_LDB(B1, 0, 1); PG8_SCHED; PG8_LDA(At, 0, 0); PG8_STAGE(PG8_SA(1, 1), a1 + hstepA, voffA);
;             PG8_WAIT_V(8); PG8_WAIT_L(0); PG8_BAR; PG8_MMA(0, 0, At, B0); PG8_MMA(0, 1, At, B1); PG8_BAR; PG8_SCHED;
;             PG8_LDA(At, 0, 1); PG8_STAGE(PG8_SB(0, 0), b2, voffB); PG8_STAGE(PG8_SB(0, 1), b2 + hstepB, voffB); PG8_STAGE(PG8_SA(0, 0), a2, voffA);
;             PG8_WAIT_V(8); PG8_WAIT_L(0); PG8_BAR; PG8_MMA(1, 0, At, B0); PG8_MMA(1, 1, At, B1); PG8_BAR; PG8_SCHED;
;             PG8_LDB(B0, 1, 0); PG8_LDB(B1, 1, 1); PG8_SCHED; PG8_LDA(At, 1, 0); PG8_STAGE(PG8_SA(0, 1), a2 + hstepA, voffA);
;             PG8_WAIT_V(8); PG8_WAIT_L(0); PG8_BAR; PG8_MMA(0, 0, At, B0); PG8_MMA(0, 1, At, B1); PG8_BAR; PG8_SCHED;
;             PG8_LDA(At, 1, 1); PG8_STAGE(PG8_SB(1, 0), b3, voffB); PG8_STAGE(PG8_SB(1, 1), b3 + hstepB, voffB); PG8_STAGE(PG8_SA(1, 0), a3, voffA);
;             PG8_WAIT_V(8); PG8_WAIT_L(0); PG8_BAR; PG8_MMA(1, 0, At, B0); PG8_MMA(1, 1, At, B1); PG8_BAR; PG8_SCHED;
;         }
	s_add_i32 s34, s34, s0
	v_lshl_add_u64 v[188:189], v[188:189], 0, s[12:13]
	s_mov_b32 m0, s34
	ds_read_b128 v[196:199], v155 offset:49152
	ds_read_b128 v[200:203], v155 offset:50176
	ds_read_b128 v[204:207], v155 offset:51200
	ds_read_b128 v[208:211], v155 offset:52224
	ds_read_b128 v[212:215], v155 offset:53248
	ds_read_b128 v[216:219], v155 offset:54272
	ds_read_b128 v[220:223], v155 offset:55296
	ds_read_b128 v[224:227], v155 offset:56320
	global_load_lds_dwordx4 v[188:189], off
	s_add_i32 m0, s34, 0x2000
	s_add_u32 s46, s46, 0x40080
	v_lshl_add_u64 v[188:189], v[228:229], 0, s[12:13]
	s_addc_u32 s47, s47, 0
	s_add_i32 s34, s57, s0
	global_load_lds_dwordx4 v[188:189], off
	v_lshl_add_u64 v[188:189], s[46:47], 0, v[132:133]
	s_mov_b32 m0, s34
	s_nop 0
	global_load_lds_dwordx4 v[188:189], off
	v_lshl_add_u64 v[188:189], s[46:47], 0, v[136:137]
	s_add_i32 m0, s34, 0x2000
	s_nop 0
	global_load_lds_dwordx4 v[188:189], off
	v_lshl_add_u64 v[188:189], v[230:231], 0, s[12:13]
	s_mov_b32 m0, s51
	s_nop 0
	global_load_lds_dwordx4 v[188:189], off
	v_lshl_add_u64 v[188:189], v[232:233], 0, s[12:13]
	s_mov_b32 m0, s52
	s_nop 0
	global_load_lds_dwordx4 v[188:189], off
	s_waitcnt vmcnt(8)
	s_waitcnt lgkmcnt(0)
	s_barrier
	s_waitcnt lgkmcnt(0)
	v_mfma_f32_16x16x32_bf16 v[60:63], v[156:159], v[196:199], v[60:63]
	v_mfma_f32_16x16x32_bf16 v[56:59], v[168:171], v[196:199], v[56:59]
	v_mfma_f32_16x16x32_bf16 v[52:55], v[156:159], v[204:207], v[52:55]
	v_mfma_f32_16x16x32_bf16 v[48:51], v[168:171], v[204:207], v[48:51]
	v_mfma_f32_16x16x32_bf16 v[36:39], v[156:159], v[212:215], v[36:39]
	v_mfma_f32_16x16x32_bf16 v[32:35], v[168:171], v[212:215], v[32:35]
	v_mfma_f32_16x16x32_bf16 v[20:23], v[156:159], v[220:223], v[20:23]
	v_mfma_f32_16x16x32_bf16 v[16:19], v[168:171], v[220:223], v[16:19]
	v_mfma_f32_16x16x32_bf16 v[60:63], v[164:167], v[200:203], v[60:63]
	v_mfma_f32_16x16x32_bf16 v[56:59], v[172:175], v[200:203], v[56:59]
	v_mfma_f32_16x16x32_bf16 v[52:55], v[164:167], v[208:211], v[52:55]
	v_mfma_f32_16x16x32_bf16 v[48:51], v[172:175], v[208:211], v[48:51]
	v_mfma_f32_16x16x32_bf16 v[36:39], v[164:167], v[216:219], v[36:39]
	v_mfma_f32_16x16x32_bf16 v[32:35], v[172:175], v[216:219], v[32:35]
	v_mfma_f32_16x16x32_bf16 v[20:23], v[164:167], v[224:227], v[20:23]
	v_mfma_f32_16x16x32_bf16 v[16:19], v[172:175], v[224:227], v[16:19]
	v_mfma_f32_16x16x32_bf16 v[44:47], v[176:179], v[196:199], v[44:47]
	v_mfma_f32_16x16x32_bf16 v[40:43], v[184:187], v[196:199], v[40:43]
	v_mfma_f32_16x16x32_bf16 v[28:31], v[176:179], v[204:207], v[28:31]
	v_mfma_f32_16x16x32_bf16 v[24:27], v[184:187], v[204:207], v[24:27]
	v_mfma_f32_16x16x32_bf16 v[12:15], v[176:179], v[212:215], v[12:15]
	v_mfma_f32_16x16x32_bf16 v[8:11], v[184:187], v[212:215], v[8:11]
	v_mfma_f32_16x16x32_bf16 v[4:7], v[176:179], v[220:223], v[4:7]
	v_mfma_f32_16x16x32_bf16 v[0:3], v[184:187], v[220:223], v[0:3]
	v_mfma_f32_16x16x32_bf16 v[44:47], v[180:183], v[200:203], v[44:47]
	v_mfma_f32_16x16x32_bf16 v[40:43], v[192:195], v[200:203], v[40:43]
	v_mfma_f32_16x16x32_bf16 v[28:31], v[180:183], v[208:211], v[28:31]
	v_mfma_f32_16x16x32_bf16 v[24:27], v[192:195], v[208:211], v[24:27]
	v_mfma_f32_16x16x32_bf16 v[12:15], v[180:183], v[216:219], v[12:15]
	v_mfma_f32_16x16x32_bf16 v[8:11], v[192:195], v[216:219], v[8:11]
	v_mfma_f32_16x16x32_bf16 v[4:7], v[180:183], v[224:227], v[4:7]
	v_mfma_f32_16x16x32_bf16 v[0:3], v[192:195], v[224:227], v[0:3]
	s_barrier
	s_add_i32 s19, s19, 2
	s_add_u32 s44, s44, 0x100
	s_addc_u32 s45, s45, 0
	s_add_u32 s16, s16, 0x100
	s_addc_u32 s17, s17, 0
	s_cmp_gt_u32 s19, 13
	s_cbranch_scc0 .LBB0_697
	s_branch .Lpeel_exit_7
.LBB0_697:
	ds_read_b128 v[156:159], v153
	ds_read_b128 v[164:167], v153 offset:1024
	ds_read_b128 v[168:171], v153 offset:2048
	ds_read_b128 v[172:175], v153 offset:3072
	ds_read_b128 v[176:179], v154
	ds_read_b128 v[180:183], v154 offset:1024
	ds_read_b128 v[184:187], v154 offset:2048
	ds_read_b128 v[192:195], v154 offset:3072
	s_add_u32 s34, s44, 0xfffc0080
	s_addc_u32 s46, s45, -1
	s_cmp_eq_u32 s19, 12
	s_cselect_b32 s49, s39, s46
	s_cselect_b32 s48, s38, s34
	s_cselect_b32 s47, s41, s17
	s_cselect_b32 s46, s40, s16
	v_lshl_add_u64 v[188:189], s[44:45], 0, v[140:141]
	s_add_i32 m0, s25, 0xc000
	ds_read_b128 v[196:199], v155
	ds_read_b128 v[200:203], v155 offset:1024
	ds_read_b128 v[204:207], v155 offset:2048
	ds_read_b128 v[208:211], v155 offset:3072
	ds_read_b128 v[212:215], v155 offset:4096
	ds_read_b128 v[216:219], v155 offset:5120
	ds_read_b128 v[220:223], v155 offset:6144
	ds_read_b128 v[224:227], v155 offset:7168
	global_load_lds_dwordx4 v[188:189], off
	v_lshl_add_u64 v[188:189], s[44:45], 0, v[142:143]
	s_add_i32 m0, s25, 0xe000
	s_nop 0
	global_load_lds_dwordx4 v[188:189], off
	s_waitcnt vmcnt(8)
	s_waitcnt lgkmcnt(0)
	s_barrier
; #define PG8_STAGE(bufoff, gbase, voff) do { _Pragma("unroll") for (int _i = 0; _i < 2; ++_i) \
;         __builtin_amdgcn_global_load_lds((const unsigned*)((const char*)(gbase) + (voff)[_i]), (LAS unsigned*)(lds + (bufoff) + ldsw + _i * 8192), 16, 0, 0); } while (0)
; #define PG8_LDA(dst, b, h) do { _Pragma("unroll") for (int m = 0; m < 4; ++m) _Pragma("unroll") for (int k = 0; k < 2; ++k) dst[m][k] = *(const LAS bf16x8*)(lds + PG8_SA(b, h) + aoff + m * 2048 + k * 1024); } while (0)
; #define PG8_MMA(ai, bj, At, Bt) do { __builtin_amdgcn_s_setprio(1); _Pragma("unroll") for (int m = 0; m < 4; ++m) _Pragma("unroll") for (int n = 0; n < 2; ++n) _Pragma("unroll") for (int k = 0; k < 2; ++k) \
;         acc[ai][bj][m][n] = __builtin_amdgcn_mfma_f32_16x16x32_bf16(Bt[n][k], At[m][k], acc[ai][bj][m][n], 0, 0, 0); __builtin_amdgcn_s_setprio(0); } while (0)
; #define PG8_WAIT_V(n) asm volatile("s_waitcnt vmcnt(" #n ")" ::: "memory")
; #define PG8_WAIT_L(n) asm volatile("s_waitcnt lgkmcnt(" #n ")" ::: "memory")
; #define PG8_BAR __builtin_amdgcn_s_barrier()
; #define PG8_SCHED __builtin_amdgcn_sched_barrier(0)
; template <int GI>
; __device__ __forceinline__ void gemm_phase(LAS unsigned char* lds, unsigned char* ws, int G, int cblk) {
;     ...
;             PG8_WAIT_V(8); PG8_WAIT_L(0); PG8_BAR; PG8_MMA(0, 0, At, B0); PG8_MMA(0, 1, At, B1); PG8_BAR; PG8_SCHED;
;             PG8_LDA(At, 0, 1); PG8_STAGE(PG8_SB(0, 0), b2, voffB); PG8_STAGE(PG8_SB(0, 1), b2 + hstepB, voffB); PG8_STAGE(PG8_SA(0, 0), a2, voffA);
;             PG8_WAIT_V(8); PG8_WAIT_L(0); PG8_BAR; PG8_MMA(1, 0, At, B0); PG8_MMA(1, 1, At, B1); PG8_BAR; PG8_SCHED;
	s_waitcnt lgkmcnt(0)
	v_mfma_f32_16x16x32_bf16 v[124:127], v[156:159], v[196:199], v[124:127]
	v_mfma_f32_16x16x32_bf16 v[120:123], v[168:171], v[196:199], v[120:123]
	v_mfma_f32_16x16x32_bf16 v[116:119], v[156:159], v[204:207], v[116:119]
	v_mfma_f32_16x16x32_bf16 v[112:115], v[168:171], v[204:207], v[112:115]
	v_mfma_f32_16x16x32_bf16 v[100:103], v[156:159], v[212:215], v[100:103]
	v_mfma_f32_16x16x32_bf16 v[96:99], v[168:171], v[212:215], v[96:99]
	v_mfma_f32_16x16x32_bf16 v[84:87], v[156:159], v[220:223], v[84:87]
	v_mfma_f32_16x16x32_bf16 v[80:83], v[168:171], v[220:223], v[80:83]
	v_mfma_f32_16x16x32_bf16 v[124:127], v[164:167], v[200:203], v[124:127]
	v_mfma_f32_16x16x32_bf16 v[120:123], v[172:175], v[200:203], v[120:123]
	v_mfma_f32_16x16x32_bf16 v[116:119], v[164:167], v[208:211], v[116:119]
	v_mfma_f32_16x16x32_bf16 v[112:115], v[172:175], v[208:211], v[112:115]
	v_mfma_f32_16x16x32_bf16 v[100:103], v[164:167], v[216:219], v[100:103]
	v_mfma_f32_16x16x32_bf16 v[96:99], v[172:175], v[216:219], v[96:99]
	v_mfma_f32_16x16x32_bf16 v[84:87], v[164:167], v[224:227], v[84:87]
	v_mfma_f32_16x16x32_bf16 v[80:83], v[172:175], v[224:227], v[80:83]
	v_mfma_f32_16x16x32_bf16 v[108:111], v[176:179], v[196:199], v[108:111]
	v_mfma_f32_16x16x32_bf16 v[104:107], v[184:187], v[196:199], v[104:107]
	v_mfma_f32_16x16x32_bf16 v[92:95], v[176:179], v[204:207], v[92:95]
	v_mfma_f32_16x16x32_bf16 v[88:91], v[184:187], v[204:207], v[88:91]
	v_mfma_f32_16x16x32_bf16 v[76:79], v[176:179], v[212:215], v[76:79]
	v_mfma_f32_16x16x32_bf16 v[72:75], v[184:187], v[212:215], v[72:75]
	v_mfma_f32_16x16x32_bf16 v[68:71], v[176:179], v[220:223], v[68:71]
	v_mfma_f32_16x16x32_bf16 v[64:67], v[184:187], v[220:223], v[64:67]
	v_mfma_f32_16x16x32_bf16 v[108:111], v[180:183], v[200:203], v[108:111]
	v_mfma_f32_16x16x32_bf16 v[104:107], v[192:195], v[200:203], v[104:107]
	v_mfma_f32_16x16x32_bf16 v[92:95], v[180:183], v[208:211], v[92:95]
	v_mfma_f32_16x16x32_bf16 v[88:91], v[192:195], v[208:211], v[88:91]
	v_mfma_f32_16x16x32_bf16 v[76:79], v[180:183], v[216:219], v[76:79]
	v_mfma_f32_16x16x32_bf16 v[72:75], v[192:195], v[216:219], v[72:75]
	v_mfma_f32_16x16x32_bf16 v[68:71], v[180:183], v[224:227], v[68:71]
	v_mfma_f32_16x16x32_bf16 v[64:67], v[192:195], v[224:227], v[64:67]
	s_barrier
	s_add_i32 s34, s53, s0
	v_lshl_add_u64 v[188:189], s[46:47], 0, v[132:133]
	s_mov_b32 m0, s34
	ds_read_b128 v[196:199], v155 offset:16384
	ds_read_b128 v[200:203], v155 offset:17408
	ds_read_b128 v[204:207], v155 offset:18432
	ds_read_b128 v[208:211], v155 offset:19456
	ds_read_b128 v[212:215], v155 offset:20480
	ds_read_b128 v[216:219], v155 offset:21504
	ds_read_b128 v[220:223], v155 offset:22528
	ds_read_b128 v[224:227], v155 offset:23552
	global_load_lds_dwordx4 v[188:189], off
	s_add_i32 m0, s34, 0x2000
	s_add_u32 s58, s46, 0x40000
	v_lshl_add_u64 v[228:229], s[46:47], 0, v[136:137]
	s_addc_u32 s59, s47, 0
	s_add_i32 s34, s55, s0
	global_load_lds_dwordx4 v[228:229], off
	v_lshl_add_u64 v[230:231], s[58:59], 0, v[132:133]
	s_mov_b32 m0, s34
	v_lshl_add_u64 v[232:233], s[48:49], 0, v[134:135]
	global_load_lds_dwordx4 v[230:231], off
	v_lshl_add_u64 v[230:231], s[58:59], 0, v[136:137]
	s_add_i32 m0, s34, 0x2000
	s_nop 0
	global_load_lds_dwordx4 v[230:231], off
	v_lshl_add_u64 v[230:231], s[48:49], 0, v[130:131]
	s_mov_b32 m0, s25
	s_nop 0
	global_load_lds_dwordx4 v[230:231], off
	s_mov_b32 m0, s26
	s_nop 0
	global_load_lds_dwordx4 v[232:233], off
	s_waitcnt vmcnt(8)
	s_waitcnt lgkmcnt(0)
	s_barrier
	s_waitcnt lgkmcnt(0)
	v_mfma_f32_16x16x32_bf16 v[60:63], v[156:159], v[196:199], v[60:63]
	v_mfma_f32_16x16x32_bf16 v[56:59], v[168:171], v[196:199], v[56:59]
	v_mfma_f32_16x16x32_bf16 v[52:55], v[156:159], v[204:207], v[52:55]
	v_mfma_f32_16x16x32_bf16 v[48:51], v[168:171], v[204:207], v[48:51]
	v_mfma_f32_16x16x32_bf16 v[36:39], v[156:159], v[212:215], v[36:39]
	v_mfma_f32_16x16x32_bf16 v[32:35], v[168:171], v[212:215], v[32:35]
	v_mfma_f32_16x16x32_bf16 v[20:23], v[156:159], v[220:223], v[20:23]
	v_mfma_f32_16x16x32_bf16 v[16:19], v[168:171], v[220:223], v[16:19]
	v_mfma_f32_16x16x32_bf16 v[60:63], v[164:167], v[200:203], v[60:63]
	v_mfma_f32_16x16x32_bf16 v[56:59], v[172:175], v[200:203], v[56:59]
	v_mfma_f32_16x16x32_bf16 v[52:55], v[164:167], v[208:211], v[52:55]
	v_mfma_f32_16x16x32_bf16 v[48:51], v[172:175], v[208:211], v[48:51]
	v_mfma_f32_16x16x32_bf16 v[36:39], v[164:167], v[216:219], v[36:39]
	v_mfma_f32_16x16x32_bf16 v[32:35], v[172:175], v[216:219], v[32:35]
	v_mfma_f32_16x16x32_bf16 v[20:23], v[164:167], v[224:227], v[20:23]
	v_mfma_f32_16x16x32_bf16 v[16:19], v[172:175], v[224:227], v[16:19]
	v_mfma_f32_16x16x32_bf16 v[44:47], v[176:179], v[196:199], v[44:47]
	v_mfma_f32_16x16x32_bf16 v[40:43], v[184:187], v[196:199], v[40:43]
	v_mfma_f32_16x16x32_bf16 v[28:31], v[176:179], v[204:207], v[28:31]
	v_mfma_f32_16x16x32_bf16 v[24:27], v[184:187], v[204:207], v[24:27]
	v_mfma_f32_16x16x32_bf16 v[12:15], v[176:179], v[212:215], v[12:15]
	v_mfma_f32_16x16x32_bf16 v[8:11], v[184:187], v[212:215], v[8:11]
	v_mfma_f32_16x16x32_bf16 v[4:7], v[176:179], v[220:223], v[4:7]
	v_mfma_f32_16x16x32_bf16 v[0:3], v[184:187], v[220:223], v[0:3]
	v_mfma_f32_16x16x32_bf16 v[44:47], v[180:183], v[200:203], v[44:47]
	v_mfma_f32_16x16x32_bf16 v[40:43], v[192:195], v[200:203], v[40:43]
	v_mfma_f32_16x16x32_bf16 v[28:31], v[180:183], v[208:211], v[28:31]
	v_mfma_f32_16x16x32_bf16 v[24:27], v[192:195], v[208:211], v[24:27]
	v_mfma_f32_16x16x32_bf16 v[12:15], v[180:183], v[216:219], v[12:15]
	v_mfma_f32_16x16x32_bf16 v[8:11], v[192:195], v[216:219], v[8:11]
	v_mfma_f32_16x16x32_bf16 v[4:7], v[180:183], v[224:227], v[4:7]
	v_mfma_f32_16x16x32_bf16 v[0:3], v[192:195], v[224:227], v[0:3]
	s_barrier
; #define PG8_STAGE(bufoff, gbase, voff) do { _Pragma("unroll") for (int _i = 0; _i < 2; ++_i) \
;         __builtin_amdgcn_global_load_lds((const unsigned*)((const char*)(gbase) + (voff)[_i]), (LAS unsigned*)(lds + (bufoff) + ldsw + _i * 8192), 16, 0, 0); } while (0)
; #define PG8_LDA(dst, b, h) do { _Pragma("unroll") for (int m = 0; m < 4; ++m) _Pragma("unroll") for (int k = 0; k < 2; ++k) dst[m][k] = *(const LAS bf16x8*)(lds + PG8_SA(b, h) + aoff + m * 2048 + k * 1024); } while (0)
; #define PG8_LDB(dst, b, h) do { _Pragma("unroll") for (int n = 0; n < 2; ++n) _Pragma("unroll") for (int k = 0; k < 2; ++k) dst[n][k] = *(const LAS bf16x8*)(lds + PG8_SB(b, h) + boff + n * 2048 + k * 1024); } while (0)
; #define PG8_MMA(ai, bj, At, Bt) do { __builtin_amdgcn_s_setprio(1); _Pragma("unroll") for (int m = 0; m < 4; ++m) _Pragma("unroll") for (int n = 0; n < 2; ++n) _Pragma("unroll") for (int k = 0; k < 2; ++k) \
;         acc[ai][bj][m][n] = __builtin_amdgcn_mfma_f32_16x16x32_bf16(Bt[n][k], At[m][k], acc[ai][bj][m][n], 0, 0, 0); __builtin_amdgcn_s_setprio(0); } while (0)
; #define PG8_WAIT_V(n) asm volatile("s_waitcnt vmcnt(" #n ")" ::: "memory")
; #define PG8_WAIT_L(n) asm volatile("s_waitcnt lgkmcnt(" #n ")" ::: "memory")
; #define PG8_BAR __builtin_amdgcn_s_barrier()
; #define PG8_SCHED __builtin_amdgcn_sched_barrier(0)
; template <int GI>
; __device__ __forceinline__ void gemm_phase(LAS unsigned char* lds, unsigned char* ws, int G, int cblk) {
;     ...
;             PG8_LDB(B0, 1, 0); PG8_LDB(B1, 1, 1); PG8_SCHED; PG8_LDA(At, 1, 0); PG8_STAGE(PG8_SA(0, 1), a2 + hstepA, voffA);
;             PG8_WAIT_V(8); PG8_WAIT_L(0); PG8_BAR; PG8_MMA(0, 0, At, B0); PG8_MMA(0, 1, At, B1); PG8_BAR; PG8_SCHED;
;             PG8_LDA(At, 1, 1); PG8_STAGE(PG8_SB(1, 0), b3, voffB); PG8_STAGE(PG8_SB(1, 1), b3 + hstepB, voffB); PG8_STAGE(PG8_SA(1, 0), a3, voffA);
;             PG8_WAIT_V(8); PG8_WAIT_L(0); PG8_BAR; PG8_MMA(1, 0, At, B0); PG8_MMA(1, 1, At, B1); PG8_BAR; PG8_SCHED;
;         }
	s_add_i32 s34, 0, 0x18000
	v_add_u32_e32 v161, s34, v152
	s_add_i32 s57, 0, 0x1c000
	ds_read_b128 v[156:159], v161
	ds_read_b128 v[164:167], v161 offset:1024
	ds_read_b128 v[168:171], v161 offset:2048
	ds_read_b128 v[172:175], v161 offset:3072
	v_add_u32_e32 v161, s57, v152
	ds_read_b128 v[176:179], v161
	ds_read_b128 v[180:183], v161 offset:1024
	ds_read_b128 v[184:187], v161 offset:2048
	ds_read_b128 v[192:195], v161 offset:3072
	s_add_u32 s48, s48, 0x40000
	s_addc_u32 s49, s49, 0
	s_mov_b32 m0, s27
	v_lshl_add_u64 v[234:235], s[48:49], 0, v[130:131]
	ds_read_b128 v[196:199], v155 offset:32768
	ds_read_b128 v[200:203], v155 offset:33792
	ds_read_b128 v[204:207], v155 offset:34816
	ds_read_b128 v[208:211], v155 offset:35840
	ds_read_b128 v[212:215], v155 offset:36864
	ds_read_b128 v[216:219], v155 offset:37888
	ds_read_b128 v[220:223], v155 offset:38912
	ds_read_b128 v[224:227], v155 offset:39936
	global_load_lds_dwordx4 v[234:235], off
	v_lshl_add_u64 v[234:235], s[48:49], 0, v[134:135]
	s_mov_b32 m0, s33
	s_nop 0
	global_load_lds_dwordx4 v[234:235], off
	s_waitcnt vmcnt(8)
	s_waitcnt lgkmcnt(0)
	s_barrier
	s_waitcnt lgkmcnt(0)
	v_mfma_f32_16x16x32_bf16 v[124:127], v[156:159], v[196:199], v[124:127]
	v_mfma_f32_16x16x32_bf16 v[120:123], v[168:171], v[196:199], v[120:123]
	v_mfma_f32_16x16x32_bf16 v[116:119], v[156:159], v[204:207], v[116:119]
	v_mfma_f32_16x16x32_bf16 v[112:115], v[168:171], v[204:207], v[112:115]
	v_mfma_f32_16x16x32_bf16 v[100:103], v[156:159], v[212:215], v[100:103]
	v_mfma_f32_16x16x32_bf16 v[96:99], v[168:171], v[212:215], v[96:99]
	v_mfma_f32_16x16x32_bf16 v[84:87], v[156:159], v[220:223], v[84:87]
	v_mfma_f32_16x16x32_bf16 v[80:83], v[168:171], v[220:223], v[80:83]
	v_mfma_f32_16x16x32_bf16 v[124:127], v[164:167], v[200:203], v[124:127]
	v_mfma_f32_16x16x32_bf16 v[120:123], v[172:175], v[200:203], v[120:123]
	v_mfma_f32_16x16x32_bf16 v[116:119], v[164:167], v[208:211], v[116:119]
	v_mfma_f32_16x16x32_bf16 v[112:115], v[172:175], v[208:211], v[112:115]
	v_mfma_f32_16x16x32_bf16 v[100:103], v[164:167], v[216:219], v[100:103]
	v_mfma_f32_16x16x32_bf16 v[96:99], v[172:175], v[216:219], v[96:99]
	v_mfma_f32_16x16x32_bf16 v[84:87], v[164:167], v[224:227], v[84:87]
	v_mfma_f32_16x16x32_bf16 v[80:83], v[172:175], v[224:227], v[80:83]
	v_mfma_f32_16x16x32_bf16 v[108:111], v[176:179], v[196:199], v[108:111]
	v_mfma_f32_16x16x32_bf16 v[104:107], v[184:187], v[196:199], v[104:107]
	v_mfma_f32_16x16x32_bf16 v[92:95], v[176:179], v[204:207], v[92:95]
	v_mfma_f32_16x16x32_bf16 v[88:91], v[184:187], v[204:207], v[88:91]
	v_mfma_f32_16x16x32_bf16 v[76:79], v[176:179], v[212:215], v[76:79]
	v_mfma_f32_16x16x32_bf16 v[72:75], v[184:187], v[212:215], v[72:75]
	v_mfma_f32_16x16x32_bf16 v[68:71], v[176:179], v[220:223], v[68:71]
	v_mfma_f32_16x16x32_bf16 v[64:67], v[184:187], v[220:223], v[64:67]
	v_mfma_f32_16x16x32_bf16 v[108:111], v[180:183], v[200:203], v[108:111]
	v_mfma_f32_16x16x32_bf16 v[104:107], v[192:195], v[200:203], v[104:107]
	v_mfma_f32_16x16x32_bf16 v[92:95], v[180:183], v[208:211], v[92:95]
	v_mfma_f32_16x16x32_bf16 v[88:91], v[192:195], v[208:211], v[88:91]
	v_mfma_f32_16x16x32_bf16 v[76:79], v[180:183], v[216:219], v[76:79]
	v_mfma_f32_16x16x32_bf16 v[72:75], v[192:195], v[216:219], v[72:75]
	v_mfma_f32_16x16x32_bf16 v[68:71], v[180:183], v[224:227], v[68:71]
	v_mfma_f32_16x16x32_bf16 v[64:67], v[192:195], v[224:227], v[64:67]
	s_barrier
	s_add_i32 s34, s34, s0
	v_lshl_add_u64 v[188:189], v[188:189], 0, s[12:13]
	s_mov_b32 m0, s34
	ds_read_b128 v[196:199], v155 offset:49152
	ds_read_b128 v[200:203], v155 offset:50176
	ds_read_b128 v[204:207], v155 offset:51200
	ds_read_b128 v[208:211], v155 offset:52224
	ds_read_b128 v[212:215], v155 offset:53248
	ds_read_b128 v[216:219], v155 offset:54272
	ds_read_b128 v[220:223], v155 offset:55296
	ds_read_b128 v[224:227], v155 offset:56320
	global_load_lds_dwordx4 v[188:189], off
	s_add_i32 m0, s34, 0x2000
	s_add_u32 s46, s46, 0x40080
	v_lshl_add_u64 v[188:189], v[228:229], 0, s[12:13]
	s_addc_u32 s47, s47, 0
	s_add_i32 s34, s57, s0
	global_load_lds_dwordx4 v[188:189], off
	v_lshl_add_u64 v[188:189], s[46:47], 0, v[132:133]
	s_mov_b32 m0, s34
	s_nop 0
	global_load_lds_dwordx4 v[188:189], off
	v_lshl_add_u64 v[188:189], s[46:47], 0, v[136:137]
	s_add_i32 m0, s34, 0x2000
	s_nop 0
	global_load_lds_dwordx4 v[188:189], off
	v_lshl_add_u64 v[188:189], v[230:231], 0, s[12:13]
	s_mov_b32 m0, s51
	s_nop 0
	global_load_lds_dwordx4 v[188:189], off
	v_lshl_add_u64 v[188:189], v[232:233], 0, s[12:13]
	s_mov_b32 m0, s52
	s_nop 0
	global_load_lds_dwordx4 v[188:189], off
	s_waitcnt vmcnt(8)
	s_waitcnt lgkmcnt(0)
	s_barrier
	s_waitcnt lgkmcnt(0)
	v_mfma_f32_16x16x32_bf16 v[60:63], v[156:159], v[196:199], v[60:63]
	v_mfma_f32_16x16x32_bf16 v[56:59], v[168:171], v[196:199], v[56:59]
	v_mfma_f32_16x16x32_bf16 v[52:55], v[156:159], v[204:207], v[52:55]
	v_mfma_f32_16x16x32_bf16 v[48:51], v[168:171], v[204:207], v[48:51]
	v_mfma_f32_16x16x32_bf16 v[36:39], v[156:159], v[212:215], v[36:39]
	v_mfma_f32_16x16x32_bf16 v[32:35], v[168:171], v[212:215], v[32:35]
	v_mfma_f32_16x16x32_bf16 v[20:23], v[156:159], v[220:223], v[20:23]
	v_mfma_f32_16x16x32_bf16 v[16:19], v[168:171], v[220:223], v[16:19]
	v_mfma_f32_16x16x32_bf16 v[60:63], v[164:167], v[200:203], v[60:63]
	v_mfma_f32_16x16x32_bf16 v[56:59], v[172:175], v[200:203], v[56:59]
	v_mfma_f32_16x16x32_bf16 v[52:55], v[164:167], v[208:211], v[52:55]
	v_mfma_f32_16x16x32_bf16 v[48:51], v[172:175], v[208:211], v[48:51]
	v_mfma_f32_16x16x32_bf16 v[36:39], v[164:167], v[216:219], v[36:39]
	v_mfma_f32_16x16x32_bf16 v[32:35], v[172:175], v[216:219], v[32:35]
	v_mfma_f32_16x16x32_bf16 v[20:23], v[164:167], v[224:227], v[20:23]
	v_mfma_f32_16x16x32_bf16 v[16:19], v[172:175], v[224:227], v[16:19]
	v_mfma_f32_16x16x32_bf16 v[44:47], v[176:179], v[196:199], v[44:47]
	v_mfma_f32_16x16x32_bf16 v[40:43], v[184:187], v[196:199], v[40:43]
	v_mfma_f32_16x16x32_bf16 v[28:31], v[176:179], v[204:207], v[28:31]
	v_mfma_f32_16x16x32_bf16 v[24:27], v[184:187], v[204:207], v[24:27]
	v_mfma_f32_16x16x32_bf16 v[12:15], v[176:179], v[212:215], v[12:15]
	v_mfma_f32_16x16x32_bf16 v[8:11], v[184:187], v[212:215], v[8:11]
	v_mfma_f32_16x16x32_bf16 v[4:7], v[176:179], v[220:223], v[4:7]
	v_mfma_f32_16x16x32_bf16 v[0:3], v[184:187], v[220:223], v[0:3]
	v_mfma_f32_16x16x32_bf16 v[44:47], v[180:183], v[200:203], v[44:47]
	v_mfma_f32_16x16x32_bf16 v[40:43], v[192:195], v[200:203], v[40:43]
	v_mfma_f32_16x16x32_bf16 v[28:31], v[180:183], v[208:211], v[28:31]
	v_mfma_f32_16x16x32_bf16 v[24:27], v[192:195], v[208:211], v[24:27]
	v_mfma_f32_16x16x32_bf16 v[12:15], v[180:183], v[216:219], v[12:15]
	v_mfma_f32_16x16x32_bf16 v[8:11], v[192:195], v[216:219], v[8:11]
	v_mfma_f32_16x16x32_bf16 v[4:7], v[180:183], v[224:227], v[4:7]
	v_mfma_f32_16x16x32_bf16 v[0:3], v[192:195], v[224:227], v[0:3]
	s_barrier
	s_add_i32 s19, s19, 2
	s_add_u32 s44, s44, 0x100
	s_addc_u32 s45, s45, 0
	s_add_u32 s16, s16, 0x100
	s_addc_u32 s17, s17, 0
	s_cmp_gt_u32 s19, 13
	s_cbranch_scc0 .LBB0_697

; #define PG8_STAGE(bufoff, gbase, voff) do { _Pragma("unroll") for (int _i = 0; _i < 2; ++_i) \
;         __builtin_amdgcn_global_load_lds((const unsigned*)((const char*)(gbase) + (voff)[_i]), (LAS unsigned*)(lds + (bufoff) + ldsw + _i * 8192), 16, 0, 0); } while (0)
; #define PG8_LDA(dst, b, h) do { _Pragma("unroll") for (int m = 0; m < 4; ++m) _Pragma("unroll") for (int k = 0; k < 2; ++k) dst[m][k] = *(const LAS bf16x8*)(lds + PG8_SA(b, h) + aoff + m * 2048 + k * 1024); } while (0)
; #define PG8_LDB(dst, b, h) do { _Pragma("unroll") for (int n = 0; n < 2; ++n) _Pragma("unroll") for (int k = 0; k < 2; ++k) dst[n][k] = *(const LAS bf16x8*)(lds + PG8_SB(b, h) + boff + n * 2048 + k * 1024); } while (0)
; #define PG8_MMA(ai, bj, At, Bt) do { __builtin_amdgcn_s_setprio(1); _Pragma("unroll") for (int m = 0; m < 4; ++m) _Pragma("unroll") for (int n = 0; n < 2; ++n) _Pragma("unroll") for (int k = 0; k < 2; ++k) \
;         acc[ai][bj][m][n] = __builtin_amdgcn_mfma_f32_16x16x32_bf16(Bt[n][k], At[m][k], acc[ai][bj][m][n], 0, 0, 0); __builtin_amdgcn_s_setprio(0); } while (0)
; #define PG8_WAIT_V(n) asm volatile("s_waitcnt vmcnt(" #n ")" ::: "memory")
; #define PG8_WAIT_L(n) asm volatile("s_waitcnt lgkmcnt(" #n ")" ::: "memory")
; #define PG8_BAR __builtin_amdgcn_s_barrier()
; template <int GI>
; __device__ __forceinline__ void gemm_phase(LAS unsigned char* lds, unsigned char* ws, int G, int cblk) {
;     ...
;         const char* nA = has_next ? nxt.A : cA; const char* nB = has_next ? nxt.B : cB;
;         for (int t = 0; t < nt; t += 2) {
;             const bool last = (t == nt - 2);
;             const char* a1 = cA + (size_t)(t + 1) * kstep;
;             const char* a2 = last ? nA : cA + (size_t)(t + 2) * kstep; const char* b2 = last ? nB : cB + (size_t)(t + 2) * kstep;
;             const char* a3 = a2 + kstep; const char* b3 = b2 + kstep;
;             PG8_LDB(B0, 0, 0); PG8_LDB(B1, 0, 1); PG8_SCHED; PG8_LDA(At, 0, 0); PG8_STAGE(PG8_SA(1, 1), a1 + hstepA, voffA);
;             PG8_WAIT_V(8); PG8_WAIT_L(0); PG8_BAR; PG8_MMA(0, 0, At, B0); PG8_MMA(0, 1, At, B1); PG8_BAR; PG8_SCHED;
;             PG8_LDA(At, 0, 1); PG8_STAGE(PG8_SB(0, 0), b2, voffB); PG8_STAGE(PG8_SB(0, 1), b2 + hstepB, voffB); PG8_STAGE(PG8_SA(0, 0), a2, voffA);
;             PG8_WAIT_V(8); PG8_WAIT_L(0); PG8_BAR; PG8_MMA(1, 0, At, B0); PG8_MMA(1, 1, At, B1); PG8_BAR; PG8_SCHED;
.LBB0_819:
	s_add_u32 s40, s40, 0x80080
	s_addc_u32 s41, s41, 0
	s_add_u32 s0, s42, 0x100
	s_addc_u32 s1, s43, 0
	s_mov_b32 s17, -2
	ds_read_b128 v[156:159], v153
	ds_read_b128 v[164:167], v153 offset:1024
	ds_read_b128 v[168:171], v153 offset:2048
	ds_read_b128 v[172:175], v153 offset:3072
	ds_read_b128 v[176:179], v154
	ds_read_b128 v[180:183], v154 offset:1024
	ds_read_b128 v[184:187], v154 offset:2048
	ds_read_b128 v[192:195], v154 offset:3072
	s_add_u32 s24, s40, 0xfff80080
	s_addc_u32 s25, s41, -1
	s_cmp_eq_u32 s17, 28
	s_cselect_b32 s45, s19, s25
	s_cselect_b32 s44, s18, s24
	s_cselect_b32 s43, s21, s1
	s_cselect_b32 s42, s20, s0
	v_lshl_add_u64 v[188:189], s[40:41], 0, v[140:141]
	s_add_i32 m0, s49, 0xc000
	ds_read_b128 v[196:199], v155
	ds_read_b128 v[200:203], v155 offset:1024
	ds_read_b128 v[204:207], v155 offset:2048
	ds_read_b128 v[208:211], v155 offset:3072
	ds_read_b128 v[212:215], v155 offset:4096
	ds_read_b128 v[216:219], v155 offset:5120
	ds_read_b128 v[220:223], v155 offset:6144
	ds_read_b128 v[224:227], v155 offset:7168
	global_load_lds_dwordx4 v[188:189], off
	v_lshl_add_u64 v[188:189], s[40:41], 0, v[142:143]
	s_add_i32 m0, s49, 0xe000
	s_nop 0
	global_load_lds_dwordx4 v[188:189], off
	s_waitcnt vmcnt(8)
	s_waitcnt lgkmcnt(0)
	s_barrier
	s_waitcnt lgkmcnt(0)
	v_mfma_f32_16x16x32_bf16 v[124:127], v[156:159], v[196:199], 0
	v_mfma_f32_16x16x32_bf16 v[120:123], v[168:171], v[196:199], 0
	v_mfma_f32_16x16x32_bf16 v[108:111], v[156:159], v[204:207], 0
	v_mfma_f32_16x16x32_bf16 v[104:107], v[168:171], v[204:207], 0
	v_mfma_f32_16x16x32_bf16 v[92:95], v[156:159], v[212:215], 0
	v_mfma_f32_16x16x32_bf16 v[88:91], v[168:171], v[212:215], 0
	v_mfma_f32_16x16x32_bf16 v[76:79], v[156:159], v[220:223], 0
	v_mfma_f32_16x16x32_bf16 v[72:75], v[168:171], v[220:223], 0
	v_mfma_f32_16x16x32_bf16 v[124:127], v[164:167], v[200:203], v[124:127]
	v_mfma_f32_16x16x32_bf16 v[120:123], v[172:175], v[200:203], v[120:123]
	v_mfma_f32_16x16x32_bf16 v[108:111], v[164:167], v[208:211], v[108:111]
	v_mfma_f32_16x16x32_bf16 v[104:107], v[172:175], v[208:211], v[104:107]
	v_mfma_f32_16x16x32_bf16 v[92:95], v[164:167], v[216:219], v[92:95]
	v_mfma_f32_16x16x32_bf16 v[88:91], v[172:175], v[216:219], v[88:91]
	v_mfma_f32_16x16x32_bf16 v[76:79], v[164:167], v[224:227], v[76:79]
	v_mfma_f32_16x16x32_bf16 v[72:75], v[172:175], v[224:227], v[72:75]
	v_mfma_f32_16x16x32_bf16 v[116:119], v[176:179], v[196:199], 0
	v_mfma_f32_16x16x32_bf16 v[112:115], v[184:187], v[196:199], 0
	v_mfma_f32_16x16x32_bf16 v[100:103], v[176:179], v[204:207], 0
	v_mfma_f32_16x16x32_bf16 v[96:99], v[184:187], v[204:207], 0
	v_mfma_f32_16x16x32_bf16 v[84:87], v[176:179], v[212:215], 0
	v_mfma_f32_16x16x32_bf16 v[80:83], v[184:187], v[212:215], 0
	v_mfma_f32_16x16x32_bf16 v[68:71], v[176:179], v[220:223], 0
	v_mfma_f32_16x16x32_bf16 v[64:67], v[184:187], v[220:223], 0
	v_mfma_f32_16x16x32_bf16 v[116:119], v[180:183], v[200:203], v[116:119]
	v_mfma_f32_16x16x32_bf16 v[112:115], v[192:195], v[200:203], v[112:115]
	v_mfma_f32_16x16x32_bf16 v[100:103], v[180:183], v[208:211], v[100:103]
	v_mfma_f32_16x16x32_bf16 v[96:99], v[192:195], v[208:211], v[96:99]
	v_mfma_f32_16x16x32_bf16 v[84:87], v[180:183], v[216:219], v[84:87]
	v_mfma_f32_16x16x32_bf16 v[80:83], v[192:195], v[216:219], v[80:83]
	v_mfma_f32_16x16x32_bf16 v[68:71], v[180:183], v[224:227], v[68:71]
	v_mfma_f32_16x16x32_bf16 v[64:67], v[192:195], v[224:227], v[64:67]
	s_barrier
	s_add_i32 s24, s56, s26
	v_lshl_add_u64 v[188:189], s[42:43], 0, v[134:135]
	s_mov_b32 m0, s24
	ds_read_b128 v[196:199], v155 offset:16384
	ds_read_b128 v[200:203], v155 offset:17408
	ds_read_b128 v[204:207], v155 offset:18432
	ds_read_b128 v[208:211], v155 offset:19456
	ds_read_b128 v[212:215], v155 offset:20480
	ds_read_b128 v[216:219], v155 offset:21504
	ds_read_b128 v[220:223], v155 offset:22528
	ds_read_b128 v[224:227], v155 offset:23552
	global_load_lds_dwordx4 v[188:189], off
	s_add_i32 m0, s24, 0x2000
	s_add_u32 s24, s42, 0x80000
	v_lshl_add_u64 v[228:229], s[42:43], 0, v[130:131]
	s_addc_u32 s25, s43, 0
	s_add_i32 s33, s57, s26
	global_load_lds_dwordx4 v[228:229], off
	v_lshl_add_u64 v[230:231], s[24:25], 0, v[134:135]
	s_mov_b32 m0, s33
	v_lshl_add_u64 v[232:233], s[44:45], 0, v[132:133]
	global_load_lds_dwordx4 v[230:231], off
	v_lshl_add_u64 v[230:231], s[24:25], 0, v[130:131]
	s_add_i32 m0, s33, 0x2000
	s_nop 0
	global_load_lds_dwordx4 v[230:231], off
	v_lshl_add_u64 v[230:231], s[44:45], 0, v[136:137]
	s_mov_b32 m0, s49
	s_nop 0
	global_load_lds_dwordx4 v[230:231], off
	s_mov_b32 m0, s50
	s_nop 0
	global_load_lds_dwordx4 v[232:233], off
	s_waitcnt vmcnt(8)
	s_waitcnt lgkmcnt(0)
	s_barrier
; #define PG8_STAGE(bufoff, gbase, voff) do { _Pragma("unroll") for (int _i = 0; _i < 2; ++_i) \
;         __builtin_amdgcn_global_load_lds((const unsigned*)((const char*)(gbase) + (voff)[_i]), (LAS unsigned*)(lds + (bufoff) + ldsw + _i * 8192), 16, 0, 0); } while (0)
; #define PG8_LDA(dst, b, h) do { _Pragma("unroll") for (int m = 0; m < 4; ++m) _Pragma("unroll") for (int k = 0; k < 2; ++k) dst[m][k] = *(const LAS bf16x8*)(lds + PG8_SA(b, h) + aoff + m * 2048 + k * 1024); } while (0)
; #define PG8_LDB(dst, b, h) do { _Pragma("unroll") for (int n = 0; n < 2; ++n) _Pragma("unroll") for (int k = 0; k < 2; ++k) dst[n][k] = *(const LAS bf16x8*)(lds + PG8_SB(b, h) + boff + n * 2048 + k * 1024); } while (0)
; #define PG8_MMA(ai, bj, At, Bt) do { __builtin_amdgcn_s_setprio(1); _Pragma("unroll") for (int m = 0; m < 4; ++m) _Pragma("unroll") for (int n = 0; n < 2; ++n) _Pragma("unroll") for (int k = 0; k < 2; ++k) \
;         acc[ai][bj][m][n] = __builtin_amdgcn_mfma_f32_16x16x32_bf16(Bt[n][k], At[m][k], acc[ai][bj][m][n], 0, 0, 0); __builtin_amdgcn_s_setprio(0); } while (0)
; #define PG8_WAIT_V(n) asm volatile("s_waitcnt vmcnt(" #n ")" ::: "memory")
; #define PG8_WAIT_L(n) asm volatile("s_waitcnt lgkmcnt(" #n ")" ::: "memory")
; #define PG8_BAR __builtin_amdgcn_s_barrier()
; #define PG8_SCHED __builtin_amdgcn_sched_barrier(0)
; template <int GI>
; __device__ __forceinline__ void gemm_phase(LAS unsigned char* lds, unsigned char* ws, int G, int cblk) {
;     ...
;             PG8_WAIT_V(8); PG8_WAIT_L(0); PG8_BAR; PG8_MMA(1, 0, At, B0); PG8_MMA(1, 1, At, B1); PG8_BAR; PG8_SCHED;
;             PG8_LDB(B0, 1, 0); PG8_LDB(B1, 1, 1); PG8_SCHED; PG8_LDA(At, 1, 0); PG8_STAGE(PG8_SA(0, 1), a2 + hstepA, voffA);
;             PG8_WAIT_V(8); PG8_WAIT_L(0); PG8_BAR; PG8_MMA(0, 0, At, B0); PG8_MMA(0, 1, At, B1); PG8_BAR; PG8_SCHED;
	s_waitcnt lgkmcnt(0)
	v_mfma_f32_16x16x32_bf16 v[60:63], v[156:159], v[196:199], 0
	v_mfma_f32_16x16x32_bf16 v[56:59], v[168:171], v[196:199], 0
	v_mfma_f32_16x16x32_bf16 v[44:47], v[156:159], v[204:207], 0
	v_mfma_f32_16x16x32_bf16 v[40:43], v[168:171], v[204:207], 0
	v_mfma_f32_16x16x32_bf16 v[28:31], v[156:159], v[212:215], 0
	v_mfma_f32_16x16x32_bf16 v[24:27], v[168:171], v[212:215], 0
	v_mfma_f32_16x16x32_bf16 v[12:15], v[156:159], v[220:223], 0
	v_mfma_f32_16x16x32_bf16 v[8:11], v[168:171], v[220:223], 0
	v_mfma_f32_16x16x32_bf16 v[60:63], v[164:167], v[200:203], v[60:63]
	v_mfma_f32_16x16x32_bf16 v[56:59], v[172:175], v[200:203], v[56:59]
	v_mfma_f32_16x16x32_bf16 v[44:47], v[164:167], v[208:211], v[44:47]
	v_mfma_f32_16x16x32_bf16 v[40:43], v[172:175], v[208:211], v[40:43]
	v_mfma_f32_16x16x32_bf16 v[28:31], v[164:167], v[216:219], v[28:31]
	v_mfma_f32_16x16x32_bf16 v[24:27], v[172:175], v[216:219], v[24:27]
	v_mfma_f32_16x16x32_bf16 v[12:15], v[164:167], v[224:227], v[12:15]
	v_mfma_f32_16x16x32_bf16 v[8:11], v[172:175], v[224:227], v[8:11]
	v_mfma_f32_16x16x32_bf16 v[52:55], v[176:179], v[196:199], 0
	v_mfma_f32_16x16x32_bf16 v[48:51], v[184:187], v[196:199], 0
	v_mfma_f32_16x16x32_bf16 v[36:39], v[176:179], v[204:207], 0
	v_mfma_f32_16x16x32_bf16 v[32:35], v[184:187], v[204:207], 0
	v_mfma_f32_16x16x32_bf16 v[20:23], v[176:179], v[212:215], 0
	v_mfma_f32_16x16x32_bf16 v[16:19], v[184:187], v[212:215], 0
	v_mfma_f32_16x16x32_bf16 v[4:7], v[176:179], v[220:223], 0
	v_mfma_f32_16x16x32_bf16 v[0:3], v[184:187], v[220:223], 0
	v_mfma_f32_16x16x32_bf16 v[52:55], v[180:183], v[200:203], v[52:55]
	v_mfma_f32_16x16x32_bf16 v[48:51], v[192:195], v[200:203], v[48:51]
	v_mfma_f32_16x16x32_bf16 v[36:39], v[180:183], v[208:211], v[36:39]
	v_mfma_f32_16x16x32_bf16 v[32:35], v[192:195], v[208:211], v[32:35]
	v_mfma_f32_16x16x32_bf16 v[20:23], v[180:183], v[216:219], v[20:23]
	v_mfma_f32_16x16x32_bf16 v[16:19], v[192:195], v[216:219], v[16:19]
	v_mfma_f32_16x16x32_bf16 v[4:7], v[180:183], v[224:227], v[4:7]
	v_mfma_f32_16x16x32_bf16 v[0:3], v[192:195], v[224:227], v[0:3]
	s_barrier
	s_add_i32 s33, 0, 0x18000
	v_add_u32_e32 v161, s33, v152
	s_add_i32 s34, 0, 0x1c000
	ds_read_b128 v[156:159], v161
	ds_read_b128 v[164:167], v161 offset:1024
	ds_read_b128 v[168:171], v161 offset:2048
	ds_read_b128 v[172:175], v161 offset:3072
	v_add_u32_e32 v161, s34, v152
	ds_read_b128 v[176:179], v161
	ds_read_b128 v[180:183], v161 offset:1024
	ds_read_b128 v[184:187], v161 offset:2048
	ds_read_b128 v[192:195], v161 offset:3072
	s_add_u32 s24, s44, 0x80000
	s_addc_u32 s25, s45, 0
	s_mov_b32 m0, s51
	v_lshl_add_u64 v[234:235], s[24:25], 0, v[136:137]
	ds_read_b128 v[196:199], v155 offset:32768
	ds_read_b128 v[200:203], v155 offset:33792
	ds_read_b128 v[204:207], v155 offset:34816
	ds_read_b128 v[208:211], v155 offset:35840
	ds_read_b128 v[212:215], v155 offset:36864
	ds_read_b128 v[216:219], v155 offset:37888
	ds_read_b128 v[220:223], v155 offset:38912
	ds_read_b128 v[224:227], v155 offset:39936
	global_load_lds_dwordx4 v[234:235], off
	v_lshl_add_u64 v[234:235], s[24:25], 0, v[132:133]
	s_mov_b32 m0, s52
	s_nop 0
	global_load_lds_dwordx4 v[234:235], off
	s_waitcnt vmcnt(8)
	s_waitcnt lgkmcnt(0)
	s_barrier
	s_waitcnt lgkmcnt(0)
	v_mfma_f32_16x16x32_bf16 v[124:127], v[156:159], v[196:199], v[124:127]
	v_mfma_f32_16x16x32_bf16 v[120:123], v[168:171], v[196:199], v[120:123]
	v_mfma_f32_16x16x32_bf16 v[108:111], v[156:159], v[204:207], v[108:111]
	v_mfma_f32_16x16x32_bf16 v[104:107], v[168:171], v[204:207], v[104:107]
	v_mfma_f32_16x16x32_bf16 v[92:95], v[156:159], v[212:215], v[92:95]
	v_mfma_f32_16x16x32_bf16 v[88:91], v[168:171], v[212:215], v[88:91]
	v_mfma_f32_16x16x32_bf16 v[76:79], v[156:159], v[220:223], v[76:79]
	v_mfma_f32_16x16x32_bf16 v[72:75], v[168:171], v[220:223], v[72:75]
	v_mfma_f32_16x16x32_bf16 v[124:127], v[164:167], v[200:203], v[124:127]
	v_mfma_f32_16x16x32_bf16 v[120:123], v[172:175], v[200:203], v[120:123]
	v_mfma_f32_16x16x32_bf16 v[108:111], v[164:167], v[208:211], v[108:111]
	v_mfma_f32_16x16x32_bf16 v[104:107], v[172:175], v[208:211], v[104:107]
	v_mfma_f32_16x16x32_bf16 v[92:95], v[164:167], v[216:219], v[92:95]
	v_mfma_f32_16x16x32_bf16 v[88:91], v[172:175], v[216:219], v[88:91]
	v_mfma_f32_16x16x32_bf16 v[76:79], v[164:167], v[224:227], v[76:79]
	v_mfma_f32_16x16x32_bf16 v[72:75], v[172:175], v[224:227], v[72:75]
	v_mfma_f32_16x16x32_bf16 v[116:119], v[176:179], v[196:199], v[116:119]
	v_mfma_f32_16x16x32_bf16 v[112:115], v[184:187], v[196:199], v[112:115]
	v_mfma_f32_16x16x32_bf16 v[100:103], v[176:179], v[204:207], v[100:103]
	v_mfma_f32_16x16x32_bf16 v[96:99], v[184:187], v[204:207], v[96:99]
	v_mfma_f32_16x16x32_bf16 v[84:87], v[176:179], v[212:215], v[84:87]
	v_mfma_f32_16x16x32_bf16 v[80:83], v[184:187], v[212:215], v[80:83]
	v_mfma_f32_16x16x32_bf16 v[68:71], v[176:179], v[220:223], v[68:71]
	v_mfma_f32_16x16x32_bf16 v[64:67], v[184:187], v[220:223], v[64:67]
	v_mfma_f32_16x16x32_bf16 v[116:119], v[180:183], v[200:203], v[116:119]
	v_mfma_f32_16x16x32_bf16 v[112:115], v[192:195], v[200:203], v[112:115]
	v_mfma_f32_16x16x32_bf16 v[100:103], v[180:183], v[208:211], v[100:103]
	v_mfma_f32_16x16x32_bf16 v[96:99], v[192:195], v[208:211], v[96:99]
	v_mfma_f32_16x16x32_bf16 v[84:87], v[180:183], v[216:219], v[84:87]
	v_mfma_f32_16x16x32_bf16 v[80:83], v[192:195], v[216:219], v[80:83]
	v_mfma_f32_16x16x32_bf16 v[68:71], v[180:183], v[224:227], v[68:71]
	v_mfma_f32_16x16x32_bf16 v[64:67], v[192:195], v[224:227], v[64:67]
	s_barrier
; #define PG8_STAGE(bufoff, gbase, voff) do { _Pragma("unroll") for (int _i = 0; _i < 2; ++_i) \
;         __builtin_amdgcn_global_load_lds((const unsigned*)((const char*)(gbase) + (voff)[_i]), (LAS unsigned*)(lds + (bufoff) + ldsw + _i * 8192), 16, 0, 0); } while (0)
; #define PG8_LDA(dst, b, h) do { _Pragma("unroll") for (int m = 0; m < 4; ++m) _Pragma("unroll") for (int k = 0; k < 2; ++k) dst[m][k] = *(const LAS bf16x8*)(lds + PG8_SA(b, h) + aoff + m * 2048 + k * 1024); } while (0)
; #define PG8_LDB(dst, b, h) do { _Pragma("unroll") for (int n = 0; n < 2; ++n) _Pragma("unroll") for (int k = 0; k < 2; ++k) dst[n][k] = *(const LAS bf16x8*)(lds + PG8_SB(b, h) + boff + n * 2048 + k * 1024); } while (0)
; #define PG8_MMA(ai, bj, At, Bt) do { __builtin_amdgcn_s_setprio(1); _Pragma("unroll") for (int m = 0; m < 4; ++m) _Pragma("unroll") for (int n = 0; n < 2; ++n) _Pragma("unroll") for (int k = 0; k < 2; ++k) \
;         acc[ai][bj][m][n] = __builtin_amdgcn_mfma_f32_16x16x32_bf16(Bt[n][k], At[m][k], acc[ai][bj][m][n], 0, 0, 0); __builtin_amdgcn_s_setprio(0); } while (0)
; #define PG8_WAIT_V(n) asm volatile("s_waitcnt vmcnt(" #n ")" ::: "memory")
; #define PG8_BAR __builtin_amdgcn_s_barrier()
; template <int GI>
; __device__ __forceinline__ void gemm_phase(LAS unsigned char* lds, unsigned char* ws, int G, int cblk) {
;     ...
;             PG8_LDB(B0, 0, 0); PG8_LDB(B1, 0, 1); PG8_SCHED; PG8_LDA(At, 0, 0); PG8_STAGE(PG8_SA(1, 1), a1 + hstepA, voffA);
;             PG8_WAIT_V(8); PG8_WAIT_L(0); PG8_BAR; PG8_MMA(0, 0, At, B0); PG8_MMA(0, 1, At, B1); PG8_BAR; PG8_SCHED;
;             PG8_LDA(At, 0, 1); PG8_STAGE(PG8_SB(0, 0), b2, voffB); PG8_STAGE(PG8_SB(0, 1), b2 + hstepB, voffB); PG8_STAGE(PG8_SA(0, 0), a2, voffA);
;             PG8_WAIT_V(8); PG8_WAIT_L(0); PG8_BAR; PG8_MMA(1, 0, At, B0); PG8_MMA(1, 1, At, B1); PG8_BAR; PG8_SCHED;
;             PG8_LDB(B0, 1, 0); PG8_LDB(B1, 1, 1); PG8_SCHED; PG8_LDA(At, 1, 0); PG8_STAGE(PG8_SA(0, 1), a2 + hstepA, voffA);
;             PG8_WAIT_V(8); PG8_WAIT_L(0); PG8_BAR; PG8_MMA(0, 0, At, B0); PG8_MMA(0, 1, At, B1); PG8_BAR; PG8_SCHED;
;             PG8_LDA(At, 1, 1); PG8_STAGE(PG8_SB(1, 0), b3, voffB); PG8_STAGE(PG8_SB(1, 1), b3 + hstepB, voffB); PG8_STAGE(PG8_SA(1, 0), a3, voffA);
;             PG8_WAIT_V(8); PG8_WAIT_L(0); PG8_BAR; PG8_MMA(1, 0, At, B0); PG8_MMA(1, 1, At, B1); PG8_BAR; PG8_SCHED;
;         }
	s_add_i32 s24, s33, s26
	v_lshl_add_u64 v[188:189], v[188:189], 0, s[12:13]
	s_mov_b32 m0, s24
	ds_read_b128 v[196:199], v155 offset:49152
	ds_read_b128 v[200:203], v155 offset:50176
	ds_read_b128 v[204:207], v155 offset:51200
	ds_read_b128 v[208:211], v155 offset:52224
	ds_read_b128 v[212:215], v155 offset:53248
	ds_read_b128 v[216:219], v155 offset:54272
	ds_read_b128 v[220:223], v155 offset:55296
	ds_read_b128 v[224:227], v155 offset:56320
	global_load_lds_dwordx4 v[188:189], off
	s_add_i32 m0, s24, 0x2000
	s_add_u32 s24, s42, 0x80080
	v_lshl_add_u64 v[188:189], v[228:229], 0, s[12:13]
	s_addc_u32 s25, s43, 0
	s_add_i32 s33, s34, s26
	global_load_lds_dwordx4 v[188:189], off
	v_lshl_add_u64 v[188:189], s[24:25], 0, v[134:135]
	s_mov_b32 m0, s33
	s_nop 0
	global_load_lds_dwordx4 v[188:189], off
	v_lshl_add_u64 v[188:189], s[24:25], 0, v[130:131]
	s_add_i32 m0, s33, 0x2000
	s_nop 0
	global_load_lds_dwordx4 v[188:189], off
	v_lshl_add_u64 v[188:189], v[230:231], 0, s[12:13]
	s_mov_b32 m0, s53
	s_nop 0
	global_load_lds_dwordx4 v[188:189], off
	v_lshl_add_u64 v[188:189], v[232:233], 0, s[12:13]
	s_mov_b32 m0, s55
	s_nop 0
	global_load_lds_dwordx4 v[188:189], off
	s_waitcnt vmcnt(8)
	s_waitcnt lgkmcnt(0)
	s_barrier
	s_waitcnt lgkmcnt(0)
	v_mfma_f32_16x16x32_bf16 v[60:63], v[156:159], v[196:199], v[60:63]
	v_mfma_f32_16x16x32_bf16 v[56:59], v[168:171], v[196:199], v[56:59]
	v_mfma_f32_16x16x32_bf16 v[44:47], v[156:159], v[204:207], v[44:47]
	v_mfma_f32_16x16x32_bf16 v[40:43], v[168:171], v[204:207], v[40:43]
	v_mfma_f32_16x16x32_bf16 v[28:31], v[156:159], v[212:215], v[28:31]
	v_mfma_f32_16x16x32_bf16 v[24:27], v[168:171], v[212:215], v[24:27]
	v_mfma_f32_16x16x32_bf16 v[12:15], v[156:159], v[220:223], v[12:15]
	v_mfma_f32_16x16x32_bf16 v[8:11], v[168:171], v[220:223], v[8:11]
	v_mfma_f32_16x16x32_bf16 v[60:63], v[164:167], v[200:203], v[60:63]
	v_mfma_f32_16x16x32_bf16 v[56:59], v[172:175], v[200:203], v[56:59]
	v_mfma_f32_16x16x32_bf16 v[44:47], v[164:167], v[208:211], v[44:47]
	v_mfma_f32_16x16x32_bf16 v[40:43], v[172:175], v[208:211], v[40:43]
	v_mfma_f32_16x16x32_bf16 v[28:31], v[164:167], v[216:219], v[28:31]
	v_mfma_f32_16x16x32_bf16 v[24:27], v[172:175], v[216:219], v[24:27]
	v_mfma_f32_16x16x32_bf16 v[12:15], v[164:167], v[224:227], v[12:15]
	v_mfma_f32_16x16x32_bf16 v[8:11], v[172:175], v[224:227], v[8:11]
	v_mfma_f32_16x16x32_bf16 v[52:55], v[176:179], v[196:199], v[52:55]
	v_mfma_f32_16x16x32_bf16 v[48:51], v[184:187], v[196:199], v[48:51]
	v_mfma_f32_16x16x32_bf16 v[36:39], v[176:179], v[204:207], v[36:39]
	v_mfma_f32_16x16x32_bf16 v[32:35], v[184:187], v[204:207], v[32:35]
	v_mfma_f32_16x16x32_bf16 v[20:23], v[176:179], v[212:215], v[20:23]
	v_mfma_f32_16x16x32_bf16 v[16:19], v[184:187], v[212:215], v[16:19]
	v_mfma_f32_16x16x32_bf16 v[4:7], v[176:179], v[220:223], v[4:7]
	v_mfma_f32_16x16x32_bf16 v[0:3], v[184:187], v[220:223], v[0:3]
	v_mfma_f32_16x16x32_bf16 v[52:55], v[180:183], v[200:203], v[52:55]
	v_mfma_f32_16x16x32_bf16 v[48:51], v[192:195], v[200:203], v[48:51]
	v_mfma_f32_16x16x32_bf16 v[36:39], v[180:183], v[208:211], v[36:39]
	v_mfma_f32_16x16x32_bf16 v[32:35], v[192:195], v[208:211], v[32:35]
	v_mfma_f32_16x16x32_bf16 v[20:23], v[180:183], v[216:219], v[20:23]
	v_mfma_f32_16x16x32_bf16 v[16:19], v[192:195], v[216:219], v[16:19]
	v_mfma_f32_16x16x32_bf16 v[4:7], v[180:183], v[224:227], v[4:7]
	v_mfma_f32_16x16x32_bf16 v[0:3], v[192:195], v[224:227], v[0:3]
	s_barrier
	s_add_i32 s17, s17, 2
	s_add_u32 s40, s40, 0x100
	s_addc_u32 s41, s41, 0
	s_add_u32 s0, s0, 0x100
	s_addc_u32 s1, s1, 0
	s_cmp_gt_u32 s17, 29
	s_cbranch_scc0 .LBB0_820
	s_branch .Lpeel_exit_8
.LBB0_820:
	ds_read_b128 v[156:159], v153
	ds_read_b128 v[164:167], v153 offset:1024
	ds_read_b128 v[168:171], v153 offset:2048
	ds_read_b128 v[172:175], v153 offset:3072
	ds_read_b128 v[176:179], v154
	ds_read_b128 v[180:183], v154 offset:1024
	ds_read_b128 v[184:187], v154 offset:2048
	ds_read_b128 v[192:195], v154 offset:3072
	s_add_u32 s24, s40, 0xfff80080
	s_addc_u32 s25, s41, -1
	s_cmp_eq_u32 s17, 28
	s_cselect_b32 s45, s19, s25
	s_cselect_b32 s44, s18, s24
	s_cselect_b32 s43, s21, s1
	s_cselect_b32 s42, s20, s0
	v_lshl_add_u64 v[188:189], s[40:41], 0, v[140:141]
	s_add_i32 m0, s49, 0xc000
	ds_read_b128 v[196:199], v155
	ds_read_b128 v[200:203], v155 offset:1024
	ds_read_b128 v[204:207], v155 offset:2048
	ds_read_b128 v[208:211], v155 offset:3072
	ds_read_b128 v[212:215], v155 offset:4096
	ds_read_b128 v[216:219], v155 offset:5120
	ds_read_b128 v[220:223], v155 offset:6144
	ds_read_b128 v[224:227], v155 offset:7168
	global_load_lds_dwordx4 v[188:189], off
	v_lshl_add_u64 v[188:189], s[40:41], 0, v[142:143]
	s_add_i32 m0, s49, 0xe000
	s_nop 0
	global_load_lds_dwordx4 v[188:189], off
	s_waitcnt vmcnt(8)
	s_waitcnt lgkmcnt(0)
	s_barrier
; #define PG8_STAGE(bufoff, gbase, voff) do { _Pragma("unroll") for (int _i = 0; _i < 2; ++_i) \
;         __builtin_amdgcn_global_load_lds((const unsigned*)((const char*)(gbase) + (voff)[_i]), (LAS unsigned*)(lds + (bufoff) + ldsw + _i * 8192), 16, 0, 0); } while (0)
; #define PG8_LDA(dst, b, h) do { _Pragma("unroll") for (int m = 0; m < 4; ++m) _Pragma("unroll") for (int k = 0; k < 2; ++k) dst[m][k] = *(const LAS bf16x8*)(lds + PG8_SA(b, h) + aoff + m * 2048 + k * 1024); } while (0)
; #define PG8_MMA(ai, bj, At, Bt) do { __builtin_amdgcn_s_setprio(1); _Pragma("unroll") for (int m = 0; m < 4; ++m) _Pragma("unroll") for (int n = 0; n < 2; ++n) _Pragma("unroll") for (int k = 0; k < 2; ++k) \
;         acc[ai][bj][m][n] = __builtin_amdgcn_mfma_f32_16x16x32_bf16(Bt[n][k], At[m][k], acc[ai][bj][m][n], 0, 0, 0); __builtin_amdgcn_s_setprio(0); } while (0)
; #define PG8_WAIT_V(n) asm volatile("s_waitcnt vmcnt(" #n ")" ::: "memory")
; #define PG8_WAIT_L(n) asm volatile("s_waitcnt lgkmcnt(" #n ")" ::: "memory")
; #define PG8_BAR __builtin_amdgcn_s_barrier()
; #define PG8_SCHED __builtin_amdgcn_sched_barrier(0)
; template <int GI>
; __device__ __forceinline__ void gemm_phase(LAS unsigned char* lds, unsigned char* ws, int G, int cblk) {
;     ...
;             PG8_WAIT_V(8); PG8_WAIT_L(0); PG8_BAR; PG8_MMA(0, 0, At, B0); PG8_MMA(0, 1, At, B1); PG8_BAR; PG8_SCHED;
;             PG8_LDA(At, 0, 1); PG8_STAGE(PG8_SB(0, 0), b2, voffB); PG8_STAGE(PG8_SB(0, 1), b2 + hstepB, voffB); PG8_STAGE(PG8_SA(0, 0), a2, voffA);
;             PG8_WAIT_V(8); PG8_WAIT_L(0); PG8_BAR; PG8_MMA(1, 0, At, B0); PG8_MMA(1, 1, At, B1); PG8_BAR; PG8_SCHED;
	s_waitcnt lgkmcnt(0)
	v_mfma_f32_16x16x32_bf16 v[124:127], v[156:159], v[196:199], v[124:127]
	v_mfma_f32_16x16x32_bf16 v[120:123], v[168:171], v[196:199], v[120:123]
	v_mfma_f32_16x16x32_bf16 v[108:111], v[156:159], v[204:207], v[108:111]
	v_mfma_f32_16x16x32_bf16 v[104:107], v[168:171], v[204:207], v[104:107]
	v_mfma_f32_16x16x32_bf16 v[92:95], v[156:159], v[212:215], v[92:95]
	v_mfma_f32_16x16x32_bf16 v[88:91], v[168:171], v[212:215], v[88:91]
	v_mfma_f32_16x16x32_bf16 v[76:79], v[156:159], v[220:223], v[76:79]
	v_mfma_f32_16x16x32_bf16 v[72:75], v[168:171], v[220:223], v[72:75]
	v_mfma_f32_16x16x32_bf16 v[124:127], v[164:167], v[200:203], v[124:127]
	v_mfma_f32_16x16x32_bf16 v[120:123], v[172:175], v[200:203], v[120:123]
	v_mfma_f32_16x16x32_bf16 v[108:111], v[164:167], v[208:211], v[108:111]
	v_mfma_f32_16x16x32_bf16 v[104:107], v[172:175], v[208:211], v[104:107]
	v_mfma_f32_16x16x32_bf16 v[92:95], v[164:167], v[216:219], v[92:95]
	v_mfma_f32_16x16x32_bf16 v[88:91], v[172:175], v[216:219], v[88:91]
	v_mfma_f32_16x16x32_bf16 v[76:79], v[164:167], v[224:227], v[76:79]
	v_mfma_f32_16x16x32_bf16 v[72:75], v[172:175], v[224:227], v[72:75]
	v_mfma_f32_16x16x32_bf16 v[116:119], v[176:179], v[196:199], v[116:119]
	v_mfma_f32_16x16x32_bf16 v[112:115], v[184:187], v[196:199], v[112:115]
	v_mfma_f32_16x16x32_bf16 v[100:103], v[176:179], v[204:207], v[100:103]
	v_mfma_f32_16x16x32_bf16 v[96:99], v[184:187], v[204:207], v[96:99]
	v_mfma_f32_16x16x32_bf16 v[84:87], v[176:179], v[212:215], v[84:87]
	v_mfma_f32_16x16x32_bf16 v[80:83], v[184:187], v[212:215], v[80:83]
	v_mfma_f32_16x16x32_bf16 v[68:71], v[176:179], v[220:223], v[68:71]
	v_mfma_f32_16x16x32_bf16 v[64:67], v[184:187], v[220:223], v[64:67]
	v_mfma_f32_16x16x32_bf16 v[116:119], v[180:183], v[200:203], v[116:119]
	v_mfma_f32_16x16x32_bf16 v[112:115], v[192:195], v[200:203], v[112:115]
	v_mfma_f32_16x16x32_bf16 v[100:103], v[180:183], v[208:211], v[100:103]
	v_mfma_f32_16x16x32_bf16 v[96:99], v[192:195], v[208:211], v[96:99]
	v_mfma_f32_16x16x32_bf16 v[84:87], v[180:183], v[216:219], v[84:87]
	v_mfma_f32_16x16x32_bf16 v[80:83], v[192:195], v[216:219], v[80:83]
	v_mfma_f32_16x16x32_bf16 v[68:71], v[180:183], v[224:227], v[68:71]
	v_mfma_f32_16x16x32_bf16 v[64:67], v[192:195], v[224:227], v[64:67]
	s_barrier
	s_add_i32 s24, s56, s26
	v_lshl_add_u64 v[188:189], s[42:43], 0, v[134:135]
	s_mov_b32 m0, s24
	ds_read_b128 v[196:199], v155 offset:16384
	ds_read_b128 v[200:203], v155 offset:17408
	ds_read_b128 v[204:207], v155 offset:18432
	ds_read_b128 v[208:211], v155 offset:19456
	ds_read_b128 v[212:215], v155 offset:20480
	ds_read_b128 v[216:219], v155 offset:21504
	ds_read_b128 v[220:223], v155 offset:22528
	ds_read_b128 v[224:227], v155 offset:23552
	global_load_lds_dwordx4 v[188:189], off
	s_add_i32 m0, s24, 0x2000
	s_add_u32 s24, s42, 0x80000
	v_lshl_add_u64 v[228:229], s[42:43], 0, v[130:131]
	s_addc_u32 s25, s43, 0
	s_add_i32 s33, s57, s26
	global_load_lds_dwordx4 v[228:229], off
	v_lshl_add_u64 v[230:231], s[24:25], 0, v[134:135]
	s_mov_b32 m0, s33
	v_lshl_add_u64 v[232:233], s[44:45], 0, v[132:133]
	global_load_lds_dwordx4 v[230:231], off
	v_lshl_add_u64 v[230:231], s[24:25], 0, v[130:131]
	s_add_i32 m0, s33, 0x2000
	s_nop 0
	global_load_lds_dwordx4 v[230:231], off
	v_lshl_add_u64 v[230:231], s[44:45], 0, v[136:137]
	s_mov_b32 m0, s49
	s_nop 0
	global_load_lds_dwordx4 v[230:231], off
	s_mov_b32 m0, s50
	s_nop 0
	global_load_lds_dwordx4 v[232:233], off
	s_waitcnt vmcnt(8)
	s_waitcnt lgkmcnt(0)
	s_barrier
	s_waitcnt lgkmcnt(0)
	v_mfma_f32_16x16x32_bf16 v[60:63], v[156:159], v[196:199], v[60:63]
	v_mfma_f32_16x16x32_bf16 v[56:59], v[168:171], v[196:199], v[56:59]
	v_mfma_f32_16x16x32_bf16 v[44:47], v[156:159], v[204:207], v[44:47]
	v_mfma_f32_16x16x32_bf16 v[40:43], v[168:171], v[204:207], v[40:43]
	v_mfma_f32_16x16x32_bf16 v[28:31], v[156:159], v[212:215], v[28:31]
	v_mfma_f32_16x16x32_bf16 v[24:27], v[168:171], v[212:215], v[24:27]
	v_mfma_f32_16x16x32_bf16 v[12:15], v[156:159], v[220:223], v[12:15]
	v_mfma_f32_16x16x32_bf16 v[8:11], v[168:171], v[220:223], v[8:11]
	v_mfma_f32_16x16x32_bf16 v[60:63], v[164:167], v[200:203], v[60:63]
	v_mfma_f32_16x16x32_bf16 v[56:59], v[172:175], v[200:203], v[56:59]
	v_mfma_f32_16x16x32_bf16 v[44:47], v[164:167], v[208:211], v[44:47]
	v_mfma_f32_16x16x32_bf16 v[40:43], v[172:175], v[208:211], v[40:43]
	v_mfma_f32_16x16x32_bf16 v[28:31], v[164:167], v[216:219], v[28:31]
	v_mfma_f32_16x16x32_bf16 v[24:27], v[172:175], v[216:219], v[24:27]
	v_mfma_f32_16x16x32_bf16 v[12:15], v[164:167], v[224:227], v[12:15]
	v_mfma_f32_16x16x32_bf16 v[8:11], v[172:175], v[224:227], v[8:11]
	v_mfma_f32_16x16x32_bf16 v[52:55], v[176:179], v[196:199], v[52:55]
	v_mfma_f32_16x16x32_bf16 v[48:51], v[184:187], v[196:199], v[48:51]
	v_mfma_f32_16x16x32_bf16 v[36:39], v[176:179], v[204:207], v[36:39]
	v_mfma_f32_16x16x32_bf16 v[32:35], v[184:187], v[204:207], v[32:35]
	v_mfma_f32_16x16x32_bf16 v[20:23], v[176:179], v[212:215], v[20:23]
	v_mfma_f32_16x16x32_bf16 v[16:19], v[184:187], v[212:215], v[16:19]
	v_mfma_f32_16x16x32_bf16 v[4:7], v[176:179], v[220:223], v[4:7]
	v_mfma_f32_16x16x32_bf16 v[0:3], v[184:187], v[220:223], v[0:3]
	v_mfma_f32_16x16x32_bf16 v[52:55], v[180:183], v[200:203], v[52:55]
	v_mfma_f32_16x16x32_bf16 v[48:51], v[192:195], v[200:203], v[48:51]
	v_mfma_f32_16x16x32_bf16 v[36:39], v[180:183], v[208:211], v[36:39]
	v_mfma_f32_16x16x32_bf16 v[32:35], v[192:195], v[208:211], v[32:35]
	v_mfma_f32_16x16x32_bf16 v[20:23], v[180:183], v[216:219], v[20:23]
	v_mfma_f32_16x16x32_bf16 v[16:19], v[192:195], v[216:219], v[16:19]
	v_mfma_f32_16x16x32_bf16 v[4:7], v[180:183], v[224:227], v[4:7]
	v_mfma_f32_16x16x32_bf16 v[0:3], v[192:195], v[224:227], v[0:3]
	s_barrier
; #define PG8_STAGE(bufoff, gbase, voff) do { _Pragma("unroll") for (int _i = 0; _i < 2; ++_i) \
;         __builtin_amdgcn_global_load_lds((const unsigned*)((const char*)(gbase) + (voff)[_i]), (LAS unsigned*)(lds + (bufoff) + ldsw + _i * 8192), 16, 0, 0); } while (0)
; #define PG8_LDA(dst, b, h) do { _Pragma("unroll") for (int m = 0; m < 4; ++m) _Pragma("unroll") for (int k = 0; k < 2; ++k) dst[m][k] = *(const LAS bf16x8*)(lds + PG8_SA(b, h) + aoff + m * 2048 + k * 1024); } while (0)
; #define PG8_LDB(dst, b, h) do { _Pragma("unroll") for (int n = 0; n < 2; ++n) _Pragma("unroll") for (int k = 0; k < 2; ++k) dst[n][k] = *(const LAS bf16x8*)(lds + PG8_SB(b, h) + boff + n * 2048 + k * 1024); } while (0)
; #define PG8_MMA(ai, bj, At, Bt) do { __builtin_amdgcn_s_setprio(1); _Pragma("unroll") for (int m = 0; m < 4; ++m) _Pragma("unroll") for (int n = 0; n < 2; ++n) _Pragma("unroll") for (int k = 0; k < 2; ++k) \
;         acc[ai][bj][m][n] = __builtin_amdgcn_mfma_f32_16x16x32_bf16(Bt[n][k], At[m][k], acc[ai][bj][m][n], 0, 0, 0); __builtin_amdgcn_s_setprio(0); } while (0)
; #define PG8_WAIT_V(n) asm volatile("s_waitcnt vmcnt(" #n ")" ::: "memory")
; #define PG8_WAIT_L(n) asm volatile("s_waitcnt lgkmcnt(" #n ")" ::: "memory")
; #define PG8_BAR __builtin_amdgcn_s_barrier()
; #define PG8_SCHED __builtin_amdgcn_sched_barrier(0)
; template <int GI>
; __device__ __forceinline__ void gemm_phase(LAS unsigned char* lds, unsigned char* ws, int G, int cblk) {
;     ...
;             PG8_LDB(B0, 1, 0); PG8_LDB(B1, 1, 1); PG8_SCHED; PG8_LDA(At, 1, 0); PG8_STAGE(PG8_SA(0, 1), a2 + hstepA, voffA);
;             PG8_WAIT_V(8); PG8_WAIT_L(0); PG8_BAR; PG8_MMA(0, 0, At, B0); PG8_MMA(0, 1, At, B1); PG8_BAR; PG8_SCHED;
;             PG8_LDA(At, 1, 1); PG8_STAGE(PG8_SB(1, 0), b3, voffB); PG8_STAGE(PG8_SB(1, 1), b3 + hstepB, voffB); PG8_STAGE(PG8_SA(1, 0), a3, voffA);
;             PG8_WAIT_V(8); PG8_WAIT_L(0); PG8_BAR; PG8_MMA(1, 0, At, B0); PG8_MMA(1, 1, At, B1); PG8_BAR; PG8_SCHED;
;         }
	s_add_i32 s33, 0, 0x18000
	v_add_u32_e32 v161, s33, v152
	s_add_i32 s34, 0, 0x1c000
	ds_read_b128 v[156:159], v161
	ds_read_b128 v[164:167], v161 offset:1024
	ds_read_b128 v[168:171], v161 offset:2048
	ds_read_b128 v[172:175], v161 offset:3072
	v_add_u32_e32 v161, s34, v152
	ds_read_b128 v[176:179], v161
	ds_read_b128 v[180:183], v161 offset:1024
	ds_read_b128 v[184:187], v161 offset:2048
	ds_read_b128 v[192:195], v161 offset:3072
	s_add_u32 s24, s44, 0x80000
	s_addc_u32 s25, s45, 0
	s_mov_b32 m0, s51
	v_lshl_add_u64 v[234:235], s[24:25], 0, v[136:137]
	ds_read_b128 v[196:199], v155 offset:32768
	ds_read_b128 v[200:203], v155 offset:33792
	ds_read_b128 v[204:207], v155 offset:34816
	ds_read_b128 v[208:211], v155 offset:35840
	ds_read_b128 v[212:215], v155 offset:36864
	ds_read_b128 v[216:219], v155 offset:37888
	ds_read_b128 v[220:223], v155 offset:38912
	ds_read_b128 v[224:227], v155 offset:39936
	global_load_lds_dwordx4 v[234:235], off
	v_lshl_add_u64 v[234:235], s[24:25], 0, v[132:133]
	s_mov_b32 m0, s52
	s_nop 0
	global_load_lds_dwordx4 v[234:235], off
	s_waitcnt vmcnt(8)
	s_waitcnt lgkmcnt(0)
	s_barrier
	s_waitcnt lgkmcnt(0)
	v_mfma_f32_16x16x32_bf16 v[124:127], v[156:159], v[196:199], v[124:127]
	v_mfma_f32_16x16x32_bf16 v[120:123], v[168:171], v[196:199], v[120:123]
	v_mfma_f32_16x16x32_bf16 v[108:111], v[156:159], v[204:207], v[108:111]
	v_mfma_f32_16x16x32_bf16 v[104:107], v[168:171], v[204:207], v[104:107]
	v_mfma_f32_16x16x32_bf16 v[92:95], v[156:159], v[212:215], v[92:95]
	v_mfma_f32_16x16x32_bf16 v[88:91], v[168:171], v[212:215], v[88:91]
	v_mfma_f32_16x16x32_bf16 v[76:79], v[156:159], v[220:223], v[76:79]
	v_mfma_f32_16x16x32_bf16 v[72:75], v[168:171], v[220:223], v[72:75]
	v_mfma_f32_16x16x32_bf16 v[124:127], v[164:167], v[200:203], v[124:127]
	v_mfma_f32_16x16x32_bf16 v[120:123], v[172:175], v[200:203], v[120:123]
	v_mfma_f32_16x16x32_bf16 v[108:111], v[164:167], v[208:211], v[108:111]
	v_mfma_f32_16x16x32_bf16 v[104:107], v[172:175], v[208:211], v[104:107]
	v_mfma_f32_16x16x32_bf16 v[92:95], v[164:167], v[216:219], v[92:95]
	v_mfma_f32_16x16x32_bf16 v[88:91], v[172:175], v[216:219], v[88:91]
	v_mfma_f32_16x16x32_bf16 v[76:79], v[164:167], v[224:227], v[76:79]
	v_mfma_f32_16x16x32_bf16 v[72:75], v[172:175], v[224:227], v[72:75]
	v_mfma_f32_16x16x32_bf16 v[116:119], v[176:179], v[196:199], v[116:119]
	v_mfma_f32_16x16x32_bf16 v[112:115], v[184:187], v[196:199], v[112:115]
	v_mfma_f32_16x16x32_bf16 v[100:103], v[176:179], v[204:207], v[100:103]
	v_mfma_f32_16x16x32_bf16 v[96:99], v[184:187], v[204:207], v[96:99]
	v_mfma_f32_16x16x32_bf16 v[84:87], v[176:179], v[212:215], v[84:87]
	v_mfma_f32_16x16x32_bf16 v[80:83], v[184:187], v[212:215], v[80:83]
	v_mfma_f32_16x16x32_bf16 v[68:71], v[176:179], v[220:223], v[68:71]
	v_mfma_f32_16x16x32_bf16 v[64:67], v[184:187], v[220:223], v[64:67]
	v_mfma_f32_16x16x32_bf16 v[116:119], v[180:183], v[200:203], v[116:119]
	v_mfma_f32_16x16x32_bf16 v[112:115], v[192:195], v[200:203], v[112:115]
	v_mfma_f32_16x16x32_bf16 v[100:103], v[180:183], v[208:211], v[100:103]
	v_mfma_f32_16x16x32_bf16 v[96:99], v[192:195], v[208:211], v[96:99]
	v_mfma_f32_16x16x32_bf16 v[84:87], v[180:183], v[216:219], v[84:87]
	v_mfma_f32_16x16x32_bf16 v[80:83], v[192:195], v[216:219], v[80:83]
	v_mfma_f32_16x16x32_bf16 v[68:71], v[180:183], v[224:227], v[68:71]
	v_mfma_f32_16x16x32_bf16 v[64:67], v[192:195], v[224:227], v[64:67]
	s_barrier
	s_add_i32 s24, s33, s26
	v_lshl_add_u64 v[188:189], v[188:189], 0, s[12:13]
	s_mov_b32 m0, s24
	ds_read_b128 v[196:199], v155 offset:49152
	ds_read_b128 v[200:203], v155 offset:50176
	ds_read_b128 v[204:207], v155 offset:51200
	ds_read_b128 v[208:211], v155 offset:52224
	ds_read_b128 v[212:215], v155 offset:53248
	ds_read_b128 v[216:219], v155 offset:54272
	ds_read_b128 v[220:223], v155 offset:55296
	ds_read_b128 v[224:227], v155 offset:56320
	global_load_lds_dwordx4 v[188:189], off
	s_add_i32 m0, s24, 0x2000
	s_add_u32 s24, s42, 0x80080
	v_lshl_add_u64 v[188:189], v[228:229], 0, s[12:13]
	s_addc_u32 s25, s43, 0
	s_add_i32 s33, s34, s26
	global_load_lds_dwordx4 v[188:189], off
	v_lshl_add_u64 v[188:189], s[24:25], 0, v[134:135]
	s_mov_b32 m0, s33
	s_nop 0
	global_load_lds_dwordx4 v[188:189], off
	v_lshl_add_u64 v[188:189], s[24:25], 0, v[130:131]
	s_add_i32 m0, s33, 0x2000
	s_nop 0
	global_load_lds_dwordx4 v[188:189], off
	v_lshl_add_u64 v[188:189], v[230:231], 0, s[12:13]
	s_mov_b32 m0, s53
	s_nop 0
	global_load_lds_dwordx4 v[188:189], off
	v_lshl_add_u64 v[188:189], v[232:233], 0, s[12:13]
	s_mov_b32 m0, s55
	s_nop 0
	global_load_lds_dwordx4 v[188:189], off
	s_waitcnt vmcnt(8)
	s_waitcnt lgkmcnt(0)
	s_barrier
	s_waitcnt lgkmcnt(0)
	v_mfma_f32_16x16x32_bf16 v[60:63], v[156:159], v[196:199], v[60:63]
	v_mfma_f32_16x16x32_bf16 v[56:59], v[168:171], v[196:199], v[56:59]
	v_mfma_f32_16x16x32_bf16 v[44:47], v[156:159], v[204:207], v[44:47]
	v_mfma_f32_16x16x32_bf16 v[40:43], v[168:171], v[204:207], v[40:43]
	v_mfma_f32_16x16x32_bf16 v[28:31], v[156:159], v[212:215], v[28:31]
	v_mfma_f32_16x16x32_bf16 v[24:27], v[168:171], v[212:215], v[24:27]
	v_mfma_f32_16x16x32_bf16 v[12:15], v[156:159], v[220:223], v[12:15]
	v_mfma_f32_16x16x32_bf16 v[8:11], v[168:171], v[220:223], v[8:11]
	v_mfma_f32_16x16x32_bf16 v[60:63], v[164:167], v[200:203], v[60:63]
	v_mfma_f32_16x16x32_bf16 v[56:59], v[172:175], v[200:203], v[56:59]
	v_mfma_f32_16x16x32_bf16 v[44:47], v[164:167], v[208:211], v[44:47]
	v_mfma_f32_16x16x32_bf16 v[40:43], v[172:175], v[208:211], v[40:43]
	v_mfma_f32_16x16x32_bf16 v[28:31], v[164:167], v[216:219], v[28:31]
	v_mfma_f32_16x16x32_bf16 v[24:27], v[172:175], v[216:219], v[24:27]
	v_mfma_f32_16x16x32_bf16 v[12:15], v[164:167], v[224:227], v[12:15]
	v_mfma_f32_16x16x32_bf16 v[8:11], v[172:175], v[224:227], v[8:11]
	v_mfma_f32_16x16x32_bf16 v[52:55], v[176:179], v[196:199], v[52:55]
	v_mfma_f32_16x16x32_bf16 v[48:51], v[184:187], v[196:199], v[48:51]
	v_mfma_f32_16x16x32_bf16 v[36:39], v[176:179], v[204:207], v[36:39]
	v_mfma_f32_16x16x32_bf16 v[32:35], v[184:187], v[204:207], v[32:35]
	v_mfma_f32_16x16x32_bf16 v[20:23], v[176:179], v[212:215], v[20:23]
	v_mfma_f32_16x16x32_bf16 v[16:19], v[184:187], v[212:215], v[16:19]
	v_mfma_f32_16x16x32_bf16 v[4:7], v[176:179], v[220:223], v[4:7]
	v_mfma_f32_16x16x32_bf16 v[0:3], v[184:187], v[220:223], v[0:3]
	v_mfma_f32_16x16x32_bf16 v[52:55], v[180:183], v[200:203], v[52:55]
	v_mfma_f32_16x16x32_bf16 v[48:51], v[192:195], v[200:203], v[48:51]
	v_mfma_f32_16x16x32_bf16 v[36:39], v[180:183], v[208:211], v[36:39]
	v_mfma_f32_16x16x32_bf16 v[32:35], v[192:195], v[208:211], v[32:35]
	v_mfma_f32_16x16x32_bf16 v[20:23], v[180:183], v[216:219], v[20:23]
	v_mfma_f32_16x16x32_bf16 v[16:19], v[192:195], v[216:219], v[16:19]
	v_mfma_f32_16x16x32_bf16 v[4:7], v[180:183], v[224:227], v[4:7]
	v_mfma_f32_16x16x32_bf16 v[0:3], v[192:195], v[224:227], v[0:3]
	s_barrier
	s_add_i32 s17, s17, 2
	s_add_u32 s40, s40, 0x100
	s_addc_u32 s41, s41, 0
	s_add_u32 s0, s0, 0x100
	s_addc_u32 s1, s1, 0
	s_cmp_gt_u32 s17, 29
	s_cbranch_scc0 .LBB0_820

; #define PG8_STAGE(bufoff, gbase, voff) do { _Pragma("unroll") for (int _i = 0; _i < 2; ++_i) \
;         __builtin_amdgcn_global_load_lds((const unsigned*)((const char*)(gbase) + (voff)[_i]), (LAS unsigned*)(lds + (bufoff) + ldsw + _i * 8192), 16, 0, 0); } while (0)
; #define PG8_LDA(dst, b, h) do { _Pragma("unroll") for (int m = 0; m < 4; ++m) _Pragma("unroll") for (int k = 0; k < 2; ++k) dst[m][k] = *(const LAS bf16x8*)(lds + PG8_SA(b, h) + aoff + m * 2048 + k * 1024); } while (0)
; #define PG8_LDB(dst, b, h) do { _Pragma("unroll") for (int n = 0; n < 2; ++n) _Pragma("unroll") for (int k = 0; k < 2; ++k) dst[n][k] = *(const LAS bf16x8*)(lds + PG8_SB(b, h) + boff + n * 2048 + k * 1024); } while (0)
; #define PG8_MMA(ai, bj, At, Bt) do { __builtin_amdgcn_s_setprio(1); _Pragma("unroll") for (int m = 0; m < 4; ++m) _Pragma("unroll") for (int n = 0; n < 2; ++n) _Pragma("unroll") for (int k = 0; k < 2; ++k) \
;         acc[ai][bj][m][n] = __builtin_amdgcn_mfma_f32_16x16x32_bf16(Bt[n][k], At[m][k], acc[ai][bj][m][n], 0, 0, 0); __builtin_amdgcn_s_setprio(0); } while (0)
; #define PG8_WAIT_V(n) asm volatile("s_waitcnt vmcnt(" #n ")" ::: "memory")
; #define PG8_WAIT_L(n) asm volatile("s_waitcnt lgkmcnt(" #n ")" ::: "memory")
; #define PG8_BAR __builtin_amdgcn_s_barrier()
; template <int GI>
; __device__ __forceinline__ void gemm_phase(LAS unsigned char* lds, unsigned char* ws, int G, int cblk) {
;     ...
;         const char* nA = has_next ? nxt.A : cA; const char* nB = has_next ? nxt.B : cB;
;         for (int t = 0; t < nt; t += 2) {
;             const bool last = (t == nt - 2);
;             const char* a1 = cA + (size_t)(t + 1) * kstep;
;             const char* a2 = last ? nA : cA + (size_t)(t + 2) * kstep; const char* b2 = last ? nB : cB + (size_t)(t + 2) * kstep;
;             const char* a3 = a2 + kstep; const char* b3 = b2 + kstep;
;             PG8_LDB(B0, 0, 0); PG8_LDB(B1, 0, 1); PG8_SCHED; PG8_LDA(At, 0, 0); PG8_STAGE(PG8_SA(1, 1), a1 + hstepA, voffA);
;             PG8_WAIT_V(8); PG8_WAIT_L(0); PG8_BAR; PG8_MMA(0, 0, At, B0); PG8_MMA(0, 1, At, B1); PG8_BAR; PG8_SCHED;
;             PG8_LDA(At, 0, 1); PG8_STAGE(PG8_SB(0, 0), b2, voffB); PG8_STAGE(PG8_SB(0, 1), b2 + hstepB, voffB); PG8_STAGE(PG8_SA(0, 0), a2, voffA);
;             PG8_WAIT_V(8); PG8_WAIT_L(0); PG8_BAR; PG8_MMA(1, 0, At, B0); PG8_MMA(1, 1, At, B1); PG8_BAR; PG8_SCHED;
.LBB0_895:
	s_add_u32 s15, s40, 0x100
	s_addc_u32 s53, s41, 0
	s_mov_b32 s54, -2
	ds_read_b128 v[156:159], v153
	ds_read_b128 v[164:167], v153 offset:1024
	ds_read_b128 v[168:171], v153 offset:2048
	ds_read_b128 v[172:175], v153 offset:3072
	ds_read_b128 v[176:179], v154
	ds_read_b128 v[180:183], v154 offset:1024
	ds_read_b128 v[184:187], v154 offset:2048
	ds_read_b128 v[192:195], v154 offset:3072
	s_add_u32 s40, s38, 0x100
	s_addc_u32 s41, s39, 0
	s_cmpk_eq_i32 s54, 0x54
	s_cselect_b32 s45, s21, s41
	s_cselect_b32 s44, s20, s40
	s_cselect_b32 s43, s23, s53
	s_cselect_b32 s42, s22, s15
	v_lshl_add_u64 v[188:189], s[38:39], 0, v[140:141]
	s_add_i32 m0, s24, 0xc000
	ds_read_b128 v[196:199], v155
	ds_read_b128 v[200:203], v155 offset:1024
	ds_read_b128 v[204:207], v155 offset:2048
	ds_read_b128 v[208:211], v155 offset:3072
	ds_read_b128 v[212:215], v155 offset:4096
	ds_read_b128 v[216:219], v155 offset:5120
	ds_read_b128 v[220:223], v155 offset:6144
	ds_read_b128 v[224:227], v155 offset:7168
	global_load_lds_dwordx4 v[188:189], off
	v_lshl_add_u64 v[188:189], s[38:39], 0, v[142:143]
	s_add_i32 m0, s24, 0xe000
	s_nop 0
	global_load_lds_dwordx4 v[188:189], off
	s_waitcnt vmcnt(8)
	s_waitcnt lgkmcnt(0)
	s_barrier
	s_waitcnt lgkmcnt(0)
	v_mfma_f32_16x16x32_bf16 v[124:127], v[156:159], v[196:199], 0
	v_mfma_f32_16x16x32_bf16 v[120:123], v[168:171], v[196:199], 0
	v_mfma_f32_16x16x32_bf16 v[116:119], v[156:159], v[204:207], 0
	v_mfma_f32_16x16x32_bf16 v[112:115], v[168:171], v[204:207], 0
	v_mfma_f32_16x16x32_bf16 v[100:103], v[156:159], v[212:215], 0
	v_mfma_f32_16x16x32_bf16 v[96:99], v[168:171], v[212:215], 0
	v_mfma_f32_16x16x32_bf16 v[84:87], v[156:159], v[220:223], 0
	v_mfma_f32_16x16x32_bf16 v[80:83], v[168:171], v[220:223], 0
	v_mfma_f32_16x16x32_bf16 v[124:127], v[164:167], v[200:203], v[124:127]
	v_mfma_f32_16x16x32_bf16 v[120:123], v[172:175], v[200:203], v[120:123]
	v_mfma_f32_16x16x32_bf16 v[116:119], v[164:167], v[208:211], v[116:119]
	v_mfma_f32_16x16x32_bf16 v[112:115], v[172:175], v[208:211], v[112:115]
	v_mfma_f32_16x16x32_bf16 v[100:103], v[164:167], v[216:219], v[100:103]
	v_mfma_f32_16x16x32_bf16 v[96:99], v[172:175], v[216:219], v[96:99]
	v_mfma_f32_16x16x32_bf16 v[84:87], v[164:167], v[224:227], v[84:87]
	v_mfma_f32_16x16x32_bf16 v[80:83], v[172:175], v[224:227], v[80:83]
	v_mfma_f32_16x16x32_bf16 v[108:111], v[176:179], v[196:199], 0
	v_mfma_f32_16x16x32_bf16 v[104:107], v[184:187], v[196:199], 0
	v_mfma_f32_16x16x32_bf16 v[92:95], v[176:179], v[204:207], 0
	v_mfma_f32_16x16x32_bf16 v[88:91], v[184:187], v[204:207], 0
	v_mfma_f32_16x16x32_bf16 v[76:79], v[176:179], v[212:215], 0
	v_mfma_f32_16x16x32_bf16 v[72:75], v[184:187], v[212:215], 0
	v_mfma_f32_16x16x32_bf16 v[68:71], v[176:179], v[220:223], 0
	v_mfma_f32_16x16x32_bf16 v[64:67], v[184:187], v[220:223], 0
	v_mfma_f32_16x16x32_bf16 v[108:111], v[180:183], v[200:203], v[108:111]
	v_mfma_f32_16x16x32_bf16 v[104:107], v[192:195], v[200:203], v[104:107]
	v_mfma_f32_16x16x32_bf16 v[92:95], v[180:183], v[208:211], v[92:95]
	v_mfma_f32_16x16x32_bf16 v[88:91], v[192:195], v[208:211], v[88:91]
	v_mfma_f32_16x16x32_bf16 v[76:79], v[180:183], v[216:219], v[76:79]
	v_mfma_f32_16x16x32_bf16 v[72:75], v[192:195], v[216:219], v[72:75]
	v_mfma_f32_16x16x32_bf16 v[68:71], v[180:183], v[224:227], v[68:71]
	v_mfma_f32_16x16x32_bf16 v[64:67], v[192:195], v[224:227], v[64:67]
	s_barrier
	s_add_i32 s34, s50, s0
	v_lshl_add_u64 v[188:189], s[42:43], 0, v[132:133]
	s_mov_b32 m0, s34
	ds_read_b128 v[196:199], v155 offset:16384
	ds_read_b128 v[200:203], v155 offset:17408
	ds_read_b128 v[204:207], v155 offset:18432
	ds_read_b128 v[208:211], v155 offset:19456
	ds_read_b128 v[212:215], v155 offset:20480
	ds_read_b128 v[216:219], v155 offset:21504
	ds_read_b128 v[220:223], v155 offset:22528
	ds_read_b128 v[224:227], v155 offset:23552
	global_load_lds_dwordx4 v[188:189], off
	s_add_i32 m0, s34, 0x2000
	s_add_u32 s38, s42, 0x160000
	v_lshl_add_u64 v[228:229], s[42:43], 0, v[136:137]
	s_addc_u32 s39, s43, 0
	s_add_i32 s34, s51, s0
	global_load_lds_dwordx4 v[228:229], off
	v_lshl_add_u64 v[230:231], s[38:39], 0, v[132:133]
	s_mov_b32 m0, s34
	v_lshl_add_u64 v[232:233], s[44:45], 0, v[134:135]
	global_load_lds_dwordx4 v[230:231], off
	v_lshl_add_u64 v[230:231], s[38:39], 0, v[136:137]
	s_add_i32 m0, s34, 0x2000
	s_nop 0
	global_load_lds_dwordx4 v[230:231], off
	v_lshl_add_u64 v[230:231], s[44:45], 0, v[130:131]
	s_mov_b32 m0, s24
	s_nop 0
	global_load_lds_dwordx4 v[230:231], off
	s_mov_b32 m0, s25
	s_nop 0
	global_load_lds_dwordx4 v[232:233], off
	s_waitcnt vmcnt(8)
	s_waitcnt lgkmcnt(0)
	s_barrier
; #define PG8_STAGE(bufoff, gbase, voff) do { _Pragma("unroll") for (int _i = 0; _i < 2; ++_i) \
;         __builtin_amdgcn_global_load_lds((const unsigned*)((const char*)(gbase) + (voff)[_i]), (LAS unsigned*)(lds + (bufoff) + ldsw + _i * 8192), 16, 0, 0); } while (0)
; #define PG8_LDA(dst, b, h) do { _Pragma("unroll") for (int m = 0; m < 4; ++m) _Pragma("unroll") for (int k = 0; k < 2; ++k) dst[m][k] = *(const LAS bf16x8*)(lds + PG8_SA(b, h) + aoff + m * 2048 + k * 1024); } while (0)
; #define PG8_LDB(dst, b, h) do { _Pragma("unroll") for (int n = 0; n < 2; ++n) _Pragma("unroll") for (int k = 0; k < 2; ++k) dst[n][k] = *(const LAS bf16x8*)(lds + PG8_SB(b, h) + boff + n * 2048 + k * 1024); } while (0)
; #define PG8_MMA(ai, bj, At, Bt) do { __builtin_amdgcn_s_setprio(1); _Pragma("unroll") for (int m = 0; m < 4; ++m) _Pragma("unroll") for (int n = 0; n < 2; ++n) _Pragma("unroll") for (int k = 0; k < 2; ++k) \
;         acc[ai][bj][m][n] = __builtin_amdgcn_mfma_f32_16x16x32_bf16(Bt[n][k], At[m][k], acc[ai][bj][m][n], 0, 0, 0); __builtin_amdgcn_s_setprio(0); } while (0)
; #define PG8_WAIT_V(n) asm volatile("s_waitcnt vmcnt(" #n ")" ::: "memory")
; #define PG8_WAIT_L(n) asm volatile("s_waitcnt lgkmcnt(" #n ")" ::: "memory")
; #define PG8_BAR __builtin_amdgcn_s_barrier()
; #define PG8_SCHED __builtin_amdgcn_sched_barrier(0)
; template <int GI>
; __device__ __forceinline__ void gemm_phase(LAS unsigned char* lds, unsigned char* ws, int G, int cblk) {
;     ...
;             PG8_WAIT_V(8); PG8_WAIT_L(0); PG8_BAR; PG8_MMA(1, 0, At, B0); PG8_MMA(1, 1, At, B1); PG8_BAR; PG8_SCHED;
;             PG8_LDB(B0, 1, 0); PG8_LDB(B1, 1, 1); PG8_SCHED; PG8_LDA(At, 1, 0); PG8_STAGE(PG8_SA(0, 1), a2 + hstepA, voffA);
;             PG8_WAIT_V(8); PG8_WAIT_L(0); PG8_BAR; PG8_MMA(0, 0, At, B0); PG8_MMA(0, 1, At, B1); PG8_BAR; PG8_SCHED;
	s_waitcnt lgkmcnt(0)
	v_mfma_f32_16x16x32_bf16 v[60:63], v[156:159], v[196:199], 0
	v_mfma_f32_16x16x32_bf16 v[56:59], v[168:171], v[196:199], 0
	v_mfma_f32_16x16x32_bf16 v[52:55], v[156:159], v[204:207], 0
	v_mfma_f32_16x16x32_bf16 v[48:51], v[168:171], v[204:207], 0
	v_mfma_f32_16x16x32_bf16 v[36:39], v[156:159], v[212:215], 0
	v_mfma_f32_16x16x32_bf16 v[32:35], v[168:171], v[212:215], 0
	v_mfma_f32_16x16x32_bf16 v[20:23], v[156:159], v[220:223], 0
	v_mfma_f32_16x16x32_bf16 v[16:19], v[168:171], v[220:223], 0
	v_mfma_f32_16x16x32_bf16 v[60:63], v[164:167], v[200:203], v[60:63]
	v_mfma_f32_16x16x32_bf16 v[56:59], v[172:175], v[200:203], v[56:59]
	v_mfma_f32_16x16x32_bf16 v[52:55], v[164:167], v[208:211], v[52:55]
	v_mfma_f32_16x16x32_bf16 v[48:51], v[172:175], v[208:211], v[48:51]
	v_mfma_f32_16x16x32_bf16 v[36:39], v[164:167], v[216:219], v[36:39]
	v_mfma_f32_16x16x32_bf16 v[32:35], v[172:175], v[216:219], v[32:35]
	v_mfma_f32_16x16x32_bf16 v[20:23], v[164:167], v[224:227], v[20:23]
	v_mfma_f32_16x16x32_bf16 v[16:19], v[172:175], v[224:227], v[16:19]
	v_mfma_f32_16x16x32_bf16 v[44:47], v[176:179], v[196:199], 0
	v_mfma_f32_16x16x32_bf16 v[40:43], v[184:187], v[196:199], 0
	v_mfma_f32_16x16x32_bf16 v[28:31], v[176:179], v[204:207], 0
	v_mfma_f32_16x16x32_bf16 v[24:27], v[184:187], v[204:207], 0
	v_mfma_f32_16x16x32_bf16 v[12:15], v[176:179], v[212:215], 0
	v_mfma_f32_16x16x32_bf16 v[8:11], v[184:187], v[212:215], 0
	v_mfma_f32_16x16x32_bf16 v[4:7], v[176:179], v[220:223], 0
	v_mfma_f32_16x16x32_bf16 v[0:3], v[184:187], v[220:223], 0
	v_mfma_f32_16x16x32_bf16 v[44:47], v[180:183], v[200:203], v[44:47]
	v_mfma_f32_16x16x32_bf16 v[40:43], v[192:195], v[200:203], v[40:43]
	v_mfma_f32_16x16x32_bf16 v[28:31], v[180:183], v[208:211], v[28:31]
	v_mfma_f32_16x16x32_bf16 v[24:27], v[192:195], v[208:211], v[24:27]
	v_mfma_f32_16x16x32_bf16 v[12:15], v[180:183], v[216:219], v[12:15]
	v_mfma_f32_16x16x32_bf16 v[8:11], v[192:195], v[216:219], v[8:11]
	v_mfma_f32_16x16x32_bf16 v[4:7], v[180:183], v[224:227], v[4:7]
	v_mfma_f32_16x16x32_bf16 v[0:3], v[192:195], v[224:227], v[0:3]
	s_barrier
	s_add_i32 s34, 0, 0x18000
	v_add_u32_e32 v161, s34, v152
	s_add_i32 s55, 0, 0x1c000
	ds_read_b128 v[156:159], v161
	ds_read_b128 v[164:167], v161 offset:1024
	ds_read_b128 v[168:171], v161 offset:2048
	ds_read_b128 v[172:175], v161 offset:3072
	v_add_u32_e32 v161, s55, v152
	ds_read_b128 v[176:179], v161
	ds_read_b128 v[180:183], v161 offset:1024
	ds_read_b128 v[184:187], v161 offset:2048
	ds_read_b128 v[192:195], v161 offset:3072
	s_add_u32 s38, s44, 0x160000
	s_addc_u32 s39, s45, 0
	s_mov_b32 m0, s26
	v_lshl_add_u64 v[234:235], s[38:39], 0, v[130:131]
	ds_read_b128 v[196:199], v155 offset:32768
	ds_read_b128 v[200:203], v155 offset:33792
	ds_read_b128 v[204:207], v155 offset:34816
	ds_read_b128 v[208:211], v155 offset:35840
	ds_read_b128 v[212:215], v155 offset:36864
	ds_read_b128 v[216:219], v155 offset:37888
	ds_read_b128 v[220:223], v155 offset:38912
	ds_read_b128 v[224:227], v155 offset:39936
	global_load_lds_dwordx4 v[234:235], off
	v_lshl_add_u64 v[234:235], s[38:39], 0, v[134:135]
	s_mov_b32 m0, s27
	s_nop 0
	global_load_lds_dwordx4 v[234:235], off
	s_waitcnt vmcnt(8)
	s_waitcnt lgkmcnt(0)
	s_barrier
	s_waitcnt lgkmcnt(0)
	v_mfma_f32_16x16x32_bf16 v[124:127], v[156:159], v[196:199], v[124:127]
	v_mfma_f32_16x16x32_bf16 v[120:123], v[168:171], v[196:199], v[120:123]
	v_mfma_f32_16x16x32_bf16 v[116:119], v[156:159], v[204:207], v[116:119]
	v_mfma_f32_16x16x32_bf16 v[112:115], v[168:171], v[204:207], v[112:115]
	v_mfma_f32_16x16x32_bf16 v[100:103], v[156:159], v[212:215], v[100:103]
	v_mfma_f32_16x16x32_bf16 v[96:99], v[168:171], v[212:215], v[96:99]
	v_mfma_f32_16x16x32_bf16 v[84:87], v[156:159], v[220:223], v[84:87]
	v_mfma_f32_16x16x32_bf16 v[80:83], v[168:171], v[220:223], v[80:83]
	v_mfma_f32_16x16x32_bf16 v[124:127], v[164:167], v[200:203], v[124:127]
	v_mfma_f32_16x16x32_bf16 v[120:123], v[172:175], v[200:203], v[120:123]
	v_mfma_f32_16x16x32_bf16 v[116:119], v[164:167], v[208:211], v[116:119]
	v_mfma_f32_16x16x32_bf16 v[112:115], v[172:175], v[208:211], v[112:115]
	v_mfma_f32_16x16x32_bf16 v[100:103], v[164:167], v[216:219], v[100:103]
	v_mfma_f32_16x16x32_bf16 v[96:99], v[172:175], v[216:219], v[96:99]
	v_mfma_f32_16x16x32_bf16 v[84:87], v[164:167], v[224:227], v[84:87]
	v_mfma_f32_16x16x32_bf16 v[80:83], v[172:175], v[224:227], v[80:83]
	v_mfma_f32_16x16x32_bf16 v[108:111], v[176:179], v[196:199], v[108:111]
	v_mfma_f32_16x16x32_bf16 v[104:107], v[184:187], v[196:199], v[104:107]
	v_mfma_f32_16x16x32_bf16 v[92:95], v[176:179], v[204:207], v[92:95]
	v_mfma_f32_16x16x32_bf16 v[88:91], v[184:187], v[204:207], v[88:91]
	v_mfma_f32_16x16x32_bf16 v[76:79], v[176:179], v[212:215], v[76:79]
	v_mfma_f32_16x16x32_bf16 v[72:75], v[184:187], v[212:215], v[72:75]
	v_mfma_f32_16x16x32_bf16 v[68:71], v[176:179], v[220:223], v[68:71]
	v_mfma_f32_16x16x32_bf16 v[64:67], v[184:187], v[220:223], v[64:67]
	v_mfma_f32_16x16x32_bf16 v[108:111], v[180:183], v[200:203], v[108:111]
	v_mfma_f32_16x16x32_bf16 v[104:107], v[192:195], v[200:203], v[104:107]
	v_mfma_f32_16x16x32_bf16 v[92:95], v[180:183], v[208:211], v[92:95]
	v_mfma_f32_16x16x32_bf16 v[88:91], v[192:195], v[208:211], v[88:91]
	v_mfma_f32_16x16x32_bf16 v[76:79], v[180:183], v[216:219], v[76:79]
	v_mfma_f32_16x16x32_bf16 v[72:75], v[192:195], v[216:219], v[72:75]
	v_mfma_f32_16x16x32_bf16 v[68:71], v[180:183], v[224:227], v[68:71]
	v_mfma_f32_16x16x32_bf16 v[64:67], v[192:195], v[224:227], v[64:67]
	s_barrier
; #define PG8_STAGE(bufoff, gbase, voff) do { _Pragma("unroll") for (int _i = 0; _i < 2; ++_i) \
;         __builtin_amdgcn_global_load_lds((const unsigned*)((const char*)(gbase) + (voff)[_i]), (LAS unsigned*)(lds + (bufoff) + ldsw + _i * 8192), 16, 0, 0); } while (0)
; #define PG8_LDA(dst, b, h) do { _Pragma("unroll") for (int m = 0; m < 4; ++m) _Pragma("unroll") for (int k = 0; k < 2; ++k) dst[m][k] = *(const LAS bf16x8*)(lds + PG8_SA(b, h) + aoff + m * 2048 + k * 1024); } while (0)
; #define PG8_LDB(dst, b, h) do { _Pragma("unroll") for (int n = 0; n < 2; ++n) _Pragma("unroll") for (int k = 0; k < 2; ++k) dst[n][k] = *(const LAS bf16x8*)(lds + PG8_SB(b, h) + boff + n * 2048 + k * 1024); } while (0)
; #define PG8_MMA(ai, bj, At, Bt) do { __builtin_amdgcn_s_setprio(1); _Pragma("unroll") for (int m = 0; m < 4; ++m) _Pragma("unroll") for (int n = 0; n < 2; ++n) _Pragma("unroll") for (int k = 0; k < 2; ++k) \
;         acc[ai][bj][m][n] = __builtin_amdgcn_mfma_f32_16x16x32_bf16(Bt[n][k], At[m][k], acc[ai][bj][m][n], 0, 0, 0); __builtin_amdgcn_s_setprio(0); } while (0)
; #define PG8_WAIT_V(n) asm volatile("s_waitcnt vmcnt(" #n ")" ::: "memory")
; #define PG8_BAR __builtin_amdgcn_s_barrier()
; template <int GI>
; __device__ __forceinline__ void gemm_phase(LAS unsigned char* lds, unsigned char* ws, int G, int cblk) {
;     ...
;             PG8_LDB(B0, 0, 0); PG8_LDB(B1, 0, 1); PG8_SCHED; PG8_LDA(At, 0, 0); PG8_STAGE(PG8_SA(1, 1), a1 + hstepA, voffA);
;             PG8_WAIT_V(8); PG8_WAIT_L(0); PG8_BAR; PG8_MMA(0, 0, At, B0); PG8_MMA(0, 1, At, B1); PG8_BAR; PG8_SCHED;
;             PG8_LDA(At, 0, 1); PG8_STAGE(PG8_SB(0, 0), b2, voffB); PG8_STAGE(PG8_SB(0, 1), b2 + hstepB, voffB); PG8_STAGE(PG8_SA(0, 0), a2, voffA);
;             PG8_WAIT_V(8); PG8_WAIT_L(0); PG8_BAR; PG8_MMA(1, 0, At, B0); PG8_MMA(1, 1, At, B1); PG8_BAR; PG8_SCHED;
;             PG8_LDB(B0, 1, 0); PG8_LDB(B1, 1, 1); PG8_SCHED; PG8_LDA(At, 1, 0); PG8_STAGE(PG8_SA(0, 1), a2 + hstepA, voffA);
;             PG8_WAIT_V(8); PG8_WAIT_L(0); PG8_BAR; PG8_MMA(0, 0, At, B0); PG8_MMA(0, 1, At, B1); PG8_BAR; PG8_SCHED;
;             PG8_LDA(At, 1, 1); PG8_STAGE(PG8_SB(1, 0), b3, voffB); PG8_STAGE(PG8_SB(1, 1), b3 + hstepB, voffB); PG8_STAGE(PG8_SA(1, 0), a3, voffA);
;             PG8_WAIT_V(8); PG8_WAIT_L(0); PG8_BAR; PG8_MMA(1, 0, At, B0); PG8_MMA(1, 1, At, B1); PG8_BAR; PG8_SCHED;
;         }
	s_add_i32 s34, s34, s0
	v_lshl_add_u64 v[188:189], v[188:189], 0, s[10:11]
	s_mov_b32 m0, s34
	ds_read_b128 v[196:199], v155 offset:49152
	ds_read_b128 v[200:203], v155 offset:50176
	ds_read_b128 v[204:207], v155 offset:51200
	ds_read_b128 v[208:211], v155 offset:52224
	ds_read_b128 v[212:215], v155 offset:53248
	ds_read_b128 v[216:219], v155 offset:54272
	ds_read_b128 v[220:223], v155 offset:55296
	ds_read_b128 v[224:227], v155 offset:56320
	global_load_lds_dwordx4 v[188:189], off
	s_add_i32 m0, s34, 0x2000
	s_add_u32 s38, s42, 0x160080
	v_lshl_add_u64 v[188:189], v[228:229], 0, s[10:11]
	s_addc_u32 s39, s43, 0
	s_add_i32 s34, s55, s0
	global_load_lds_dwordx4 v[188:189], off
	v_lshl_add_u64 v[188:189], s[38:39], 0, v[132:133]
	s_mov_b32 m0, s34
	s_nop 0
	global_load_lds_dwordx4 v[188:189], off
	v_lshl_add_u64 v[188:189], s[38:39], 0, v[136:137]
	s_add_i32 m0, s34, 0x2000
	s_nop 0
	global_load_lds_dwordx4 v[188:189], off
	v_lshl_add_u64 v[188:189], v[230:231], 0, s[10:11]
	s_mov_b32 m0, s48
	s_nop 0
	global_load_lds_dwordx4 v[188:189], off
	v_lshl_add_u64 v[188:189], v[232:233], 0, s[10:11]
	s_mov_b32 m0, s49
	s_nop 0
	global_load_lds_dwordx4 v[188:189], off
	s_waitcnt vmcnt(8)
	s_waitcnt lgkmcnt(0)
	s_barrier
	s_waitcnt lgkmcnt(0)
	v_mfma_f32_16x16x32_bf16 v[60:63], v[156:159], v[196:199], v[60:63]
	v_mfma_f32_16x16x32_bf16 v[56:59], v[168:171], v[196:199], v[56:59]
	v_mfma_f32_16x16x32_bf16 v[52:55], v[156:159], v[204:207], v[52:55]
	v_mfma_f32_16x16x32_bf16 v[48:51], v[168:171], v[204:207], v[48:51]
	v_mfma_f32_16x16x32_bf16 v[36:39], v[156:159], v[212:215], v[36:39]
	v_mfma_f32_16x16x32_bf16 v[32:35], v[168:171], v[212:215], v[32:35]
	v_mfma_f32_16x16x32_bf16 v[20:23], v[156:159], v[220:223], v[20:23]
	v_mfma_f32_16x16x32_bf16 v[16:19], v[168:171], v[220:223], v[16:19]
	v_mfma_f32_16x16x32_bf16 v[60:63], v[164:167], v[200:203], v[60:63]
	v_mfma_f32_16x16x32_bf16 v[56:59], v[172:175], v[200:203], v[56:59]
	v_mfma_f32_16x16x32_bf16 v[52:55], v[164:167], v[208:211], v[52:55]
	v_mfma_f32_16x16x32_bf16 v[48:51], v[172:175], v[208:211], v[48:51]
	v_mfma_f32_16x16x32_bf16 v[36:39], v[164:167], v[216:219], v[36:39]
	v_mfma_f32_16x16x32_bf16 v[32:35], v[172:175], v[216:219], v[32:35]
	v_mfma_f32_16x16x32_bf16 v[20:23], v[164:167], v[224:227], v[20:23]
	v_mfma_f32_16x16x32_bf16 v[16:19], v[172:175], v[224:227], v[16:19]
	v_mfma_f32_16x16x32_bf16 v[44:47], v[176:179], v[196:199], v[44:47]
	v_mfma_f32_16x16x32_bf16 v[40:43], v[184:187], v[196:199], v[40:43]
	v_mfma_f32_16x16x32_bf16 v[28:31], v[176:179], v[204:207], v[28:31]
	v_mfma_f32_16x16x32_bf16 v[24:27], v[184:187], v[204:207], v[24:27]
	v_mfma_f32_16x16x32_bf16 v[12:15], v[176:179], v[212:215], v[12:15]
	v_mfma_f32_16x16x32_bf16 v[8:11], v[184:187], v[212:215], v[8:11]
	v_mfma_f32_16x16x32_bf16 v[4:7], v[176:179], v[220:223], v[4:7]
	v_mfma_f32_16x16x32_bf16 v[0:3], v[184:187], v[220:223], v[0:3]
	v_mfma_f32_16x16x32_bf16 v[44:47], v[180:183], v[200:203], v[44:47]
	v_mfma_f32_16x16x32_bf16 v[40:43], v[192:195], v[200:203], v[40:43]
	v_mfma_f32_16x16x32_bf16 v[28:31], v[180:183], v[208:211], v[28:31]
	v_mfma_f32_16x16x32_bf16 v[24:27], v[192:195], v[208:211], v[24:27]
	v_mfma_f32_16x16x32_bf16 v[12:15], v[180:183], v[216:219], v[12:15]
	v_mfma_f32_16x16x32_bf16 v[8:11], v[192:195], v[216:219], v[8:11]
	v_mfma_f32_16x16x32_bf16 v[4:7], v[180:183], v[224:227], v[4:7]
	v_mfma_f32_16x16x32_bf16 v[0:3], v[192:195], v[224:227], v[0:3]
	s_barrier
	s_add_i32 s54, s54, 2
	s_add_u32 s15, s15, 0x100
	s_addc_u32 s53, s53, 0
	s_cmpk_gt_u32 s54, 0x55
	s_mov_b64 s[38:39], s[40:41]
	s_cbranch_scc0 .LBB0_896
	s_branch .Lpeel_exit_9
.LBB0_896:
	ds_read_b128 v[156:159], v153
	ds_read_b128 v[164:167], v153 offset:1024
	ds_read_b128 v[168:171], v153 offset:2048
	ds_read_b128 v[172:175], v153 offset:3072
	ds_read_b128 v[176:179], v154
	ds_read_b128 v[180:183], v154 offset:1024
	ds_read_b128 v[184:187], v154 offset:2048
	ds_read_b128 v[192:195], v154 offset:3072
	s_add_u32 s40, s38, 0x100
	s_addc_u32 s41, s39, 0
	s_cmpk_eq_i32 s54, 0x54
	s_cselect_b32 s45, s21, s41
	s_cselect_b32 s44, s20, s40
	s_cselect_b32 s43, s23, s53
	s_cselect_b32 s42, s22, s15
	v_lshl_add_u64 v[188:189], s[38:39], 0, v[140:141]
	s_add_i32 m0, s24, 0xc000
	ds_read_b128 v[196:199], v155
	ds_read_b128 v[200:203], v155 offset:1024
	ds_read_b128 v[204:207], v155 offset:2048
	ds_read_b128 v[208:211], v155 offset:3072
	ds_read_b128 v[212:215], v155 offset:4096
	ds_read_b128 v[216:219], v155 offset:5120
	ds_read_b128 v[220:223], v155 offset:6144
	ds_read_b128 v[224:227], v155 offset:7168
	global_load_lds_dwordx4 v[188:189], off
	v_lshl_add_u64 v[188:189], s[38:39], 0, v[142:143]
	s_add_i32 m0, s24, 0xe000
	s_nop 0
	global_load_lds_dwordx4 v[188:189], off
	s_waitcnt vmcnt(8)
	s_waitcnt lgkmcnt(0)
	s_barrier
; #define PG8_STAGE(bufoff, gbase, voff) do { _Pragma("unroll") for (int _i = 0; _i < 2; ++_i) \
;         __builtin_amdgcn_global_load_lds((const unsigned*)((const char*)(gbase) + (voff)[_i]), (LAS unsigned*)(lds + (bufoff) + ldsw + _i * 8192), 16, 0, 0); } while (0)
; #define PG8_LDA(dst, b, h) do { _Pragma("unroll") for (int m = 0; m < 4; ++m) _Pragma("unroll") for (int k = 0; k < 2; ++k) dst[m][k] = *(const LAS bf16x8*)(lds + PG8_SA(b, h) + aoff + m * 2048 + k * 1024); } while (0)
; #define PG8_MMA(ai, bj, At, Bt) do { __builtin_amdgcn_s_setprio(1); _Pragma("unroll") for (int m = 0; m < 4; ++m) _Pragma("unroll") for (int n = 0; n < 2; ++n) _Pragma("unroll") for (int k = 0; k < 2; ++k) \
;         acc[ai][bj][m][n] = __builtin_amdgcn_mfma_f32_16x16x32_bf16(Bt[n][k], At[m][k], acc[ai][bj][m][n], 0, 0, 0); __builtin_amdgcn_s_setprio(0); } while (0)
; #define PG8_WAIT_V(n) asm volatile("s_waitcnt vmcnt(" #n ")" ::: "memory")
; #define PG8_WAIT_L(n) asm volatile("s_waitcnt lgkmcnt(" #n ")" ::: "memory")
; #define PG8_BAR __builtin_amdgcn_s_barrier()
; #define PG8_SCHED __builtin_amdgcn_sched_barrier(0)
; template <int GI>
; __device__ __forceinline__ void gemm_phase(LAS unsigned char* lds, unsigned char* ws, int G, int cblk) {
;     ...
;             PG8_WAIT_V(8); PG8_WAIT_L(0); PG8_BAR; PG8_MMA(0, 0, At, B0); PG8_MMA(0, 1, At, B1); PG8_BAR; PG8_SCHED;
;             PG8_LDA(At, 0, 1); PG8_STAGE(PG8_SB(0, 0), b2, voffB); PG8_STAGE(PG8_SB(0, 1), b2 + hstepB, voffB); PG8_STAGE(PG8_SA(0, 0), a2, voffA);
;             PG8_WAIT_V(8); PG8_WAIT_L(0); PG8_BAR; PG8_MMA(1, 0, At, B0); PG8_MMA(1, 1, At, B1); PG8_BAR; PG8_SCHED;
	s_waitcnt lgkmcnt(0)
	v_mfma_f32_16x16x32_bf16 v[124:127], v[156:159], v[196:199], v[124:127]
	v_mfma_f32_16x16x32_bf16 v[120:123], v[168:171], v[196:199], v[120:123]
	v_mfma_f32_16x16x32_bf16 v[116:119], v[156:159], v[204:207], v[116:119]
	v_mfma_f32_16x16x32_bf16 v[112:115], v[168:171], v[204:207], v[112:115]
	v_mfma_f32_16x16x32_bf16 v[100:103], v[156:159], v[212:215], v[100:103]
	v_mfma_f32_16x16x32_bf16 v[96:99], v[168:171], v[212:215], v[96:99]
	v_mfma_f32_16x16x32_bf16 v[84:87], v[156:159], v[220:223], v[84:87]
	v_mfma_f32_16x16x32_bf16 v[80:83], v[168:171], v[220:223], v[80:83]
	v_mfma_f32_16x16x32_bf16 v[124:127], v[164:167], v[200:203], v[124:127]
	v_mfma_f32_16x16x32_bf16 v[120:123], v[172:175], v[200:203], v[120:123]
	v_mfma_f32_16x16x32_bf16 v[116:119], v[164:167], v[208:211], v[116:119]
	v_mfma_f32_16x16x32_bf16 v[112:115], v[172:175], v[208:211], v[112:115]
	v_mfma_f32_16x16x32_bf16 v[100:103], v[164:167], v[216:219], v[100:103]
	v_mfma_f32_16x16x32_bf16 v[96:99], v[172:175], v[216:219], v[96:99]
	v_mfma_f32_16x16x32_bf16 v[84:87], v[164:167], v[224:227], v[84:87]
	v_mfma_f32_16x16x32_bf16 v[80:83], v[172:175], v[224:227], v[80:83]
	v_mfma_f32_16x16x32_bf16 v[108:111], v[176:179], v[196:199], v[108:111]
	v_mfma_f32_16x16x32_bf16 v[104:107], v[184:187], v[196:199], v[104:107]
	v_mfma_f32_16x16x32_bf16 v[92:95], v[176:179], v[204:207], v[92:95]
	v_mfma_f32_16x16x32_bf16 v[88:91], v[184:187], v[204:207], v[88:91]
	v_mfma_f32_16x16x32_bf16 v[76:79], v[176:179], v[212:215], v[76:79]
	v_mfma_f32_16x16x32_bf16 v[72:75], v[184:187], v[212:215], v[72:75]
	v_mfma_f32_16x16x32_bf16 v[68:71], v[176:179], v[220:223], v[68:71]
	v_mfma_f32_16x16x32_bf16 v[64:67], v[184:187], v[220:223], v[64:67]
	v_mfma_f32_16x16x32_bf16 v[108:111], v[180:183], v[200:203], v[108:111]
	v_mfma_f32_16x16x32_bf16 v[104:107], v[192:195], v[200:203], v[104:107]
	v_mfma_f32_16x16x32_bf16 v[92:95], v[180:183], v[208:211], v[92:95]
	v_mfma_f32_16x16x32_bf16 v[88:91], v[192:195], v[208:211], v[88:91]
	v_mfma_f32_16x16x32_bf16 v[76:79], v[180:183], v[216:219], v[76:79]
	v_mfma_f32_16x16x32_bf16 v[72:75], v[192:195], v[216:219], v[72:75]
	v_mfma_f32_16x16x32_bf16 v[68:71], v[180:183], v[224:227], v[68:71]
	v_mfma_f32_16x16x32_bf16 v[64:67], v[192:195], v[224:227], v[64:67]
	s_barrier
	s_add_i32 s34, s50, s0
	v_lshl_add_u64 v[188:189], s[42:43], 0, v[132:133]
	s_mov_b32 m0, s34
	ds_read_b128 v[196:199], v155 offset:16384
	ds_read_b128 v[200:203], v155 offset:17408
	ds_read_b128 v[204:207], v155 offset:18432
	ds_read_b128 v[208:211], v155 offset:19456
	ds_read_b128 v[212:215], v155 offset:20480
	ds_read_b128 v[216:219], v155 offset:21504
	ds_read_b128 v[220:223], v155 offset:22528
	ds_read_b128 v[224:227], v155 offset:23552
	global_load_lds_dwordx4 v[188:189], off
	s_add_i32 m0, s34, 0x2000
	s_add_u32 s38, s42, 0x160000
	v_lshl_add_u64 v[228:229], s[42:43], 0, v[136:137]
	s_addc_u32 s39, s43, 0
	s_add_i32 s34, s51, s0
	global_load_lds_dwordx4 v[228:229], off
	v_lshl_add_u64 v[230:231], s[38:39], 0, v[132:133]
	s_mov_b32 m0, s34
	v_lshl_add_u64 v[232:233], s[44:45], 0, v[134:135]
	global_load_lds_dwordx4 v[230:231], off
	v_lshl_add_u64 v[230:231], s[38:39], 0, v[136:137]
	s_add_i32 m0, s34, 0x2000
	s_nop 0
	global_load_lds_dwordx4 v[230:231], off
	v_lshl_add_u64 v[230:231], s[44:45], 0, v[130:131]
	s_mov_b32 m0, s24
	s_nop 0
	global_load_lds_dwordx4 v[230:231], off
	s_mov_b32 m0, s25
	s_nop 0
	global_load_lds_dwordx4 v[232:233], off
	s_waitcnt vmcnt(8)
	s_waitcnt lgkmcnt(0)
	s_barrier
	s_waitcnt lgkmcnt(0)
	v_mfma_f32_16x16x32_bf16 v[60:63], v[156:159], v[196:199], v[60:63]
	v_mfma_f32_16x16x32_bf16 v[56:59], v[168:171], v[196:199], v[56:59]
	v_mfma_f32_16x16x32_bf16 v[52:55], v[156:159], v[204:207], v[52:55]
	v_mfma_f32_16x16x32_bf16 v[48:51], v[168:171], v[204:207], v[48:51]
	v_mfma_f32_16x16x32_bf16 v[36:39], v[156:159], v[212:215], v[36:39]
	v_mfma_f32_16x16x32_bf16 v[32:35], v[168:171], v[212:215], v[32:35]
	v_mfma_f32_16x16x32_bf16 v[20:23], v[156:159], v[220:223], v[20:23]
	v_mfma_f32_16x16x32_bf16 v[16:19], v[168:171], v[220:223], v[16:19]
	v_mfma_f32_16x16x32_bf16 v[60:63], v[164:167], v[200:203], v[60:63]
	v_mfma_f32_16x16x32_bf16 v[56:59], v[172:175], v[200:203], v[56:59]
	v_mfma_f32_16x16x32_bf16 v[52:55], v[164:167], v[208:211], v[52:55]
	v_mfma_f32_16x16x32_bf16 v[48:51], v[172:175], v[208:211], v[48:51]
	v_mfma_f32_16x16x32_bf16 v[36:39], v[164:167], v[216:219], v[36:39]
	v_mfma_f32_16x16x32_bf16 v[32:35], v[172:175], v[216:219], v[32:35]
	v_mfma_f32_16x16x32_bf16 v[20:23], v[164:167], v[224:227], v[20:23]
	v_mfma_f32_16x16x32_bf16 v[16:19], v[172:175], v[224:227], v[16:19]
	v_mfma_f32_16x16x32_bf16 v[44:47], v[176:179], v[196:199], v[44:47]
	v_mfma_f32_16x16x32_bf16 v[40:43], v[184:187], v[196:199], v[40:43]
	v_mfma_f32_16x16x32_bf16 v[28:31], v[176:179], v[204:207], v[28:31]
	v_mfma_f32_16x16x32_bf16 v[24:27], v[184:187], v[204:207], v[24:27]
	v_mfma_f32_16x16x32_bf16 v[12:15], v[176:179], v[212:215], v[12:15]
	v_mfma_f32_16x16x32_bf16 v[8:11], v[184:187], v[212:215], v[8:11]
	v_mfma_f32_16x16x32_bf16 v[4:7], v[176:179], v[220:223], v[4:7]
	v_mfma_f32_16x16x32_bf16 v[0:3], v[184:187], v[220:223], v[0:3]
	v_mfma_f32_16x16x32_bf16 v[44:47], v[180:183], v[200:203], v[44:47]
	v_mfma_f32_16x16x32_bf16 v[40:43], v[192:195], v[200:203], v[40:43]
	v_mfma_f32_16x16x32_bf16 v[28:31], v[180:183], v[208:211], v[28:31]
	v_mfma_f32_16x16x32_bf16 v[24:27], v[192:195], v[208:211], v[24:27]
	v_mfma_f32_16x16x32_bf16 v[12:15], v[180:183], v[216:219], v[12:15]
	v_mfma_f32_16x16x32_bf16 v[8:11], v[192:195], v[216:219], v[8:11]
	v_mfma_f32_16x16x32_bf16 v[4:7], v[180:183], v[224:227], v[4:7]
	v_mfma_f32_16x16x32_bf16 v[0:3], v[192:195], v[224:227], v[0:3]
	s_barrier
; #define PG8_STAGE(bufoff, gbase, voff) do { _Pragma("unroll") for (int _i = 0; _i < 2; ++_i) \
;         __builtin_amdgcn_global_load_lds((const unsigned*)((const char*)(gbase) + (voff)[_i]), (LAS unsigned*)(lds + (bufoff) + ldsw + _i * 8192), 16, 0, 0); } while (0)
; #define PG8_LDA(dst, b, h) do { _Pragma("unroll") for (int m = 0; m < 4; ++m) _Pragma("unroll") for (int k = 0; k < 2; ++k) dst[m][k] = *(const LAS bf16x8*)(lds + PG8_SA(b, h) + aoff + m * 2048 + k * 1024); } while (0)
; #define PG8_LDB(dst, b, h) do { _Pragma("unroll") for (int n = 0; n < 2; ++n) _Pragma("unroll") for (int k = 0; k < 2; ++k) dst[n][k] = *(const LAS bf16x8*)(lds + PG8_SB(b, h) + boff + n * 2048 + k * 1024); } while (0)
; #define PG8_MMA(ai, bj, At, Bt) do { __builtin_amdgcn_s_setprio(1); _Pragma("unroll") for (int m = 0; m < 4; ++m) _Pragma("unroll") for (int n = 0; n < 2; ++n) _Pragma("unroll") for (int k = 0; k < 2; ++k) \
;         acc[ai][bj][m][n] = __builtin_amdgcn_mfma_f32_16x16x32_bf16(Bt[n][k], At[m][k], acc[ai][bj][m][n], 0, 0, 0); __builtin_amdgcn_s_setprio(0); } while (0)
; #define PG8_WAIT_V(n) asm volatile("s_waitcnt vmcnt(" #n ")" ::: "memory")
; #define PG8_WAIT_L(n) asm volatile("s_waitcnt lgkmcnt(" #n ")" ::: "memory")
; #define PG8_BAR __builtin_amdgcn_s_barrier()
; #define PG8_SCHED __builtin_amdgcn_sched_barrier(0)
; template <int GI>
; __device__ __forceinline__ void gemm_phase(LAS unsigned char* lds, unsigned char* ws, int G, int cblk) {
;     ...
;             PG8_LDB(B0, 1, 0); PG8_LDB(B1, 1, 1); PG8_SCHED; PG8_LDA(At, 1, 0); PG8_STAGE(PG8_SA(0, 1), a2 + hstepA, voffA);
;             PG8_WAIT_V(8); PG8_WAIT_L(0); PG8_BAR; PG8_MMA(0, 0, At, B0); PG8_MMA(0, 1, At, B1); PG8_BAR; PG8_SCHED;
;             PG8_LDA(At, 1, 1); PG8_STAGE(PG8_SB(1, 0), b3, voffB); PG8_STAGE(PG8_SB(1, 1), b3 + hstepB, voffB); PG8_STAGE(PG8_SA(1, 0), a3, voffA);
;             PG8_WAIT_V(8); PG8_WAIT_L(0); PG8_BAR; PG8_MMA(1, 0, At, B0); PG8_MMA(1, 1, At, B1); PG8_BAR; PG8_SCHED;
;         }
	s_add_i32 s34, 0, 0x18000
	v_add_u32_e32 v161, s34, v152
	s_add_i32 s55, 0, 0x1c000
	ds_read_b128 v[156:159], v161
	ds_read_b128 v[164:167], v161 offset:1024
	ds_read_b128 v[168:171], v161 offset:2048
	ds_read_b128 v[172:175], v161 offset:3072
	v_add_u32_e32 v161, s55, v152
	ds_read_b128 v[176:179], v161
	ds_read_b128 v[180:183], v161 offset:1024
	ds_read_b128 v[184:187], v161 offset:2048
	ds_read_b128 v[192:195], v161 offset:3072
	s_add_u32 s38, s44, 0x160000
	s_addc_u32 s39, s45, 0
	s_mov_b32 m0, s26
	v_lshl_add_u64 v[234:235], s[38:39], 0, v[130:131]
	ds_read_b128 v[196:199], v155 offset:32768
	ds_read_b128 v[200:203], v155 offset:33792
	ds_read_b128 v[204:207], v155 offset:34816
	ds_read_b128 v[208:211], v155 offset:35840
	ds_read_b128 v[212:215], v155 offset:36864
	ds_read_b128 v[216:219], v155 offset:37888
	ds_read_b128 v[220:223], v155 offset:38912
	ds_read_b128 v[224:227], v155 offset:39936
	global_load_lds_dwordx4 v[234:235], off
	v_lshl_add_u64 v[234:235], s[38:39], 0, v[134:135]
	s_mov_b32 m0, s27
	s_nop 0
	global_load_lds_dwordx4 v[234:235], off
	s_waitcnt vmcnt(8)
	s_waitcnt lgkmcnt(0)
	s_barrier
	s_waitcnt lgkmcnt(0)
	v_mfma_f32_16x16x32_bf16 v[124:127], v[156:159], v[196:199], v[124:127]
	v_mfma_f32_16x16x32_bf16 v[120:123], v[168:171], v[196:199], v[120:123]
	v_mfma_f32_16x16x32_bf16 v[116:119], v[156:159], v[204:207], v[116:119]
	v_mfma_f32_16x16x32_bf16 v[112:115], v[168:171], v[204:207], v[112:115]
	v_mfma_f32_16x16x32_bf16 v[100:103], v[156:159], v[212:215], v[100:103]
	v_mfma_f32_16x16x32_bf16 v[96:99], v[168:171], v[212:215], v[96:99]
	v_mfma_f32_16x16x32_bf16 v[84:87], v[156:159], v[220:223], v[84:87]
	v_mfma_f32_16x16x32_bf16 v[80:83], v[168:171], v[220:223], v[80:83]
	v_mfma_f32_16x16x32_bf16 v[124:127], v[164:167], v[200:203], v[124:127]
	v_mfma_f32_16x16x32_bf16 v[120:123], v[172:175], v[200:203], v[120:123]
	v_mfma_f32_16x16x32_bf16 v[116:119], v[164:167], v[208:211], v[116:119]
	v_mfma_f32_16x16x32_bf16 v[112:115], v[172:175], v[208:211], v[112:115]
	v_mfma_f32_16x16x32_bf16 v[100:103], v[164:167], v[216:219], v[100:103]
	v_mfma_f32_16x16x32_bf16 v[96:99], v[172:175], v[216:219], v[96:99]
	v_mfma_f32_16x16x32_bf16 v[84:87], v[164:167], v[224:227], v[84:87]
	v_mfma_f32_16x16x32_bf16 v[80:83], v[172:175], v[224:227], v[80:83]
	v_mfma_f32_16x16x32_bf16 v[108:111], v[176:179], v[196:199], v[108:111]
	v_mfma_f32_16x16x32_bf16 v[104:107], v[184:187], v[196:199], v[104:107]
	v_mfma_f32_16x16x32_bf16 v[92:95], v[176:179], v[204:207], v[92:95]
	v_mfma_f32_16x16x32_bf16 v[88:91], v[184:187], v[204:207], v[88:91]
	v_mfma_f32_16x16x32_bf16 v[76:79], v[176:179], v[212:215], v[76:79]
	v_mfma_f32_16x16x32_bf16 v[72:75], v[184:187], v[212:215], v[72:75]
	v_mfma_f32_16x16x32_bf16 v[68:71], v[176:179], v[220:223], v[68:71]
	v_mfma_f32_16x16x32_bf16 v[64:67], v[184:187], v[220:223], v[64:67]
	v_mfma_f32_16x16x32_bf16 v[108:111], v[180:183], v[200:203], v[108:111]
	v_mfma_f32_16x16x32_bf16 v[104:107], v[192:195], v[200:203], v[104:107]
	v_mfma_f32_16x16x32_bf16 v[92:95], v[180:183], v[208:211], v[92:95]
	v_mfma_f32_16x16x32_bf16 v[88:91], v[192:195], v[208:211], v[88:91]
	v_mfma_f32_16x16x32_bf16 v[76:79], v[180:183], v[216:219], v[76:79]
	v_mfma_f32_16x16x32_bf16 v[72:75], v[192:195], v[216:219], v[72:75]
	v_mfma_f32_16x16x32_bf16 v[68:71], v[180:183], v[224:227], v[68:71]
	v_mfma_f32_16x16x32_bf16 v[64:67], v[192:195], v[224:227], v[64:67]
	s_barrier
	s_add_i32 s34, s34, s0
	v_lshl_add_u64 v[188:189], v[188:189], 0, s[10:11]
	s_mov_b32 m0, s34
	ds_read_b128 v[196:199], v155 offset:49152
	ds_read_b128 v[200:203], v155 offset:50176
	ds_read_b128 v[204:207], v155 offset:51200
	ds_read_b128 v[208:211], v155 offset:52224
	ds_read_b128 v[212:215], v155 offset:53248
	ds_read_b128 v[216:219], v155 offset:54272
	ds_read_b128 v[220:223], v155 offset:55296
	ds_read_b128 v[224:227], v155 offset:56320
	global_load_lds_dwordx4 v[188:189], off
	s_add_i32 m0, s34, 0x2000
	s_add_u32 s38, s42, 0x160080
	v_lshl_add_u64 v[188:189], v[228:229], 0, s[10:11]
	s_addc_u32 s39, s43, 0
	s_add_i32 s34, s55, s0
	global_load_lds_dwordx4 v[188:189], off
	v_lshl_add_u64 v[188:189], s[38:39], 0, v[132:133]
	s_mov_b32 m0, s34
	s_nop 0
	global_load_lds_dwordx4 v[188:189], off
	v_lshl_add_u64 v[188:189], s[38:39], 0, v[136:137]
	s_add_i32 m0, s34, 0x2000
	s_nop 0
	global_load_lds_dwordx4 v[188:189], off
	v_lshl_add_u64 v[188:189], v[230:231], 0, s[10:11]
	s_mov_b32 m0, s48
	s_nop 0
	global_load_lds_dwordx4 v[188:189], off
	v_lshl_add_u64 v[188:189], v[232:233], 0, s[10:11]
	s_mov_b32 m0, s49
	s_nop 0
	global_load_lds_dwordx4 v[188:189], off
	s_waitcnt vmcnt(8)
	s_waitcnt lgkmcnt(0)
	s_barrier
	s_waitcnt lgkmcnt(0)
	v_mfma_f32_16x16x32_bf16 v[60:63], v[156:159], v[196:199], v[60:63]
	v_mfma_f32_16x16x32_bf16 v[56:59], v[168:171], v[196:199], v[56:59]
	v_mfma_f32_16x16x32_bf16 v[52:55], v[156:159], v[204:207], v[52:55]
	v_mfma_f32_16x16x32_bf16 v[48:51], v[168:171], v[204:207], v[48:51]
	v_mfma_f32_16x16x32_bf16 v[36:39], v[156:159], v[212:215], v[36:39]
	v_mfma_f32_16x16x32_bf16 v[32:35], v[168:171], v[212:215], v[32:35]
	v_mfma_f32_16x16x32_bf16 v[20:23], v[156:159], v[220:223], v[20:23]
	v_mfma_f32_16x16x32_bf16 v[16:19], v[168:171], v[220:223], v[16:19]
	v_mfma_f32_16x16x32_bf16 v[60:63], v[164:167], v[200:203], v[60:63]
	v_mfma_f32_16x16x32_bf16 v[56:59], v[172:175], v[200:203], v[56:59]
	v_mfma_f32_16x16x32_bf16 v[52:55], v[164:167], v[208:211], v[52:55]
	v_mfma_f32_16x16x32_bf16 v[48:51], v[172:175], v[208:211], v[48:51]
	v_mfma_f32_16x16x32_bf16 v[36:39], v[164:167], v[216:219], v[36:39]
	v_mfma_f32_16x16x32_bf16 v[32:35], v[172:175], v[216:219], v[32:35]
	v_mfma_f32_16x16x32_bf16 v[20:23], v[164:167], v[224:227], v[20:23]
	v_mfma_f32_16x16x32_bf16 v[16:19], v[172:175], v[224:227], v[16:19]
	v_mfma_f32_16x16x32_bf16 v[44:47], v[176:179], v[196:199], v[44:47]
	v_mfma_f32_16x16x32_bf16 v[40:43], v[184:187], v[196:199], v[40:43]
	v_mfma_f32_16x16x32_bf16 v[28:31], v[176:179], v[204:207], v[28:31]
	v_mfma_f32_16x16x32_bf16 v[24:27], v[184:187], v[204:207], v[24:27]
	v_mfma_f32_16x16x32_bf16 v[12:15], v[176:179], v[212:215], v[12:15]
	v_mfma_f32_16x16x32_bf16 v[8:11], v[184:187], v[212:215], v[8:11]
	v_mfma_f32_16x16x32_bf16 v[4:7], v[176:179], v[220:223], v[4:7]
	v_mfma_f32_16x16x32_bf16 v[0:3], v[184:187], v[220:223], v[0:3]
	v_mfma_f32_16x16x32_bf16 v[44:47], v[180:183], v[200:203], v[44:47]
	v_mfma_f32_16x16x32_bf16 v[40:43], v[192:195], v[200:203], v[40:43]
	v_mfma_f32_16x16x32_bf16 v[28:31], v[180:183], v[208:211], v[28:31]
	v_mfma_f32_16x16x32_bf16 v[24:27], v[192:195], v[208:211], v[24:27]
	v_mfma_f32_16x16x32_bf16 v[12:15], v[180:183], v[216:219], v[12:15]
	v_mfma_f32_16x16x32_bf16 v[8:11], v[192:195], v[216:219], v[8:11]
	v_mfma_f32_16x16x32_bf16 v[4:7], v[180:183], v[224:227], v[4:7]
	v_mfma_f32_16x16x32_bf16 v[0:3], v[192:195], v[224:227], v[0:3]
	s_barrier
	s_add_i32 s54, s54, 2
	s_add_u32 s15, s15, 0x100
	s_addc_u32 s53, s53, 0
	s_cmpk_gt_u32 s54, 0x55
	s_mov_b64 s[38:39], s[40:41]
	s_cbranch_scc0 .LBB0_896
